# nt (streaming) cache hint on the once-read paged K/V cache loads of the decode
# speedup vs baseline: 1.0371x; 1.0371x over previous
; __device__ __forceinline__ float bf2f(bf16_t b) { return __uint_as_float(((unsigned)b) << 16); }
; template <int NB>
; __device__ __forceinline__ void sb_decode_task(const Params& P, float* lds, int task) {
;     const int tid = threadIdx.x, lane = tid & 63, wave = tid >> 6;
;     const bf16_t* qb = (const bf16_t*)(P.ws + WS_QB);
;     float* dpart = (float*)(P.ws + WS_DPART); float* dl = (float*)(P.ws + WS_DL);
;     float* zl = lds + DEC_LDS_OFF / 4 + wave * 256; float* wl = zl + 128;
;     const int c = lane & 15, g = lane >> 4;
;     constexpr int NBT = 32 / NB;
;     const int h = task % SH, bj = task / SH, b = bj / NPAGES;
;     const int page = P.page_table[bj];
;     const float* Kp = P.cache_k + ((size_t)page * PAGE * SH + h) * HD + 4 * c;
;     const float* Vp = P.cache_v + ((size_t)page * PAGE * SH + h) * HD + 4 * c;
;     const bf16_t* qp = qb + (size_t)(NTOK + b) * SBW + h * 64 + 4 * c;
;     const float q0 = bf2f(qp[0]), q1 = bf2f(qp[1]), q2 = bf2f(qp[2]), q3 = bf2f(qp[3]);
;     const float bias = P.sb_bias[h] * LOG2E;
;     float4 cur[NB], nx[NB];
; #pragma unroll
;     for (int i = 0; i < NB; ++i) cur[i] = *(const float4*)(Kp + (size_t)(4 * i + g) * (SH * HD));
; #pragma unroll
;     for (int kb = 0; kb < NBT; ++kb) {
;         const float* np = (kb + 1 < NBT) ? Kp + (size_t)(4 * NB * (kb + 1)) * (SH * HD) : Vp;
; #pragma unroll
;         for (int i = 0; i < NB; ++i) nx[i] = *(const float4*)(np + (size_t)(4 * i + g) * (SH * HD));
; #pragma unroll
;         for (int i = 0; i < NB; ++i) { const int s = 4 * NB * kb + 4 * i + g;
;             float part = q0 * cur[i].x + q1 * cur[i].y + q2 * cur[i].z + q3 * cur[i].w; part = sum16(part);
;             if (c == 0) zl[s] = part + bias; }
; #pragma unroll
;         for (int i = 0; i < NB; ++i) cur[i] = nx[i];
.LBB0_956:
	s_or_b64 exec, exec, s[0:1]
	v_readlane_b32 s36, v252, 48
	v_readlane_b32 s37, v252, 49
	s_mul_hi_i32 s1, s34, 0x2aaaaaab
	s_load_dwordx16 s[56:71], s[36:37], 0x0
	s_lshr_b32 s3, s1, 31
	s_add_i32 s0, s1, s3
	s_ashr_i32 s1, s1, 7
	s_mul_i32 s2, s0, 6
	s_add_i32 s33, s1, s3
	s_ashr_i32 s1, s0, 31
	s_sub_i32 s2, s34, s2
	s_lshl_b64 s[0:1], s[0:1], 2
	s_waitcnt lgkmcnt(0)
	s_add_u32 s0, s66, s0
	s_addc_u32 s1, s67, s1
	global_load_dword v2, v83, s[0:1]
	s_add_i32 s0, s33, 0x4000
	s_ashr_i32 s3, s2, 31
	s_mul_hi_i32 s1, s0, 0x300
	s_mulk_i32 s0, 0x300
	s_add_u32 s33, s38, s0
	s_addc_u32 s35, s39, s1
	s_lshl_b32 s0, s2, 6
	s_ashr_i32 s1, s0, 31
	s_lshl_b64 s[0:1], s[0:1], 1
	s_add_u32 s0, s33, s0
	s_addc_u32 s1, s35, s1
	v_readlane_b32 s56, v252, 16
	v_readlane_b32 s57, v252, 17
	v_readlane_b32 s64, v252, 24
	v_readlane_b32 s65, v252, 25
	s_mov_b64 s[56:57], s[64:65]
	v_mov_b32_e32 v91, v83
	v_readlane_b32 s58, v252, 18
	v_readlane_b32 s59, v252, 19
	v_readlane_b32 s60, v252, 20
	v_readlane_b32 s61, v252, 21
	v_readlane_b32 s62, v252, 22
	v_readlane_b32 s63, v252, 23
	v_readlane_b32 s66, v252, 26
	v_readlane_b32 s67, v252, 27
	v_readlane_b32 s68, v252, 28
	v_readlane_b32 s69, v252, 29
	v_readlane_b32 s70, v252, 30
	v_readlane_b32 s71, v252, 31
	s_waitcnt vmcnt(0)
	v_mul_hi_i32 v3, v2, s42
	v_mul_lo_u32 v2, v2, s42
	v_lshl_add_u64 v[92:93], v[2:3], 0, s[2:3]
	v_lshlrev_b64 v[2:3], 8, v[92:93]
	v_lshl_add_u64 v[66:67], v[84:85], 0, v[2:3]
	global_load_dwordx2 v[2:3], v99, s[0:1]
	s_lshl_b64 s[0:1], s[2:3], 2
	s_add_u32 s0, s56, s0
	s_addc_u32 s1, s57, s1
	global_load_dword v22, v83, s[0:1]
	v_lshl_add_u64 v[18:19], v[66:67], 0, v[82:83]
	v_lshl_add_u64 v[20:21], v[66:67], 0, v[90:91]
	global_load_dwordx4 v[14:17], v[18:19], off nt
	global_load_dwordx4 v[62:65], v[20:21], off nt
	s_waitcnt vmcnt(3)
	v_lshlrev_b32_e32 v105, 16, v2
	v_and_b32_e32 v107, 0xffff0000, v2
	v_add_co_u32_e32 v2, vcc, s44, v18
	v_lshlrev_b32_e32 v106, 16, v3
	v_and_b32_e32 v104, 0xffff0000, v3
	v_addc_co_u32_e32 v3, vcc, 0, v19, vcc
	global_load_dwordx4 v[10:13], v[2:3], off offset:2048 nt
	v_add_co_u32_e32 v2, vcc, s45, v18
	s_waitcnt vmcnt(3)
	v_mul_f32_e32 v108, 0x3fb8aa3b, v22
	v_addc_co_u32_e32 v3, vcc, 0, v19, vcc
	global_load_dwordx4 v[6:9], v[2:3], off nt
	v_add_co_u32_e32 v2, vcc, s43, v18
	v_lshl_add_u64 v[22:23], v[66:67], 0, s[26:27]
	s_nop 0
	v_addc_co_u32_e32 v3, vcc, 0, v19, vcc
	v_add_co_u32_e32 v20, vcc, s46, v18
	v_lshl_add_u64 v[30:31], v[22:23], 0, v[82:83]
	s_nop 0
	v_addc_co_u32_e32 v21, vcc, 0, v19, vcc
	global_load_dwordx4 v[58:61], v[20:21], off offset:2048 nt
	v_add_co_u32_e32 v20, vcc, s47, v18
	v_lshl_add_u64 v[22:23], v[22:23], 0, v[90:91]
	s_nop 0
	v_addc_co_u32_e32 v21, vcc, 0, v19, vcc
	v_add_co_u32_e32 v18, vcc, s48, v18
	global_load_dwordx4 v[54:57], v[20:21], off nt
	s_nop 0
	v_addc_co_u32_e32 v19, vcc, 0, v19, vcc
	global_load_dwordx4 v[50:53], v[18:19], off offset:2048 nt
	v_add_co_u32_e32 v18, vcc, s44, v30
	global_load_dwordx4 v[22:25], v[22:23], off nt
	s_nop 0
	v_addc_co_u32_e32 v19, vcc, 0, v31, vcc
	global_load_dwordx4 v[34:37], v[18:19], off offset:2048 nt
	v_add_co_u32_e32 v18, vcc, s45, v30
	global_load_dwordx4 v[2:5], v[2:3], off offset:2048 nt
	s_nop 0
	v_addc_co_u32_e32 v19, vcc, 0, v31, vcc
	global_load_dwordx4 v[26:29], v[18:19], off nt
	v_add_co_u32_e32 v18, vcc, s43, v30
	global_load_dwordx4 v[46:49], v[30:31], off nt
	s_nop 0
	v_addc_co_u32_e32 v19, vcc, 0, v31, vcc
	v_add_co_u32_e32 v32, vcc, s46, v30
	global_load_dwordx4 v[18:21], v[18:19], off offset:2048 nt
	s_nop 0
	v_addc_co_u32_e32 v33, vcc, 0, v31, vcc
	global_load_dwordx4 v[38:41], v[32:33], off offset:2048 nt
	v_add_co_u32_e32 v32, vcc, s47, v30
	s_waitcnt vmcnt(13)
	v_mul_f32_e32 v15, v15, v107
	v_addc_co_u32_e32 v33, vcc, 0, v31, vcc
	v_add_co_u32_e32 v30, vcc, s48, v30
	global_load_dwordx4 v[42:45], v[32:33], off nt
	s_nop 0
	v_addc_co_u32_e32 v31, vcc, 0, v31, vcc
	global_load_dwordx4 v[30:33], v[30:31], off offset:2048 nt
	v_fmac_f32_e32 v15, v14, v105
	v_fmac_f32_e32 v15, v16, v106
	v_fmac_f32_e32 v15, v17, v104
	s_nop 1
	v_add_f32_dpp v14, v15, v15 quad_perm:[1,0,3,2] row_mask:0xf bank_mask:0xf bound_ctrl:1
	s_nop 1
	v_add_f32_dpp v14, v14, v14 quad_perm:[2,3,0,1] row_mask:0xf bank_mask:0xf bound_ctrl:1
	s_nop 1
	v_add_f32_dpp v14, v14, v14 row_ror:4 row_mask:0xf bank_mask:0xf bound_ctrl:1
	s_nop 1
	v_mov_b32_dpp v15, v14 row_ror:8 row_mask:0xf bank_mask:0xf bound_ctrl:1
	s_and_saveexec_b64 s[0:1], s[6:7]
	v_add_f32_e32 v14, v14, v15
	v_add_f32_e32 v14, v108, v14
	ds_write_b32 v96, v14
	s_or_b64 exec, exec, s[0:1]
	s_waitcnt vmcnt(13)
	v_mul_f32_e32 v11, v11, v107
	v_fmac_f32_e32 v11, v10, v105
	v_fmac_f32_e32 v11, v12, v106
	v_fmac_f32_e32 v11, v13, v104
	s_nop 1
	v_add_f32_dpp v10, v11, v11 quad_perm:[1,0,3,2] row_mask:0xf bank_mask:0xf bound_ctrl:1
	s_nop 1
	v_add_f32_dpp v10, v10, v10 quad_perm:[2,3,0,1] row_mask:0xf bank_mask:0xf bound_ctrl:1
	s_nop 1
	v_add_f32_dpp v10, v10, v10 row_ror:4 row_mask:0xf bank_mask:0xf bound_ctrl:1
	s_nop 1
	v_mov_b32_dpp v11, v10 row_ror:8 row_mask:0xf bank_mask:0xf bound_ctrl:1
	s_and_saveexec_b64 s[0:1], s[6:7]
	v_add_f32_e32 v10, v10, v11
	v_add_f32_e32 v10, v108, v10
	ds_write_b32 v96, v10 offset:16
	s_or_b64 exec, exec, s[0:1]
	s_waitcnt vmcnt(12)
	v_mul_f32_e32 v7, v7, v107
	v_fmac_f32_e32 v7, v6, v105
	v_fmac_f32_e32 v7, v8, v106
	v_fmac_f32_e32 v7, v9, v104
	s_nop 1
	v_add_f32_dpp v6, v7, v7 quad_perm:[1,0,3,2] row_mask:0xf bank_mask:0xf bound_ctrl:1
	s_nop 1
	v_add_f32_dpp v6, v6, v6 quad_perm:[2,3,0,1] row_mask:0xf bank_mask:0xf bound_ctrl:1
	s_nop 1
	v_add_f32_dpp v6, v6, v6 row_ror:4 row_mask:0xf bank_mask:0xf bound_ctrl:1
	s_nop 1
	v_mov_b32_dpp v7, v6 row_ror:8 row_mask:0xf bank_mask:0xf bound_ctrl:1
	s_and_saveexec_b64 s[0:1], s[6:7]
	v_add_f32_e32 v6, v6, v7
	v_add_f32_e32 v6, v108, v6
	ds_write_b32 v96, v6 offset:32
	s_or_b64 exec, exec, s[0:1]
	s_waitcnt vmcnt(6)
; template <int NB>
; __device__ __forceinline__ void sb_decode_task(const Params& P, float* lds, int task) {
;     ...
;     for (int i = 0; i < NB; ++i) cur[i] = *(const float4*)(Kp + (size_t)(4 * i + g) * (SH * HD));
; #pragma unroll
;     for (int kb = 0; kb < NBT; ++kb) {
;         const float* np = (kb + 1 < NBT) ? Kp + (size_t)(4 * NB * (kb + 1)) * (SH * HD) : Vp;
; #pragma unroll
;         for (int i = 0; i < NB; ++i) nx[i] = *(const float4*)(np + (size_t)(4 * i + g) * (SH * HD));
; #pragma unroll
;         for (int i = 0; i < NB; ++i) { const int s = 4 * NB * kb + 4 * i + g;
;             float part = q0 * cur[i].x + q1 * cur[i].y + q2 * cur[i].z + q3 * cur[i].w; part = sum16(part);
;             if (c == 0) zl[s] = part + bias; }
; #pragma unroll
;         for (int i = 0; i < NB; ++i) cur[i] = nx[i];
	v_mul_f32_e32 v3, v3, v107
	v_fmac_f32_e32 v3, v2, v105
	v_fmac_f32_e32 v3, v4, v106
	v_fmac_f32_e32 v3, v5, v104
	s_nop 1
	v_add_f32_dpp v2, v3, v3 quad_perm:[1,0,3,2] row_mask:0xf bank_mask:0xf bound_ctrl:1
	s_nop 1
	v_add_f32_dpp v2, v2, v2 quad_perm:[2,3,0,1] row_mask:0xf bank_mask:0xf bound_ctrl:1
	s_nop 1
	v_add_f32_dpp v2, v2, v2 row_ror:4 row_mask:0xf bank_mask:0xf bound_ctrl:1
	s_nop 1
	v_mov_b32_dpp v3, v2 row_ror:8 row_mask:0xf bank_mask:0xf bound_ctrl:1
	s_and_saveexec_b64 s[0:1], s[6:7]
	v_add_f32_e32 v2, v2, v3
	v_add_f32_e32 v2, v108, v2
	ds_write_b32 v96, v2 offset:48
	s_or_b64 exec, exec, s[0:1]
	v_mul_f32_e32 v2, v63, v107
	v_fmac_f32_e32 v2, v62, v105
	v_fmac_f32_e32 v2, v64, v106
	v_fmac_f32_e32 v2, v65, v104
	s_nop 1
	v_add_f32_dpp v2, v2, v2 quad_perm:[1,0,3,2] row_mask:0xf bank_mask:0xf bound_ctrl:1
	s_nop 1
	v_add_f32_dpp v2, v2, v2 quad_perm:[2,3,0,1] row_mask:0xf bank_mask:0xf bound_ctrl:1
	s_nop 1
	v_add_f32_dpp v2, v2, v2 row_ror:4 row_mask:0xf bank_mask:0xf bound_ctrl:1
	s_nop 1
	v_mov_b32_dpp v3, v2 row_ror:8 row_mask:0xf bank_mask:0xf bound_ctrl:1
	s_and_saveexec_b64 s[0:1], s[6:7]
	v_add_f32_e32 v2, v2, v3
	v_add_f32_e32 v2, v108, v2
	ds_write_b32 v96, v2 offset:64
	s_or_b64 exec, exec, s[0:1]
	v_mul_f32_e32 v2, v59, v107
	v_fmac_f32_e32 v2, v58, v105
	v_fmac_f32_e32 v2, v60, v106
	v_fmac_f32_e32 v2, v61, v104
	s_nop 1
	v_add_f32_dpp v2, v2, v2 quad_perm:[1,0,3,2] row_mask:0xf bank_mask:0xf bound_ctrl:1
	s_nop 1
	v_add_f32_dpp v2, v2, v2 quad_perm:[2,3,0,1] row_mask:0xf bank_mask:0xf bound_ctrl:1
	s_nop 1
	v_add_f32_dpp v2, v2, v2 row_ror:4 row_mask:0xf bank_mask:0xf bound_ctrl:1
	s_nop 1
	v_mov_b32_dpp v3, v2 row_ror:8 row_mask:0xf bank_mask:0xf bound_ctrl:1
	s_and_saveexec_b64 s[0:1], s[6:7]
	v_add_f32_e32 v2, v2, v3
	v_add_f32_e32 v2, v108, v2
	ds_write_b32 v96, v2 offset:80
	s_or_b64 exec, exec, s[0:1]
	v_mul_f32_e32 v2, v55, v107
	v_fmac_f32_e32 v2, v54, v105
	v_fmac_f32_e32 v2, v56, v106
	v_fmac_f32_e32 v2, v57, v104
	s_nop 1
	v_add_f32_dpp v2, v2, v2 quad_perm:[1,0,3,2] row_mask:0xf bank_mask:0xf bound_ctrl:1
	s_nop 1
	v_add_f32_dpp v2, v2, v2 quad_perm:[2,3,0,1] row_mask:0xf bank_mask:0xf bound_ctrl:1
	s_nop 1
	v_add_f32_dpp v2, v2, v2 row_ror:4 row_mask:0xf bank_mask:0xf bound_ctrl:1
	s_nop 1
	v_mov_b32_dpp v3, v2 row_ror:8 row_mask:0xf bank_mask:0xf bound_ctrl:1
	s_and_saveexec_b64 s[0:1], s[6:7]
	v_add_f32_e32 v2, v2, v3
	v_add_f32_e32 v2, v108, v2
	ds_write_b32 v96, v2 offset:96
	s_or_b64 exec, exec, s[0:1]
	v_mul_f32_e32 v2, v51, v107
	v_fmac_f32_e32 v2, v50, v105
	v_fmac_f32_e32 v2, v52, v106
	v_fmac_f32_e32 v2, v53, v104
	s_nop 1
	v_add_f32_dpp v2, v2, v2 quad_perm:[1,0,3,2] row_mask:0xf bank_mask:0xf bound_ctrl:1
	s_nop 1
	v_add_f32_dpp v2, v2, v2 quad_perm:[2,3,0,1] row_mask:0xf bank_mask:0xf bound_ctrl:1
	s_nop 1
	v_add_f32_dpp v2, v2, v2 row_ror:4 row_mask:0xf bank_mask:0xf bound_ctrl:1
	s_nop 1
	v_mov_b32_dpp v3, v2 row_ror:8 row_mask:0xf bank_mask:0xf bound_ctrl:1
	s_and_saveexec_b64 s[0:1], s[6:7]
	v_add_f32_e32 v2, v2, v3
	v_add_f32_e32 v2, v108, v2
	ds_write_b32 v96, v2 offset:112
	s_or_b64 exec, exec, s[0:1]
	v_lshl_add_u64 v[2:3], v[66:67], 0, s[28:29]
	v_lshl_add_u64 v[4:5], v[2:3], 0, v[82:83]
	v_add_co_u32_e32 v6, vcc, 0x1000, v4
	v_mov_b32_e32 v91, v83
	s_nop 0
	v_addc_co_u32_e32 v7, vcc, 0, v5, vcc
	global_load_dwordx4 v[78:81], v[4:5], off nt
	global_load_dwordx4 v[70:73], v[6:7], off offset:2048 nt
	v_add_co_u32_e32 v6, vcc, 0x3000, v4
	v_lshl_add_u64 v[2:3], v[2:3], 0, v[90:91]
	s_nop 0
	v_addc_co_u32_e32 v7, vcc, 0, v5, vcc
	v_add_co_u32_e32 v8, vcc, s43, v4
	s_waitcnt vmcnt(6)
	v_mul_f32_e32 v47, v47, v107
	v_addc_co_u32_e32 v9, vcc, 0, v5, vcc
	global_load_dwordx4 v[62:65], v[6:7], off nt
	global_load_dwordx4 v[54:57], v[8:9], off offset:2048 nt
	v_add_co_u32_e32 v6, vcc, 0x7000, v4
	v_fmac_f32_e32 v47, v46, v105
	s_nop 0
	v_addc_co_u32_e32 v7, vcc, 0, v5, vcc
	global_load_dwordx4 v[14:17], v[2:3], off nt
	global_load_dwordx4 v[10:13], v[6:7], off offset:2048 nt
	v_add_co_u32_e32 v2, vcc, 0x9000, v4
	v_fmac_f32_e32 v47, v48, v106
	s_nop 0
	v_addc_co_u32_e32 v3, vcc, 0, v5, vcc
	v_add_co_u32_e32 v4, vcc, 0xa000, v4
	v_fmac_f32_e32 v47, v49, v104
	s_nop 0
	v_addc_co_u32_e32 v5, vcc, 0, v5, vcc
	global_load_dwordx4 v[6:9], v[2:3], off nt
	s_nop 0
	global_load_dwordx4 v[2:5], v[4:5], off offset:2048 nt
	v_add_f32_dpp v46, v47, v47 quad_perm:[1,0,3,2] row_mask:0xf bank_mask:0xf bound_ctrl:1
	s_nop 1
	v_add_f32_dpp v46, v46, v46 quad_perm:[2,3,0,1] row_mask:0xf bank_mask:0xf bound_ctrl:1
	s_nop 1
	v_add_f32_dpp v46, v46, v46 row_ror:4 row_mask:0xf bank_mask:0xf bound_ctrl:1
	s_nop 1
	v_mov_b32_dpp v47, v46 row_ror:8 row_mask:0xf bank_mask:0xf bound_ctrl:1
	s_and_saveexec_b64 s[0:1], s[6:7]
	v_add_f32_e32 v46, v46, v47
	v_add_f32_e32 v46, v108, v46
	ds_write_b32 v96, v46 offset:128
	s_or_b64 exec, exec, s[0:1]
	v_mul_f32_e32 v35, v35, v107
	v_fmac_f32_e32 v35, v34, v105
	v_fmac_f32_e32 v35, v36, v106
	v_fmac_f32_e32 v35, v37, v104
	s_nop 1
	v_add_f32_dpp v34, v35, v35 quad_perm:[1,0,3,2] row_mask:0xf bank_mask:0xf bound_ctrl:1
	s_nop 1
	v_add_f32_dpp v34, v34, v34 quad_perm:[2,3,0,1] row_mask:0xf bank_mask:0xf bound_ctrl:1
	s_nop 1
	v_add_f32_dpp v34, v34, v34 row_ror:4 row_mask:0xf bank_mask:0xf bound_ctrl:1
	s_nop 1
	v_mov_b32_dpp v35, v34 row_ror:8 row_mask:0xf bank_mask:0xf bound_ctrl:1
	s_and_saveexec_b64 s[0:1], s[6:7]
	v_add_f32_e32 v34, v34, v35
	v_add_f32_e32 v34, v108, v34
	ds_write_b32 v96, v34 offset:144
	s_or_b64 exec, exec, s[0:1]
	v_mul_f32_e32 v27, v27, v107
	v_fmac_f32_e32 v27, v26, v105
	v_fmac_f32_e32 v27, v28, v106
	v_fmac_f32_e32 v27, v29, v104
	s_nop 1
	v_add_f32_dpp v26, v27, v27 quad_perm:[1,0,3,2] row_mask:0xf bank_mask:0xf bound_ctrl:1
	s_nop 1
	v_add_f32_dpp v26, v26, v26 quad_perm:[2,3,0,1] row_mask:0xf bank_mask:0xf bound_ctrl:1
	s_nop 1
	v_add_f32_dpp v26, v26, v26 row_ror:4 row_mask:0xf bank_mask:0xf bound_ctrl:1
	s_nop 1
	v_mov_b32_dpp v27, v26 row_ror:8 row_mask:0xf bank_mask:0xf bound_ctrl:1
	s_and_saveexec_b64 s[0:1], s[6:7]
	v_add_f32_e32 v26, v26, v27
	v_add_f32_e32 v26, v108, v26
	ds_write_b32 v96, v26 offset:160
	s_or_b64 exec, exec, s[0:1]
	s_waitcnt vmcnt(11)
; template <int NB>
; __device__ __forceinline__ void sb_decode_task(const Params& P, float* lds, int task) {
;     ...
;     for (int i = 0; i < NB; ++i) cur[i] = *(const float4*)(Kp + (size_t)(4 * i + g) * (SH * HD));
; #pragma unroll
;     for (int kb = 0; kb < NBT; ++kb) {
;         const float* np = (kb + 1 < NBT) ? Kp + (size_t)(4 * NB * (kb + 1)) * (SH * HD) : Vp;
; #pragma unroll
;         for (int i = 0; i < NB; ++i) nx[i] = *(const float4*)(np + (size_t)(4 * i + g) * (SH * HD));
; #pragma unroll
;         for (int i = 0; i < NB; ++i) { const int s = 4 * NB * kb + 4 * i + g;
;             float part = q0 * cur[i].x + q1 * cur[i].y + q2 * cur[i].z + q3 * cur[i].w; part = sum16(part);
;             if (c == 0) zl[s] = part + bias; }
; #pragma unroll
;         for (int i = 0; i < NB; ++i) cur[i] = nx[i];
	v_mul_f32_e32 v19, v19, v107
	v_fmac_f32_e32 v19, v18, v105
	v_fmac_f32_e32 v19, v20, v106
	v_fmac_f32_e32 v19, v21, v104
	s_nop 1
	v_add_f32_dpp v18, v19, v19 quad_perm:[1,0,3,2] row_mask:0xf bank_mask:0xf bound_ctrl:1
	s_nop 1
	v_add_f32_dpp v18, v18, v18 quad_perm:[2,3,0,1] row_mask:0xf bank_mask:0xf bound_ctrl:1
	s_nop 1
	v_add_f32_dpp v18, v18, v18 row_ror:4 row_mask:0xf bank_mask:0xf bound_ctrl:1
	s_nop 1
	v_mov_b32_dpp v19, v18 row_ror:8 row_mask:0xf bank_mask:0xf bound_ctrl:1
	s_and_saveexec_b64 s[0:1], s[6:7]
	v_add_f32_e32 v18, v18, v19
	v_add_f32_e32 v18, v108, v18
	ds_write_b32 v96, v18 offset:176
	s_or_b64 exec, exec, s[0:1]
	v_mul_f32_e32 v18, v23, v107
	v_fmac_f32_e32 v18, v22, v105
	v_fmac_f32_e32 v18, v24, v106
	v_fmac_f32_e32 v18, v25, v104
	s_nop 1
	v_add_f32_dpp v18, v18, v18 quad_perm:[1,0,3,2] row_mask:0xf bank_mask:0xf bound_ctrl:1
	s_nop 1
	v_add_f32_dpp v18, v18, v18 quad_perm:[2,3,0,1] row_mask:0xf bank_mask:0xf bound_ctrl:1
	s_nop 1
	v_add_f32_dpp v18, v18, v18 row_ror:4 row_mask:0xf bank_mask:0xf bound_ctrl:1
	s_nop 1
	v_mov_b32_dpp v19, v18 row_ror:8 row_mask:0xf bank_mask:0xf bound_ctrl:1
	s_and_saveexec_b64 s[0:1], s[6:7]
	v_add_f32_e32 v18, v18, v19
	v_add_f32_e32 v18, v108, v18
	ds_write_b32 v96, v18 offset:192
	s_or_b64 exec, exec, s[0:1]
	s_waitcnt vmcnt(10)
	v_mul_f32_e32 v18, v39, v107
	v_fmac_f32_e32 v18, v38, v105
	v_fmac_f32_e32 v18, v40, v106
	v_fmac_f32_e32 v18, v41, v104
	s_nop 1
	v_add_f32_dpp v18, v18, v18 quad_perm:[1,0,3,2] row_mask:0xf bank_mask:0xf bound_ctrl:1
	s_nop 1
	v_add_f32_dpp v18, v18, v18 quad_perm:[2,3,0,1] row_mask:0xf bank_mask:0xf bound_ctrl:1
	s_nop 1
	v_add_f32_dpp v18, v18, v18 row_ror:4 row_mask:0xf bank_mask:0xf bound_ctrl:1
	s_nop 1
	v_mov_b32_dpp v19, v18 row_ror:8 row_mask:0xf bank_mask:0xf bound_ctrl:1
	s_and_saveexec_b64 s[0:1], s[6:7]
	v_add_f32_e32 v18, v18, v19
	v_add_f32_e32 v18, v108, v18
	ds_write_b32 v96, v18 offset:208
	s_or_b64 exec, exec, s[0:1]
	s_waitcnt vmcnt(9)
	v_mul_f32_e32 v18, v43, v107
	v_fmac_f32_e32 v18, v42, v105
	v_fmac_f32_e32 v18, v44, v106
	v_fmac_f32_e32 v18, v45, v104
	s_nop 1
	v_add_f32_dpp v18, v18, v18 quad_perm:[1,0,3,2] row_mask:0xf bank_mask:0xf bound_ctrl:1
	s_nop 1
	v_add_f32_dpp v18, v18, v18 quad_perm:[2,3,0,1] row_mask:0xf bank_mask:0xf bound_ctrl:1
	s_nop 1
	v_add_f32_dpp v18, v18, v18 row_ror:4 row_mask:0xf bank_mask:0xf bound_ctrl:1
	s_nop 1
	v_mov_b32_dpp v19, v18 row_ror:8 row_mask:0xf bank_mask:0xf bound_ctrl:1
	s_and_saveexec_b64 s[0:1], s[6:7]
	v_add_f32_e32 v18, v18, v19
	v_add_f32_e32 v18, v108, v18
	ds_write_b32 v96, v18 offset:224
	s_or_b64 exec, exec, s[0:1]
	s_waitcnt vmcnt(8)
	v_mul_f32_e32 v18, v31, v107
	v_fmac_f32_e32 v18, v30, v105
	v_fmac_f32_e32 v18, v32, v106
	v_fmac_f32_e32 v18, v33, v104
	s_nop 1
	v_add_f32_dpp v18, v18, v18 quad_perm:[1,0,3,2] row_mask:0xf bank_mask:0xf bound_ctrl:1
	s_nop 1
	v_add_f32_dpp v18, v18, v18 quad_perm:[2,3,0,1] row_mask:0xf bank_mask:0xf bound_ctrl:1
	s_nop 1
	v_add_f32_dpp v18, v18, v18 row_ror:4 row_mask:0xf bank_mask:0xf bound_ctrl:1
	s_nop 1
	v_mov_b32_dpp v19, v18 row_ror:8 row_mask:0xf bank_mask:0xf bound_ctrl:1
	s_and_saveexec_b64 s[0:1], s[6:7]
	v_add_f32_e32 v18, v18, v19
	v_add_f32_e32 v18, v108, v18
	ds_write_b32 v96, v18 offset:240
	s_or_b64 exec, exec, s[0:1]
	v_lshl_add_u64 v[18:19], v[66:67], 0, s[30:31]
	v_lshl_add_u64 v[20:21], v[18:19], 0, v[82:83]
	v_add_co_u32_e32 v22, vcc, 0x1000, v20
	v_mov_b32_e32 v91, v83
	s_nop 0
	v_addc_co_u32_e32 v23, vcc, 0, v21, vcc
	global_load_dwordx4 v[74:77], v[20:21], off nt
	global_load_dwordx4 v[66:69], v[22:23], off offset:2048 nt
	v_add_co_u32_e32 v22, vcc, 0x3000, v20
	v_lshl_add_u64 v[18:19], v[18:19], 0, v[90:91]
	s_nop 0
	v_addc_co_u32_e32 v23, vcc, 0, v21, vcc
	v_add_co_u32_e32 v24, vcc, s43, v20
	s_nop 1
	v_addc_co_u32_e32 v25, vcc, 0, v21, vcc
	global_load_dwordx4 v[58:61], v[22:23], off nt
	global_load_dwordx4 v[50:53], v[24:25], off offset:2048 nt
	v_add_co_u32_e32 v22, vcc, 0x7000, v20
	s_nop 1
	v_addc_co_u32_e32 v23, vcc, 0, v21, vcc
	global_load_dwordx4 v[46:49], v[18:19], off nt
	global_load_dwordx4 v[42:45], v[22:23], off offset:2048 nt
	v_add_co_u32_e32 v18, vcc, 0x9000, v20
	s_nop 1
	v_addc_co_u32_e32 v19, vcc, 0, v21, vcc
	v_add_co_u32_e32 v20, vcc, 0xa000, v20
	s_nop 1
	v_addc_co_u32_e32 v21, vcc, 0, v21, vcc
	global_load_dwordx4 v[38:41], v[18:19], off nt
	global_load_dwordx4 v[34:37], v[20:21], off offset:2048 nt
	s_waitcnt vmcnt(15)
	v_mul_f32_e32 v18, v79, v107
	v_fmac_f32_e32 v18, v78, v105
	v_fmac_f32_e32 v18, v80, v106
	v_fmac_f32_e32 v18, v81, v104
	s_nop 1
	v_add_f32_dpp v18, v18, v18 quad_perm:[1,0,3,2] row_mask:0xf bank_mask:0xf bound_ctrl:1
	s_nop 1
	v_add_f32_dpp v18, v18, v18 quad_perm:[2,3,0,1] row_mask:0xf bank_mask:0xf bound_ctrl:1
	s_nop 1
	v_add_f32_dpp v18, v18, v18 row_ror:4 row_mask:0xf bank_mask:0xf bound_ctrl:1
	s_nop 1
	v_mov_b32_dpp v19, v18 row_ror:8 row_mask:0xf bank_mask:0xf bound_ctrl:1
	s_and_saveexec_b64 s[0:1], s[6:7]
	v_add_f32_e32 v18, v18, v19
	v_add_f32_e32 v18, v108, v18
	ds_write_b32 v96, v18 offset:256
	s_or_b64 exec, exec, s[0:1]
	s_waitcnt vmcnt(14)
	v_mul_f32_e32 v18, v71, v107
	v_fmac_f32_e32 v18, v70, v105
	v_fmac_f32_e32 v18, v72, v106
	v_fmac_f32_e32 v18, v73, v104
	s_nop 1
	v_add_f32_dpp v18, v18, v18 quad_perm:[1,0,3,2] row_mask:0xf bank_mask:0xf bound_ctrl:1
	s_nop 1
	v_add_f32_dpp v18, v18, v18 quad_perm:[2,3,0,1] row_mask:0xf bank_mask:0xf bound_ctrl:1
	s_nop 1
	v_add_f32_dpp v18, v18, v18 row_ror:4 row_mask:0xf bank_mask:0xf bound_ctrl:1
	s_nop 1
	v_mov_b32_dpp v19, v18 row_ror:8 row_mask:0xf bank_mask:0xf bound_ctrl:1
	s_and_saveexec_b64 s[0:1], s[6:7]
	v_add_f32_e32 v18, v18, v19
	v_add_f32_e32 v18, v108, v18
	ds_write_b32 v96, v18 offset:272
	s_or_b64 exec, exec, s[0:1]
	s_waitcnt vmcnt(13)
; template <int NB>
; __device__ __forceinline__ void sb_decode_task(const Params& P, float* lds, int task) {
;     ...
;     for (int i = 0; i < NB; ++i) cur[i] = *(const float4*)(Kp + (size_t)(4 * i + g) * (SH * HD));
; #pragma unroll
;     for (int kb = 0; kb < NBT; ++kb) {
;         const float* np = (kb + 1 < NBT) ? Kp + (size_t)(4 * NB * (kb + 1)) * (SH * HD) : Vp;
; #pragma unroll
;         for (int i = 0; i < NB; ++i) nx[i] = *(const float4*)(np + (size_t)(4 * i + g) * (SH * HD));
; #pragma unroll
;         for (int i = 0; i < NB; ++i) { const int s = 4 * NB * kb + 4 * i + g;
;             float part = q0 * cur[i].x + q1 * cur[i].y + q2 * cur[i].z + q3 * cur[i].w; part = sum16(part);
;             if (c == 0) zl[s] = part + bias; }
; #pragma unroll
;         for (int i = 0; i < NB; ++i) cur[i] = nx[i];
	v_mul_f32_e32 v18, v63, v107
	v_fmac_f32_e32 v18, v62, v105
	v_fmac_f32_e32 v18, v64, v106
	v_fmac_f32_e32 v18, v65, v104
	s_nop 1
	v_add_f32_dpp v18, v18, v18 quad_perm:[1,0,3,2] row_mask:0xf bank_mask:0xf bound_ctrl:1
	s_nop 1
	v_add_f32_dpp v18, v18, v18 quad_perm:[2,3,0,1] row_mask:0xf bank_mask:0xf bound_ctrl:1
	s_nop 1
	v_add_f32_dpp v18, v18, v18 row_ror:4 row_mask:0xf bank_mask:0xf bound_ctrl:1
	s_nop 1
	v_mov_b32_dpp v19, v18 row_ror:8 row_mask:0xf bank_mask:0xf bound_ctrl:1
	s_and_saveexec_b64 s[0:1], s[6:7]
	v_add_f32_e32 v18, v18, v19
	v_add_f32_e32 v18, v108, v18
	ds_write_b32 v96, v18 offset:288
	s_or_b64 exec, exec, s[0:1]
	s_waitcnt vmcnt(12)
	v_mul_f32_e32 v18, v55, v107
	v_fmac_f32_e32 v18, v54, v105
	v_fmac_f32_e32 v18, v56, v106
	v_fmac_f32_e32 v18, v57, v104
	s_nop 1
	v_add_f32_dpp v18, v18, v18 quad_perm:[1,0,3,2] row_mask:0xf bank_mask:0xf bound_ctrl:1
	s_nop 1
	v_add_f32_dpp v18, v18, v18 quad_perm:[2,3,0,1] row_mask:0xf bank_mask:0xf bound_ctrl:1
	s_nop 1
	v_add_f32_dpp v18, v18, v18 row_ror:4 row_mask:0xf bank_mask:0xf bound_ctrl:1
	s_nop 1
	v_mov_b32_dpp v19, v18 row_ror:8 row_mask:0xf bank_mask:0xf bound_ctrl:1
	s_and_saveexec_b64 s[0:1], s[6:7]
	v_add_f32_e32 v18, v18, v19
	v_add_f32_e32 v18, v108, v18
	ds_write_b32 v96, v18 offset:304
	s_or_b64 exec, exec, s[0:1]
	s_waitcnt vmcnt(11)
	v_mul_f32_e32 v15, v15, v107
	v_fmac_f32_e32 v15, v14, v105
	v_fmac_f32_e32 v15, v16, v106
	v_fmac_f32_e32 v15, v17, v104
	s_nop 1
	v_add_f32_dpp v14, v15, v15 quad_perm:[1,0,3,2] row_mask:0xf bank_mask:0xf bound_ctrl:1
	s_nop 1
	v_add_f32_dpp v14, v14, v14 quad_perm:[2,3,0,1] row_mask:0xf bank_mask:0xf bound_ctrl:1
	s_nop 1
	v_add_f32_dpp v14, v14, v14 row_ror:4 row_mask:0xf bank_mask:0xf bound_ctrl:1
	s_nop 1
	v_mov_b32_dpp v15, v14 row_ror:8 row_mask:0xf bank_mask:0xf bound_ctrl:1
	s_and_saveexec_b64 s[0:1], s[6:7]
	v_add_f32_e32 v14, v14, v15
	v_add_f32_e32 v14, v108, v14
	ds_write_b32 v96, v14 offset:320
	s_or_b64 exec, exec, s[0:1]
	s_waitcnt vmcnt(10)
	v_mul_f32_e32 v11, v11, v107
	v_fmac_f32_e32 v11, v10, v105
	v_fmac_f32_e32 v11, v12, v106
	v_fmac_f32_e32 v11, v13, v104
	s_nop 1
	v_add_f32_dpp v10, v11, v11 quad_perm:[1,0,3,2] row_mask:0xf bank_mask:0xf bound_ctrl:1
	s_nop 1
	v_add_f32_dpp v10, v10, v10 quad_perm:[2,3,0,1] row_mask:0xf bank_mask:0xf bound_ctrl:1
	s_nop 1
	v_add_f32_dpp v10, v10, v10 row_ror:4 row_mask:0xf bank_mask:0xf bound_ctrl:1
	s_nop 1
	v_mov_b32_dpp v11, v10 row_ror:8 row_mask:0xf bank_mask:0xf bound_ctrl:1
	s_and_saveexec_b64 s[0:1], s[6:7]
	v_add_f32_e32 v10, v10, v11
	v_add_f32_e32 v10, v108, v10
	ds_write_b32 v96, v10 offset:336
	s_or_b64 exec, exec, s[0:1]
	s_waitcnt vmcnt(9)
	v_mul_f32_e32 v7, v7, v107
	v_fmac_f32_e32 v7, v6, v105
	v_fmac_f32_e32 v7, v8, v106
	v_fmac_f32_e32 v7, v9, v104
	s_nop 1
	v_add_f32_dpp v6, v7, v7 quad_perm:[1,0,3,2] row_mask:0xf bank_mask:0xf bound_ctrl:1
	s_nop 1
	v_add_f32_dpp v6, v6, v6 quad_perm:[2,3,0,1] row_mask:0xf bank_mask:0xf bound_ctrl:1
	s_nop 1
	v_add_f32_dpp v6, v6, v6 row_ror:4 row_mask:0xf bank_mask:0xf bound_ctrl:1
	s_nop 1
	v_mov_b32_dpp v7, v6 row_ror:8 row_mask:0xf bank_mask:0xf bound_ctrl:1
	s_and_saveexec_b64 s[0:1], s[6:7]
	v_add_f32_e32 v6, v6, v7
	v_add_f32_e32 v6, v108, v6
	ds_write_b32 v96, v6 offset:352
	s_or_b64 exec, exec, s[0:1]
	s_waitcnt vmcnt(8)
	v_mul_f32_e32 v3, v3, v107
	v_fmac_f32_e32 v3, v2, v105
	v_fmac_f32_e32 v3, v4, v106
	v_fmac_f32_e32 v3, v5, v104
	s_nop 1
	v_add_f32_dpp v2, v3, v3 quad_perm:[1,0,3,2] row_mask:0xf bank_mask:0xf bound_ctrl:1
	s_nop 1
	v_add_f32_dpp v2, v2, v2 quad_perm:[2,3,0,1] row_mask:0xf bank_mask:0xf bound_ctrl:1
	s_nop 1
	v_add_f32_dpp v2, v2, v2 row_ror:4 row_mask:0xf bank_mask:0xf bound_ctrl:1
	s_nop 1
	v_mov_b32_dpp v3, v2 row_ror:8 row_mask:0xf bank_mask:0xf bound_ctrl:1
	s_and_saveexec_b64 s[0:1], s[6:7]
	v_add_f32_e32 v2, v2, v3
	v_add_f32_e32 v2, v108, v2
	ds_write_b32 v96, v2 offset:368
	s_or_b64 exec, exec, s[0:1]
	v_lshlrev_b64 v[2:3], 6, v[92:93]
	v_lshl_add_u64 v[6:7], v[2:3], 2, v[86:87]
	v_lshl_add_u64 v[54:55], v[6:7], 0, v[82:83]
	v_add_co_u32_e32 v2, vcc, 0x1000, v54
	v_mov_b32_e32 v91, v83
	s_nop 0
	v_addc_co_u32_e32 v3, vcc, 0, v55, vcc
	v_add_co_u32_e32 v8, vcc, 0x3000, v54
	v_lshl_add_u64 v[10:11], v[6:7], 0, v[90:91]
	s_nop 0
	v_addc_co_u32_e32 v9, vcc, 0, v55, vcc
	v_add_co_u32_e32 v14, vcc, s43, v54
	global_load_dwordx4 v[30:33], v[54:55], off nt
	s_nop 0
	global_load_dwordx4 v[2:5], v[2:3], off offset:2048 nt
	v_addc_co_u32_e32 v15, vcc, 0, v55, vcc
	v_add_co_u32_e32 v18, vcc, 0x7000, v54
	global_load_dwordx4 v[6:9], v[8:9], off nt
	s_nop 0
	global_load_dwordx4 v[10:13], v[10:11], off nt
	v_addc_co_u32_e32 v19, vcc, 0, v55, vcc
	v_add_co_u32_e32 v22, vcc, 0x9000, v54
	global_load_dwordx4 v[14:17], v[14:15], off offset:2048 nt
	s_nop 0
	global_load_dwordx4 v[18:21], v[18:19], off offset:2048 nt
	v_addc_co_u32_e32 v23, vcc, 0, v55, vcc
	v_add_co_u32_e32 v26, vcc, 0xa000, v54
	s_waitcnt vmcnt(13)
	v_mul_f32_e32 v56, v75, v107
	v_addc_co_u32_e32 v27, vcc, 0, v55, vcc
	global_load_dwordx4 v[22:25], v[22:23], off nt
	s_nop 0
	global_load_dwordx4 v[26:29], v[26:27], off offset:2048 nt
	v_fmac_f32_e32 v56, v74, v105
	v_fmac_f32_e32 v56, v76, v106
	v_fmac_f32_e32 v56, v77, v104
	s_nop 1
	v_add_f32_dpp v56, v56, v56 quad_perm:[1,0,3,2] row_mask:0xf bank_mask:0xf bound_ctrl:1
	s_nop 1
	v_add_f32_dpp v56, v56, v56 quad_perm:[2,3,0,1] row_mask:0xf bank_mask:0xf bound_ctrl:1
	s_nop 1
	v_add_f32_dpp v56, v56, v56 row_ror:4 row_mask:0xf bank_mask:0xf bound_ctrl:1
	s_nop 1
	v_mov_b32_dpp v57, v56 row_ror:8 row_mask:0xf bank_mask:0xf bound_ctrl:1
	s_and_saveexec_b64 s[0:1], s[6:7]
	v_add_f32_e32 v56, v56, v57
	v_add_f32_e32 v56, v108, v56
	ds_write_b32 v96, v56 offset:384
	s_or_b64 exec, exec, s[0:1]
	s_waitcnt vmcnt(14)
; template <int NB>
; __device__ __forceinline__ void sb_decode_task(const Params& P, float* lds, int task) {
;     ...
;         for (int i = 0; i < NB; ++i) { const int s = 4 * NB * kb + 4 * i + g;
;             float part = q0 * cur[i].x + q1 * cur[i].y + q2 * cur[i].z + q3 * cur[i].w; part = sum16(part);
;             if (c == 0) zl[s] = part + bias; }
; #pragma unroll
;         for (int i = 0; i < NB; ++i) cur[i] = nx[i];
;     }
;     asm volatile("s_waitcnt lgkmcnt(0)" ::: "memory");
;     __builtin_amdgcn_wave_barrier();
;     const float z0 = zl[2 * lane], z1 = zl[2 * lane + 1];
	v_mul_f32_e32 v56, v67, v107
	v_fmac_f32_e32 v56, v66, v105
	v_fmac_f32_e32 v56, v68, v106
	v_fmac_f32_e32 v56, v69, v104
	s_nop 1
	v_add_f32_dpp v56, v56, v56 quad_perm:[1,0,3,2] row_mask:0xf bank_mask:0xf bound_ctrl:1
	s_nop 1
	v_add_f32_dpp v56, v56, v56 quad_perm:[2,3,0,1] row_mask:0xf bank_mask:0xf bound_ctrl:1
	s_nop 1
	v_add_f32_dpp v56, v56, v56 row_ror:4 row_mask:0xf bank_mask:0xf bound_ctrl:1
	s_nop 1
	v_mov_b32_dpp v57, v56 row_ror:8 row_mask:0xf bank_mask:0xf bound_ctrl:1
	s_and_saveexec_b64 s[0:1], s[6:7]
	v_add_f32_e32 v56, v56, v57
	v_add_f32_e32 v56, v108, v56
	ds_write_b32 v96, v56 offset:400
	s_or_b64 exec, exec, s[0:1]
	s_waitcnt vmcnt(13)
	v_mul_f32_e32 v56, v59, v107
	v_fmac_f32_e32 v56, v58, v105
	v_fmac_f32_e32 v56, v60, v106
	v_fmac_f32_e32 v56, v61, v104
	s_nop 1
	v_add_f32_dpp v56, v56, v56 quad_perm:[1,0,3,2] row_mask:0xf bank_mask:0xf bound_ctrl:1
	s_nop 1
	v_add_f32_dpp v56, v56, v56 quad_perm:[2,3,0,1] row_mask:0xf bank_mask:0xf bound_ctrl:1
	s_nop 1
	v_add_f32_dpp v56, v56, v56 row_ror:4 row_mask:0xf bank_mask:0xf bound_ctrl:1
	s_nop 1
	v_mov_b32_dpp v57, v56 row_ror:8 row_mask:0xf bank_mask:0xf bound_ctrl:1
	s_and_saveexec_b64 s[0:1], s[6:7]
	v_add_f32_e32 v56, v56, v57
	v_add_f32_e32 v56, v108, v56
	ds_write_b32 v96, v56 offset:416
	s_or_b64 exec, exec, s[0:1]
	s_waitcnt vmcnt(12)
	v_mul_f32_e32 v51, v51, v107
	v_fmac_f32_e32 v51, v50, v105
	v_fmac_f32_e32 v51, v52, v106
	v_fmac_f32_e32 v51, v53, v104
	s_nop 1
	v_add_f32_dpp v50, v51, v51 quad_perm:[1,0,3,2] row_mask:0xf bank_mask:0xf bound_ctrl:1
	s_nop 1
	v_add_f32_dpp v50, v50, v50 quad_perm:[2,3,0,1] row_mask:0xf bank_mask:0xf bound_ctrl:1
	s_nop 1
	v_add_f32_dpp v50, v50, v50 row_ror:4 row_mask:0xf bank_mask:0xf bound_ctrl:1
	s_nop 1
	v_mov_b32_dpp v51, v50 row_ror:8 row_mask:0xf bank_mask:0xf bound_ctrl:1
	s_and_saveexec_b64 s[0:1], s[6:7]
	v_add_f32_e32 v50, v50, v51
	v_add_f32_e32 v50, v108, v50
	ds_write_b32 v96, v50 offset:432
	s_or_b64 exec, exec, s[0:1]
	s_waitcnt vmcnt(11)
	v_mul_f32_e32 v47, v47, v107
	v_fmac_f32_e32 v47, v46, v105
	v_fmac_f32_e32 v47, v48, v106
	v_fmac_f32_e32 v47, v49, v104
	s_nop 1
	v_add_f32_dpp v46, v47, v47 quad_perm:[1,0,3,2] row_mask:0xf bank_mask:0xf bound_ctrl:1
	s_nop 1
	v_add_f32_dpp v46, v46, v46 quad_perm:[2,3,0,1] row_mask:0xf bank_mask:0xf bound_ctrl:1
	s_nop 1
	v_add_f32_dpp v46, v46, v46 row_ror:4 row_mask:0xf bank_mask:0xf bound_ctrl:1
	s_nop 1
	v_mov_b32_dpp v47, v46 row_ror:8 row_mask:0xf bank_mask:0xf bound_ctrl:1
	s_and_saveexec_b64 s[0:1], s[6:7]
	v_add_f32_e32 v46, v46, v47
	v_add_f32_e32 v46, v108, v46
	ds_write_b32 v96, v46 offset:448
	s_or_b64 exec, exec, s[0:1]
	s_waitcnt vmcnt(10)
	v_mul_f32_e32 v43, v43, v107
	v_fmac_f32_e32 v43, v42, v105
	v_fmac_f32_e32 v43, v44, v106
	v_fmac_f32_e32 v43, v45, v104
	s_nop 1
	v_add_f32_dpp v42, v43, v43 quad_perm:[1,0,3,2] row_mask:0xf bank_mask:0xf bound_ctrl:1
	s_nop 1
	v_add_f32_dpp v42, v42, v42 quad_perm:[2,3,0,1] row_mask:0xf bank_mask:0xf bound_ctrl:1
	s_nop 1
	v_add_f32_dpp v42, v42, v42 row_ror:4 row_mask:0xf bank_mask:0xf bound_ctrl:1
	s_nop 1
	v_mov_b32_dpp v43, v42 row_ror:8 row_mask:0xf bank_mask:0xf bound_ctrl:1
	s_and_saveexec_b64 s[0:1], s[6:7]
	v_add_f32_e32 v42, v42, v43
	v_add_f32_e32 v42, v108, v42
	ds_write_b32 v96, v42 offset:464
	s_or_b64 exec, exec, s[0:1]
	s_waitcnt vmcnt(9)
	v_mul_f32_e32 v39, v39, v107
	v_fmac_f32_e32 v39, v38, v105
	v_fmac_f32_e32 v39, v40, v106
	v_fmac_f32_e32 v39, v41, v104
	s_nop 1
	v_add_f32_dpp v38, v39, v39 quad_perm:[1,0,3,2] row_mask:0xf bank_mask:0xf bound_ctrl:1
	s_nop 1
	v_add_f32_dpp v38, v38, v38 quad_perm:[2,3,0,1] row_mask:0xf bank_mask:0xf bound_ctrl:1
	s_nop 1
	v_add_f32_dpp v38, v38, v38 row_ror:4 row_mask:0xf bank_mask:0xf bound_ctrl:1
	s_nop 1
	v_mov_b32_dpp v39, v38 row_ror:8 row_mask:0xf bank_mask:0xf bound_ctrl:1
	s_and_saveexec_b64 s[0:1], s[6:7]
	v_add_f32_e32 v38, v38, v39
	v_add_f32_e32 v38, v108, v38
	ds_write_b32 v96, v38 offset:480
	s_or_b64 exec, exec, s[0:1]
	s_waitcnt vmcnt(8)
	v_mul_f32_e32 v35, v35, v107
	v_fmac_f32_e32 v35, v34, v105
	v_fmac_f32_e32 v35, v36, v106
	v_fmac_f32_e32 v35, v37, v104
	s_nop 1
	v_add_f32_dpp v34, v35, v35 quad_perm:[1,0,3,2] row_mask:0xf bank_mask:0xf bound_ctrl:1
	s_nop 1
	v_add_f32_dpp v34, v34, v34 quad_perm:[2,3,0,1] row_mask:0xf bank_mask:0xf bound_ctrl:1
	s_nop 1
	v_add_f32_dpp v34, v34, v34 row_ror:4 row_mask:0xf bank_mask:0xf bound_ctrl:1
	s_nop 1
	v_mov_b32_dpp v35, v34 row_ror:8 row_mask:0xf bank_mask:0xf bound_ctrl:1
	s_and_saveexec_b64 s[0:1], s[6:7]
	v_add_f32_e32 v34, v34, v35
	v_add_f32_e32 v34, v108, v34
	ds_write_b32 v96, v34 offset:496
	s_or_b64 exec, exec, s[0:1]
	s_waitcnt lgkmcnt(0)
	ds_read_b64 v[34:35], v97
	s_waitcnt lgkmcnt(0)
; __device__ __forceinline__ float softplus2_(float z2) { return fmaxf(z2, 0.f) + log1pf(exp2f(-fabsf(z2))) * LOG2E; }
; template <int NB>
; __device__ __forceinline__ void sb_decode_task(const Params& P, float* lds, int task) {
;     ...
;     const float z0 = zl[2 * lane], z1 = zl[2 * lane + 1];
;     const float sp0 = softplus2_(z0), sp1 = softplus2_(z1);
	v_cmp_gt_f32_e64 vcc, |v34|, s49
	s_nop 1
	v_cndmask_b32_e32 v37, 0, v101, vcc
	v_sub_f32_e64 v37, v37, |v34|
	v_exp_f32_e32 v37, v37
	v_max_f32_e32 v36, v34, v34
	v_max_f32_e32 v38, 0, v36
	v_cndmask_b32_e32 v36, 0, v100, vcc
	v_ldexp_f32 v39, v37, v36
	v_add_f32_e32 v40, 1.0, v39
	v_add_f32_e32 v36, -1.0, v40
	v_sub_f32_e32 v37, v36, v40
	v_add_f32_e32 v37, 1.0, v37
	v_sub_f32_e32 v36, v39, v36
	v_add_f32_e32 v41, v36, v37
	v_frexp_mant_f32_e32 v36, v40
	v_cmp_gt_f32_e32 vcc, s50, v36
	v_cvt_f64_f32_e32 v[36:37], v40
	v_frexp_exp_i32_f64_e32 v36, v[36:37]
	v_subbrev_co_u32_e32 v36, vcc, 0, v36, vcc
	v_sub_u32_e32 v37, 0, v36
	v_ldexp_f32 v40, v40, v37
	v_ldexp_f32 v37, v41, v37
	v_add_f32_e32 v41, -1.0, v40
	v_add_f32_e32 v42, 1.0, v41
	v_sub_f32_e32 v42, v40, v42
	v_add_f32_e32 v42, v37, v42
	v_add_f32_e32 v43, v41, v42
	v_sub_f32_e32 v41, v41, v43
	v_add_f32_e32 v41, v42, v41
	v_add_f32_e32 v42, 1.0, v40
	v_add_f32_e32 v44, -1.0, v42
	v_sub_f32_e32 v40, v40, v44
	v_add_f32_e32 v37, v37, v40
	v_add_f32_e32 v40, v42, v37
	v_sub_f32_e32 v42, v42, v40
	v_add_f32_e32 v37, v37, v42
	v_rcp_f32_e32 v42, v40
	v_cvt_f32_i32_e32 v36, v36
	v_cmp_neq_f32_e32 vcc, s52, v39
	v_mul_f32_e32 v44, v43, v42
	v_mul_f32_e32 v45, v40, v44
	v_fma_f32 v46, v44, v40, -v45
	v_fmac_f32_e32 v46, v44, v37
	v_add_f32_e32 v47, v45, v46
	v_sub_f32_e32 v48, v43, v47
	v_sub_f32_e32 v43, v43, v48
	v_sub_f32_e32 v45, v47, v45
	v_sub_f32_e32 v43, v43, v47
	v_add_f32_e32 v41, v41, v43
	v_sub_f32_e32 v43, v45, v46
	v_add_f32_e32 v41, v43, v41
	v_add_f32_e32 v43, v48, v41
	v_mul_f32_e32 v45, v42, v43
	v_mul_f32_e32 v46, v40, v45
	v_fma_f32 v40, v45, v40, -v46
	v_fmac_f32_e32 v40, v45, v37
	v_sub_f32_e32 v37, v48, v43
	v_add_f32_e32 v37, v41, v37
	v_add_f32_e32 v41, v46, v40
	v_sub_f32_e32 v47, v43, v41
	v_sub_f32_e32 v43, v43, v47
	v_sub_f32_e32 v46, v41, v46
	v_sub_f32_e32 v41, v43, v41
	v_add_f32_e32 v37, v37, v41
	v_sub_f32_e32 v40, v46, v40
	v_add_f32_e32 v37, v40, v37
	v_add_f32_e32 v40, v44, v45
	v_add_f32_e32 v37, v47, v37
	v_sub_f32_e32 v41, v40, v44
	v_mul_f32_e32 v37, v42, v37
	v_sub_f32_e32 v41, v45, v41
	v_add_f32_e32 v37, v41, v37
	v_mul_f32_e32 v44, 0x3f317218, v36
	v_add_f32_e32 v41, v40, v37
	v_fma_f32 v45, v36, s51, -v44
	v_mul_f32_e32 v42, v41, v41
	v_fmac_f32_e32 v45, 0xb102e308, v36
	v_sub_f32_e32 v36, v41, v40
	v_fmamk_f32 v43, v42, 0x3e9b6dac, v98
	v_sub_f32_e32 v36, v37, v36
	v_add_f32_e32 v37, v44, v45
	v_fmaak_f32 v43, v42, v43, 0x3f2aaada
	v_sub_f32_e32 v40, v37, v44
	v_ldexp_f32 v44, v41, 1
	v_mul_f32_e32 v41, v41, v42
	v_mul_f32_e32 v41, v41, v43
	v_add_f32_e32 v42, v44, v41
	v_sub_f32_e32 v43, v42, v44
	v_ldexp_f32 v36, v36, 1
	v_sub_f32_e32 v41, v41, v43
	v_add_f32_e32 v36, v36, v41
	v_add_f32_e32 v41, v42, v36
	v_sub_f32_e32 v42, v41, v42
	v_sub_f32_e32 v36, v36, v42
	v_add_f32_e32 v42, v37, v41
	v_sub_f32_e32 v43, v42, v37
	v_sub_f32_e32 v44, v42, v43
	v_sub_f32_e32 v40, v45, v40
	v_sub_f32_e32 v37, v37, v44
	v_sub_f32_e32 v41, v41, v43
	v_add_f32_e32 v37, v41, v37
	v_add_f32_e32 v41, v40, v36
	v_sub_f32_e32 v43, v41, v40
	v_sub_f32_e32 v44, v41, v43
	v_sub_f32_e32 v40, v40, v44
	v_sub_f32_e32 v36, v36, v43
	v_add_f32_e32 v37, v41, v37
	v_add_f32_e32 v36, v36, v40
	v_add_f32_e32 v40, v42, v37
	v_sub_f32_e32 v41, v40, v42
	v_sub_f32_e32 v37, v37, v41
	v_add_f32_e32 v36, v36, v37
	v_add_f32_e32 v36, v40, v36
	v_cndmask_b32_e32 v36, v102, v36, vcc
	v_cmp_lt_f32_e64 vcc, |v39|, s53
	s_nop 1
	v_cndmask_b32_e32 v36, v36, v39, vcc
	v_cmp_gt_f32_e64 vcc, |v35|, s49
	v_fmac_f32_e32 v38, 0x3fb8aa3b, v36
	v_max_f32_e32 v36, v35, v35
	v_cndmask_b32_e32 v37, 0, v101, vcc
	v_sub_f32_e64 v37, v37, |v35|
	v_exp_f32_e32 v37, v37
	v_max_f32_e32 v39, 0, v36
	v_cndmask_b32_e32 v36, 0, v100, vcc
	v_sub_f32_e32 v34, v34, v38
	v_ldexp_f32 v40, v37, v36
	v_add_f32_e32 v41, 1.0, v40
	v_add_f32_e32 v36, -1.0, v41
	v_sub_f32_e32 v37, v36, v41
	v_add_f32_e32 v37, 1.0, v37
	v_sub_f32_e32 v36, v40, v36
	v_add_f32_e32 v42, v36, v37
	v_frexp_mant_f32_e32 v36, v41
	v_cmp_gt_f32_e32 vcc, s50, v36
	v_cvt_f64_f32_e32 v[36:37], v41
	v_frexp_exp_i32_f64_e32 v36, v[36:37]
	v_subbrev_co_u32_e32 v36, vcc, 0, v36, vcc
	v_sub_u32_e32 v37, 0, v36
	v_ldexp_f32 v41, v41, v37
	v_ldexp_f32 v37, v42, v37
	v_add_f32_e32 v42, -1.0, v41
	v_add_f32_e32 v43, 1.0, v42
	v_sub_f32_e32 v43, v41, v43
	v_add_f32_e32 v43, v37, v43
	v_add_f32_e32 v44, v42, v43
	v_sub_f32_e32 v42, v42, v44
	v_add_f32_e32 v42, v43, v42
	v_add_f32_e32 v43, 1.0, v41
	v_add_f32_e32 v45, -1.0, v43
	v_sub_f32_e32 v41, v41, v45
	v_add_f32_e32 v37, v37, v41
	v_add_f32_e32 v41, v43, v37
	v_sub_f32_e32 v43, v43, v41
	v_add_f32_e32 v37, v37, v43
	v_rcp_f32_e32 v43, v41
	v_cvt_f32_i32_e32 v36, v36
	v_cmp_neq_f32_e32 vcc, s52, v40
	v_mul_f32_e32 v45, v44, v43
	v_mul_f32_e32 v46, v41, v45
	v_fma_f32 v47, v45, v41, -v46
	v_fmac_f32_e32 v47, v45, v37
	v_add_f32_e32 v48, v46, v47
	v_sub_f32_e32 v49, v44, v48
	v_sub_f32_e32 v44, v44, v49
	v_sub_f32_e32 v46, v48, v46
	v_sub_f32_e32 v44, v44, v48
	v_add_f32_e32 v42, v42, v44
	v_sub_f32_e32 v44, v46, v47
	v_add_f32_e32 v42, v44, v42
	v_add_f32_e32 v44, v49, v42
	v_mul_f32_e32 v46, v43, v44
	v_mul_f32_e32 v47, v41, v46
	v_fma_f32 v41, v46, v41, -v47
	v_fmac_f32_e32 v41, v46, v37
	v_sub_f32_e32 v37, v49, v44
	v_add_f32_e32 v37, v42, v37
	v_add_f32_e32 v42, v47, v41
	v_sub_f32_e32 v48, v44, v42
	v_sub_f32_e32 v44, v44, v48
	v_sub_f32_e32 v47, v42, v47
	v_sub_f32_e32 v42, v44, v42
	v_add_f32_e32 v37, v37, v42
	v_sub_f32_e32 v41, v47, v41
	v_add_f32_e32 v37, v41, v37
	v_add_f32_e32 v41, v45, v46
	v_add_f32_e32 v37, v48, v37
	v_sub_f32_e32 v42, v41, v45
	v_mul_f32_e32 v37, v43, v37
; __device__ __forceinline__ float softplus2_(float z2) { return fmaxf(z2, 0.f) + log1pf(exp2f(-fabsf(z2))) * LOG2E; }
; template <int NB>
; __device__ __forceinline__ void sb_decode_task(const Params& P, float* lds, int task) {
;     ...
;     const float sp0 = softplus2_(z0), sp1 = softplus2_(z1);
;     float incl = sp0 + sp1;
; #pragma unroll
;     for (int off = 1; off < 64; off <<= 1) { const float t = __shfl_down(incl, off); if (lane + off < 64) incl += t; }
;     const float excl = incl - (sp0 + sp1);
;     wl[2 * lane] = exp2f(z0 - sp0 - (excl + sp1));
;     wl[2 * lane + 1] = exp2f(z1 - sp1 - excl);
;     const float Ltot = __shfl(incl, 0);
;     asm volatile("s_waitcnt lgkmcnt(0)" ::: "memory");
;     __builtin_amdgcn_wave_barrier();
;     float4 o4 = make_float4(0.f, 0.f, 0.f, 0.f);
; #pragma unroll
;     for (int vb = 0; vb < NBT; ++vb) {
;         if (vb + 1 < NBT) {
; #pragma unroll
;             for (int i = 0; i < NB; ++i) nx[i] = *(const float4*)(Vp + (size_t)(4 * NB * (vb + 1) + 4 * i + g) * (SH * HD)); }
; #pragma unroll
;         for (int i = 0; i < NB; ++i) { const float w = wl[4 * NB * vb + 4 * i + g]; o4.x += w * cur[i].x; o4.y += w * cur[i].y; o4.z += w * cur[i].z; o4.w += w * cur[i].w; }
	v_sub_f32_e32 v42, v46, v42
	v_add_f32_e32 v37, v42, v37
	v_mul_f32_e32 v45, 0x3f317218, v36
	v_add_f32_e32 v42, v41, v37
	v_fma_f32 v46, v36, s51, -v45
	v_mul_f32_e32 v43, v42, v42
	v_fmac_f32_e32 v46, 0xb102e308, v36
	v_sub_f32_e32 v36, v42, v41
	v_fmamk_f32 v44, v43, 0x3e9b6dac, v98
	v_sub_f32_e32 v36, v37, v36
	v_add_f32_e32 v37, v45, v46
	v_fmaak_f32 v44, v43, v44, 0x3f2aaada
	v_sub_f32_e32 v41, v37, v45
	v_ldexp_f32 v45, v42, 1
	v_mul_f32_e32 v42, v42, v43
	v_mul_f32_e32 v42, v42, v44
	v_add_f32_e32 v43, v45, v42
	v_sub_f32_e32 v44, v43, v45
	v_ldexp_f32 v36, v36, 1
	v_sub_f32_e32 v42, v42, v44
	v_add_f32_e32 v36, v36, v42
	v_add_f32_e32 v42, v43, v36
	v_sub_f32_e32 v43, v42, v43
	v_sub_f32_e32 v36, v36, v43
	v_add_f32_e32 v43, v37, v42
	v_sub_f32_e32 v44, v43, v37
	v_sub_f32_e32 v45, v43, v44
	v_sub_f32_e32 v41, v46, v41
	v_sub_f32_e32 v37, v37, v45
	v_sub_f32_e32 v42, v42, v44
	v_add_f32_e32 v37, v42, v37
	v_add_f32_e32 v42, v41, v36
	v_sub_f32_e32 v44, v42, v41
	v_sub_f32_e32 v45, v42, v44
	v_sub_f32_e32 v41, v41, v45
	v_sub_f32_e32 v36, v36, v44
	v_add_f32_e32 v37, v42, v37
	v_add_f32_e32 v36, v36, v41
	v_add_f32_e32 v41, v43, v37
	v_sub_f32_e32 v42, v41, v43
	v_sub_f32_e32 v37, v37, v42
	v_add_f32_e32 v36, v36, v37
	v_add_f32_e32 v36, v41, v36
	v_cndmask_b32_e32 v36, v102, v36, vcc
	v_cmp_lt_f32_e64 vcc, |v40|, s53
	v_and_b32_e32 v37, 63, v103
	s_nop 0
	v_cndmask_b32_e32 v36, v36, v40, vcc
	v_cmp_ne_u32_e32 vcc, 63, v37
	v_fmac_f32_e32 v39, 0x3fb8aa3b, v36
	v_add_f32_e32 v36, v38, v39
	v_addc_co_u32_e32 v40, vcc, 0, v103, vcc
	v_lshlrev_b32_e32 v106, 2, v40
	ds_bpermute_b32 v40, v106, v36
	v_cmp_gt_u32_e32 vcc, 62, v37
	v_sub_f32_e32 v35, v35, v39
	s_waitcnt lgkmcnt(0)
	v_add_f32_e32 v40, v36, v40
	v_cndmask_b32_e64 v41, 0, 2, vcc
	v_cndmask_b32_e64 v40, v40, v36, s[8:9]
	v_add_lshl_u32 v107, v41, v103, 2
	ds_bpermute_b32 v41, v107, v40
	v_cmp_gt_u32_e32 vcc, 60, v37
	s_waitcnt lgkmcnt(0)
	v_add_f32_e32 v41, v40, v41
	v_cndmask_b32_e64 v40, v40, v41, s[10:11]
	v_cndmask_b32_e64 v41, 0, 4, vcc
	v_add_lshl_u32 v108, v41, v103, 2
	ds_bpermute_b32 v41, v108, v40
	v_cmp_gt_u32_e32 vcc, 56, v37
	s_waitcnt lgkmcnt(0)
	v_add_f32_e32 v41, v40, v41
	v_cndmask_b32_e64 v40, v40, v41, s[12:13]
	v_cndmask_b32_e64 v41, 0, 8, vcc
	v_add_lshl_u32 v109, v41, v103, 2
	ds_bpermute_b32 v41, v109, v40
	v_cmp_gt_u32_e32 vcc, 48, v37
	s_waitcnt lgkmcnt(0)
	v_add_f32_e32 v41, v40, v41
	v_cndmask_b32_e64 v37, 0, 16, vcc
	v_cndmask_b32_e64 v40, v40, v41, s[14:15]
	v_add_lshl_u32 v110, v37, v103, 2
	ds_bpermute_b32 v37, v110, v40
	s_waitcnt lgkmcnt(0)
	v_add_f32_e32 v37, v40, v37
	v_cndmask_b32_e64 v37, v40, v37, s[16:17]
	v_lshlrev_b32_e32 v40, 2, v103
	v_or_b32_e32 v111, 0x80, v40
	ds_bpermute_b32 v41, v111, v37
	v_and_b32_e32 v104, 0x100, v40
	s_waitcnt lgkmcnt(0)
	v_add_f32_e32 v41, v37, v41
	v_cndmask_b32_e64 v44, v37, v41, s[18:19]
	v_sub_f32_e32 v36, v44, v36
	v_add_f32_e32 v37, v39, v36
	v_sub_f32_e32 v34, v34, v37
	v_cmp_gt_f32_e32 vcc, s54, v34
	v_sub_f32_e32 v35, v35, v36
	s_nop 0
	v_cndmask_b32_e32 v37, 0, v101, vcc
	v_add_f32_e32 v34, v34, v37
	v_cndmask_b32_e32 v37, 0, v100, vcc
	v_cmp_gt_f32_e32 vcc, s54, v35
	v_exp_f32_e32 v34, v34
	s_nop 0
	v_cndmask_b32_e32 v36, 0, v101, vcc
	v_add_f32_e32 v35, v35, v36
	v_exp_f32_e32 v35, v35
	v_cndmask_b32_e32 v36, 0, v100, vcc
	v_ldexp_f32 v34, v34, v37
	v_ldexp_f32 v35, v35, v36
	ds_write_b64 v97, v[34:35] offset:512
	s_waitcnt lgkmcnt(0)
	ds_read2_b32 v[34:35], v96 offset0:128 offset1:132
	ds_read2_b32 v[42:43], v96 offset0:136 offset1:140
	ds_read2_b32 v[66:67], v96 offset0:144 offset1:148
	ds_read2_b32 v[68:69], v96 offset0:152 offset1:156
	ds_read2_b32 v[74:75], v96 offset0:160 offset1:164
	ds_read2_b32 v[76:77], v96 offset0:168 offset1:172
	ds_read2_b32 v[38:39], v96 offset0:176 offset1:180
	ds_read2_b32 v[40:41], v96 offset0:184 offset1:188
	s_waitcnt vmcnt(7) lgkmcnt(7)
	v_pk_fma_f32 v[70:71], v[30:31], v[34:35], 0 op_sel_hi:[1,0,0]
	v_add_co_u32_e32 v30, vcc, s55, v54
	v_pk_fma_f32 v[72:73], v[32:33], v[34:35], 0 op_sel_hi:[1,0,0]
	s_nop 0
	v_addc_co_u32_e32 v31, vcc, 0, v55, vcc
	v_add_co_u32_e32 v34, vcc, s83, v54
	v_mov_b32_e32 v64, v35
	s_nop 0
	v_addc_co_u32_e32 v35, vcc, 0, v55, vcc
	v_add_co_u32_e32 v46, vcc, s86, v54
	s_waitcnt vmcnt(6)
	v_pk_fma_f32 v[2:3], v[2:3], v[64:65], v[70:71] op_sel_hi:[1,0,1]
	v_addc_co_u32_e32 v47, vcc, 0, v55, vcc
	v_add_co_u32_e32 v50, vcc, s87, v54
	global_load_dwordx4 v[46:49], v[46:47], off nt
	s_nop 0
	v_addc_co_u32_e32 v51, vcc, 0, v55, vcc
	v_add_co_u32_e32 v56, vcc, s88, v54
	global_load_dwordx4 v[50:53], v[50:51], off offset:2048 nt
	s_nop 0
	v_addc_co_u32_e32 v57, vcc, 0, v55, vcc
	v_add_co_u32_e32 v60, vcc, s89, v54
	global_load_dwordx4 v[56:59], v[56:57], off nt
	s_nop 0
	v_addc_co_u32_e32 v61, vcc, 0, v55, vcc
	global_load_dwordx4 v[60:63], v[60:61], off offset:2048 nt
	s_waitcnt lgkmcnt(6)
	v_mov_b32_e32 v78, v43
	s_waitcnt vmcnt(9)
	v_pk_fma_f32 v[2:3], v[6:7], v[42:43], v[2:3] op_sel_hi:[1,0,1]
	s_waitcnt lgkmcnt(5)
	v_mov_b32_e32 v80, v67
	s_waitcnt vmcnt(7)
	v_pk_fma_f32 v[2:3], v[14:15], v[78:79], v[2:3] op_sel_hi:[1,0,1]
	s_waitcnt lgkmcnt(4)
	v_mov_b32_e32 v92, v69
	v_pk_fma_f32 v[2:3], v[10:11], v[66:67], v[2:3] op_sel_hi:[1,0,1]
	s_waitcnt lgkmcnt(3)
	v_mov_b32_e32 v10, v75
	s_waitcnt vmcnt(6)
	v_pk_fma_f32 v[2:3], v[18:19], v[80:81], v[2:3] op_sel_hi:[1,0,1]
	s_waitcnt lgkmcnt(2)
	v_mov_b32_e32 v14, v77
	s_waitcnt vmcnt(5)
	v_pk_fma_f32 v[2:3], v[22:23], v[68:69], v[2:3] op_sel_hi:[1,0,1]
	global_load_dwordx4 v[30:33], v[30:31], off nt
	s_waitcnt vmcnt(5)
; template <int NB>
; __device__ __forceinline__ void sb_decode_task(const Params& P, float* lds, int task) {
;     ...
;     for (int vb = 0; vb < NBT; ++vb) {
;         if (vb + 1 < NBT) {
; #pragma unroll
;             for (int i = 0; i < NB; ++i) nx[i] = *(const float4*)(Vp + (size_t)(4 * NB * (vb + 1) + 4 * i + g) * (SH * HD)); }
; #pragma unroll
;         for (int i = 0; i < NB; ++i) { const float w = wl[4 * NB * vb + 4 * i + g]; o4.x += w * cur[i].x; o4.y += w * cur[i].y; o4.z += w * cur[i].z; o4.w += w * cur[i].w; }
; #pragma unroll
;         for (int i = 0; i < NB; ++i) cur[i] = nx[i];
	v_pk_fma_f32 v[2:3], v[26:27], v[92:93], v[2:3] op_sel_hi:[1,0,1]
	global_load_dwordx4 v[34:37], v[34:35], off offset:2048 nt
	s_waitcnt vmcnt(5)
	v_pk_fma_f32 v[2:3], v[46:47], v[74:75], v[2:3] op_sel_hi:[1,0,1]
	s_waitcnt vmcnt(4)
	v_pk_fma_f32 v[2:3], v[50:51], v[10:11], v[2:3] op_sel_hi:[1,0,1]
	s_waitcnt vmcnt(3)
	v_pk_fma_f32 v[2:3], v[56:57], v[76:77], v[2:3] op_sel_hi:[1,0,1]
	s_waitcnt vmcnt(2)
	v_pk_fma_f32 v[6:7], v[60:61], v[14:15], v[2:3] op_sel_hi:[1,0,1]
	v_pk_fma_f32 v[2:3], v[4:5], v[64:65], v[72:73] op_sel_hi:[1,0,1]
	v_add_co_u32_e32 v4, vcc, s90, v54
	v_pk_fma_f32 v[2:3], v[8:9], v[42:43], v[2:3] op_sel_hi:[1,0,1]
	s_nop 0
	v_addc_co_u32_e32 v5, vcc, 0, v55, vcc
	v_pk_fma_f32 v[2:3], v[16:17], v[78:79], v[2:3] op_sel_hi:[1,0,1]
	s_waitcnt lgkmcnt(0)
	v_mov_b32_e32 v42, v41
	v_pk_fma_f32 v[2:3], v[12:13], v[66:67], v[2:3] op_sel_hi:[1,0,1]
	s_waitcnt vmcnt(1)
	v_pk_fma_f32 v[6:7], v[30:31], v[38:39], v[6:7] op_sel_hi:[1,0,1]
	v_pk_fma_f32 v[2:3], v[20:21], v[80:81], v[2:3] op_sel_hi:[1,0,1]
	s_nop 0
	v_pk_fma_f32 v[2:3], v[24:25], v[68:69], v[2:3] op_sel_hi:[1,0,1]
	s_nop 0
	v_pk_fma_f32 v[2:3], v[28:29], v[92:93], v[2:3] op_sel_hi:[1,0,1]
	v_mov_b32_e32 v28, v39
	v_pk_fma_f32 v[2:3], v[48:49], v[74:75], v[2:3] op_sel_hi:[1,0,1]
	s_waitcnt vmcnt(0)
	v_pk_fma_f32 v[6:7], v[34:35], v[28:29], v[6:7] op_sel_hi:[1,0,1]
	v_pk_fma_f32 v[2:3], v[52:53], v[10:11], v[2:3] op_sel_hi:[1,0,1]
	s_nop 0
	v_pk_fma_f32 v[2:3], v[58:59], v[76:77], v[2:3] op_sel_hi:[1,0,1]
	s_nop 0
	v_pk_fma_f32 v[2:3], v[62:63], v[14:15], v[2:3] op_sel_hi:[1,0,1]
	ds_read2_b32 v[14:15], v96 offset0:192 offset1:196
	ds_read2_b32 v[12:13], v96 offset0:200 offset1:204
	ds_read2_b32 v[10:11], v96 offset0:208 offset1:212
	ds_read2_b32 v[8:9], v96 offset0:216 offset1:220
	global_load_dwordx4 v[16:19], v[4:5], off nt
	v_add_co_u32_e32 v4, vcc, s91, v54
	v_pk_fma_f32 v[2:3], v[32:33], v[38:39], v[2:3] op_sel_hi:[1,0,1]
	s_nop 0
	v_addc_co_u32_e32 v5, vcc, 0, v55, vcc
	global_load_dwordx4 v[20:23], v[4:5], off offset:2048 nt
	v_add_co_u32_e32 v4, vcc, s92, v54
	v_pk_fma_f32 v[2:3], v[36:37], v[28:29], v[2:3] op_sel_hi:[1,0,1]
	s_nop 0
	v_addc_co_u32_e32 v5, vcc, 0, v55, vcc
	global_load_dwordx4 v[24:27], v[4:5], off nt
	v_add_co_u32_e32 v4, vcc, s93, v54
	s_waitcnt lgkmcnt(0)
	v_mov_b32_e32 v36, v9
	v_addc_co_u32_e32 v5, vcc, 0, v55, vcc
	global_load_dwordx4 v[46:49], v[4:5], off offset:2048 nt
	v_add_co_u32_e32 v4, vcc, s94, v54
	ds_read2_b32 v[30:31], v96 offset0:224 offset1:228
	s_nop 0
	v_addc_co_u32_e32 v5, vcc, 0, v55, vcc
	global_load_dwordx4 v[50:53], v[4:5], off nt
	v_add_co_u32_e32 v4, vcc, s95, v54
	s_waitcnt vmcnt(4)
	v_pk_fma_f32 v[2:3], v[18:19], v[40:41], v[2:3] op_sel_hi:[1,0,1]
	v_addc_co_u32_e32 v5, vcc, 0, v55, vcc
	global_load_dwordx4 v[56:59], v[4:5], off offset:2048 nt
	v_add_co_u32_e32 v4, vcc, s96, v54
	s_waitcnt vmcnt(4)
	v_pk_fma_f32 v[2:3], v[22:23], v[42:43], v[2:3] op_sel_hi:[1,0,1]
	v_addc_co_u32_e32 v5, vcc, 0, v55, vcc
	global_load_dwordx4 v[60:63], v[4:5], off nt
	v_add_co_u32_e32 v4, vcc, s97, v54
	s_waitcnt vmcnt(4)
	v_pk_fma_f32 v[2:3], v[26:27], v[14:15], v[2:3] op_sel_hi:[1,0,1]
	v_addc_co_u32_e32 v5, vcc, 0, v55, vcc
	global_load_dwordx4 v[64:67], v[4:5], off offset:2048 nt
	v_add_co_u32_e32 v4, vcc, s22, v54
	v_mov_b32_e32 v18, v15
	s_nop 0
	v_addc_co_u32_e32 v5, vcc, 0, v55, vcc
	global_load_dwordx4 v[68:71], v[4:5], off nt
	v_pk_fma_f32 v[6:7], v[16:17], v[40:41], v[6:7] op_sel_hi:[1,0,1]
	s_waitcnt vmcnt(5)
	v_pk_fma_f32 v[2:3], v[48:49], v[18:19], v[2:3] op_sel_hi:[1,0,1]
	v_pk_fma_f32 v[6:7], v[20:21], v[42:43], v[6:7] op_sel_hi:[1,0,1]
	s_waitcnt vmcnt(4)
	v_pk_fma_f32 v[2:3], v[52:53], v[12:13], v[2:3] op_sel_hi:[1,0,1]
	v_mov_b32_e32 v22, v13
	v_pk_fma_f32 v[6:7], v[24:25], v[14:15], v[6:7] op_sel_hi:[1,0,1]
	v_mov_b32_e32 v26, v11
	v_pk_fma_f32 v[6:7], v[46:47], v[18:19], v[6:7] op_sel_hi:[1,0,1]
	s_waitcnt vmcnt(3)
	v_pk_fma_f32 v[2:3], v[58:59], v[22:23], v[2:3] op_sel_hi:[1,0,1]
	v_pk_fma_f32 v[6:7], v[50:51], v[12:13], v[6:7] op_sel_hi:[1,0,1]
	s_waitcnt vmcnt(2)
	v_pk_fma_f32 v[2:3], v[62:63], v[10:11], v[2:3] op_sel_hi:[1,0,1]
	v_pk_fma_f32 v[6:7], v[56:57], v[22:23], v[6:7] op_sel_hi:[1,0,1]
	s_waitcnt vmcnt(1)
; template <int NB>
; __device__ __forceinline__ void sb_decode_task(const Params& P, float* lds, int task) {
;     ...
;     for (int vb = 0; vb < NBT; ++vb) {
;         if (vb + 1 < NBT) {
; #pragma unroll
;             for (int i = 0; i < NB; ++i) nx[i] = *(const float4*)(Vp + (size_t)(4 * NB * (vb + 1) + 4 * i + g) * (SH * HD)); }
; #pragma unroll
;         for (int i = 0; i < NB; ++i) { const float w = wl[4 * NB * vb + 4 * i + g]; o4.x += w * cur[i].x; o4.y += w * cur[i].y; o4.z += w * cur[i].z; o4.w += w * cur[i].w; }
; #pragma unroll
;         for (int i = 0; i < NB; ++i) cur[i] = nx[i];
;     }
; #pragma unroll
;     for (int off = 16; off < 64; off <<= 1) { o4.x += __shfl_xor(o4.x, off); o4.y += __shfl_xor(o4.y, off); o4.z += __shfl_xor(o4.z, off); o4.w += __shfl_xor(o4.w, off); }
;     if (g == 0) *(float4*)(dpart + (size_t)task * HD + 4 * c) = o4;
;     if (lane == 0) dl[task] = Ltot;
	v_pk_fma_f32 v[2:3], v[66:67], v[26:27], v[2:3] op_sel_hi:[1,0,1]
	v_pk_fma_f32 v[6:7], v[60:61], v[10:11], v[6:7] op_sel_hi:[1,0,1]
	v_and_b32_e32 v10, 64, v103
	v_pk_fma_f32 v[6:7], v[64:65], v[26:27], v[6:7] op_sel_hi:[1,0,1]
	v_add_u32_e32 v37, 64, v10
	v_xor_b32_e32 v10, 16, v103
	s_waitcnt vmcnt(0)
	v_pk_fma_f32 v[32:33], v[70:71], v[8:9], v[2:3] op_sel_hi:[1,0,1]
	v_add_co_u32_e32 v2, vcc, s23, v54
	v_pk_fma_f32 v[34:35], v[68:69], v[8:9], v[6:7] op_sel_hi:[1,0,1]
	s_nop 0
	v_addc_co_u32_e32 v3, vcc, 0, v55, vcc
	v_add_co_u32_e32 v6, vcc, s24, v54
	global_load_dwordx4 v[2:5], v[2:3], off offset:2048 nt
	s_nop 0
	v_addc_co_u32_e32 v7, vcc, 0, v55, vcc
	v_cmp_lt_i32_e32 vcc, v10, v37
	global_load_dwordx4 v[6:9], v[6:7], off nt
	ds_read2_b32 v[42:43], v96 offset0:232 offset1:236
	ds_read2_b32 v[40:41], v96 offset0:240 offset1:244
	ds_read2_b32 v[38:39], v96 offset0:248 offset1:252
	v_cndmask_b32_e32 v10, v103, v10, vcc
	v_lshlrev_b32_e32 v105, 2, v10
	v_add_co_u32_e32 v10, vcc, s72, v54
	s_waitcnt lgkmcnt(1)
	v_mov_b32_e32 v56, v41
	v_addc_co_u32_e32 v11, vcc, 0, v55, vcc
	v_add_co_u32_e32 v14, vcc, s73, v54
	global_load_dwordx4 v[10:13], v[10:11], off offset:2048 nt
	s_nop 0
	v_addc_co_u32_e32 v15, vcc, 0, v55, vcc
	v_add_co_u32_e32 v18, vcc, s74, v54
	global_load_dwordx4 v[14:17], v[14:15], off nt
	s_nop 0
	v_addc_co_u32_e32 v19, vcc, 0, v55, vcc
	v_add_co_u32_e32 v22, vcc, s75, v54
	global_load_dwordx4 v[18:21], v[18:19], off offset:2048 nt
	s_nop 0
	v_addc_co_u32_e32 v23, vcc, 0, v55, vcc
	v_add_co_u32_e32 v26, vcc, s80, v54
	global_load_dwordx4 v[22:25], v[22:23], off nt
	s_nop 0
	v_addc_co_u32_e32 v27, vcc, 0, v55, vcc
	v_add_co_u32_e32 v46, vcc, s81, v54
	global_load_dwordx4 v[26:29], v[26:27], off offset:2048 nt
	s_nop 0
	v_addc_co_u32_e32 v47, vcc, 0, v55, vcc
	v_add_co_u32_e32 v50, vcc, s82, v54
	global_load_dwordx4 v[46:49], v[46:47], off nt
	s_nop 0
	v_addc_co_u32_e32 v51, vcc, 0, v55, vcc
	global_load_dwordx4 v[50:53], v[50:51], off offset:2048 nt
	v_mov_b32_e32 v54, v43
	s_waitcnt lgkmcnt(0)
	v_mov_b32_e32 v58, v39
	s_waitcnt vmcnt(8)
	v_pk_fma_f32 v[2:3], v[2:3], v[36:37], v[34:35] op_sel_hi:[1,0,1]
	v_mov_b32_e32 v34, v31
	v_pk_fma_f32 v[4:5], v[4:5], v[36:37], v[32:33] op_sel_hi:[1,0,1]
	s_waitcnt vmcnt(7)
	v_pk_fma_f32 v[2:3], v[6:7], v[30:31], v[2:3] op_sel_hi:[1,0,1]
	v_pk_fma_f32 v[4:5], v[8:9], v[30:31], v[4:5] op_sel_hi:[1,0,1]
	s_waitcnt vmcnt(6)
	v_pk_fma_f32 v[2:3], v[10:11], v[34:35], v[2:3] op_sel_hi:[1,0,1]
	v_pk_fma_f32 v[4:5], v[12:13], v[34:35], v[4:5] op_sel_hi:[1,0,1]
	ds_bpermute_b32 v10, v104, v44
	s_waitcnt vmcnt(5)
	v_pk_fma_f32 v[2:3], v[14:15], v[42:43], v[2:3] op_sel_hi:[1,0,1]
	v_pk_fma_f32 v[4:5], v[16:17], v[42:43], v[4:5] op_sel_hi:[1,0,1]
	s_waitcnt vmcnt(4)
	v_pk_fma_f32 v[2:3], v[18:19], v[54:55], v[2:3] op_sel_hi:[1,0,1]
	v_pk_fma_f32 v[4:5], v[20:21], v[54:55], v[4:5] op_sel_hi:[1,0,1]
	s_waitcnt vmcnt(3)
	v_pk_fma_f32 v[2:3], v[22:23], v[40:41], v[2:3] op_sel_hi:[1,0,1]
	v_pk_fma_f32 v[4:5], v[24:25], v[40:41], v[4:5] op_sel_hi:[1,0,1]
	s_waitcnt vmcnt(2)
	v_pk_fma_f32 v[2:3], v[26:27], v[56:57], v[2:3] op_sel_hi:[1,0,1]
	v_pk_fma_f32 v[4:5], v[28:29], v[56:57], v[4:5] op_sel_hi:[1,0,1]
	s_waitcnt vmcnt(1)
	v_pk_fma_f32 v[2:3], v[46:47], v[38:39], v[2:3] op_sel_hi:[1,0,1]
	v_pk_fma_f32 v[4:5], v[48:49], v[38:39], v[4:5] op_sel_hi:[1,0,1]
	s_waitcnt vmcnt(0)
	v_pk_fma_f32 v[2:3], v[50:51], v[58:59], v[2:3] op_sel_hi:[1,0,1]
	ds_bpermute_b32 v6, v105, v2
	ds_bpermute_b32 v7, v105, v3
	v_pk_fma_f32 v[4:5], v[52:53], v[58:59], v[4:5] op_sel_hi:[1,0,1]
	s_waitcnt lgkmcnt(0)
	v_pk_add_f32 v[2:3], v[2:3], v[6:7]
	ds_bpermute_b32 v6, v105, v4
	ds_bpermute_b32 v7, v105, v5
	s_waitcnt lgkmcnt(0)
	v_pk_add_f32 v[4:5], v[4:5], v[6:7]
	v_xor_b32_e32 v6, 32, v103
	v_cmp_lt_i32_e32 vcc, v6, v37
	s_nop 1
	v_cndmask_b32_e32 v6, v103, v6, vcc
	v_lshlrev_b32_e32 v112, 2, v6
	ds_bpermute_b32 v6, v112, v2
	ds_bpermute_b32 v7, v112, v3
	ds_bpermute_b32 v8, v112, v4
	ds_bpermute_b32 v9, v112, v5
	s_and_saveexec_b64 s[0:1], s[20:21]
	s_cbranch_execz .LBB0_1022
	s_ashr_i32 s35, s34, 31
	s_lshl_b64 s[2:3], s[34:35], 8
	v_lshl_add_u64 v[12:13], v[88:89], 0, s[2:3]
	s_waitcnt lgkmcnt(2)
	v_pk_add_f32 v[2:3], v[2:3], v[6:7]
	s_waitcnt lgkmcnt(0)
	v_pk_add_f32 v[4:5], v[4:5], v[8:9]
	global_store_dwordx4 v[12:13], v[2:5], off

; __device__ __forceinline__ float bf2f(bf16_t b) { return __uint_as_float(((unsigned)b) << 16); }
; template <int NB>
; __device__ __forceinline__ void sb_decode_task(const Params& P, float* lds, int task) {
;     const int tid = threadIdx.x, lane = tid & 63, wave = tid >> 6;
;     const bf16_t* qb = (const bf16_t*)(P.ws + WS_QB);
;     float* dpart = (float*)(P.ws + WS_DPART); float* dl = (float*)(P.ws + WS_DL);
;     float* zl = lds + DEC_LDS_OFF / 4 + wave * 256; float* wl = zl + 128;
;     const int c = lane & 15, g = lane >> 4;
;     constexpr int NBT = 32 / NB;
;     const int h = task % SH, bj = task / SH, b = bj / NPAGES;
;     const int page = P.page_table[bj];
;     const float* Kp = P.cache_k + ((size_t)page * PAGE * SH + h) * HD + 4 * c;
;     const float* Vp = P.cache_v + ((size_t)page * PAGE * SH + h) * HD + 4 * c;
;     const bf16_t* qp = qb + (size_t)(NTOK + b) * SBW + h * 64 + 4 * c;
;     const float q0 = bf2f(qp[0]), q1 = bf2f(qp[1]), q2 = bf2f(qp[2]), q3 = bf2f(qp[3]);
;     const float bias = P.sb_bias[h] * LOG2E;
;     float4 cur[NB], nx[NB];
; #pragma unroll
;     for (int i = 0; i < NB; ++i) cur[i] = *(const float4*)(Kp + (size_t)(4 * i + g) * (SH * HD));
; #pragma unroll
;     for (int kb = 0; kb < NBT; ++kb) {
;         const float* np = (kb + 1 < NBT) ? Kp + (size_t)(4 * NB * (kb + 1)) * (SH * HD) : Vp;
; #pragma unroll
;         for (int i = 0; i < NB; ++i) nx[i] = *(const float4*)(np + (size_t)(4 * i + g) * (SH * HD));
; #pragma unroll
;         for (int i = 0; i < NB; ++i) { const int s = 4 * NB * kb + 4 * i + g;
;             float part = q0 * cur[i].x + q1 * cur[i].y + q2 * cur[i].z + q3 * cur[i].w; part = sum16(part);
;             if (c == 0) zl[s] = part + bias; }
; #pragma unroll
;         for (int i = 0; i < NB; ++i) cur[i] = nx[i];
.LBB0_1024:
	s_or_b64 exec, exec, s[0:1]
	v_readlane_b32 s36, v252, 48
	s_add_i32 s34, s34, 1
	v_readlane_b32 s37, v252, 49
	s_mul_hi_i32 s1, s34, 0x2aaaaaab
	s_load_dwordx16 s[56:71], s[36:37], 0x0
	s_lshr_b32 s3, s1, 31
	s_add_i32 s0, s1, s3
	s_ashr_i32 s1, s1, 7
	s_mul_i32 s2, s0, 6
	s_add_i32 s33, s1, s3
	s_ashr_i32 s1, s0, 31
	s_sub_i32 s2, s34, s2
	s_lshl_b64 s[0:1], s[0:1], 2
	s_waitcnt lgkmcnt(0)
	s_add_u32 s0, s66, s0
	s_addc_u32 s1, s67, s1
	global_load_dword v2, v83, s[0:1]
	s_add_i32 s0, s33, 0x4000
	s_ashr_i32 s3, s2, 31
	s_mul_hi_i32 s1, s0, 0x300
	s_mulk_i32 s0, 0x300
	s_add_u32 s33, s38, s0
	s_addc_u32 s35, s39, s1
	s_lshl_b32 s0, s2, 6
	s_ashr_i32 s1, s0, 31
	s_lshl_b64 s[0:1], s[0:1], 1
	s_add_u32 s0, s33, s0
	s_addc_u32 s1, s35, s1
	v_readlane_b32 s56, v252, 16
	v_readlane_b32 s57, v252, 17
	v_readlane_b32 s64, v252, 24
	v_readlane_b32 s65, v252, 25
	s_mov_b64 s[56:57], s[64:65]
	v_mov_b32_e32 v91, v83
	v_readlane_b32 s58, v252, 18
	v_readlane_b32 s59, v252, 19
	v_readlane_b32 s60, v252, 20
	v_readlane_b32 s61, v252, 21
	v_readlane_b32 s62, v252, 22
	v_readlane_b32 s63, v252, 23
	v_readlane_b32 s66, v252, 26
	v_readlane_b32 s67, v252, 27
	v_readlane_b32 s68, v252, 28
	v_readlane_b32 s69, v252, 29
	v_readlane_b32 s70, v252, 30
	v_readlane_b32 s71, v252, 31
	s_waitcnt vmcnt(0)
	v_mul_hi_i32 v3, v2, s42
	v_mul_lo_u32 v2, v2, s42
	v_lshl_add_u64 v[92:93], v[2:3], 0, s[2:3]
	v_lshlrev_b64 v[2:3], 8, v[92:93]
	v_lshl_add_u64 v[66:67], v[84:85], 0, v[2:3]
	global_load_dwordx2 v[2:3], v99, s[0:1]
	s_lshl_b64 s[0:1], s[2:3], 2
	s_add_u32 s0, s56, s0
	s_addc_u32 s1, s57, s1
	global_load_dword v22, v83, s[0:1]
	v_lshl_add_u64 v[18:19], v[66:67], 0, v[82:83]
	v_lshl_add_u64 v[20:21], v[66:67], 0, v[90:91]
	global_load_dwordx4 v[14:17], v[18:19], off nt
	global_load_dwordx4 v[62:65], v[20:21], off nt
	s_waitcnt vmcnt(3)
	v_lshlrev_b32_e32 v114, 16, v2
	v_and_b32_e32 v116, 0xffff0000, v2
	v_add_co_u32_e32 v2, vcc, s44, v18
	v_lshlrev_b32_e32 v115, 16, v3
	v_and_b32_e32 v113, 0xffff0000, v3
	v_addc_co_u32_e32 v3, vcc, 0, v19, vcc
	global_load_dwordx4 v[10:13], v[2:3], off offset:2048 nt
	v_add_co_u32_e32 v2, vcc, s45, v18
	s_waitcnt vmcnt(3)
	v_mul_f32_e32 v117, 0x3fb8aa3b, v22
	v_addc_co_u32_e32 v3, vcc, 0, v19, vcc
	global_load_dwordx4 v[6:9], v[2:3], off nt
	v_add_co_u32_e32 v2, vcc, s43, v18
	v_lshl_add_u64 v[22:23], v[66:67], 0, s[26:27]
	s_nop 0
	v_addc_co_u32_e32 v3, vcc, 0, v19, vcc
	v_add_co_u32_e32 v20, vcc, s46, v18
	v_lshl_add_u64 v[30:31], v[22:23], 0, v[82:83]
	s_nop 0
	v_addc_co_u32_e32 v21, vcc, 0, v19, vcc
	global_load_dwordx4 v[58:61], v[20:21], off offset:2048 nt
	v_add_co_u32_e32 v20, vcc, s47, v18
	v_lshl_add_u64 v[22:23], v[22:23], 0, v[90:91]
	s_nop 0
	v_addc_co_u32_e32 v21, vcc, 0, v19, vcc
	v_add_co_u32_e32 v18, vcc, s48, v18
	global_load_dwordx4 v[54:57], v[20:21], off nt
	s_nop 0
	v_addc_co_u32_e32 v19, vcc, 0, v19, vcc
	global_load_dwordx4 v[50:53], v[18:19], off offset:2048 nt
	v_add_co_u32_e32 v18, vcc, s44, v30
	global_load_dwordx4 v[22:25], v[22:23], off nt
	s_nop 0
	v_addc_co_u32_e32 v19, vcc, 0, v31, vcc
	global_load_dwordx4 v[34:37], v[18:19], off offset:2048 nt
	v_add_co_u32_e32 v18, vcc, s45, v30
	global_load_dwordx4 v[2:5], v[2:3], off offset:2048 nt
	s_nop 0
	v_addc_co_u32_e32 v19, vcc, 0, v31, vcc
	global_load_dwordx4 v[26:29], v[18:19], off nt
	v_add_co_u32_e32 v18, vcc, s43, v30
	global_load_dwordx4 v[46:49], v[30:31], off nt
	s_nop 0
	v_addc_co_u32_e32 v19, vcc, 0, v31, vcc
	v_add_co_u32_e32 v32, vcc, s46, v30
	global_load_dwordx4 v[18:21], v[18:19], off offset:2048 nt
	s_nop 0
	v_addc_co_u32_e32 v33, vcc, 0, v31, vcc
	global_load_dwordx4 v[38:41], v[32:33], off offset:2048 nt
	v_add_co_u32_e32 v32, vcc, s47, v30
	s_waitcnt vmcnt(13)
	v_mul_f32_e32 v15, v15, v116
	v_addc_co_u32_e32 v33, vcc, 0, v31, vcc
	v_add_co_u32_e32 v30, vcc, s48, v30
	global_load_dwordx4 v[42:45], v[32:33], off nt
	s_nop 0
	v_addc_co_u32_e32 v31, vcc, 0, v31, vcc
	global_load_dwordx4 v[30:33], v[30:31], off offset:2048 nt
	v_fmac_f32_e32 v15, v14, v114
	v_fmac_f32_e32 v15, v16, v115
	v_fmac_f32_e32 v15, v17, v113
	s_nop 1
	v_add_f32_dpp v14, v15, v15 quad_perm:[1,0,3,2] row_mask:0xf bank_mask:0xf bound_ctrl:1
	s_nop 1
	v_add_f32_dpp v14, v14, v14 quad_perm:[2,3,0,1] row_mask:0xf bank_mask:0xf bound_ctrl:1
	s_nop 1
	v_add_f32_dpp v14, v14, v14 row_ror:4 row_mask:0xf bank_mask:0xf bound_ctrl:1
	s_nop 1
	v_mov_b32_dpp v15, v14 row_ror:8 row_mask:0xf bank_mask:0xf bound_ctrl:1
	s_and_saveexec_b64 s[0:1], s[6:7]
	v_add_f32_e32 v14, v14, v15
	v_add_f32_e32 v14, v117, v14
	ds_write_b32 v96, v14
	s_or_b64 exec, exec, s[0:1]
	s_waitcnt vmcnt(13)
	v_mul_f32_e32 v11, v11, v116
	v_fmac_f32_e32 v11, v10, v114
	v_fmac_f32_e32 v11, v12, v115
	v_fmac_f32_e32 v11, v13, v113
	s_nop 1
	v_add_f32_dpp v10, v11, v11 quad_perm:[1,0,3,2] row_mask:0xf bank_mask:0xf bound_ctrl:1
	s_nop 1
	v_add_f32_dpp v10, v10, v10 quad_perm:[2,3,0,1] row_mask:0xf bank_mask:0xf bound_ctrl:1
	s_nop 1
	v_add_f32_dpp v10, v10, v10 row_ror:4 row_mask:0xf bank_mask:0xf bound_ctrl:1
	s_nop 1
	v_mov_b32_dpp v11, v10 row_ror:8 row_mask:0xf bank_mask:0xf bound_ctrl:1
	s_and_saveexec_b64 s[0:1], s[6:7]
	v_add_f32_e32 v10, v10, v11
	v_add_f32_e32 v10, v117, v10
	ds_write_b32 v96, v10 offset:16
	s_or_b64 exec, exec, s[0:1]
	s_waitcnt vmcnt(12)
	v_mul_f32_e32 v7, v7, v116
	v_fmac_f32_e32 v7, v6, v114
	v_fmac_f32_e32 v7, v8, v115
	v_fmac_f32_e32 v7, v9, v113
	s_nop 1
	v_add_f32_dpp v6, v7, v7 quad_perm:[1,0,3,2] row_mask:0xf bank_mask:0xf bound_ctrl:1
	s_nop 1
	v_add_f32_dpp v6, v6, v6 quad_perm:[2,3,0,1] row_mask:0xf bank_mask:0xf bound_ctrl:1
	s_nop 1
	v_add_f32_dpp v6, v6, v6 row_ror:4 row_mask:0xf bank_mask:0xf bound_ctrl:1
	s_nop 1
	v_mov_b32_dpp v7, v6 row_ror:8 row_mask:0xf bank_mask:0xf bound_ctrl:1
	s_and_saveexec_b64 s[0:1], s[6:7]
	v_add_f32_e32 v6, v6, v7
	v_add_f32_e32 v6, v117, v6
	ds_write_b32 v96, v6 offset:32
	s_or_b64 exec, exec, s[0:1]
	s_waitcnt vmcnt(6)
; template <int NB>
; __device__ __forceinline__ void sb_decode_task(const Params& P, float* lds, int task) {
;     ...
;     for (int i = 0; i < NB; ++i) cur[i] = *(const float4*)(Kp + (size_t)(4 * i + g) * (SH * HD));
; #pragma unroll
;     for (int kb = 0; kb < NBT; ++kb) {
;         const float* np = (kb + 1 < NBT) ? Kp + (size_t)(4 * NB * (kb + 1)) * (SH * HD) : Vp;
; #pragma unroll
;         for (int i = 0; i < NB; ++i) nx[i] = *(const float4*)(np + (size_t)(4 * i + g) * (SH * HD));
; #pragma unroll
;         for (int i = 0; i < NB; ++i) { const int s = 4 * NB * kb + 4 * i + g;
;             float part = q0 * cur[i].x + q1 * cur[i].y + q2 * cur[i].z + q3 * cur[i].w; part = sum16(part);
;             if (c == 0) zl[s] = part + bias; }
; #pragma unroll
;         for (int i = 0; i < NB; ++i) cur[i] = nx[i];
	v_mul_f32_e32 v3, v3, v116
	v_fmac_f32_e32 v3, v2, v114
	v_fmac_f32_e32 v3, v4, v115
	v_fmac_f32_e32 v3, v5, v113
	s_nop 1
	v_add_f32_dpp v2, v3, v3 quad_perm:[1,0,3,2] row_mask:0xf bank_mask:0xf bound_ctrl:1
	s_nop 1
	v_add_f32_dpp v2, v2, v2 quad_perm:[2,3,0,1] row_mask:0xf bank_mask:0xf bound_ctrl:1
	s_nop 1
	v_add_f32_dpp v2, v2, v2 row_ror:4 row_mask:0xf bank_mask:0xf bound_ctrl:1
	s_nop 1
	v_mov_b32_dpp v3, v2 row_ror:8 row_mask:0xf bank_mask:0xf bound_ctrl:1
	s_and_saveexec_b64 s[0:1], s[6:7]
	v_add_f32_e32 v2, v2, v3
	v_add_f32_e32 v2, v117, v2
	ds_write_b32 v96, v2 offset:48
	s_or_b64 exec, exec, s[0:1]
	v_mul_f32_e32 v2, v63, v116
	v_fmac_f32_e32 v2, v62, v114
	v_fmac_f32_e32 v2, v64, v115
	v_fmac_f32_e32 v2, v65, v113
	s_nop 1
	v_add_f32_dpp v2, v2, v2 quad_perm:[1,0,3,2] row_mask:0xf bank_mask:0xf bound_ctrl:1
	s_nop 1
	v_add_f32_dpp v2, v2, v2 quad_perm:[2,3,0,1] row_mask:0xf bank_mask:0xf bound_ctrl:1
	s_nop 1
	v_add_f32_dpp v2, v2, v2 row_ror:4 row_mask:0xf bank_mask:0xf bound_ctrl:1
	s_nop 1
	v_mov_b32_dpp v3, v2 row_ror:8 row_mask:0xf bank_mask:0xf bound_ctrl:1
	s_and_saveexec_b64 s[0:1], s[6:7]
	v_add_f32_e32 v2, v2, v3
	v_add_f32_e32 v2, v117, v2
	ds_write_b32 v96, v2 offset:64
	s_or_b64 exec, exec, s[0:1]
	v_mul_f32_e32 v2, v59, v116
	v_fmac_f32_e32 v2, v58, v114
	v_fmac_f32_e32 v2, v60, v115
	v_fmac_f32_e32 v2, v61, v113
	s_nop 1
	v_add_f32_dpp v2, v2, v2 quad_perm:[1,0,3,2] row_mask:0xf bank_mask:0xf bound_ctrl:1
	s_nop 1
	v_add_f32_dpp v2, v2, v2 quad_perm:[2,3,0,1] row_mask:0xf bank_mask:0xf bound_ctrl:1
	s_nop 1
	v_add_f32_dpp v2, v2, v2 row_ror:4 row_mask:0xf bank_mask:0xf bound_ctrl:1
	s_nop 1
	v_mov_b32_dpp v3, v2 row_ror:8 row_mask:0xf bank_mask:0xf bound_ctrl:1
	s_and_saveexec_b64 s[0:1], s[6:7]
	v_add_f32_e32 v2, v2, v3
	v_add_f32_e32 v2, v117, v2
	ds_write_b32 v96, v2 offset:80
	s_or_b64 exec, exec, s[0:1]
	v_mul_f32_e32 v2, v55, v116
	v_fmac_f32_e32 v2, v54, v114
	v_fmac_f32_e32 v2, v56, v115
	v_fmac_f32_e32 v2, v57, v113
	s_nop 1
	v_add_f32_dpp v2, v2, v2 quad_perm:[1,0,3,2] row_mask:0xf bank_mask:0xf bound_ctrl:1
	s_nop 1
	v_add_f32_dpp v2, v2, v2 quad_perm:[2,3,0,1] row_mask:0xf bank_mask:0xf bound_ctrl:1
	s_nop 1
	v_add_f32_dpp v2, v2, v2 row_ror:4 row_mask:0xf bank_mask:0xf bound_ctrl:1
	s_nop 1
	v_mov_b32_dpp v3, v2 row_ror:8 row_mask:0xf bank_mask:0xf bound_ctrl:1
	s_and_saveexec_b64 s[0:1], s[6:7]
	v_add_f32_e32 v2, v2, v3
	v_add_f32_e32 v2, v117, v2
	ds_write_b32 v96, v2 offset:96
	s_or_b64 exec, exec, s[0:1]
	v_mul_f32_e32 v2, v51, v116
	v_fmac_f32_e32 v2, v50, v114
	v_fmac_f32_e32 v2, v52, v115
	v_fmac_f32_e32 v2, v53, v113
	s_nop 1
	v_add_f32_dpp v2, v2, v2 quad_perm:[1,0,3,2] row_mask:0xf bank_mask:0xf bound_ctrl:1
	s_nop 1
	v_add_f32_dpp v2, v2, v2 quad_perm:[2,3,0,1] row_mask:0xf bank_mask:0xf bound_ctrl:1
	s_nop 1
	v_add_f32_dpp v2, v2, v2 row_ror:4 row_mask:0xf bank_mask:0xf bound_ctrl:1
	s_nop 1
	v_mov_b32_dpp v3, v2 row_ror:8 row_mask:0xf bank_mask:0xf bound_ctrl:1
	s_and_saveexec_b64 s[0:1], s[6:7]
	v_add_f32_e32 v2, v2, v3
	v_add_f32_e32 v2, v117, v2
	ds_write_b32 v96, v2 offset:112
	s_or_b64 exec, exec, s[0:1]
	v_lshl_add_u64 v[2:3], v[66:67], 0, s[28:29]
	v_lshl_add_u64 v[4:5], v[2:3], 0, v[82:83]
	v_add_co_u32_e32 v6, vcc, 0x1000, v4
	v_mov_b32_e32 v91, v83
	s_nop 0
	v_addc_co_u32_e32 v7, vcc, 0, v5, vcc
	global_load_dwordx4 v[78:81], v[4:5], off nt
	global_load_dwordx4 v[70:73], v[6:7], off offset:2048 nt
	v_add_co_u32_e32 v6, vcc, 0x3000, v4
	v_lshl_add_u64 v[2:3], v[2:3], 0, v[90:91]
	s_nop 0
	v_addc_co_u32_e32 v7, vcc, 0, v5, vcc
	v_add_co_u32_e32 v8, vcc, s43, v4
	s_waitcnt vmcnt(6)
	v_mul_f32_e32 v47, v47, v116
	v_addc_co_u32_e32 v9, vcc, 0, v5, vcc
	global_load_dwordx4 v[62:65], v[6:7], off nt
	global_load_dwordx4 v[54:57], v[8:9], off offset:2048 nt
	v_add_co_u32_e32 v6, vcc, 0x7000, v4
	v_fmac_f32_e32 v47, v46, v114
	s_nop 0
	v_addc_co_u32_e32 v7, vcc, 0, v5, vcc
	global_load_dwordx4 v[14:17], v[2:3], off nt
	global_load_dwordx4 v[10:13], v[6:7], off offset:2048 nt
	v_add_co_u32_e32 v2, vcc, 0x9000, v4
	v_fmac_f32_e32 v47, v48, v115
	s_nop 0
	v_addc_co_u32_e32 v3, vcc, 0, v5, vcc
	v_add_co_u32_e32 v4, vcc, 0xa000, v4
	v_fmac_f32_e32 v47, v49, v113
	s_nop 0
	v_addc_co_u32_e32 v5, vcc, 0, v5, vcc
	global_load_dwordx4 v[6:9], v[2:3], off nt
	s_nop 0
	global_load_dwordx4 v[2:5], v[4:5], off offset:2048 nt
	v_add_f32_dpp v46, v47, v47 quad_perm:[1,0,3,2] row_mask:0xf bank_mask:0xf bound_ctrl:1
	s_nop 1
	v_add_f32_dpp v46, v46, v46 quad_perm:[2,3,0,1] row_mask:0xf bank_mask:0xf bound_ctrl:1
	s_nop 1
	v_add_f32_dpp v46, v46, v46 row_ror:4 row_mask:0xf bank_mask:0xf bound_ctrl:1
	s_nop 1
	v_mov_b32_dpp v47, v46 row_ror:8 row_mask:0xf bank_mask:0xf bound_ctrl:1
	s_and_saveexec_b64 s[0:1], s[6:7]
	v_add_f32_e32 v46, v46, v47
	v_add_f32_e32 v46, v117, v46
	ds_write_b32 v96, v46 offset:128
	s_or_b64 exec, exec, s[0:1]
	v_mul_f32_e32 v35, v35, v116
	v_fmac_f32_e32 v35, v34, v114
	v_fmac_f32_e32 v35, v36, v115
	v_fmac_f32_e32 v35, v37, v113
	s_nop 1
	v_add_f32_dpp v34, v35, v35 quad_perm:[1,0,3,2] row_mask:0xf bank_mask:0xf bound_ctrl:1
	s_nop 1
	v_add_f32_dpp v34, v34, v34 quad_perm:[2,3,0,1] row_mask:0xf bank_mask:0xf bound_ctrl:1
	s_nop 1
	v_add_f32_dpp v34, v34, v34 row_ror:4 row_mask:0xf bank_mask:0xf bound_ctrl:1
	s_nop 1
	v_mov_b32_dpp v35, v34 row_ror:8 row_mask:0xf bank_mask:0xf bound_ctrl:1
	s_and_saveexec_b64 s[0:1], s[6:7]
	v_add_f32_e32 v34, v34, v35
	v_add_f32_e32 v34, v117, v34
	ds_write_b32 v96, v34 offset:144
	s_or_b64 exec, exec, s[0:1]
	v_mul_f32_e32 v27, v27, v116
	v_fmac_f32_e32 v27, v26, v114
	v_fmac_f32_e32 v27, v28, v115
	v_fmac_f32_e32 v27, v29, v113
	s_nop 1
	v_add_f32_dpp v26, v27, v27 quad_perm:[1,0,3,2] row_mask:0xf bank_mask:0xf bound_ctrl:1
	s_nop 1
	v_add_f32_dpp v26, v26, v26 quad_perm:[2,3,0,1] row_mask:0xf bank_mask:0xf bound_ctrl:1
	s_nop 1
	v_add_f32_dpp v26, v26, v26 row_ror:4 row_mask:0xf bank_mask:0xf bound_ctrl:1
	s_nop 1
	v_mov_b32_dpp v27, v26 row_ror:8 row_mask:0xf bank_mask:0xf bound_ctrl:1
	s_and_saveexec_b64 s[0:1], s[6:7]
	v_add_f32_e32 v26, v26, v27
	v_add_f32_e32 v26, v117, v26
	ds_write_b32 v96, v26 offset:160
	s_or_b64 exec, exec, s[0:1]
	s_waitcnt vmcnt(11)
; template <int NB>
; __device__ __forceinline__ void sb_decode_task(const Params& P, float* lds, int task) {
;     ...
;     for (int i = 0; i < NB; ++i) cur[i] = *(const float4*)(Kp + (size_t)(4 * i + g) * (SH * HD));
; #pragma unroll
;     for (int kb = 0; kb < NBT; ++kb) {
;         const float* np = (kb + 1 < NBT) ? Kp + (size_t)(4 * NB * (kb + 1)) * (SH * HD) : Vp;
; #pragma unroll
;         for (int i = 0; i < NB; ++i) nx[i] = *(const float4*)(np + (size_t)(4 * i + g) * (SH * HD));
; #pragma unroll
;         for (int i = 0; i < NB; ++i) { const int s = 4 * NB * kb + 4 * i + g;
;             float part = q0 * cur[i].x + q1 * cur[i].y + q2 * cur[i].z + q3 * cur[i].w; part = sum16(part);
;             if (c == 0) zl[s] = part + bias; }
; #pragma unroll
;         for (int i = 0; i < NB; ++i) cur[i] = nx[i];
	v_mul_f32_e32 v19, v19, v116
	v_fmac_f32_e32 v19, v18, v114
	v_fmac_f32_e32 v19, v20, v115
	v_fmac_f32_e32 v19, v21, v113
	s_nop 1
	v_add_f32_dpp v18, v19, v19 quad_perm:[1,0,3,2] row_mask:0xf bank_mask:0xf bound_ctrl:1
	s_nop 1
	v_add_f32_dpp v18, v18, v18 quad_perm:[2,3,0,1] row_mask:0xf bank_mask:0xf bound_ctrl:1
	s_nop 1
	v_add_f32_dpp v18, v18, v18 row_ror:4 row_mask:0xf bank_mask:0xf bound_ctrl:1
	s_nop 1
	v_mov_b32_dpp v19, v18 row_ror:8 row_mask:0xf bank_mask:0xf bound_ctrl:1
	s_and_saveexec_b64 s[0:1], s[6:7]
	v_add_f32_e32 v18, v18, v19
	v_add_f32_e32 v18, v117, v18
	ds_write_b32 v96, v18 offset:176
	s_or_b64 exec, exec, s[0:1]
	v_mul_f32_e32 v18, v23, v116
	v_fmac_f32_e32 v18, v22, v114
	v_fmac_f32_e32 v18, v24, v115
	v_fmac_f32_e32 v18, v25, v113
	s_nop 1
	v_add_f32_dpp v18, v18, v18 quad_perm:[1,0,3,2] row_mask:0xf bank_mask:0xf bound_ctrl:1
	s_nop 1
	v_add_f32_dpp v18, v18, v18 quad_perm:[2,3,0,1] row_mask:0xf bank_mask:0xf bound_ctrl:1
	s_nop 1
	v_add_f32_dpp v18, v18, v18 row_ror:4 row_mask:0xf bank_mask:0xf bound_ctrl:1
	s_nop 1
	v_mov_b32_dpp v19, v18 row_ror:8 row_mask:0xf bank_mask:0xf bound_ctrl:1
	s_and_saveexec_b64 s[0:1], s[6:7]
	v_add_f32_e32 v18, v18, v19
	v_add_f32_e32 v18, v117, v18
	ds_write_b32 v96, v18 offset:192
	s_or_b64 exec, exec, s[0:1]
	s_waitcnt vmcnt(10)
	v_mul_f32_e32 v18, v39, v116
	v_fmac_f32_e32 v18, v38, v114
	v_fmac_f32_e32 v18, v40, v115
	v_fmac_f32_e32 v18, v41, v113
	s_nop 1
	v_add_f32_dpp v18, v18, v18 quad_perm:[1,0,3,2] row_mask:0xf bank_mask:0xf bound_ctrl:1
	s_nop 1
	v_add_f32_dpp v18, v18, v18 quad_perm:[2,3,0,1] row_mask:0xf bank_mask:0xf bound_ctrl:1
	s_nop 1
	v_add_f32_dpp v18, v18, v18 row_ror:4 row_mask:0xf bank_mask:0xf bound_ctrl:1
	s_nop 1
	v_mov_b32_dpp v19, v18 row_ror:8 row_mask:0xf bank_mask:0xf bound_ctrl:1
	s_and_saveexec_b64 s[0:1], s[6:7]
	v_add_f32_e32 v18, v18, v19
	v_add_f32_e32 v18, v117, v18
	ds_write_b32 v96, v18 offset:208
	s_or_b64 exec, exec, s[0:1]
	s_waitcnt vmcnt(9)
	v_mul_f32_e32 v18, v43, v116
	v_fmac_f32_e32 v18, v42, v114
	v_fmac_f32_e32 v18, v44, v115
	v_fmac_f32_e32 v18, v45, v113
	s_nop 1
	v_add_f32_dpp v18, v18, v18 quad_perm:[1,0,3,2] row_mask:0xf bank_mask:0xf bound_ctrl:1
	s_nop 1
	v_add_f32_dpp v18, v18, v18 quad_perm:[2,3,0,1] row_mask:0xf bank_mask:0xf bound_ctrl:1
	s_nop 1
	v_add_f32_dpp v18, v18, v18 row_ror:4 row_mask:0xf bank_mask:0xf bound_ctrl:1
	s_nop 1
	v_mov_b32_dpp v19, v18 row_ror:8 row_mask:0xf bank_mask:0xf bound_ctrl:1
	s_and_saveexec_b64 s[0:1], s[6:7]
	v_add_f32_e32 v18, v18, v19
	v_add_f32_e32 v18, v117, v18
	ds_write_b32 v96, v18 offset:224
	s_or_b64 exec, exec, s[0:1]
	s_waitcnt vmcnt(8)
	v_mul_f32_e32 v18, v31, v116
	v_fmac_f32_e32 v18, v30, v114
	v_fmac_f32_e32 v18, v32, v115
	v_fmac_f32_e32 v18, v33, v113
	s_nop 1
	v_add_f32_dpp v18, v18, v18 quad_perm:[1,0,3,2] row_mask:0xf bank_mask:0xf bound_ctrl:1
	s_nop 1
	v_add_f32_dpp v18, v18, v18 quad_perm:[2,3,0,1] row_mask:0xf bank_mask:0xf bound_ctrl:1
	s_nop 1
	v_add_f32_dpp v18, v18, v18 row_ror:4 row_mask:0xf bank_mask:0xf bound_ctrl:1
	s_nop 1
	v_mov_b32_dpp v19, v18 row_ror:8 row_mask:0xf bank_mask:0xf bound_ctrl:1
	s_and_saveexec_b64 s[0:1], s[6:7]
	v_add_f32_e32 v18, v18, v19
	v_add_f32_e32 v18, v117, v18
	ds_write_b32 v96, v18 offset:240
	s_or_b64 exec, exec, s[0:1]
	v_lshl_add_u64 v[18:19], v[66:67], 0, s[30:31]
	v_lshl_add_u64 v[20:21], v[18:19], 0, v[82:83]
	v_add_co_u32_e32 v22, vcc, 0x1000, v20
	v_mov_b32_e32 v91, v83
	s_nop 0
	v_addc_co_u32_e32 v23, vcc, 0, v21, vcc
	global_load_dwordx4 v[74:77], v[20:21], off nt
	global_load_dwordx4 v[66:69], v[22:23], off offset:2048 nt
	v_add_co_u32_e32 v22, vcc, 0x3000, v20
	v_lshl_add_u64 v[18:19], v[18:19], 0, v[90:91]
	s_nop 0
	v_addc_co_u32_e32 v23, vcc, 0, v21, vcc
	v_add_co_u32_e32 v24, vcc, s43, v20
	s_nop 1
	v_addc_co_u32_e32 v25, vcc, 0, v21, vcc
	global_load_dwordx4 v[58:61], v[22:23], off nt
	global_load_dwordx4 v[50:53], v[24:25], off offset:2048 nt
	v_add_co_u32_e32 v22, vcc, 0x7000, v20
	s_nop 1
	v_addc_co_u32_e32 v23, vcc, 0, v21, vcc
	global_load_dwordx4 v[46:49], v[18:19], off nt
	global_load_dwordx4 v[42:45], v[22:23], off offset:2048 nt
	v_add_co_u32_e32 v18, vcc, 0x9000, v20
	s_nop 1
	v_addc_co_u32_e32 v19, vcc, 0, v21, vcc
	v_add_co_u32_e32 v20, vcc, 0xa000, v20
	s_nop 1
	v_addc_co_u32_e32 v21, vcc, 0, v21, vcc
	global_load_dwordx4 v[38:41], v[18:19], off nt
	global_load_dwordx4 v[34:37], v[20:21], off offset:2048 nt
	s_waitcnt vmcnt(15)
	v_mul_f32_e32 v18, v79, v116
	v_fmac_f32_e32 v18, v78, v114
	v_fmac_f32_e32 v18, v80, v115
	v_fmac_f32_e32 v18, v81, v113
	s_nop 1
	v_add_f32_dpp v18, v18, v18 quad_perm:[1,0,3,2] row_mask:0xf bank_mask:0xf bound_ctrl:1
	s_nop 1
	v_add_f32_dpp v18, v18, v18 quad_perm:[2,3,0,1] row_mask:0xf bank_mask:0xf bound_ctrl:1
	s_nop 1
	v_add_f32_dpp v18, v18, v18 row_ror:4 row_mask:0xf bank_mask:0xf bound_ctrl:1
	s_nop 1
	v_mov_b32_dpp v19, v18 row_ror:8 row_mask:0xf bank_mask:0xf bound_ctrl:1
	s_and_saveexec_b64 s[0:1], s[6:7]
	v_add_f32_e32 v18, v18, v19
	v_add_f32_e32 v18, v117, v18
	ds_write_b32 v96, v18 offset:256
	s_or_b64 exec, exec, s[0:1]
	s_waitcnt vmcnt(14)
	v_mul_f32_e32 v18, v71, v116
	v_fmac_f32_e32 v18, v70, v114
	v_fmac_f32_e32 v18, v72, v115
	v_fmac_f32_e32 v18, v73, v113
	s_nop 1
	v_add_f32_dpp v18, v18, v18 quad_perm:[1,0,3,2] row_mask:0xf bank_mask:0xf bound_ctrl:1
	s_nop 1
	v_add_f32_dpp v18, v18, v18 quad_perm:[2,3,0,1] row_mask:0xf bank_mask:0xf bound_ctrl:1
	s_nop 1
	v_add_f32_dpp v18, v18, v18 row_ror:4 row_mask:0xf bank_mask:0xf bound_ctrl:1
	s_nop 1
	v_mov_b32_dpp v19, v18 row_ror:8 row_mask:0xf bank_mask:0xf bound_ctrl:1
	s_and_saveexec_b64 s[0:1], s[6:7]
	v_add_f32_e32 v18, v18, v19
	v_add_f32_e32 v18, v117, v18
	ds_write_b32 v96, v18 offset:272
	s_or_b64 exec, exec, s[0:1]
	s_waitcnt vmcnt(13)
; template <int NB>
; __device__ __forceinline__ void sb_decode_task(const Params& P, float* lds, int task) {
;     ...
;     for (int i = 0; i < NB; ++i) cur[i] = *(const float4*)(Kp + (size_t)(4 * i + g) * (SH * HD));
; #pragma unroll
;     for (int kb = 0; kb < NBT; ++kb) {
;         const float* np = (kb + 1 < NBT) ? Kp + (size_t)(4 * NB * (kb + 1)) * (SH * HD) : Vp;
; #pragma unroll
;         for (int i = 0; i < NB; ++i) nx[i] = *(const float4*)(np + (size_t)(4 * i + g) * (SH * HD));
; #pragma unroll
;         for (int i = 0; i < NB; ++i) { const int s = 4 * NB * kb + 4 * i + g;
;             float part = q0 * cur[i].x + q1 * cur[i].y + q2 * cur[i].z + q3 * cur[i].w; part = sum16(part);
;             if (c == 0) zl[s] = part + bias; }
; #pragma unroll
;         for (int i = 0; i < NB; ++i) cur[i] = nx[i];
	v_mul_f32_e32 v18, v63, v116
	v_fmac_f32_e32 v18, v62, v114
	v_fmac_f32_e32 v18, v64, v115
	v_fmac_f32_e32 v18, v65, v113
	s_nop 1
	v_add_f32_dpp v18, v18, v18 quad_perm:[1,0,3,2] row_mask:0xf bank_mask:0xf bound_ctrl:1
	s_nop 1
	v_add_f32_dpp v18, v18, v18 quad_perm:[2,3,0,1] row_mask:0xf bank_mask:0xf bound_ctrl:1
	s_nop 1
	v_add_f32_dpp v18, v18, v18 row_ror:4 row_mask:0xf bank_mask:0xf bound_ctrl:1
	s_nop 1
	v_mov_b32_dpp v19, v18 row_ror:8 row_mask:0xf bank_mask:0xf bound_ctrl:1
	s_and_saveexec_b64 s[0:1], s[6:7]
	v_add_f32_e32 v18, v18, v19
	v_add_f32_e32 v18, v117, v18
	ds_write_b32 v96, v18 offset:288
	s_or_b64 exec, exec, s[0:1]
	s_waitcnt vmcnt(12)
	v_mul_f32_e32 v18, v55, v116
	v_fmac_f32_e32 v18, v54, v114
	v_fmac_f32_e32 v18, v56, v115
	v_fmac_f32_e32 v18, v57, v113
	s_nop 1
	v_add_f32_dpp v18, v18, v18 quad_perm:[1,0,3,2] row_mask:0xf bank_mask:0xf bound_ctrl:1
	s_nop 1
	v_add_f32_dpp v18, v18, v18 quad_perm:[2,3,0,1] row_mask:0xf bank_mask:0xf bound_ctrl:1
	s_nop 1
	v_add_f32_dpp v18, v18, v18 row_ror:4 row_mask:0xf bank_mask:0xf bound_ctrl:1
	s_nop 1
	v_mov_b32_dpp v19, v18 row_ror:8 row_mask:0xf bank_mask:0xf bound_ctrl:1
	s_and_saveexec_b64 s[0:1], s[6:7]
	v_add_f32_e32 v18, v18, v19
	v_add_f32_e32 v18, v117, v18
	ds_write_b32 v96, v18 offset:304
	s_or_b64 exec, exec, s[0:1]
	s_waitcnt vmcnt(11)
	v_mul_f32_e32 v15, v15, v116
	v_fmac_f32_e32 v15, v14, v114
	v_fmac_f32_e32 v15, v16, v115
	v_fmac_f32_e32 v15, v17, v113
	s_nop 1
	v_add_f32_dpp v14, v15, v15 quad_perm:[1,0,3,2] row_mask:0xf bank_mask:0xf bound_ctrl:1
	s_nop 1
	v_add_f32_dpp v14, v14, v14 quad_perm:[2,3,0,1] row_mask:0xf bank_mask:0xf bound_ctrl:1
	s_nop 1
	v_add_f32_dpp v14, v14, v14 row_ror:4 row_mask:0xf bank_mask:0xf bound_ctrl:1
	s_nop 1
	v_mov_b32_dpp v15, v14 row_ror:8 row_mask:0xf bank_mask:0xf bound_ctrl:1
	s_and_saveexec_b64 s[0:1], s[6:7]
	v_add_f32_e32 v14, v14, v15
	v_add_f32_e32 v14, v117, v14
	ds_write_b32 v96, v14 offset:320
	s_or_b64 exec, exec, s[0:1]
	s_waitcnt vmcnt(10)
	v_mul_f32_e32 v11, v11, v116
	v_fmac_f32_e32 v11, v10, v114
	v_fmac_f32_e32 v11, v12, v115
	v_fmac_f32_e32 v11, v13, v113
	s_nop 1
	v_add_f32_dpp v10, v11, v11 quad_perm:[1,0,3,2] row_mask:0xf bank_mask:0xf bound_ctrl:1
	s_nop 1
	v_add_f32_dpp v10, v10, v10 quad_perm:[2,3,0,1] row_mask:0xf bank_mask:0xf bound_ctrl:1
	s_nop 1
	v_add_f32_dpp v10, v10, v10 row_ror:4 row_mask:0xf bank_mask:0xf bound_ctrl:1
	s_nop 1
	v_mov_b32_dpp v11, v10 row_ror:8 row_mask:0xf bank_mask:0xf bound_ctrl:1
	s_and_saveexec_b64 s[0:1], s[6:7]
	v_add_f32_e32 v10, v10, v11
	v_add_f32_e32 v10, v117, v10
	ds_write_b32 v96, v10 offset:336
	s_or_b64 exec, exec, s[0:1]
	s_waitcnt vmcnt(9)
	v_mul_f32_e32 v7, v7, v116
	v_fmac_f32_e32 v7, v6, v114
	v_fmac_f32_e32 v7, v8, v115
	v_fmac_f32_e32 v7, v9, v113
	s_nop 1
	v_add_f32_dpp v6, v7, v7 quad_perm:[1,0,3,2] row_mask:0xf bank_mask:0xf bound_ctrl:1
	s_nop 1
	v_add_f32_dpp v6, v6, v6 quad_perm:[2,3,0,1] row_mask:0xf bank_mask:0xf bound_ctrl:1
	s_nop 1
	v_add_f32_dpp v6, v6, v6 row_ror:4 row_mask:0xf bank_mask:0xf bound_ctrl:1
	s_nop 1
	v_mov_b32_dpp v7, v6 row_ror:8 row_mask:0xf bank_mask:0xf bound_ctrl:1
	s_and_saveexec_b64 s[0:1], s[6:7]
	v_add_f32_e32 v6, v6, v7
	v_add_f32_e32 v6, v117, v6
	ds_write_b32 v96, v6 offset:352
	s_or_b64 exec, exec, s[0:1]
	s_waitcnt vmcnt(8)
	v_mul_f32_e32 v3, v3, v116
	v_fmac_f32_e32 v3, v2, v114
	v_fmac_f32_e32 v3, v4, v115
	v_fmac_f32_e32 v3, v5, v113
	s_nop 1
	v_add_f32_dpp v2, v3, v3 quad_perm:[1,0,3,2] row_mask:0xf bank_mask:0xf bound_ctrl:1
	s_nop 1
	v_add_f32_dpp v2, v2, v2 quad_perm:[2,3,0,1] row_mask:0xf bank_mask:0xf bound_ctrl:1
	s_nop 1
	v_add_f32_dpp v2, v2, v2 row_ror:4 row_mask:0xf bank_mask:0xf bound_ctrl:1
	s_nop 1
	v_mov_b32_dpp v3, v2 row_ror:8 row_mask:0xf bank_mask:0xf bound_ctrl:1
	s_and_saveexec_b64 s[0:1], s[6:7]
	v_add_f32_e32 v2, v2, v3
	v_add_f32_e32 v2, v117, v2
	ds_write_b32 v96, v2 offset:368
	s_or_b64 exec, exec, s[0:1]
	v_lshlrev_b64 v[2:3], 6, v[92:93]
	v_lshl_add_u64 v[6:7], v[2:3], 2, v[86:87]
	v_lshl_add_u64 v[54:55], v[6:7], 0, v[82:83]
	v_add_co_u32_e32 v2, vcc, 0x1000, v54
	v_mov_b32_e32 v91, v83
	s_nop 0
	v_addc_co_u32_e32 v3, vcc, 0, v55, vcc
	v_add_co_u32_e32 v8, vcc, 0x3000, v54
	v_lshl_add_u64 v[10:11], v[6:7], 0, v[90:91]
	s_nop 0
	v_addc_co_u32_e32 v9, vcc, 0, v55, vcc
	v_add_co_u32_e32 v14, vcc, s43, v54
	global_load_dwordx4 v[30:33], v[54:55], off nt
	s_nop 0
	global_load_dwordx4 v[2:5], v[2:3], off offset:2048 nt
	v_addc_co_u32_e32 v15, vcc, 0, v55, vcc
	v_add_co_u32_e32 v18, vcc, 0x7000, v54
	global_load_dwordx4 v[6:9], v[8:9], off nt
	s_nop 0
	global_load_dwordx4 v[10:13], v[10:11], off nt
	v_addc_co_u32_e32 v19, vcc, 0, v55, vcc
	v_add_co_u32_e32 v22, vcc, 0x9000, v54
	global_load_dwordx4 v[14:17], v[14:15], off offset:2048 nt
	s_nop 0
	global_load_dwordx4 v[18:21], v[18:19], off offset:2048 nt
	v_addc_co_u32_e32 v23, vcc, 0, v55, vcc
	v_add_co_u32_e32 v26, vcc, 0xa000, v54
	s_waitcnt vmcnt(13)
	v_mul_f32_e32 v56, v75, v116
	v_addc_co_u32_e32 v27, vcc, 0, v55, vcc
	global_load_dwordx4 v[22:25], v[22:23], off nt
	s_nop 0
	global_load_dwordx4 v[26:29], v[26:27], off offset:2048 nt
	v_fmac_f32_e32 v56, v74, v114
	v_fmac_f32_e32 v56, v76, v115
	v_fmac_f32_e32 v56, v77, v113
	s_nop 1
	v_add_f32_dpp v56, v56, v56 quad_perm:[1,0,3,2] row_mask:0xf bank_mask:0xf bound_ctrl:1
	s_nop 1
	v_add_f32_dpp v56, v56, v56 quad_perm:[2,3,0,1] row_mask:0xf bank_mask:0xf bound_ctrl:1
	s_nop 1
	v_add_f32_dpp v56, v56, v56 row_ror:4 row_mask:0xf bank_mask:0xf bound_ctrl:1
	s_nop 1
	v_mov_b32_dpp v57, v56 row_ror:8 row_mask:0xf bank_mask:0xf bound_ctrl:1
	s_and_saveexec_b64 s[0:1], s[6:7]
	v_add_f32_e32 v56, v56, v57
	v_add_f32_e32 v56, v117, v56
	ds_write_b32 v96, v56 offset:384
	s_or_b64 exec, exec, s[0:1]
	s_waitcnt vmcnt(14)
; template <int NB>
; __device__ __forceinline__ void sb_decode_task(const Params& P, float* lds, int task) {
;     ...
;         for (int i = 0; i < NB; ++i) { const int s = 4 * NB * kb + 4 * i + g;
;             float part = q0 * cur[i].x + q1 * cur[i].y + q2 * cur[i].z + q3 * cur[i].w; part = sum16(part);
;             if (c == 0) zl[s] = part + bias; }
; #pragma unroll
;         for (int i = 0; i < NB; ++i) cur[i] = nx[i];
;     }
;     asm volatile("s_waitcnt lgkmcnt(0)" ::: "memory");
;     __builtin_amdgcn_wave_barrier();
;     const float z0 = zl[2 * lane], z1 = zl[2 * lane + 1];
	v_mul_f32_e32 v56, v67, v116
	v_fmac_f32_e32 v56, v66, v114
	v_fmac_f32_e32 v56, v68, v115
	v_fmac_f32_e32 v56, v69, v113
	s_nop 1
	v_add_f32_dpp v56, v56, v56 quad_perm:[1,0,3,2] row_mask:0xf bank_mask:0xf bound_ctrl:1
	s_nop 1
	v_add_f32_dpp v56, v56, v56 quad_perm:[2,3,0,1] row_mask:0xf bank_mask:0xf bound_ctrl:1
	s_nop 1
	v_add_f32_dpp v56, v56, v56 row_ror:4 row_mask:0xf bank_mask:0xf bound_ctrl:1
	s_nop 1
	v_mov_b32_dpp v57, v56 row_ror:8 row_mask:0xf bank_mask:0xf bound_ctrl:1
	s_and_saveexec_b64 s[0:1], s[6:7]
	v_add_f32_e32 v56, v56, v57
	v_add_f32_e32 v56, v117, v56
	ds_write_b32 v96, v56 offset:400
	s_or_b64 exec, exec, s[0:1]
	s_waitcnt vmcnt(13)
	v_mul_f32_e32 v56, v59, v116
	v_fmac_f32_e32 v56, v58, v114
	v_fmac_f32_e32 v56, v60, v115
	v_fmac_f32_e32 v56, v61, v113
	s_nop 1
	v_add_f32_dpp v56, v56, v56 quad_perm:[1,0,3,2] row_mask:0xf bank_mask:0xf bound_ctrl:1
	s_nop 1
	v_add_f32_dpp v56, v56, v56 quad_perm:[2,3,0,1] row_mask:0xf bank_mask:0xf bound_ctrl:1
	s_nop 1
	v_add_f32_dpp v56, v56, v56 row_ror:4 row_mask:0xf bank_mask:0xf bound_ctrl:1
	s_nop 1
	v_mov_b32_dpp v57, v56 row_ror:8 row_mask:0xf bank_mask:0xf bound_ctrl:1
	s_and_saveexec_b64 s[0:1], s[6:7]
	v_add_f32_e32 v56, v56, v57
	v_add_f32_e32 v56, v117, v56
	ds_write_b32 v96, v56 offset:416
	s_or_b64 exec, exec, s[0:1]
	s_waitcnt vmcnt(12)
	v_mul_f32_e32 v51, v51, v116
	v_fmac_f32_e32 v51, v50, v114
	v_fmac_f32_e32 v51, v52, v115
	v_fmac_f32_e32 v51, v53, v113
	s_nop 1
	v_add_f32_dpp v50, v51, v51 quad_perm:[1,0,3,2] row_mask:0xf bank_mask:0xf bound_ctrl:1
	s_nop 1
	v_add_f32_dpp v50, v50, v50 quad_perm:[2,3,0,1] row_mask:0xf bank_mask:0xf bound_ctrl:1
	s_nop 1
	v_add_f32_dpp v50, v50, v50 row_ror:4 row_mask:0xf bank_mask:0xf bound_ctrl:1
	s_nop 1
	v_mov_b32_dpp v51, v50 row_ror:8 row_mask:0xf bank_mask:0xf bound_ctrl:1
	s_and_saveexec_b64 s[0:1], s[6:7]
	v_add_f32_e32 v50, v50, v51
	v_add_f32_e32 v50, v117, v50
	ds_write_b32 v96, v50 offset:432
	s_or_b64 exec, exec, s[0:1]
	s_waitcnt vmcnt(11)
	v_mul_f32_e32 v47, v47, v116
	v_fmac_f32_e32 v47, v46, v114
	v_fmac_f32_e32 v47, v48, v115
	v_fmac_f32_e32 v47, v49, v113
	s_nop 1
	v_add_f32_dpp v46, v47, v47 quad_perm:[1,0,3,2] row_mask:0xf bank_mask:0xf bound_ctrl:1
	s_nop 1
	v_add_f32_dpp v46, v46, v46 quad_perm:[2,3,0,1] row_mask:0xf bank_mask:0xf bound_ctrl:1
	s_nop 1
	v_add_f32_dpp v46, v46, v46 row_ror:4 row_mask:0xf bank_mask:0xf bound_ctrl:1
	s_nop 1
	v_mov_b32_dpp v47, v46 row_ror:8 row_mask:0xf bank_mask:0xf bound_ctrl:1
	s_and_saveexec_b64 s[0:1], s[6:7]
	v_add_f32_e32 v46, v46, v47
	v_add_f32_e32 v46, v117, v46
	ds_write_b32 v96, v46 offset:448
	s_or_b64 exec, exec, s[0:1]
	s_waitcnt vmcnt(10)
	v_mul_f32_e32 v43, v43, v116
	v_fmac_f32_e32 v43, v42, v114
	v_fmac_f32_e32 v43, v44, v115
	v_fmac_f32_e32 v43, v45, v113
	s_nop 1
	v_add_f32_dpp v42, v43, v43 quad_perm:[1,0,3,2] row_mask:0xf bank_mask:0xf bound_ctrl:1
	s_nop 1
	v_add_f32_dpp v42, v42, v42 quad_perm:[2,3,0,1] row_mask:0xf bank_mask:0xf bound_ctrl:1
	s_nop 1
	v_add_f32_dpp v42, v42, v42 row_ror:4 row_mask:0xf bank_mask:0xf bound_ctrl:1
	s_nop 1
	v_mov_b32_dpp v43, v42 row_ror:8 row_mask:0xf bank_mask:0xf bound_ctrl:1
	s_and_saveexec_b64 s[0:1], s[6:7]
	v_add_f32_e32 v42, v42, v43
	v_add_f32_e32 v42, v117, v42
	ds_write_b32 v96, v42 offset:464
	s_or_b64 exec, exec, s[0:1]
	s_waitcnt vmcnt(9)
	v_mul_f32_e32 v39, v39, v116
	v_fmac_f32_e32 v39, v38, v114
	v_fmac_f32_e32 v39, v40, v115
	v_fmac_f32_e32 v39, v41, v113
	s_nop 1
	v_add_f32_dpp v38, v39, v39 quad_perm:[1,0,3,2] row_mask:0xf bank_mask:0xf bound_ctrl:1
	s_nop 1
	v_add_f32_dpp v38, v38, v38 quad_perm:[2,3,0,1] row_mask:0xf bank_mask:0xf bound_ctrl:1
	s_nop 1
	v_add_f32_dpp v38, v38, v38 row_ror:4 row_mask:0xf bank_mask:0xf bound_ctrl:1
	s_nop 1
	v_mov_b32_dpp v39, v38 row_ror:8 row_mask:0xf bank_mask:0xf bound_ctrl:1
	s_and_saveexec_b64 s[0:1], s[6:7]
	v_add_f32_e32 v38, v38, v39
	v_add_f32_e32 v38, v117, v38
	ds_write_b32 v96, v38 offset:480
	s_or_b64 exec, exec, s[0:1]
	s_waitcnt vmcnt(8)
	v_mul_f32_e32 v35, v35, v116
	v_fmac_f32_e32 v35, v34, v114
	v_fmac_f32_e32 v35, v36, v115
	v_fmac_f32_e32 v35, v37, v113
	s_nop 1
	v_add_f32_dpp v34, v35, v35 quad_perm:[1,0,3,2] row_mask:0xf bank_mask:0xf bound_ctrl:1
	s_nop 1
	v_add_f32_dpp v34, v34, v34 quad_perm:[2,3,0,1] row_mask:0xf bank_mask:0xf bound_ctrl:1
	s_nop 1
	v_add_f32_dpp v34, v34, v34 row_ror:4 row_mask:0xf bank_mask:0xf bound_ctrl:1
	s_nop 1
	v_mov_b32_dpp v35, v34 row_ror:8 row_mask:0xf bank_mask:0xf bound_ctrl:1
	s_and_saveexec_b64 s[0:1], s[6:7]
	v_add_f32_e32 v34, v34, v35
	v_add_f32_e32 v34, v117, v34
	ds_write_b32 v96, v34 offset:496
	s_or_b64 exec, exec, s[0:1]
	s_waitcnt lgkmcnt(0)
	ds_read_b64 v[34:35], v97
	s_waitcnt lgkmcnt(0)
; __device__ __forceinline__ float softplus2_(float z2) { return fmaxf(z2, 0.f) + log1pf(exp2f(-fabsf(z2))) * LOG2E; }
; template <int NB>
; __device__ __forceinline__ void sb_decode_task(const Params& P, float* lds, int task) {
;     ...
;     const float z0 = zl[2 * lane], z1 = zl[2 * lane + 1];
;     const float sp0 = softplus2_(z0), sp1 = softplus2_(z1);
	v_cmp_gt_f32_e64 vcc, |v34|, s49
	s_nop 1
	v_cndmask_b32_e32 v37, 0, v101, vcc
	v_sub_f32_e64 v37, v37, |v34|
	v_exp_f32_e32 v37, v37
	v_max_f32_e32 v36, v34, v34
	v_max_f32_e32 v38, 0, v36
	v_cndmask_b32_e32 v36, 0, v100, vcc
	v_ldexp_f32 v39, v37, v36
	v_add_f32_e32 v40, 1.0, v39
	v_add_f32_e32 v36, -1.0, v40
	v_sub_f32_e32 v37, v36, v40
	v_add_f32_e32 v37, 1.0, v37
	v_sub_f32_e32 v36, v39, v36
	v_add_f32_e32 v41, v36, v37
	v_frexp_mant_f32_e32 v36, v40
	v_cmp_gt_f32_e32 vcc, s50, v36
	v_cvt_f64_f32_e32 v[36:37], v40
	v_frexp_exp_i32_f64_e32 v36, v[36:37]
	v_subbrev_co_u32_e32 v36, vcc, 0, v36, vcc
	v_sub_u32_e32 v37, 0, v36
	v_ldexp_f32 v40, v40, v37
	v_ldexp_f32 v37, v41, v37
	v_add_f32_e32 v41, -1.0, v40
	v_add_f32_e32 v42, 1.0, v41
	v_sub_f32_e32 v42, v40, v42
	v_add_f32_e32 v42, v37, v42
	v_add_f32_e32 v43, v41, v42
	v_sub_f32_e32 v41, v41, v43
	v_add_f32_e32 v41, v42, v41
	v_add_f32_e32 v42, 1.0, v40
	v_add_f32_e32 v44, -1.0, v42
	v_sub_f32_e32 v40, v40, v44
	v_add_f32_e32 v37, v37, v40
	v_add_f32_e32 v40, v42, v37
	v_sub_f32_e32 v42, v42, v40
	v_add_f32_e32 v37, v37, v42
	v_rcp_f32_e32 v42, v40
	v_cvt_f32_i32_e32 v36, v36
	v_cmp_neq_f32_e32 vcc, s52, v39
	v_mul_f32_e32 v44, v43, v42
	v_mul_f32_e32 v45, v40, v44
	v_fma_f32 v46, v44, v40, -v45
	v_fmac_f32_e32 v46, v44, v37
	v_add_f32_e32 v47, v45, v46
	v_sub_f32_e32 v48, v43, v47
	v_sub_f32_e32 v43, v43, v48
	v_sub_f32_e32 v45, v47, v45
	v_sub_f32_e32 v43, v43, v47
	v_add_f32_e32 v41, v41, v43
	v_sub_f32_e32 v43, v45, v46
	v_add_f32_e32 v41, v43, v41
	v_add_f32_e32 v43, v48, v41
	v_mul_f32_e32 v45, v42, v43
	v_mul_f32_e32 v46, v40, v45
	v_fma_f32 v40, v45, v40, -v46
	v_fmac_f32_e32 v40, v45, v37
	v_sub_f32_e32 v37, v48, v43
	v_add_f32_e32 v37, v41, v37
	v_add_f32_e32 v41, v46, v40
	v_sub_f32_e32 v47, v43, v41
	v_sub_f32_e32 v43, v43, v47
	v_sub_f32_e32 v46, v41, v46
	v_sub_f32_e32 v41, v43, v41
	v_add_f32_e32 v37, v37, v41
	v_sub_f32_e32 v40, v46, v40
	v_add_f32_e32 v37, v40, v37
	v_add_f32_e32 v40, v44, v45
	v_add_f32_e32 v37, v47, v37
	v_sub_f32_e32 v41, v40, v44
	v_mul_f32_e32 v37, v42, v37
	v_sub_f32_e32 v41, v45, v41
	v_add_f32_e32 v37, v41, v37
	v_mul_f32_e32 v44, 0x3f317218, v36
	v_add_f32_e32 v41, v40, v37
	v_fma_f32 v45, v36, s51, -v44
	v_mul_f32_e32 v42, v41, v41
	v_fmac_f32_e32 v45, 0xb102e308, v36
	v_sub_f32_e32 v36, v41, v40
	v_fmamk_f32 v43, v42, 0x3e9b6dac, v98
	v_sub_f32_e32 v36, v37, v36
	v_add_f32_e32 v37, v44, v45
	v_fmaak_f32 v43, v42, v43, 0x3f2aaada
	v_sub_f32_e32 v40, v37, v44
	v_ldexp_f32 v44, v41, 1
	v_mul_f32_e32 v41, v41, v42
	v_mul_f32_e32 v41, v41, v43
	v_add_f32_e32 v42, v44, v41
	v_sub_f32_e32 v43, v42, v44
	v_ldexp_f32 v36, v36, 1
	v_sub_f32_e32 v41, v41, v43
	v_add_f32_e32 v36, v36, v41
	v_add_f32_e32 v41, v42, v36
	v_sub_f32_e32 v42, v41, v42
	v_sub_f32_e32 v36, v36, v42
	v_add_f32_e32 v42, v37, v41
	v_sub_f32_e32 v43, v42, v37
	v_sub_f32_e32 v44, v42, v43
	v_sub_f32_e32 v40, v45, v40
	v_sub_f32_e32 v37, v37, v44
	v_sub_f32_e32 v41, v41, v43
	v_add_f32_e32 v37, v41, v37
	v_add_f32_e32 v41, v40, v36
	v_sub_f32_e32 v43, v41, v40
	v_sub_f32_e32 v44, v41, v43
	v_sub_f32_e32 v40, v40, v44
	v_sub_f32_e32 v36, v36, v43
	v_add_f32_e32 v37, v41, v37
	v_add_f32_e32 v36, v36, v40
	v_add_f32_e32 v40, v42, v37
	v_sub_f32_e32 v41, v40, v42
	v_sub_f32_e32 v37, v37, v41
	v_add_f32_e32 v36, v36, v37
	v_add_f32_e32 v36, v40, v36
	v_cndmask_b32_e32 v36, v102, v36, vcc
	v_cmp_lt_f32_e64 vcc, |v39|, s53
	s_nop 1
	v_cndmask_b32_e32 v36, v36, v39, vcc
	v_cmp_gt_f32_e64 vcc, |v35|, s49
	v_fmac_f32_e32 v38, 0x3fb8aa3b, v36
	v_max_f32_e32 v36, v35, v35
	v_cndmask_b32_e32 v37, 0, v101, vcc
	v_sub_f32_e64 v37, v37, |v35|
	v_exp_f32_e32 v37, v37
	v_max_f32_e32 v39, 0, v36
	v_cndmask_b32_e32 v36, 0, v100, vcc
	v_sub_f32_e32 v34, v34, v38
	v_ldexp_f32 v40, v37, v36
	v_add_f32_e32 v41, 1.0, v40
	v_add_f32_e32 v36, -1.0, v41
	v_sub_f32_e32 v37, v36, v41
	v_add_f32_e32 v37, 1.0, v37
	v_sub_f32_e32 v36, v40, v36
	v_add_f32_e32 v42, v36, v37
	v_frexp_mant_f32_e32 v36, v41
	v_cmp_gt_f32_e32 vcc, s50, v36
	v_cvt_f64_f32_e32 v[36:37], v41
	v_frexp_exp_i32_f64_e32 v36, v[36:37]
	v_subbrev_co_u32_e32 v36, vcc, 0, v36, vcc
	v_sub_u32_e32 v37, 0, v36
	v_ldexp_f32 v41, v41, v37
	v_ldexp_f32 v37, v42, v37
	v_add_f32_e32 v42, -1.0, v41
	v_add_f32_e32 v43, 1.0, v42
	v_sub_f32_e32 v43, v41, v43
	v_add_f32_e32 v43, v37, v43
	v_add_f32_e32 v44, v42, v43
	v_sub_f32_e32 v42, v42, v44
	v_add_f32_e32 v42, v43, v42
	v_add_f32_e32 v43, 1.0, v41
	v_add_f32_e32 v45, -1.0, v43
	v_sub_f32_e32 v41, v41, v45
	v_add_f32_e32 v37, v37, v41
	v_add_f32_e32 v41, v43, v37
	v_sub_f32_e32 v43, v43, v41
	v_add_f32_e32 v37, v37, v43
	v_rcp_f32_e32 v43, v41
	v_cvt_f32_i32_e32 v36, v36
	v_cmp_neq_f32_e32 vcc, s52, v40
	v_mul_f32_e32 v45, v44, v43
	v_mul_f32_e32 v46, v41, v45
	v_fma_f32 v47, v45, v41, -v46
	v_fmac_f32_e32 v47, v45, v37
	v_add_f32_e32 v48, v46, v47
	v_sub_f32_e32 v49, v44, v48
	v_sub_f32_e32 v44, v44, v49
	v_sub_f32_e32 v46, v48, v46
	v_sub_f32_e32 v44, v44, v48
	v_add_f32_e32 v42, v42, v44
	v_sub_f32_e32 v44, v46, v47
	v_add_f32_e32 v42, v44, v42
	v_add_f32_e32 v44, v49, v42
	v_mul_f32_e32 v46, v43, v44
	v_mul_f32_e32 v47, v41, v46
	v_fma_f32 v41, v46, v41, -v47
	v_fmac_f32_e32 v41, v46, v37
	v_sub_f32_e32 v37, v49, v44
	v_add_f32_e32 v37, v42, v37
	v_add_f32_e32 v42, v47, v41
	v_sub_f32_e32 v48, v44, v42
	v_sub_f32_e32 v44, v44, v48
	v_sub_f32_e32 v47, v42, v47
	v_sub_f32_e32 v42, v44, v42
	v_add_f32_e32 v37, v37, v42
	v_sub_f32_e32 v41, v47, v41
	v_add_f32_e32 v37, v41, v37
	v_add_f32_e32 v41, v45, v46
	v_add_f32_e32 v37, v48, v37
	v_sub_f32_e32 v42, v41, v45
	v_mul_f32_e32 v37, v43, v37
; __device__ __forceinline__ float softplus2_(float z2) { return fmaxf(z2, 0.f) + log1pf(exp2f(-fabsf(z2))) * LOG2E; }
; template <int NB>
; __device__ __forceinline__ void sb_decode_task(const Params& P, float* lds, int task) {
;     ...
;     const float sp0 = softplus2_(z0), sp1 = softplus2_(z1);
;     float incl = sp0 + sp1;
; #pragma unroll
;     for (int off = 1; off < 64; off <<= 1) { const float t = __shfl_down(incl, off); if (lane + off < 64) incl += t; }
;     const float excl = incl - (sp0 + sp1);
;     wl[2 * lane] = exp2f(z0 - sp0 - (excl + sp1));
;     wl[2 * lane + 1] = exp2f(z1 - sp1 - excl);
;     const float Ltot = __shfl(incl, 0);
;     asm volatile("s_waitcnt lgkmcnt(0)" ::: "memory");
;     __builtin_amdgcn_wave_barrier();
;     float4 o4 = make_float4(0.f, 0.f, 0.f, 0.f);
; #pragma unroll
;     for (int vb = 0; vb < NBT; ++vb) {
;         if (vb + 1 < NBT) {
; #pragma unroll
;             for (int i = 0; i < NB; ++i) nx[i] = *(const float4*)(Vp + (size_t)(4 * NB * (vb + 1) + 4 * i + g) * (SH * HD)); }
; #pragma unroll
;         for (int i = 0; i < NB; ++i) { const float w = wl[4 * NB * vb + 4 * i + g]; o4.x += w * cur[i].x; o4.y += w * cur[i].y; o4.z += w * cur[i].z; o4.w += w * cur[i].w; }
	v_sub_f32_e32 v42, v46, v42
	v_add_f32_e32 v37, v42, v37
	v_mul_f32_e32 v45, 0x3f317218, v36
	v_add_f32_e32 v42, v41, v37
	v_fma_f32 v46, v36, s51, -v45
	v_mul_f32_e32 v43, v42, v42
	v_fmac_f32_e32 v46, 0xb102e308, v36
	v_sub_f32_e32 v36, v42, v41
	v_fmamk_f32 v44, v43, 0x3e9b6dac, v98
	v_sub_f32_e32 v36, v37, v36
	v_add_f32_e32 v37, v45, v46
	v_fmaak_f32 v44, v43, v44, 0x3f2aaada
	v_sub_f32_e32 v41, v37, v45
	v_ldexp_f32 v45, v42, 1
	v_mul_f32_e32 v42, v42, v43
	v_mul_f32_e32 v42, v42, v44
	v_add_f32_e32 v43, v45, v42
	v_sub_f32_e32 v44, v43, v45
	v_ldexp_f32 v36, v36, 1
	v_sub_f32_e32 v42, v42, v44
	v_add_f32_e32 v36, v36, v42
	v_add_f32_e32 v42, v43, v36
	v_sub_f32_e32 v43, v42, v43
	v_sub_f32_e32 v36, v36, v43
	v_add_f32_e32 v43, v37, v42
	v_sub_f32_e32 v44, v43, v37
	v_sub_f32_e32 v45, v43, v44
	v_sub_f32_e32 v41, v46, v41
	v_sub_f32_e32 v37, v37, v45
	v_sub_f32_e32 v42, v42, v44
	v_add_f32_e32 v37, v42, v37
	v_add_f32_e32 v42, v41, v36
	v_sub_f32_e32 v44, v42, v41
	v_sub_f32_e32 v45, v42, v44
	v_sub_f32_e32 v41, v41, v45
	v_sub_f32_e32 v36, v36, v44
	v_add_f32_e32 v37, v42, v37
	v_add_f32_e32 v36, v36, v41
	v_add_f32_e32 v41, v43, v37
	v_sub_f32_e32 v42, v41, v43
	v_sub_f32_e32 v37, v37, v42
	v_add_f32_e32 v36, v36, v37
	v_add_f32_e32 v36, v41, v36
	v_cndmask_b32_e32 v36, v102, v36, vcc
	v_cmp_lt_f32_e64 vcc, |v40|, s53
	s_nop 1
	v_cndmask_b32_e32 v36, v36, v40, vcc
	v_fmac_f32_e32 v39, 0x3fb8aa3b, v36
	v_add_f32_e32 v36, v38, v39
	ds_bpermute_b32 v37, v106, v36
	v_sub_f32_e32 v35, v35, v39
	s_waitcnt lgkmcnt(0)
	v_add_f32_e32 v37, v36, v37
	v_cndmask_b32_e64 v37, v37, v36, s[8:9]
	ds_bpermute_b32 v40, v107, v37
	s_waitcnt lgkmcnt(0)
	v_add_f32_e32 v40, v37, v40
	v_cndmask_b32_e64 v37, v37, v40, s[10:11]
	ds_bpermute_b32 v40, v108, v37
	s_waitcnt lgkmcnt(0)
	v_add_f32_e32 v40, v37, v40
	v_cndmask_b32_e64 v37, v37, v40, s[12:13]
	ds_bpermute_b32 v40, v109, v37
	s_waitcnt lgkmcnt(0)
	v_add_f32_e32 v40, v37, v40
	v_cndmask_b32_e64 v37, v37, v40, s[14:15]
	ds_bpermute_b32 v40, v110, v37
	s_waitcnt lgkmcnt(0)
	v_add_f32_e32 v40, v37, v40
	v_cndmask_b32_e64 v37, v37, v40, s[16:17]
	ds_bpermute_b32 v40, v111, v37
	s_waitcnt lgkmcnt(0)
	v_add_f32_e32 v40, v37, v40
	v_cndmask_b32_e64 v44, v37, v40, s[18:19]
	v_sub_f32_e32 v36, v44, v36
	v_add_f32_e32 v37, v39, v36
	v_sub_f32_e32 v34, v34, v37
	v_cmp_gt_f32_e32 vcc, s54, v34
	v_sub_f32_e32 v35, v35, v36
	s_nop 0
	v_cndmask_b32_e32 v37, 0, v101, vcc
	v_add_f32_e32 v34, v34, v37
	v_cndmask_b32_e32 v37, 0, v100, vcc
	v_cmp_gt_f32_e32 vcc, s54, v35
	v_exp_f32_e32 v34, v34
	s_nop 0
	v_cndmask_b32_e32 v36, 0, v101, vcc
	v_add_f32_e32 v35, v35, v36
	v_exp_f32_e32 v35, v35
	v_cndmask_b32_e32 v36, 0, v100, vcc
	v_ldexp_f32 v34, v34, v37
	v_ldexp_f32 v35, v35, v36
	ds_write_b64 v97, v[34:35] offset:512
	s_waitcnt lgkmcnt(0)
	ds_read2_b32 v[34:35], v96 offset0:128 offset1:132
	ds_read2_b32 v[42:43], v96 offset0:136 offset1:140
	ds_read2_b32 v[66:67], v96 offset0:144 offset1:148
	ds_read2_b32 v[68:69], v96 offset0:152 offset1:156
	ds_read2_b32 v[74:75], v96 offset0:160 offset1:164
	ds_read2_b32 v[76:77], v96 offset0:168 offset1:172
	ds_read2_b32 v[38:39], v96 offset0:176 offset1:180
	ds_read2_b32 v[40:41], v96 offset0:184 offset1:188
	s_waitcnt vmcnt(7) lgkmcnt(7)
	v_pk_fma_f32 v[70:71], v[30:31], v[34:35], 0 op_sel_hi:[1,0,0]
	v_add_co_u32_e32 v30, vcc, s55, v54
	v_pk_fma_f32 v[72:73], v[32:33], v[34:35], 0 op_sel_hi:[1,0,0]
	s_nop 0
	v_addc_co_u32_e32 v31, vcc, 0, v55, vcc
	v_add_co_u32_e32 v34, vcc, s83, v54
	v_mov_b32_e32 v64, v35
	s_nop 0
	v_addc_co_u32_e32 v35, vcc, 0, v55, vcc
	v_add_co_u32_e32 v46, vcc, s86, v54
	s_waitcnt vmcnt(6)
	v_pk_fma_f32 v[2:3], v[2:3], v[64:65], v[70:71] op_sel_hi:[1,0,1]
	v_addc_co_u32_e32 v47, vcc, 0, v55, vcc
	v_add_co_u32_e32 v50, vcc, s87, v54
	global_load_dwordx4 v[46:49], v[46:47], off nt
	s_nop 0
	v_addc_co_u32_e32 v51, vcc, 0, v55, vcc
	v_add_co_u32_e32 v56, vcc, s88, v54
	global_load_dwordx4 v[50:53], v[50:51], off offset:2048 nt
	s_nop 0
	v_addc_co_u32_e32 v57, vcc, 0, v55, vcc
	v_add_co_u32_e32 v60, vcc, s89, v54
	global_load_dwordx4 v[56:59], v[56:57], off nt
	s_nop 0
	v_addc_co_u32_e32 v61, vcc, 0, v55, vcc
	global_load_dwordx4 v[60:63], v[60:61], off offset:2048 nt
	s_waitcnt lgkmcnt(6)
	v_mov_b32_e32 v78, v43
	s_waitcnt vmcnt(9)
	v_pk_fma_f32 v[2:3], v[6:7], v[42:43], v[2:3] op_sel_hi:[1,0,1]
	s_waitcnt lgkmcnt(5)
	v_mov_b32_e32 v80, v67
	s_waitcnt vmcnt(7)
	v_pk_fma_f32 v[2:3], v[14:15], v[78:79], v[2:3] op_sel_hi:[1,0,1]
	s_waitcnt lgkmcnt(4)
	v_mov_b32_e32 v92, v69
	v_pk_fma_f32 v[2:3], v[10:11], v[66:67], v[2:3] op_sel_hi:[1,0,1]
	s_waitcnt lgkmcnt(3)
	v_mov_b32_e32 v10, v75
	s_waitcnt vmcnt(6)
	v_pk_fma_f32 v[2:3], v[18:19], v[80:81], v[2:3] op_sel_hi:[1,0,1]
	s_waitcnt lgkmcnt(2)
	v_mov_b32_e32 v14, v77
	s_waitcnt vmcnt(5)
	v_pk_fma_f32 v[2:3], v[22:23], v[68:69], v[2:3] op_sel_hi:[1,0,1]
	global_load_dwordx4 v[30:33], v[30:31], off nt
	s_waitcnt vmcnt(5)
	v_pk_fma_f32 v[2:3], v[26:27], v[92:93], v[2:3] op_sel_hi:[1,0,1]
	global_load_dwordx4 v[34:37], v[34:35], off offset:2048 nt
	s_waitcnt vmcnt(5)
	v_pk_fma_f32 v[2:3], v[46:47], v[74:75], v[2:3] op_sel_hi:[1,0,1]
	s_waitcnt vmcnt(4)
	v_pk_fma_f32 v[2:3], v[50:51], v[10:11], v[2:3] op_sel_hi:[1,0,1]
	s_waitcnt vmcnt(3)
	v_pk_fma_f32 v[2:3], v[56:57], v[76:77], v[2:3] op_sel_hi:[1,0,1]
	s_waitcnt vmcnt(2)
	v_pk_fma_f32 v[6:7], v[60:61], v[14:15], v[2:3] op_sel_hi:[1,0,1]
	v_pk_fma_f32 v[2:3], v[4:5], v[64:65], v[72:73] op_sel_hi:[1,0,1]
	v_add_co_u32_e32 v4, vcc, s90, v54
	v_pk_fma_f32 v[2:3], v[8:9], v[42:43], v[2:3] op_sel_hi:[1,0,1]
	s_nop 0
	v_addc_co_u32_e32 v5, vcc, 0, v55, vcc
	v_pk_fma_f32 v[2:3], v[16:17], v[78:79], v[2:3] op_sel_hi:[1,0,1]
	s_waitcnt lgkmcnt(0)
; template <int NB>
; __device__ __forceinline__ void sb_decode_task(const Params& P, float* lds, int task) {
;     ...
;     for (int vb = 0; vb < NBT; ++vb) {
;         if (vb + 1 < NBT) {
; #pragma unroll
;             for (int i = 0; i < NB; ++i) nx[i] = *(const float4*)(Vp + (size_t)(4 * NB * (vb + 1) + 4 * i + g) * (SH * HD)); }
; #pragma unroll
;         for (int i = 0; i < NB; ++i) { const float w = wl[4 * NB * vb + 4 * i + g]; o4.x += w * cur[i].x; o4.y += w * cur[i].y; o4.z += w * cur[i].z; o4.w += w * cur[i].w; }
; #pragma unroll
;         for (int i = 0; i < NB; ++i) cur[i] = nx[i];
	v_mov_b32_e32 v42, v41
	v_pk_fma_f32 v[2:3], v[12:13], v[66:67], v[2:3] op_sel_hi:[1,0,1]
	s_waitcnt vmcnt(1)
	v_pk_fma_f32 v[6:7], v[30:31], v[38:39], v[6:7] op_sel_hi:[1,0,1]
	v_pk_fma_f32 v[2:3], v[20:21], v[80:81], v[2:3] op_sel_hi:[1,0,1]
	s_nop 0
	v_pk_fma_f32 v[2:3], v[24:25], v[68:69], v[2:3] op_sel_hi:[1,0,1]
	s_nop 0
	v_pk_fma_f32 v[2:3], v[28:29], v[92:93], v[2:3] op_sel_hi:[1,0,1]
	v_mov_b32_e32 v28, v39
	v_pk_fma_f32 v[2:3], v[48:49], v[74:75], v[2:3] op_sel_hi:[1,0,1]
	s_waitcnt vmcnt(0)
	v_pk_fma_f32 v[6:7], v[34:35], v[28:29], v[6:7] op_sel_hi:[1,0,1]
	v_pk_fma_f32 v[2:3], v[52:53], v[10:11], v[2:3] op_sel_hi:[1,0,1]
	s_nop 0
	v_pk_fma_f32 v[2:3], v[58:59], v[76:77], v[2:3] op_sel_hi:[1,0,1]
	s_nop 0
	v_pk_fma_f32 v[2:3], v[62:63], v[14:15], v[2:3] op_sel_hi:[1,0,1]
	ds_read2_b32 v[14:15], v96 offset0:192 offset1:196
	ds_read2_b32 v[12:13], v96 offset0:200 offset1:204
	ds_read2_b32 v[10:11], v96 offset0:208 offset1:212
	ds_read2_b32 v[8:9], v96 offset0:216 offset1:220
	global_load_dwordx4 v[16:19], v[4:5], off nt
	v_add_co_u32_e32 v4, vcc, s91, v54
	v_pk_fma_f32 v[2:3], v[32:33], v[38:39], v[2:3] op_sel_hi:[1,0,1]
	s_nop 0
	v_addc_co_u32_e32 v5, vcc, 0, v55, vcc
	global_load_dwordx4 v[20:23], v[4:5], off offset:2048 nt
	v_add_co_u32_e32 v4, vcc, s92, v54
	v_pk_fma_f32 v[2:3], v[36:37], v[28:29], v[2:3] op_sel_hi:[1,0,1]
	s_nop 0
	v_addc_co_u32_e32 v5, vcc, 0, v55, vcc
	global_load_dwordx4 v[24:27], v[4:5], off nt
	v_add_co_u32_e32 v4, vcc, s93, v54
	s_waitcnt lgkmcnt(0)
	v_mov_b32_e32 v36, v9
	v_addc_co_u32_e32 v5, vcc, 0, v55, vcc
	global_load_dwordx4 v[46:49], v[4:5], off offset:2048 nt
	v_add_co_u32_e32 v4, vcc, s94, v54
	ds_read2_b32 v[30:31], v96 offset0:224 offset1:228
	s_nop 0
	v_addc_co_u32_e32 v5, vcc, 0, v55, vcc
	global_load_dwordx4 v[50:53], v[4:5], off nt
	v_add_co_u32_e32 v4, vcc, s95, v54
	s_waitcnt vmcnt(4)
	v_pk_fma_f32 v[2:3], v[18:19], v[40:41], v[2:3] op_sel_hi:[1,0,1]
	v_addc_co_u32_e32 v5, vcc, 0, v55, vcc
	global_load_dwordx4 v[56:59], v[4:5], off offset:2048 nt
	v_add_co_u32_e32 v4, vcc, s96, v54
	s_waitcnt vmcnt(4)
	v_pk_fma_f32 v[2:3], v[22:23], v[42:43], v[2:3] op_sel_hi:[1,0,1]
	v_addc_co_u32_e32 v5, vcc, 0, v55, vcc
	global_load_dwordx4 v[60:63], v[4:5], off nt
	v_add_co_u32_e32 v4, vcc, s97, v54
	s_waitcnt vmcnt(4)
	v_pk_fma_f32 v[2:3], v[26:27], v[14:15], v[2:3] op_sel_hi:[1,0,1]
	v_addc_co_u32_e32 v5, vcc, 0, v55, vcc
	global_load_dwordx4 v[64:67], v[4:5], off offset:2048 nt
	v_add_co_u32_e32 v4, vcc, s22, v54
	v_mov_b32_e32 v18, v15
	s_nop 0
	v_addc_co_u32_e32 v5, vcc, 0, v55, vcc
	global_load_dwordx4 v[68:71], v[4:5], off nt
	v_pk_fma_f32 v[6:7], v[16:17], v[40:41], v[6:7] op_sel_hi:[1,0,1]
	s_waitcnt vmcnt(5)
	v_pk_fma_f32 v[2:3], v[48:49], v[18:19], v[2:3] op_sel_hi:[1,0,1]
	v_pk_fma_f32 v[6:7], v[20:21], v[42:43], v[6:7] op_sel_hi:[1,0,1]
	s_waitcnt vmcnt(4)
	v_pk_fma_f32 v[2:3], v[52:53], v[12:13], v[2:3] op_sel_hi:[1,0,1]
	v_mov_b32_e32 v22, v13
	v_pk_fma_f32 v[6:7], v[24:25], v[14:15], v[6:7] op_sel_hi:[1,0,1]
	v_mov_b32_e32 v26, v11
	v_pk_fma_f32 v[6:7], v[46:47], v[18:19], v[6:7] op_sel_hi:[1,0,1]
	s_waitcnt vmcnt(3)
	v_pk_fma_f32 v[2:3], v[58:59], v[22:23], v[2:3] op_sel_hi:[1,0,1]
	v_pk_fma_f32 v[6:7], v[50:51], v[12:13], v[6:7] op_sel_hi:[1,0,1]
	s_waitcnt vmcnt(2)
	v_pk_fma_f32 v[2:3], v[62:63], v[10:11], v[2:3] op_sel_hi:[1,0,1]
	v_pk_fma_f32 v[6:7], v[56:57], v[22:23], v[6:7] op_sel_hi:[1,0,1]
	s_waitcnt vmcnt(1)
	v_pk_fma_f32 v[2:3], v[66:67], v[26:27], v[2:3] op_sel_hi:[1,0,1]
	v_pk_fma_f32 v[6:7], v[60:61], v[10:11], v[6:7] op_sel_hi:[1,0,1]
	s_waitcnt vmcnt(0)
; template <int NB>
; __device__ __forceinline__ void sb_decode_task(const Params& P, float* lds, int task) {
;     ...
;     for (int vb = 0; vb < NBT; ++vb) {
;         if (vb + 1 < NBT) {
; #pragma unroll
;             for (int i = 0; i < NB; ++i) nx[i] = *(const float4*)(Vp + (size_t)(4 * NB * (vb + 1) + 4 * i + g) * (SH * HD)); }
; #pragma unroll
;         for (int i = 0; i < NB; ++i) { const float w = wl[4 * NB * vb + 4 * i + g]; o4.x += w * cur[i].x; o4.y += w * cur[i].y; o4.z += w * cur[i].z; o4.w += w * cur[i].w; }
; #pragma unroll
;         for (int i = 0; i < NB; ++i) cur[i] = nx[i];
;     }
; #pragma unroll
;     for (int off = 16; off < 64; off <<= 1) { o4.x += __shfl_xor(o4.x, off); o4.y += __shfl_xor(o4.y, off); o4.z += __shfl_xor(o4.z, off); o4.w += __shfl_xor(o4.w, off); }
;     if (g == 0) *(float4*)(dpart + (size_t)task * HD + 4 * c) = o4;
;     if (lane == 0) dl[task] = Ltot;
	v_pk_fma_f32 v[32:33], v[70:71], v[8:9], v[2:3] op_sel_hi:[1,0,1]
	v_add_co_u32_e32 v2, vcc, s23, v54
	v_pk_fma_f32 v[6:7], v[64:65], v[26:27], v[6:7] op_sel_hi:[1,0,1]
	s_nop 0
	v_addc_co_u32_e32 v3, vcc, 0, v55, vcc
	v_pk_fma_f32 v[34:35], v[68:69], v[8:9], v[6:7] op_sel_hi:[1,0,1]
	v_add_co_u32_e32 v6, vcc, s24, v54
	global_load_dwordx4 v[2:5], v[2:3], off offset:2048 nt
	s_nop 0
	v_addc_co_u32_e32 v7, vcc, 0, v55, vcc
	v_add_co_u32_e32 v10, vcc, s72, v54
	global_load_dwordx4 v[6:9], v[6:7], off nt
	s_nop 0
	v_addc_co_u32_e32 v11, vcc, 0, v55, vcc
	v_add_co_u32_e32 v14, vcc, s73, v54
	ds_read2_b32 v[42:43], v96 offset0:232 offset1:236
	ds_read2_b32 v[40:41], v96 offset0:240 offset1:244
	ds_read2_b32 v[38:39], v96 offset0:248 offset1:252
	v_addc_co_u32_e32 v15, vcc, 0, v55, vcc
	v_add_co_u32_e32 v18, vcc, s74, v54
	global_load_dwordx4 v[10:13], v[10:11], off offset:2048 nt
	s_nop 0
	v_addc_co_u32_e32 v19, vcc, 0, v55, vcc
	v_add_co_u32_e32 v22, vcc, s75, v54
	global_load_dwordx4 v[14:17], v[14:15], off nt
	s_nop 0
	v_addc_co_u32_e32 v23, vcc, 0, v55, vcc
	v_add_co_u32_e32 v26, vcc, s80, v54
	global_load_dwordx4 v[18:21], v[18:19], off offset:2048 nt
	s_nop 0
	v_addc_co_u32_e32 v27, vcc, 0, v55, vcc
	v_add_co_u32_e32 v46, vcc, s81, v54
	global_load_dwordx4 v[22:25], v[22:23], off nt
	s_nop 0
	v_addc_co_u32_e32 v47, vcc, 0, v55, vcc
	global_load_dwordx4 v[26:29], v[26:27], off offset:2048 nt
	v_add_co_u32_e32 v50, vcc, s82, v54
	global_load_dwordx4 v[46:49], v[46:47], off nt
	s_nop 0
	v_addc_co_u32_e32 v51, vcc, 0, v55, vcc
	global_load_dwordx4 v[50:53], v[50:51], off offset:2048 nt
	s_waitcnt lgkmcnt(2)
	v_mov_b32_e32 v54, v43
	s_waitcnt lgkmcnt(1)
	v_mov_b32_e32 v56, v41
	s_waitcnt lgkmcnt(0)
	v_mov_b32_e32 v58, v39
	s_waitcnt vmcnt(8)
	v_pk_fma_f32 v[2:3], v[2:3], v[36:37], v[34:35] op_sel_hi:[1,0,1]
	v_mov_b32_e32 v34, v31
	v_pk_fma_f32 v[4:5], v[4:5], v[36:37], v[32:33] op_sel_hi:[1,0,1]
	s_waitcnt vmcnt(7)
	v_pk_fma_f32 v[2:3], v[6:7], v[30:31], v[2:3] op_sel_hi:[1,0,1]
	v_pk_fma_f32 v[4:5], v[8:9], v[30:31], v[4:5] op_sel_hi:[1,0,1]
	s_waitcnt vmcnt(6)
	v_pk_fma_f32 v[2:3], v[10:11], v[34:35], v[2:3] op_sel_hi:[1,0,1]
	v_pk_fma_f32 v[4:5], v[12:13], v[34:35], v[4:5] op_sel_hi:[1,0,1]
	ds_bpermute_b32 v10, v104, v44
	s_waitcnt vmcnt(5)
	v_pk_fma_f32 v[2:3], v[14:15], v[42:43], v[2:3] op_sel_hi:[1,0,1]
	v_pk_fma_f32 v[4:5], v[16:17], v[42:43], v[4:5] op_sel_hi:[1,0,1]
	s_waitcnt vmcnt(4)
	v_pk_fma_f32 v[2:3], v[18:19], v[54:55], v[2:3] op_sel_hi:[1,0,1]
	v_pk_fma_f32 v[4:5], v[20:21], v[54:55], v[4:5] op_sel_hi:[1,0,1]
	s_waitcnt vmcnt(3)
	v_pk_fma_f32 v[2:3], v[22:23], v[40:41], v[2:3] op_sel_hi:[1,0,1]
	v_pk_fma_f32 v[4:5], v[24:25], v[40:41], v[4:5] op_sel_hi:[1,0,1]
	s_waitcnt vmcnt(2)
	v_pk_fma_f32 v[2:3], v[26:27], v[56:57], v[2:3] op_sel_hi:[1,0,1]
	v_pk_fma_f32 v[4:5], v[28:29], v[56:57], v[4:5] op_sel_hi:[1,0,1]
	s_waitcnt vmcnt(1)
	v_pk_fma_f32 v[2:3], v[46:47], v[38:39], v[2:3] op_sel_hi:[1,0,1]
	v_pk_fma_f32 v[4:5], v[48:49], v[38:39], v[4:5] op_sel_hi:[1,0,1]
	s_waitcnt vmcnt(0)
	v_pk_fma_f32 v[2:3], v[50:51], v[58:59], v[2:3] op_sel_hi:[1,0,1]
	ds_bpermute_b32 v6, v105, v2
	ds_bpermute_b32 v7, v105, v3
	v_pk_fma_f32 v[4:5], v[52:53], v[58:59], v[4:5] op_sel_hi:[1,0,1]
	s_waitcnt lgkmcnt(0)
	v_pk_add_f32 v[2:3], v[2:3], v[6:7]
	ds_bpermute_b32 v6, v105, v4
	ds_bpermute_b32 v7, v105, v5
	s_waitcnt lgkmcnt(0)
	v_pk_add_f32 v[4:5], v[4:5], v[6:7]
	ds_bpermute_b32 v6, v112, v2
	ds_bpermute_b32 v7, v112, v3
	ds_bpermute_b32 v8, v112, v4
	ds_bpermute_b32 v9, v112, v5
	s_and_saveexec_b64 s[0:1], s[20:21]
	s_cbranch_execz .LBB0_1090
	s_ashr_i32 s35, s34, 31
	s_lshl_b64 s[2:3], s[34:35], 8
	v_lshl_add_u64 v[12:13], v[88:89], 0, s[2:3]
	s_waitcnt lgkmcnt(2)
	v_pk_add_f32 v[2:3], v[2:3], v[6:7]
	s_waitcnt lgkmcnt(0)
	v_pk_add_f32 v[4:5], v[4:5], v[8:9]
	global_store_dwordx4 v[12:13], v[2:5], off

; __device__ __forceinline__ float bf2f(bf16_t b) { return __uint_as_float(((unsigned)b) << 16); }
; template <int NB>
; __device__ __forceinline__ void sb_decode_task(const Params& P, float* lds, int task) {
;     const int tid = threadIdx.x, lane = tid & 63, wave = tid >> 6;
;     const bf16_t* qb = (const bf16_t*)(P.ws + WS_QB);
;     float* dpart = (float*)(P.ws + WS_DPART); float* dl = (float*)(P.ws + WS_DL);
;     float* zl = lds + DEC_LDS_OFF / 4 + wave * 256; float* wl = zl + 128;
;     const int c = lane & 15, g = lane >> 4;
;     constexpr int NBT = 32 / NB;
;     const int h = task % SH, bj = task / SH, b = bj / NPAGES;
;     const int page = P.page_table[bj];
;     const float* Kp = P.cache_k + ((size_t)page * PAGE * SH + h) * HD + 4 * c;
;     const float* Vp = P.cache_v + ((size_t)page * PAGE * SH + h) * HD + 4 * c;
;     const bf16_t* qp = qb + (size_t)(NTOK + b) * SBW + h * 64 + 4 * c;
;     const float q0 = bf2f(qp[0]), q1 = bf2f(qp[1]), q2 = bf2f(qp[2]), q3 = bf2f(qp[3]);
;     const float bias = P.sb_bias[h] * LOG2E;
;     float4 cur[NB], nx[NB];
; #pragma unroll
;     for (int i = 0; i < NB; ++i) cur[i] = *(const float4*)(Kp + (size_t)(4 * i + g) * (SH * HD));
; #pragma unroll
;     for (int kb = 0; kb < NBT; ++kb) {
;         const float* np = (kb + 1 < NBT) ? Kp + (size_t)(4 * NB * (kb + 1)) * (SH * HD) : Vp;
; #pragma unroll
;         for (int i = 0; i < NB; ++i) nx[i] = *(const float4*)(np + (size_t)(4 * i + g) * (SH * HD));
; #pragma unroll
;         for (int i = 0; i < NB; ++i) { const int s = 4 * NB * kb + 4 * i + g;
;             float part = q0 * cur[i].x + q1 * cur[i].y + q2 * cur[i].z + q3 * cur[i].w; part = sum16(part);
;             if (c == 0) zl[s] = part + bias; }
; #pragma unroll
;         for (int i = 0; i < NB; ++i) cur[i] = nx[i];
.LBB0_1281:
	v_readlane_b32 s90, v252, 48
	s_lshr_b32 s1, s2, 31
	v_readlane_b32 s91, v252, 49
	s_add_i32 s0, s2, s1
	s_load_dwordx16 s[52:67], s[90:91], 0x0
	s_mul_i32 s3, s0, 6
	s_sub_i32 s36, s34, s3
	s_ashr_i32 s3, s2, 7
	s_add_i32 s3, s3, s1
	s_ashr_i32 s1, s0, 31
	s_lshl_b64 s[0:1], s[0:1], 2
	s_waitcnt lgkmcnt(0)
	s_add_u32 s0, s62, s0
	s_addc_u32 s1, s63, s1
	global_load_dword v2, v83, s[0:1]
	s_add_i32 s0, s3, 0x4000
	s_ashr_i32 s37, s36, 31
	s_mul_hi_i32 s1, s0, 0x300
	s_mulk_i32 s0, 0x300
	s_add_u32 s3, s38, s0
	s_addc_u32 s33, s39, s1
	s_lshl_b32 s0, s36, 6
	s_ashr_i32 s1, s0, 31
	s_lshl_b64 s[0:1], s[0:1], 1
	s_add_u32 s0, s3, s0
	s_addc_u32 s1, s33, s1
	v_readlane_b32 s52, v252, 16
	v_readlane_b32 s53, v252, 17
	v_readlane_b32 s60, v252, 24
	v_readlane_b32 s61, v252, 25
	s_mov_b64 s[52:53], s[60:61]
	v_mov_b32_e32 v93, v83
	v_readlane_b32 s54, v252, 18
	v_readlane_b32 s55, v252, 19
	v_readlane_b32 s56, v252, 20
	v_readlane_b32 s57, v252, 21
	v_readlane_b32 s58, v252, 22
	v_readlane_b32 s59, v252, 23
	v_readlane_b32 s62, v252, 26
	v_readlane_b32 s63, v252, 27
	v_readlane_b32 s64, v252, 28
	v_readlane_b32 s65, v252, 29
	v_readlane_b32 s66, v252, 30
	v_readlane_b32 s67, v252, 31
	s_waitcnt vmcnt(0)
	v_mul_hi_i32 v3, v2, s48
	v_mul_lo_u32 v2, v2, s48
	v_lshl_add_u64 v[94:95], v[2:3], 0, s[36:37]
	v_lshlrev_b64 v[2:3], 8, v[94:95]
	v_lshl_add_u64 v[70:71], v[84:85], 0, v[2:3]
	global_load_dwordx2 v[2:3], v101, s[0:1]
	s_lshl_b64 s[0:1], s[36:37], 2
	s_add_u32 s0, s52, s0
	s_addc_u32 s1, s53, s1
	global_load_dword v22, v83, s[0:1]
	v_lshl_add_u64 v[14:15], v[70:71], 0, v[82:83]
	v_lshl_add_u64 v[16:17], v[70:71], 0, v[92:93]
	global_load_dwordx4 v[18:21], v[14:15], off nt
	s_mov_b64 s[0:1], 0xc000
	global_load_dwordx4 v[62:65], v[16:17], off nt
	s_waitcnt vmcnt(3)
	v_lshlrev_b32_e32 v107, 16, v2
	v_and_b32_e32 v109, 0xffff0000, v2
	v_add_co_u32_e32 v2, vcc, s50, v14
	v_lshlrev_b32_e32 v108, 16, v3
	v_and_b32_e32 v106, 0xffff0000, v3
	v_addc_co_u32_e32 v3, vcc, 0, v15, vcc
	global_load_dwordx4 v[10:13], v[2:3], off offset:2048 nt
	v_add_co_u32_e32 v2, vcc, s51, v14
	s_waitcnt vmcnt(3)
	v_mul_f32_e32 v110, 0x3fb8aa3b, v22
	v_addc_co_u32_e32 v3, vcc, 0, v15, vcc
	global_load_dwordx4 v[6:9], v[2:3], off nt
	v_add_co_u32_e32 v2, vcc, s49, v14
	v_lshl_add_u64 v[22:23], v[70:71], 0, s[0:1]
	s_nop 0
	v_addc_co_u32_e32 v3, vcc, 0, v15, vcc
	v_add_co_u32_e32 v16, vcc, s92, v14
	v_lshl_add_u64 v[30:31], v[22:23], 0, v[82:83]
	s_nop 0
	v_addc_co_u32_e32 v17, vcc, 0, v15, vcc
	global_load_dwordx4 v[58:61], v[16:17], off offset:2048 nt
	v_add_co_u32_e32 v16, vcc, s93, v14
	v_lshl_add_u64 v[22:23], v[22:23], 0, v[92:93]
	s_nop 0
	v_addc_co_u32_e32 v17, vcc, 0, v15, vcc
	v_add_co_u32_e32 v14, vcc, s96, v14
	global_load_dwordx4 v[54:57], v[16:17], off nt
	s_nop 0
	v_addc_co_u32_e32 v15, vcc, 0, v15, vcc
	global_load_dwordx4 v[50:53], v[14:15], off offset:2048 nt
	v_add_co_u32_e32 v14, vcc, s50, v30
	global_load_dwordx4 v[22:25], v[22:23], off nt
	s_nop 0
	v_addc_co_u32_e32 v15, vcc, 0, v31, vcc
	global_load_dwordx4 v[34:37], v[14:15], off offset:2048 nt
	v_add_co_u32_e32 v14, vcc, s51, v30
	global_load_dwordx4 v[2:5], v[2:3], off offset:2048 nt
	s_nop 0
	v_addc_co_u32_e32 v15, vcc, 0, v31, vcc
	global_load_dwordx4 v[26:29], v[14:15], off nt
	v_add_co_u32_e32 v14, vcc, s49, v30
	global_load_dwordx4 v[46:49], v[30:31], off nt
	s_nop 0
	v_addc_co_u32_e32 v15, vcc, 0, v31, vcc
	v_add_co_u32_e32 v32, vcc, s92, v30
	global_load_dwordx4 v[14:17], v[14:15], off offset:2048 nt
	s_nop 0
	v_addc_co_u32_e32 v33, vcc, 0, v31, vcc
	global_load_dwordx4 v[38:41], v[32:33], off offset:2048 nt
	v_add_co_u32_e32 v32, vcc, s93, v30
	s_waitcnt vmcnt(13)
	v_mul_f32_e32 v19, v19, v109
	v_addc_co_u32_e32 v33, vcc, 0, v31, vcc
	v_add_co_u32_e32 v30, vcc, s96, v30
	global_load_dwordx4 v[42:45], v[32:33], off nt
	s_nop 0
	v_addc_co_u32_e32 v31, vcc, 0, v31, vcc
	global_load_dwordx4 v[30:33], v[30:31], off offset:2048 nt
	v_fmac_f32_e32 v19, v18, v107
	v_fmac_f32_e32 v19, v20, v108
	v_fmac_f32_e32 v19, v21, v106
	s_nop 1
	v_add_f32_dpp v18, v19, v19 quad_perm:[1,0,3,2] row_mask:0xf bank_mask:0xf bound_ctrl:1
	s_nop 1
	v_add_f32_dpp v18, v18, v18 quad_perm:[2,3,0,1] row_mask:0xf bank_mask:0xf bound_ctrl:1
	s_nop 1
	v_add_f32_dpp v18, v18, v18 row_ror:4 row_mask:0xf bank_mask:0xf bound_ctrl:1
	s_nop 1
	v_mov_b32_dpp v19, v18 row_ror:8 row_mask:0xf bank_mask:0xf bound_ctrl:1
	s_and_saveexec_b64 s[0:1], s[6:7]
	v_add_f32_e32 v18, v18, v19
	v_add_f32_e32 v18, v110, v18
	ds_write_b32 v99, v18
	s_or_b64 exec, exec, s[0:1]
	s_waitcnt vmcnt(13)
	v_mul_f32_e32 v11, v11, v109
	v_fmac_f32_e32 v11, v10, v107
	v_fmac_f32_e32 v11, v12, v108
	v_fmac_f32_e32 v11, v13, v106
	s_nop 1
	v_add_f32_dpp v10, v11, v11 quad_perm:[1,0,3,2] row_mask:0xf bank_mask:0xf bound_ctrl:1
	s_nop 1
	v_add_f32_dpp v10, v10, v10 quad_perm:[2,3,0,1] row_mask:0xf bank_mask:0xf bound_ctrl:1
	s_nop 1
	v_add_f32_dpp v10, v10, v10 row_ror:4 row_mask:0xf bank_mask:0xf bound_ctrl:1
	s_nop 1
	v_mov_b32_dpp v11, v10 row_ror:8 row_mask:0xf bank_mask:0xf bound_ctrl:1
	s_and_saveexec_b64 s[0:1], s[6:7]
	v_add_f32_e32 v10, v10, v11
	v_add_f32_e32 v10, v110, v10
	ds_write_b32 v99, v10 offset:16
	s_or_b64 exec, exec, s[0:1]
	s_waitcnt vmcnt(12)
	v_mul_f32_e32 v7, v7, v109
	v_fmac_f32_e32 v7, v6, v107
	v_fmac_f32_e32 v7, v8, v108
	v_fmac_f32_e32 v7, v9, v106
	s_nop 1
	v_add_f32_dpp v6, v7, v7 quad_perm:[1,0,3,2] row_mask:0xf bank_mask:0xf bound_ctrl:1
	s_nop 1
	v_add_f32_dpp v6, v6, v6 quad_perm:[2,3,0,1] row_mask:0xf bank_mask:0xf bound_ctrl:1
	s_nop 1
	v_add_f32_dpp v6, v6, v6 row_ror:4 row_mask:0xf bank_mask:0xf bound_ctrl:1
	s_nop 1
	v_mov_b32_dpp v7, v6 row_ror:8 row_mask:0xf bank_mask:0xf bound_ctrl:1
	s_and_saveexec_b64 s[0:1], s[6:7]
	v_add_f32_e32 v6, v6, v7
	v_add_f32_e32 v6, v110, v6
	ds_write_b32 v99, v6 offset:32
	s_or_b64 exec, exec, s[0:1]
	s_waitcnt vmcnt(6)
; template <int NB>
; __device__ __forceinline__ void sb_decode_task(const Params& P, float* lds, int task) {
;     ...
;     for (int i = 0; i < NB; ++i) cur[i] = *(const float4*)(Kp + (size_t)(4 * i + g) * (SH * HD));
; #pragma unroll
;     for (int kb = 0; kb < NBT; ++kb) {
;         const float* np = (kb + 1 < NBT) ? Kp + (size_t)(4 * NB * (kb + 1)) * (SH * HD) : Vp;
; #pragma unroll
;         for (int i = 0; i < NB; ++i) nx[i] = *(const float4*)(np + (size_t)(4 * i + g) * (SH * HD));
; #pragma unroll
;         for (int i = 0; i < NB; ++i) { const int s = 4 * NB * kb + 4 * i + g;
;             float part = q0 * cur[i].x + q1 * cur[i].y + q2 * cur[i].z + q3 * cur[i].w; part = sum16(part);
;             if (c == 0) zl[s] = part + bias; }
; #pragma unroll
;         for (int i = 0; i < NB; ++i) cur[i] = nx[i];
;     }
	v_mul_f32_e32 v3, v3, v109
	v_fmac_f32_e32 v3, v2, v107
	v_fmac_f32_e32 v3, v4, v108
	v_fmac_f32_e32 v3, v5, v106
	s_nop 1
	v_add_f32_dpp v2, v3, v3 quad_perm:[1,0,3,2] row_mask:0xf bank_mask:0xf bound_ctrl:1
	s_nop 1
	v_add_f32_dpp v2, v2, v2 quad_perm:[2,3,0,1] row_mask:0xf bank_mask:0xf bound_ctrl:1
	s_nop 1
	v_add_f32_dpp v2, v2, v2 row_ror:4 row_mask:0xf bank_mask:0xf bound_ctrl:1
	s_nop 1
	v_mov_b32_dpp v3, v2 row_ror:8 row_mask:0xf bank_mask:0xf bound_ctrl:1
	s_and_saveexec_b64 s[0:1], s[6:7]
	v_add_f32_e32 v2, v2, v3
	v_add_f32_e32 v2, v110, v2
	ds_write_b32 v99, v2 offset:48
	s_or_b64 exec, exec, s[0:1]
	v_mul_f32_e32 v2, v63, v109
	v_fmac_f32_e32 v2, v62, v107
	v_fmac_f32_e32 v2, v64, v108
	v_fmac_f32_e32 v2, v65, v106
	s_nop 1
	v_add_f32_dpp v2, v2, v2 quad_perm:[1,0,3,2] row_mask:0xf bank_mask:0xf bound_ctrl:1
	s_nop 1
	v_add_f32_dpp v2, v2, v2 quad_perm:[2,3,0,1] row_mask:0xf bank_mask:0xf bound_ctrl:1
	s_nop 1
	v_add_f32_dpp v2, v2, v2 row_ror:4 row_mask:0xf bank_mask:0xf bound_ctrl:1
	s_nop 1
	v_mov_b32_dpp v3, v2 row_ror:8 row_mask:0xf bank_mask:0xf bound_ctrl:1
	s_and_saveexec_b64 s[0:1], s[6:7]
	v_add_f32_e32 v2, v2, v3
	v_add_f32_e32 v2, v110, v2
	ds_write_b32 v99, v2 offset:64
	s_or_b64 exec, exec, s[0:1]
	v_mul_f32_e32 v2, v59, v109
	v_fmac_f32_e32 v2, v58, v107
	v_fmac_f32_e32 v2, v60, v108
	v_fmac_f32_e32 v2, v61, v106
	s_nop 1
	v_add_f32_dpp v2, v2, v2 quad_perm:[1,0,3,2] row_mask:0xf bank_mask:0xf bound_ctrl:1
	s_nop 1
	v_add_f32_dpp v2, v2, v2 quad_perm:[2,3,0,1] row_mask:0xf bank_mask:0xf bound_ctrl:1
	s_nop 1
	v_add_f32_dpp v2, v2, v2 row_ror:4 row_mask:0xf bank_mask:0xf bound_ctrl:1
	s_nop 1
	v_mov_b32_dpp v3, v2 row_ror:8 row_mask:0xf bank_mask:0xf bound_ctrl:1
	s_and_saveexec_b64 s[0:1], s[6:7]
	v_add_f32_e32 v2, v2, v3
	v_add_f32_e32 v2, v110, v2
	ds_write_b32 v99, v2 offset:80
	s_or_b64 exec, exec, s[0:1]
	v_mul_f32_e32 v2, v55, v109
	v_fmac_f32_e32 v2, v54, v107
	v_fmac_f32_e32 v2, v56, v108
	v_fmac_f32_e32 v2, v57, v106
	s_nop 1
	v_add_f32_dpp v2, v2, v2 quad_perm:[1,0,3,2] row_mask:0xf bank_mask:0xf bound_ctrl:1
	s_nop 1
	v_add_f32_dpp v2, v2, v2 quad_perm:[2,3,0,1] row_mask:0xf bank_mask:0xf bound_ctrl:1
	s_nop 1
	v_add_f32_dpp v2, v2, v2 row_ror:4 row_mask:0xf bank_mask:0xf bound_ctrl:1
	s_nop 1
	v_mov_b32_dpp v3, v2 row_ror:8 row_mask:0xf bank_mask:0xf bound_ctrl:1
	s_and_saveexec_b64 s[0:1], s[6:7]
	v_add_f32_e32 v2, v2, v3
	v_add_f32_e32 v2, v110, v2
	ds_write_b32 v99, v2 offset:96
	s_or_b64 exec, exec, s[0:1]
	v_mul_f32_e32 v2, v51, v109
	v_fmac_f32_e32 v2, v50, v107
	v_fmac_f32_e32 v2, v52, v108
	v_fmac_f32_e32 v2, v53, v106
	s_nop 1
	v_add_f32_dpp v2, v2, v2 quad_perm:[1,0,3,2] row_mask:0xf bank_mask:0xf bound_ctrl:1
	s_nop 1
	v_add_f32_dpp v2, v2, v2 quad_perm:[2,3,0,1] row_mask:0xf bank_mask:0xf bound_ctrl:1
	s_nop 1
	v_add_f32_dpp v2, v2, v2 row_ror:4 row_mask:0xf bank_mask:0xf bound_ctrl:1
	s_nop 1
	v_mov_b32_dpp v3, v2 row_ror:8 row_mask:0xf bank_mask:0xf bound_ctrl:1
	s_and_saveexec_b64 s[0:1], s[6:7]
	v_add_f32_e32 v2, v2, v3
	v_add_f32_e32 v2, v110, v2
	ds_write_b32 v99, v2 offset:112
	s_or_b64 exec, exec, s[0:1]
	s_mov_b64 s[0:1], 0x18000
	v_lshl_add_u64 v[2:3], v[70:71], 0, s[0:1]
	v_lshl_add_u64 v[4:5], v[2:3], 0, v[82:83]
	v_add_co_u32_e32 v6, vcc, 0x1000, v4
	v_mov_b32_e32 v93, v83
	s_nop 0
	v_addc_co_u32_e32 v7, vcc, 0, v5, vcc
	global_load_dwordx4 v[74:77], v[4:5], off nt
	global_load_dwordx4 v[66:69], v[6:7], off offset:2048 nt
	v_add_co_u32_e32 v6, vcc, 0x3000, v4
	v_lshl_add_u64 v[2:3], v[2:3], 0, v[92:93]
	s_nop 0
	v_addc_co_u32_e32 v7, vcc, 0, v5, vcc
	v_add_co_u32_e32 v8, vcc, s49, v4
	s_waitcnt vmcnt(6)
	v_mul_f32_e32 v47, v47, v109
	v_addc_co_u32_e32 v9, vcc, 0, v5, vcc
	global_load_dwordx4 v[58:61], v[6:7], off nt
	global_load_dwordx4 v[50:53], v[8:9], off offset:2048 nt
	v_add_co_u32_e32 v6, vcc, 0x7000, v4
	v_fmac_f32_e32 v47, v46, v107
	s_nop 0
	v_addc_co_u32_e32 v7, vcc, 0, v5, vcc
	global_load_dwordx4 v[18:21], v[2:3], off nt
	global_load_dwordx4 v[10:13], v[6:7], off offset:2048 nt
	v_add_co_u32_e32 v2, vcc, 0x9000, v4
	v_fmac_f32_e32 v47, v48, v108
	s_nop 0
	v_addc_co_u32_e32 v3, vcc, 0, v5, vcc
	v_add_co_u32_e32 v4, vcc, 0xa000, v4
	v_fmac_f32_e32 v47, v49, v106
	s_nop 0
	v_addc_co_u32_e32 v5, vcc, 0, v5, vcc
	global_load_dwordx4 v[6:9], v[2:3], off nt
	s_nop 0
	global_load_dwordx4 v[2:5], v[4:5], off offset:2048 nt
	v_add_f32_dpp v46, v47, v47 quad_perm:[1,0,3,2] row_mask:0xf bank_mask:0xf bound_ctrl:1
	s_nop 1
	v_add_f32_dpp v46, v46, v46 quad_perm:[2,3,0,1] row_mask:0xf bank_mask:0xf bound_ctrl:1
	s_nop 1
	v_add_f32_dpp v46, v46, v46 row_ror:4 row_mask:0xf bank_mask:0xf bound_ctrl:1
	s_nop 1
	v_mov_b32_dpp v47, v46 row_ror:8 row_mask:0xf bank_mask:0xf bound_ctrl:1
	s_and_saveexec_b64 s[0:1], s[6:7]
	v_add_f32_e32 v46, v46, v47
	v_add_f32_e32 v46, v110, v46
	ds_write_b32 v99, v46 offset:128
	s_or_b64 exec, exec, s[0:1]
	v_mul_f32_e32 v35, v35, v109
	v_fmac_f32_e32 v35, v34, v107
	v_fmac_f32_e32 v35, v36, v108
	v_fmac_f32_e32 v35, v37, v106
	s_nop 1
	v_add_f32_dpp v34, v35, v35 quad_perm:[1,0,3,2] row_mask:0xf bank_mask:0xf bound_ctrl:1
	s_nop 1
	v_add_f32_dpp v34, v34, v34 quad_perm:[2,3,0,1] row_mask:0xf bank_mask:0xf bound_ctrl:1
	s_nop 1
	v_add_f32_dpp v34, v34, v34 row_ror:4 row_mask:0xf bank_mask:0xf bound_ctrl:1
	s_nop 1
	v_mov_b32_dpp v35, v34 row_ror:8 row_mask:0xf bank_mask:0xf bound_ctrl:1
	s_and_saveexec_b64 s[0:1], s[6:7]
	v_add_f32_e32 v34, v34, v35
	v_add_f32_e32 v34, v110, v34
	ds_write_b32 v99, v34 offset:144
	s_or_b64 exec, exec, s[0:1]
	v_mul_f32_e32 v27, v27, v109
	v_fmac_f32_e32 v27, v26, v107
	v_fmac_f32_e32 v27, v28, v108
	v_fmac_f32_e32 v27, v29, v106
	s_nop 1
	v_add_f32_dpp v26, v27, v27 quad_perm:[1,0,3,2] row_mask:0xf bank_mask:0xf bound_ctrl:1
	s_nop 1
	v_add_f32_dpp v26, v26, v26 quad_perm:[2,3,0,1] row_mask:0xf bank_mask:0xf bound_ctrl:1
	s_nop 1
	v_add_f32_dpp v26, v26, v26 row_ror:4 row_mask:0xf bank_mask:0xf bound_ctrl:1
	s_nop 1
	v_mov_b32_dpp v27, v26 row_ror:8 row_mask:0xf bank_mask:0xf bound_ctrl:1
	s_and_saveexec_b64 s[0:1], s[6:7]
	v_add_f32_e32 v26, v26, v27
	v_add_f32_e32 v26, v110, v26
	ds_write_b32 v99, v26 offset:160
	s_or_b64 exec, exec, s[0:1]
	s_waitcnt vmcnt(11)
; template <int NB>
; __device__ __forceinline__ void sb_decode_task(const Params& P, float* lds, int task) {
;     ...
;     for (int i = 0; i < NB; ++i) cur[i] = *(const float4*)(Kp + (size_t)(4 * i + g) * (SH * HD));
; #pragma unroll
;     for (int kb = 0; kb < NBT; ++kb) {
;         const float* np = (kb + 1 < NBT) ? Kp + (size_t)(4 * NB * (kb + 1)) * (SH * HD) : Vp;
; #pragma unroll
;         for (int i = 0; i < NB; ++i) nx[i] = *(const float4*)(np + (size_t)(4 * i + g) * (SH * HD));
; #pragma unroll
;         for (int i = 0; i < NB; ++i) { const int s = 4 * NB * kb + 4 * i + g;
;             float part = q0 * cur[i].x + q1 * cur[i].y + q2 * cur[i].z + q3 * cur[i].w; part = sum16(part);
;             if (c == 0) zl[s] = part + bias; }
; #pragma unroll
;         for (int i = 0; i < NB; ++i) cur[i] = nx[i];
;     }
	v_mul_f32_e32 v15, v15, v109
	v_fmac_f32_e32 v15, v14, v107
	v_fmac_f32_e32 v15, v16, v108
	v_fmac_f32_e32 v15, v17, v106
	s_nop 1
	v_add_f32_dpp v14, v15, v15 quad_perm:[1,0,3,2] row_mask:0xf bank_mask:0xf bound_ctrl:1
	s_nop 1
	v_add_f32_dpp v14, v14, v14 quad_perm:[2,3,0,1] row_mask:0xf bank_mask:0xf bound_ctrl:1
	s_nop 1
	v_add_f32_dpp v14, v14, v14 row_ror:4 row_mask:0xf bank_mask:0xf bound_ctrl:1
	s_nop 1
	v_mov_b32_dpp v15, v14 row_ror:8 row_mask:0xf bank_mask:0xf bound_ctrl:1
	s_and_saveexec_b64 s[0:1], s[6:7]
	v_add_f32_e32 v14, v14, v15
	v_add_f32_e32 v14, v110, v14
	ds_write_b32 v99, v14 offset:176
	s_or_b64 exec, exec, s[0:1]
	v_mul_f32_e32 v14, v23, v109
	v_fmac_f32_e32 v14, v22, v107
	v_fmac_f32_e32 v14, v24, v108
	v_fmac_f32_e32 v14, v25, v106
	s_nop 1
	v_add_f32_dpp v14, v14, v14 quad_perm:[1,0,3,2] row_mask:0xf bank_mask:0xf bound_ctrl:1
	s_nop 1
	v_add_f32_dpp v14, v14, v14 quad_perm:[2,3,0,1] row_mask:0xf bank_mask:0xf bound_ctrl:1
	s_nop 1
	v_add_f32_dpp v14, v14, v14 row_ror:4 row_mask:0xf bank_mask:0xf bound_ctrl:1
	s_nop 1
	v_mov_b32_dpp v15, v14 row_ror:8 row_mask:0xf bank_mask:0xf bound_ctrl:1
	s_and_saveexec_b64 s[0:1], s[6:7]
	v_add_f32_e32 v14, v14, v15
	v_add_f32_e32 v14, v110, v14
	ds_write_b32 v99, v14 offset:192
	s_or_b64 exec, exec, s[0:1]
	s_waitcnt vmcnt(10)
	v_mul_f32_e32 v14, v39, v109
	v_fmac_f32_e32 v14, v38, v107
	v_fmac_f32_e32 v14, v40, v108
	v_fmac_f32_e32 v14, v41, v106
	s_nop 1
	v_add_f32_dpp v14, v14, v14 quad_perm:[1,0,3,2] row_mask:0xf bank_mask:0xf bound_ctrl:1
	s_nop 1
	v_add_f32_dpp v14, v14, v14 quad_perm:[2,3,0,1] row_mask:0xf bank_mask:0xf bound_ctrl:1
	s_nop 1
	v_add_f32_dpp v14, v14, v14 row_ror:4 row_mask:0xf bank_mask:0xf bound_ctrl:1
	s_nop 1
	v_mov_b32_dpp v15, v14 row_ror:8 row_mask:0xf bank_mask:0xf bound_ctrl:1
	s_and_saveexec_b64 s[0:1], s[6:7]
	v_add_f32_e32 v14, v14, v15
	v_add_f32_e32 v14, v110, v14
	ds_write_b32 v99, v14 offset:208
	s_or_b64 exec, exec, s[0:1]
	s_waitcnt vmcnt(9)
	v_mul_f32_e32 v14, v43, v109
	v_fmac_f32_e32 v14, v42, v107
	v_fmac_f32_e32 v14, v44, v108
	v_fmac_f32_e32 v14, v45, v106
	s_nop 1
	v_add_f32_dpp v14, v14, v14 quad_perm:[1,0,3,2] row_mask:0xf bank_mask:0xf bound_ctrl:1
	s_nop 1
	v_add_f32_dpp v14, v14, v14 quad_perm:[2,3,0,1] row_mask:0xf bank_mask:0xf bound_ctrl:1
	s_nop 1
	v_add_f32_dpp v14, v14, v14 row_ror:4 row_mask:0xf bank_mask:0xf bound_ctrl:1
	s_nop 1
	v_mov_b32_dpp v15, v14 row_ror:8 row_mask:0xf bank_mask:0xf bound_ctrl:1
	s_and_saveexec_b64 s[0:1], s[6:7]
	v_add_f32_e32 v14, v14, v15
	v_add_f32_e32 v14, v110, v14
	ds_write_b32 v99, v14 offset:224
	s_or_b64 exec, exec, s[0:1]
	s_waitcnt vmcnt(8)
	v_mul_f32_e32 v14, v31, v109
	v_fmac_f32_e32 v14, v30, v107
	v_fmac_f32_e32 v14, v32, v108
	v_fmac_f32_e32 v14, v33, v106
	s_nop 1
	v_add_f32_dpp v14, v14, v14 quad_perm:[1,0,3,2] row_mask:0xf bank_mask:0xf bound_ctrl:1
	s_nop 1
	v_add_f32_dpp v14, v14, v14 quad_perm:[2,3,0,1] row_mask:0xf bank_mask:0xf bound_ctrl:1
	s_nop 1
	v_add_f32_dpp v14, v14, v14 row_ror:4 row_mask:0xf bank_mask:0xf bound_ctrl:1
	s_nop 1
	v_mov_b32_dpp v15, v14 row_ror:8 row_mask:0xf bank_mask:0xf bound_ctrl:1
	s_and_saveexec_b64 s[0:1], s[6:7]
	v_add_f32_e32 v14, v14, v15
	v_add_f32_e32 v14, v110, v14
	ds_write_b32 v99, v14 offset:240
	s_or_b64 exec, exec, s[0:1]
	s_mov_b64 s[0:1], 0x24000
	v_lshl_add_u64 v[14:15], v[70:71], 0, s[0:1]
	v_lshl_add_u64 v[16:17], v[14:15], 0, v[82:83]
	v_add_co_u32_e32 v22, vcc, 0x1000, v16
	v_mov_b32_e32 v93, v83
	s_nop 0
	v_addc_co_u32_e32 v23, vcc, 0, v17, vcc
	global_load_dwordx4 v[78:81], v[16:17], off nt
	global_load_dwordx4 v[70:73], v[22:23], off offset:2048 nt
	v_add_co_u32_e32 v22, vcc, 0x3000, v16
	v_lshl_add_u64 v[14:15], v[14:15], 0, v[92:93]
	s_nop 0
	v_addc_co_u32_e32 v23, vcc, 0, v17, vcc
	v_add_co_u32_e32 v24, vcc, s49, v16
	s_nop 1
	v_addc_co_u32_e32 v25, vcc, 0, v17, vcc
	global_load_dwordx4 v[62:65], v[22:23], off nt
	global_load_dwordx4 v[54:57], v[24:25], off offset:2048 nt
	v_add_co_u32_e32 v22, vcc, 0x7000, v16
	s_nop 1
	v_addc_co_u32_e32 v23, vcc, 0, v17, vcc
	global_load_dwordx4 v[46:49], v[14:15], off nt
	global_load_dwordx4 v[42:45], v[22:23], off offset:2048 nt
	v_add_co_u32_e32 v14, vcc, 0x9000, v16
	s_nop 1
	v_addc_co_u32_e32 v15, vcc, 0, v17, vcc
	v_add_co_u32_e32 v16, vcc, 0xa000, v16
	s_nop 1
	v_addc_co_u32_e32 v17, vcc, 0, v17, vcc
	global_load_dwordx4 v[38:41], v[14:15], off nt
	global_load_dwordx4 v[34:37], v[16:17], off offset:2048 nt
	s_waitcnt vmcnt(15)
	v_mul_f32_e32 v14, v75, v109
	v_fmac_f32_e32 v14, v74, v107
	v_fmac_f32_e32 v14, v76, v108
	v_fmac_f32_e32 v14, v77, v106
	s_nop 1
	v_add_f32_dpp v14, v14, v14 quad_perm:[1,0,3,2] row_mask:0xf bank_mask:0xf bound_ctrl:1
	s_nop 1
	v_add_f32_dpp v14, v14, v14 quad_perm:[2,3,0,1] row_mask:0xf bank_mask:0xf bound_ctrl:1
	s_nop 1
	v_add_f32_dpp v14, v14, v14 row_ror:4 row_mask:0xf bank_mask:0xf bound_ctrl:1
	s_nop 1
	v_mov_b32_dpp v15, v14 row_ror:8 row_mask:0xf bank_mask:0xf bound_ctrl:1
	s_and_saveexec_b64 s[0:1], s[6:7]
	v_add_f32_e32 v14, v14, v15
	v_add_f32_e32 v14, v110, v14
	ds_write_b32 v99, v14 offset:256
	s_or_b64 exec, exec, s[0:1]
	s_waitcnt vmcnt(14)
	v_mul_f32_e32 v14, v67, v109
	v_fmac_f32_e32 v14, v66, v107
	v_fmac_f32_e32 v14, v68, v108
	v_fmac_f32_e32 v14, v69, v106
	s_nop 1
	v_add_f32_dpp v14, v14, v14 quad_perm:[1,0,3,2] row_mask:0xf bank_mask:0xf bound_ctrl:1
	s_nop 1
	v_add_f32_dpp v14, v14, v14 quad_perm:[2,3,0,1] row_mask:0xf bank_mask:0xf bound_ctrl:1
	s_nop 1
	v_add_f32_dpp v14, v14, v14 row_ror:4 row_mask:0xf bank_mask:0xf bound_ctrl:1
	s_nop 1
	v_mov_b32_dpp v15, v14 row_ror:8 row_mask:0xf bank_mask:0xf bound_ctrl:1
	s_and_saveexec_b64 s[0:1], s[6:7]
	v_add_f32_e32 v14, v14, v15
	v_add_f32_e32 v14, v110, v14
	ds_write_b32 v99, v14 offset:272
	s_or_b64 exec, exec, s[0:1]
	s_waitcnt vmcnt(13)
; template <int NB>
; __device__ __forceinline__ void sb_decode_task(const Params& P, float* lds, int task) {
;     ...
;     for (int i = 0; i < NB; ++i) cur[i] = *(const float4*)(Kp + (size_t)(4 * i + g) * (SH * HD));
; #pragma unroll
;     for (int kb = 0; kb < NBT; ++kb) {
;         const float* np = (kb + 1 < NBT) ? Kp + (size_t)(4 * NB * (kb + 1)) * (SH * HD) : Vp;
; #pragma unroll
;         for (int i = 0; i < NB; ++i) nx[i] = *(const float4*)(np + (size_t)(4 * i + g) * (SH * HD));
; #pragma unroll
;         for (int i = 0; i < NB; ++i) { const int s = 4 * NB * kb + 4 * i + g;
;             float part = q0 * cur[i].x + q1 * cur[i].y + q2 * cur[i].z + q3 * cur[i].w; part = sum16(part);
;             if (c == 0) zl[s] = part + bias; }
; #pragma unroll
;         for (int i = 0; i < NB; ++i) cur[i] = nx[i];
;     }
	v_mul_f32_e32 v14, v59, v109
	v_fmac_f32_e32 v14, v58, v107
	v_fmac_f32_e32 v14, v60, v108
	v_fmac_f32_e32 v14, v61, v106
	s_nop 1
	v_add_f32_dpp v14, v14, v14 quad_perm:[1,0,3,2] row_mask:0xf bank_mask:0xf bound_ctrl:1
	s_nop 1
	v_add_f32_dpp v14, v14, v14 quad_perm:[2,3,0,1] row_mask:0xf bank_mask:0xf bound_ctrl:1
	s_nop 1
	v_add_f32_dpp v14, v14, v14 row_ror:4 row_mask:0xf bank_mask:0xf bound_ctrl:1
	s_nop 1
	v_mov_b32_dpp v15, v14 row_ror:8 row_mask:0xf bank_mask:0xf bound_ctrl:1
	s_and_saveexec_b64 s[0:1], s[6:7]
	v_add_f32_e32 v14, v14, v15
	v_add_f32_e32 v14, v110, v14
	ds_write_b32 v99, v14 offset:288
	s_or_b64 exec, exec, s[0:1]
	s_waitcnt vmcnt(12)
	v_mul_f32_e32 v14, v51, v109
	v_fmac_f32_e32 v14, v50, v107
	v_fmac_f32_e32 v14, v52, v108
	v_fmac_f32_e32 v14, v53, v106
	s_nop 1
	v_add_f32_dpp v14, v14, v14 quad_perm:[1,0,3,2] row_mask:0xf bank_mask:0xf bound_ctrl:1
	s_nop 1
	v_add_f32_dpp v14, v14, v14 quad_perm:[2,3,0,1] row_mask:0xf bank_mask:0xf bound_ctrl:1
	s_nop 1
	v_add_f32_dpp v14, v14, v14 row_ror:4 row_mask:0xf bank_mask:0xf bound_ctrl:1
	s_nop 1
	v_mov_b32_dpp v15, v14 row_ror:8 row_mask:0xf bank_mask:0xf bound_ctrl:1
	s_and_saveexec_b64 s[0:1], s[6:7]
	v_add_f32_e32 v14, v14, v15
	v_add_f32_e32 v14, v110, v14
	ds_write_b32 v99, v14 offset:304
	s_or_b64 exec, exec, s[0:1]
	s_waitcnt vmcnt(11)
	v_mul_f32_e32 v14, v19, v109
	v_fmac_f32_e32 v14, v18, v107
	v_fmac_f32_e32 v14, v20, v108
	v_fmac_f32_e32 v14, v21, v106
	s_nop 1
	v_add_f32_dpp v14, v14, v14 quad_perm:[1,0,3,2] row_mask:0xf bank_mask:0xf bound_ctrl:1
	s_nop 1
	v_add_f32_dpp v14, v14, v14 quad_perm:[2,3,0,1] row_mask:0xf bank_mask:0xf bound_ctrl:1
	s_nop 1
	v_add_f32_dpp v14, v14, v14 row_ror:4 row_mask:0xf bank_mask:0xf bound_ctrl:1
	s_nop 1
	v_mov_b32_dpp v15, v14 row_ror:8 row_mask:0xf bank_mask:0xf bound_ctrl:1
	s_and_saveexec_b64 s[0:1], s[6:7]
	v_add_f32_e32 v14, v14, v15
	v_add_f32_e32 v14, v110, v14
	ds_write_b32 v99, v14 offset:320
	s_or_b64 exec, exec, s[0:1]
	s_waitcnt vmcnt(10)
	v_mul_f32_e32 v11, v11, v109
	v_fmac_f32_e32 v11, v10, v107
	v_fmac_f32_e32 v11, v12, v108
	v_fmac_f32_e32 v11, v13, v106
	s_nop 1
	v_add_f32_dpp v10, v11, v11 quad_perm:[1,0,3,2] row_mask:0xf bank_mask:0xf bound_ctrl:1
	s_nop 1
	v_add_f32_dpp v10, v10, v10 quad_perm:[2,3,0,1] row_mask:0xf bank_mask:0xf bound_ctrl:1
	s_nop 1
	v_add_f32_dpp v10, v10, v10 row_ror:4 row_mask:0xf bank_mask:0xf bound_ctrl:1
	s_nop 1
	v_mov_b32_dpp v11, v10 row_ror:8 row_mask:0xf bank_mask:0xf bound_ctrl:1
	s_and_saveexec_b64 s[0:1], s[6:7]
	v_add_f32_e32 v10, v10, v11
	v_add_f32_e32 v10, v110, v10
	ds_write_b32 v99, v10 offset:336
	s_or_b64 exec, exec, s[0:1]
	s_waitcnt vmcnt(9)
	v_mul_f32_e32 v7, v7, v109
	v_fmac_f32_e32 v7, v6, v107
	v_fmac_f32_e32 v7, v8, v108
	v_fmac_f32_e32 v7, v9, v106
	s_nop 1
	v_add_f32_dpp v6, v7, v7 quad_perm:[1,0,3,2] row_mask:0xf bank_mask:0xf bound_ctrl:1
	s_nop 1
	v_add_f32_dpp v6, v6, v6 quad_perm:[2,3,0,1] row_mask:0xf bank_mask:0xf bound_ctrl:1
	s_nop 1
	v_add_f32_dpp v6, v6, v6 row_ror:4 row_mask:0xf bank_mask:0xf bound_ctrl:1
	s_nop 1
	v_mov_b32_dpp v7, v6 row_ror:8 row_mask:0xf bank_mask:0xf bound_ctrl:1
	s_and_saveexec_b64 s[0:1], s[6:7]
	v_add_f32_e32 v6, v6, v7
	v_add_f32_e32 v6, v110, v6
	ds_write_b32 v99, v6 offset:352
	s_or_b64 exec, exec, s[0:1]
	s_waitcnt vmcnt(8)
	v_mul_f32_e32 v3, v3, v109
	v_fmac_f32_e32 v3, v2, v107
	v_fmac_f32_e32 v3, v4, v108
	v_fmac_f32_e32 v3, v5, v106
	s_nop 1
	v_add_f32_dpp v2, v3, v3 quad_perm:[1,0,3,2] row_mask:0xf bank_mask:0xf bound_ctrl:1
	s_nop 1
	v_add_f32_dpp v2, v2, v2 quad_perm:[2,3,0,1] row_mask:0xf bank_mask:0xf bound_ctrl:1
	s_nop 1
	v_add_f32_dpp v2, v2, v2 row_ror:4 row_mask:0xf bank_mask:0xf bound_ctrl:1
	s_nop 1
	v_mov_b32_dpp v3, v2 row_ror:8 row_mask:0xf bank_mask:0xf bound_ctrl:1
	s_and_saveexec_b64 s[0:1], s[6:7]
	v_add_f32_e32 v2, v2, v3
	v_add_f32_e32 v2, v110, v2
	ds_write_b32 v99, v2 offset:368
	s_or_b64 exec, exec, s[0:1]
	v_lshlrev_b64 v[2:3], 6, v[94:95]
	v_lshl_add_u64 v[6:7], v[2:3], 2, v[86:87]
	v_lshl_add_u64 v[50:51], v[6:7], 0, v[82:83]
	v_add_co_u32_e32 v2, vcc, 0x1000, v50
	v_mov_b32_e32 v93, v83
	s_nop 0
	v_addc_co_u32_e32 v3, vcc, 0, v51, vcc
	v_add_co_u32_e32 v8, vcc, 0x3000, v50
	v_lshl_add_u64 v[10:11], v[6:7], 0, v[92:93]
	s_nop 0
	v_addc_co_u32_e32 v9, vcc, 0, v51, vcc
	v_add_co_u32_e32 v14, vcc, s49, v50
	global_load_dwordx4 v[30:33], v[50:51], off nt
	s_nop 0
	global_load_dwordx4 v[2:5], v[2:3], off offset:2048 nt
	v_addc_co_u32_e32 v15, vcc, 0, v51, vcc
	v_add_co_u32_e32 v18, vcc, 0x7000, v50
	global_load_dwordx4 v[6:9], v[8:9], off nt
	s_nop 0
	global_load_dwordx4 v[10:13], v[10:11], off nt
	v_addc_co_u32_e32 v19, vcc, 0, v51, vcc
	v_add_co_u32_e32 v22, vcc, 0x9000, v50
	global_load_dwordx4 v[14:17], v[14:15], off offset:2048 nt
	s_nop 0
	global_load_dwordx4 v[18:21], v[18:19], off offset:2048 nt
	v_addc_co_u32_e32 v23, vcc, 0, v51, vcc
	v_add_co_u32_e32 v26, vcc, 0xa000, v50
	s_waitcnt vmcnt(13)
	v_mul_f32_e32 v52, v79, v109
	v_addc_co_u32_e32 v27, vcc, 0, v51, vcc
	global_load_dwordx4 v[22:25], v[22:23], off nt
	s_nop 0
	global_load_dwordx4 v[26:29], v[26:27], off offset:2048 nt
	v_fmac_f32_e32 v52, v78, v107
	v_fmac_f32_e32 v52, v80, v108
	v_fmac_f32_e32 v52, v81, v106
	s_nop 1
	v_add_f32_dpp v52, v52, v52 quad_perm:[1,0,3,2] row_mask:0xf bank_mask:0xf bound_ctrl:1
	s_nop 1
	v_add_f32_dpp v52, v52, v52 quad_perm:[2,3,0,1] row_mask:0xf bank_mask:0xf bound_ctrl:1
	s_nop 1
	v_add_f32_dpp v52, v52, v52 row_ror:4 row_mask:0xf bank_mask:0xf bound_ctrl:1
	s_nop 1
	v_mov_b32_dpp v53, v52 row_ror:8 row_mask:0xf bank_mask:0xf bound_ctrl:1
	s_and_saveexec_b64 s[0:1], s[6:7]
	v_add_f32_e32 v52, v52, v53
	v_add_f32_e32 v52, v110, v52
	ds_write_b32 v99, v52 offset:384
	s_or_b64 exec, exec, s[0:1]
	s_waitcnt vmcnt(14)
; template <int NB>
; __device__ __forceinline__ void sb_decode_task(const Params& P, float* lds, int task) {
;     ...
;         for (int i = 0; i < NB; ++i) { const int s = 4 * NB * kb + 4 * i + g;
;             float part = q0 * cur[i].x + q1 * cur[i].y + q2 * cur[i].z + q3 * cur[i].w; part = sum16(part);
;             if (c == 0) zl[s] = part + bias; }
; #pragma unroll
;         for (int i = 0; i < NB; ++i) cur[i] = nx[i];
;     }
;     asm volatile("s_waitcnt lgkmcnt(0)" ::: "memory");
;     __builtin_amdgcn_wave_barrier();
;     const float z0 = zl[2 * lane], z1 = zl[2 * lane + 1];
	v_mul_f32_e32 v52, v71, v109
	v_fmac_f32_e32 v52, v70, v107
	v_fmac_f32_e32 v52, v72, v108
	v_fmac_f32_e32 v52, v73, v106
	s_nop 1
	v_add_f32_dpp v52, v52, v52 quad_perm:[1,0,3,2] row_mask:0xf bank_mask:0xf bound_ctrl:1
	s_nop 1
	v_add_f32_dpp v52, v52, v52 quad_perm:[2,3,0,1] row_mask:0xf bank_mask:0xf bound_ctrl:1
	s_nop 1
	v_add_f32_dpp v52, v52, v52 row_ror:4 row_mask:0xf bank_mask:0xf bound_ctrl:1
	s_nop 1
	v_mov_b32_dpp v53, v52 row_ror:8 row_mask:0xf bank_mask:0xf bound_ctrl:1
	s_and_saveexec_b64 s[0:1], s[6:7]
	v_add_f32_e32 v52, v52, v53
	v_add_f32_e32 v52, v110, v52
	ds_write_b32 v99, v52 offset:400
	s_or_b64 exec, exec, s[0:1]
	s_waitcnt vmcnt(13)
	v_mul_f32_e32 v52, v63, v109
	v_fmac_f32_e32 v52, v62, v107
	v_fmac_f32_e32 v52, v64, v108
	v_fmac_f32_e32 v52, v65, v106
	s_nop 1
	v_add_f32_dpp v52, v52, v52 quad_perm:[1,0,3,2] row_mask:0xf bank_mask:0xf bound_ctrl:1
	s_nop 1
	v_add_f32_dpp v52, v52, v52 quad_perm:[2,3,0,1] row_mask:0xf bank_mask:0xf bound_ctrl:1
	s_nop 1
	v_add_f32_dpp v52, v52, v52 row_ror:4 row_mask:0xf bank_mask:0xf bound_ctrl:1
	s_nop 1
	v_mov_b32_dpp v53, v52 row_ror:8 row_mask:0xf bank_mask:0xf bound_ctrl:1
	s_and_saveexec_b64 s[0:1], s[6:7]
	v_add_f32_e32 v52, v52, v53
	v_add_f32_e32 v52, v110, v52
	ds_write_b32 v99, v52 offset:416
	s_or_b64 exec, exec, s[0:1]
	s_waitcnt vmcnt(12)
	v_mul_f32_e32 v52, v55, v109
	v_fmac_f32_e32 v52, v54, v107
	v_fmac_f32_e32 v52, v56, v108
	v_fmac_f32_e32 v52, v57, v106
	s_nop 1
	v_add_f32_dpp v52, v52, v52 quad_perm:[1,0,3,2] row_mask:0xf bank_mask:0xf bound_ctrl:1
	s_nop 1
	v_add_f32_dpp v52, v52, v52 quad_perm:[2,3,0,1] row_mask:0xf bank_mask:0xf bound_ctrl:1
	s_nop 1
	v_add_f32_dpp v52, v52, v52 row_ror:4 row_mask:0xf bank_mask:0xf bound_ctrl:1
	s_nop 1
	v_mov_b32_dpp v53, v52 row_ror:8 row_mask:0xf bank_mask:0xf bound_ctrl:1
	s_and_saveexec_b64 s[0:1], s[6:7]
	v_add_f32_e32 v52, v52, v53
	v_add_f32_e32 v52, v110, v52
	ds_write_b32 v99, v52 offset:432
	s_or_b64 exec, exec, s[0:1]
	s_waitcnt vmcnt(11)
	v_mul_f32_e32 v47, v47, v109
	v_fmac_f32_e32 v47, v46, v107
	v_fmac_f32_e32 v47, v48, v108
	v_fmac_f32_e32 v47, v49, v106
	s_nop 1
	v_add_f32_dpp v46, v47, v47 quad_perm:[1,0,3,2] row_mask:0xf bank_mask:0xf bound_ctrl:1
	s_nop 1
	v_add_f32_dpp v46, v46, v46 quad_perm:[2,3,0,1] row_mask:0xf bank_mask:0xf bound_ctrl:1
	s_nop 1
	v_add_f32_dpp v46, v46, v46 row_ror:4 row_mask:0xf bank_mask:0xf bound_ctrl:1
	s_nop 1
	v_mov_b32_dpp v47, v46 row_ror:8 row_mask:0xf bank_mask:0xf bound_ctrl:1
	s_and_saveexec_b64 s[0:1], s[6:7]
	v_add_f32_e32 v46, v46, v47
	v_add_f32_e32 v46, v110, v46
	ds_write_b32 v99, v46 offset:448
	s_or_b64 exec, exec, s[0:1]
	s_waitcnt vmcnt(10)
	v_mul_f32_e32 v43, v43, v109
	v_fmac_f32_e32 v43, v42, v107
	v_fmac_f32_e32 v43, v44, v108
	v_fmac_f32_e32 v43, v45, v106
	s_nop 1
	v_add_f32_dpp v42, v43, v43 quad_perm:[1,0,3,2] row_mask:0xf bank_mask:0xf bound_ctrl:1
	s_nop 1
	v_add_f32_dpp v42, v42, v42 quad_perm:[2,3,0,1] row_mask:0xf bank_mask:0xf bound_ctrl:1
	s_nop 1
	v_add_f32_dpp v42, v42, v42 row_ror:4 row_mask:0xf bank_mask:0xf bound_ctrl:1
	s_nop 1
	v_mov_b32_dpp v43, v42 row_ror:8 row_mask:0xf bank_mask:0xf bound_ctrl:1
	s_and_saveexec_b64 s[0:1], s[6:7]
	v_add_f32_e32 v42, v42, v43
	v_add_f32_e32 v42, v110, v42
	ds_write_b32 v99, v42 offset:464
	s_or_b64 exec, exec, s[0:1]
	s_waitcnt vmcnt(9)
	v_mul_f32_e32 v39, v39, v109
	v_fmac_f32_e32 v39, v38, v107
	v_fmac_f32_e32 v39, v40, v108
	v_fmac_f32_e32 v39, v41, v106
	s_nop 1
	v_add_f32_dpp v38, v39, v39 quad_perm:[1,0,3,2] row_mask:0xf bank_mask:0xf bound_ctrl:1
	s_nop 1
	v_add_f32_dpp v38, v38, v38 quad_perm:[2,3,0,1] row_mask:0xf bank_mask:0xf bound_ctrl:1
	s_nop 1
	v_add_f32_dpp v38, v38, v38 row_ror:4 row_mask:0xf bank_mask:0xf bound_ctrl:1
	s_nop 1
	v_mov_b32_dpp v39, v38 row_ror:8 row_mask:0xf bank_mask:0xf bound_ctrl:1
	s_and_saveexec_b64 s[0:1], s[6:7]
	v_add_f32_e32 v38, v38, v39
	v_add_f32_e32 v38, v110, v38
	ds_write_b32 v99, v38 offset:480
	s_or_b64 exec, exec, s[0:1]
	s_waitcnt vmcnt(8)
	v_mul_f32_e32 v35, v35, v109
	v_fmac_f32_e32 v35, v34, v107
	v_fmac_f32_e32 v35, v36, v108
	v_fmac_f32_e32 v35, v37, v106
	s_nop 1
	v_add_f32_dpp v34, v35, v35 quad_perm:[1,0,3,2] row_mask:0xf bank_mask:0xf bound_ctrl:1
	s_nop 1
	v_add_f32_dpp v34, v34, v34 quad_perm:[2,3,0,1] row_mask:0xf bank_mask:0xf bound_ctrl:1
	s_nop 1
	v_add_f32_dpp v34, v34, v34 row_ror:4 row_mask:0xf bank_mask:0xf bound_ctrl:1
	s_nop 1
	v_mov_b32_dpp v35, v34 row_ror:8 row_mask:0xf bank_mask:0xf bound_ctrl:1
	s_and_saveexec_b64 s[0:1], s[6:7]
	v_add_f32_e32 v34, v34, v35
	v_add_f32_e32 v34, v110, v34
	ds_write_b32 v99, v34 offset:496
	s_or_b64 exec, exec, s[0:1]
	s_waitcnt lgkmcnt(0)
	ds_read_b64 v[34:35], v100
	s_waitcnt lgkmcnt(0)
; __device__ __forceinline__ float softplus2_(float z2) { return fmaxf(z2, 0.f) + log1pf(exp2f(-fabsf(z2))) * LOG2E; }
; template <int NB>
; __device__ __forceinline__ void sb_decode_task(const Params& P, float* lds, int task) {
;     ...
;     const float z0 = zl[2 * lane], z1 = zl[2 * lane + 1];
;     const float sp0 = softplus2_(z0), sp1 = softplus2_(z1);
;     float incl = sp0 + sp1;
	v_cmp_gt_f32_e64 vcc, |v34|, s97
	s_nop 1
	v_cndmask_b32_e32 v37, 0, v103, vcc
	v_sub_f32_e64 v37, v37, |v34|
	v_exp_f32_e32 v37, v37
	v_max_f32_e32 v36, v34, v34
	v_max_f32_e32 v38, 0, v36
	v_cndmask_b32_e32 v36, 0, v102, vcc
	v_ldexp_f32 v39, v37, v36
	v_add_f32_e32 v40, 1.0, v39
	v_add_f32_e32 v36, -1.0, v40
	v_sub_f32_e32 v37, v36, v40
	v_add_f32_e32 v37, 1.0, v37
	v_sub_f32_e32 v36, v39, v36
	v_add_f32_e32 v41, v36, v37
	v_frexp_mant_f32_e32 v36, v40
	v_cmp_gt_f32_e32 vcc, s47, v36
	v_cvt_f64_f32_e32 v[36:37], v40
	v_frexp_exp_i32_f64_e32 v36, v[36:37]
	v_subbrev_co_u32_e32 v36, vcc, 0, v36, vcc
	v_sub_u32_e32 v37, 0, v36
	v_ldexp_f32 v40, v40, v37
	v_ldexp_f32 v37, v41, v37
	v_add_f32_e32 v41, -1.0, v40
	v_add_f32_e32 v42, 1.0, v41
	v_sub_f32_e32 v42, v40, v42
	v_add_f32_e32 v42, v37, v42
	v_add_f32_e32 v43, v41, v42
	v_sub_f32_e32 v41, v41, v43
	v_add_f32_e32 v41, v42, v41
	v_add_f32_e32 v42, 1.0, v40
	v_add_f32_e32 v44, -1.0, v42
	v_sub_f32_e32 v40, v40, v44
	v_add_f32_e32 v37, v37, v40
	v_add_f32_e32 v40, v42, v37
	v_sub_f32_e32 v42, v42, v40
	v_add_f32_e32 v37, v37, v42
	v_rcp_f32_e32 v42, v40
	v_cvt_f32_i32_e32 v36, v36
	v_cmp_neq_f32_e32 vcc, s46, v39
	v_mul_f32_e32 v44, v43, v42
	v_mul_f32_e32 v45, v40, v44
	v_fma_f32 v46, v44, v40, -v45
	v_fmac_f32_e32 v46, v44, v37
	v_add_f32_e32 v47, v45, v46
	v_sub_f32_e32 v48, v43, v47
	v_sub_f32_e32 v43, v43, v48
	v_sub_f32_e32 v45, v47, v45
	v_sub_f32_e32 v43, v43, v47
	v_add_f32_e32 v41, v41, v43
	v_sub_f32_e32 v43, v45, v46
	v_add_f32_e32 v41, v43, v41
	v_add_f32_e32 v43, v48, v41
	v_mul_f32_e32 v45, v42, v43
	v_mul_f32_e32 v46, v40, v45
	v_fma_f32 v40, v45, v40, -v46
	v_fmac_f32_e32 v40, v45, v37
	v_sub_f32_e32 v37, v48, v43
	v_add_f32_e32 v37, v41, v37
	v_add_f32_e32 v41, v46, v40
	v_sub_f32_e32 v47, v43, v41
	v_sub_f32_e32 v43, v43, v47
	v_sub_f32_e32 v46, v41, v46
	v_sub_f32_e32 v41, v43, v41
	v_add_f32_e32 v37, v37, v41
	v_sub_f32_e32 v40, v46, v40
	v_add_f32_e32 v37, v40, v37
	v_add_f32_e32 v40, v44, v45
	v_add_f32_e32 v37, v47, v37
	v_sub_f32_e32 v41, v40, v44
	v_mul_f32_e32 v37, v42, v37
	v_sub_f32_e32 v41, v45, v41
	v_add_f32_e32 v37, v41, v37
	v_mul_f32_e32 v44, 0x3f317218, v36
	v_add_f32_e32 v41, v40, v37
	v_fma_f32 v45, v36, s95, -v44
	v_mul_f32_e32 v42, v41, v41
	v_fmac_f32_e32 v45, 0xb102e308, v36
	v_sub_f32_e32 v36, v41, v40
	v_fmamk_f32 v43, v42, 0x3e9b6dac, v1
	v_sub_f32_e32 v36, v37, v36
	v_add_f32_e32 v37, v44, v45
	v_fmaak_f32 v43, v42, v43, 0x3f2aaada
	v_sub_f32_e32 v40, v37, v44
	v_ldexp_f32 v44, v41, 1
	v_mul_f32_e32 v41, v41, v42
	v_mul_f32_e32 v41, v41, v43
	v_add_f32_e32 v42, v44, v41
	v_sub_f32_e32 v43, v42, v44
	v_ldexp_f32 v36, v36, 1
	v_sub_f32_e32 v41, v41, v43
	v_add_f32_e32 v36, v36, v41
	v_add_f32_e32 v41, v42, v36
	v_sub_f32_e32 v42, v41, v42
	v_sub_f32_e32 v36, v36, v42
	v_add_f32_e32 v42, v37, v41
	v_sub_f32_e32 v43, v42, v37
	v_sub_f32_e32 v44, v42, v43
	v_sub_f32_e32 v40, v45, v40
	v_sub_f32_e32 v37, v37, v44
	v_sub_f32_e32 v41, v41, v43
	v_add_f32_e32 v37, v41, v37
	v_add_f32_e32 v41, v40, v36
	v_sub_f32_e32 v43, v41, v40
	v_sub_f32_e32 v44, v41, v43
	v_sub_f32_e32 v40, v40, v44
	v_sub_f32_e32 v36, v36, v43
	v_add_f32_e32 v37, v41, v37
	v_add_f32_e32 v36, v36, v40
	v_add_f32_e32 v40, v42, v37
	v_sub_f32_e32 v41, v40, v42
	v_sub_f32_e32 v37, v37, v41
	v_add_f32_e32 v36, v36, v37
	v_add_f32_e32 v36, v40, v36
	v_cndmask_b32_e32 v36, v104, v36, vcc
	v_cmp_lt_f32_e64 vcc, |v39|, s45
	s_nop 1
	v_cndmask_b32_e32 v36, v36, v39, vcc
	v_cmp_gt_f32_e64 vcc, |v35|, s97
	v_fmac_f32_e32 v38, 0x3fb8aa3b, v36
	v_max_f32_e32 v36, v35, v35
	v_cndmask_b32_e32 v37, 0, v103, vcc
	v_sub_f32_e64 v37, v37, |v35|
	v_exp_f32_e32 v37, v37
	v_max_f32_e32 v39, 0, v36
	v_cndmask_b32_e32 v36, 0, v102, vcc
	v_sub_f32_e32 v34, v34, v38
	v_ldexp_f32 v40, v37, v36
	v_add_f32_e32 v41, 1.0, v40
	v_add_f32_e32 v36, -1.0, v41
	v_sub_f32_e32 v37, v36, v41
	v_add_f32_e32 v37, 1.0, v37
	v_sub_f32_e32 v36, v40, v36
	v_add_f32_e32 v42, v36, v37
	v_frexp_mant_f32_e32 v36, v41
	v_cmp_gt_f32_e32 vcc, s47, v36
	v_cvt_f64_f32_e32 v[36:37], v41
	v_frexp_exp_i32_f64_e32 v36, v[36:37]
	v_subbrev_co_u32_e32 v36, vcc, 0, v36, vcc
	v_sub_u32_e32 v37, 0, v36
	v_ldexp_f32 v41, v41, v37
	v_ldexp_f32 v37, v42, v37
	v_add_f32_e32 v42, -1.0, v41
	v_add_f32_e32 v43, 1.0, v42
	v_sub_f32_e32 v43, v41, v43
	v_add_f32_e32 v43, v37, v43
	v_add_f32_e32 v44, v42, v43
	v_sub_f32_e32 v42, v42, v44
	v_add_f32_e32 v42, v43, v42
	v_add_f32_e32 v43, 1.0, v41
	v_add_f32_e32 v45, -1.0, v43
	v_sub_f32_e32 v41, v41, v45
	v_add_f32_e32 v37, v37, v41
	v_add_f32_e32 v41, v43, v37
	v_sub_f32_e32 v43, v43, v41
	v_add_f32_e32 v37, v37, v43
	v_rcp_f32_e32 v43, v41
	v_cvt_f32_i32_e32 v36, v36
	v_cmp_neq_f32_e32 vcc, s46, v40
	v_mul_f32_e32 v45, v44, v43
	v_mul_f32_e32 v46, v41, v45
	v_fma_f32 v47, v45, v41, -v46
	v_fmac_f32_e32 v47, v45, v37
	v_add_f32_e32 v48, v46, v47
	v_sub_f32_e32 v49, v44, v48
	v_sub_f32_e32 v44, v44, v49
	v_sub_f32_e32 v46, v48, v46
	v_sub_f32_e32 v44, v44, v48
	v_add_f32_e32 v42, v42, v44
	v_sub_f32_e32 v44, v46, v47
	v_add_f32_e32 v42, v44, v42
	v_add_f32_e32 v44, v49, v42
	v_mul_f32_e32 v46, v43, v44
	v_mul_f32_e32 v47, v41, v46
	v_fma_f32 v41, v46, v41, -v47
	v_fmac_f32_e32 v41, v46, v37
	v_sub_f32_e32 v37, v49, v44
	v_add_f32_e32 v37, v42, v37
	v_add_f32_e32 v42, v47, v41
	v_sub_f32_e32 v48, v44, v42
	v_sub_f32_e32 v44, v44, v48
	v_sub_f32_e32 v47, v42, v47
	v_sub_f32_e32 v42, v44, v42
	v_add_f32_e32 v37, v37, v42
	v_sub_f32_e32 v41, v47, v41
	v_add_f32_e32 v37, v41, v37
	v_add_f32_e32 v41, v45, v46
	v_add_f32_e32 v37, v48, v37
	v_sub_f32_e32 v42, v41, v45
	v_mul_f32_e32 v37, v43, v37
; __device__ __forceinline__ float softplus2_(float z2) { return fmaxf(z2, 0.f) + log1pf(exp2f(-fabsf(z2))) * LOG2E; }
; template <int NB>
; __device__ __forceinline__ void sb_decode_task(const Params& P, float* lds, int task) {
;     ...
;     const float sp0 = softplus2_(z0), sp1 = softplus2_(z1);
;     float incl = sp0 + sp1;
; #pragma unroll
;     for (int off = 1; off < 64; off <<= 1) { const float t = __shfl_down(incl, off); if (lane + off < 64) incl += t; }
;     const float excl = incl - (sp0 + sp1);
;     wl[2 * lane] = exp2f(z0 - sp0 - (excl + sp1));
;     wl[2 * lane + 1] = exp2f(z1 - sp1 - excl);
;     const float Ltot = __shfl(incl, 0);
;     asm volatile("s_waitcnt lgkmcnt(0)" ::: "memory");
;     __builtin_amdgcn_wave_barrier();
;     float4 o4 = make_float4(0.f, 0.f, 0.f, 0.f);
; #pragma unroll
;     for (int vb = 0; vb < NBT; ++vb) {
;         if (vb + 1 < NBT) {
; #pragma unroll
;             for (int i = 0; i < NB; ++i) nx[i] = *(const float4*)(Vp + (size_t)(4 * NB * (vb + 1) + 4 * i + g) * (SH * HD)); }
; #pragma unroll
;         for (int i = 0; i < NB; ++i) { const float w = wl[4 * NB * vb + 4 * i + g]; o4.x += w * cur[i].x; o4.y += w * cur[i].y; o4.z += w * cur[i].z; o4.w += w * cur[i].w; }
	v_sub_f32_e32 v42, v46, v42
	v_add_f32_e32 v37, v42, v37
	v_mul_f32_e32 v45, 0x3f317218, v36
	v_add_f32_e32 v42, v41, v37
	v_fma_f32 v46, v36, s95, -v45
	v_mul_f32_e32 v43, v42, v42
	v_fmac_f32_e32 v46, 0xb102e308, v36
	v_sub_f32_e32 v36, v42, v41
	v_fmamk_f32 v44, v43, 0x3e9b6dac, v1
	v_sub_f32_e32 v36, v37, v36
	v_add_f32_e32 v37, v45, v46
	v_fmaak_f32 v44, v43, v44, 0x3f2aaada
	v_sub_f32_e32 v41, v37, v45
	v_ldexp_f32 v45, v42, 1
	v_mul_f32_e32 v42, v42, v43
	v_mul_f32_e32 v42, v42, v44
	v_add_f32_e32 v43, v45, v42
	v_sub_f32_e32 v44, v43, v45
	v_ldexp_f32 v36, v36, 1
	v_sub_f32_e32 v42, v42, v44
	v_add_f32_e32 v36, v36, v42
	v_add_f32_e32 v42, v43, v36
	v_sub_f32_e32 v43, v42, v43
	v_sub_f32_e32 v36, v36, v43
	v_add_f32_e32 v43, v37, v42
	v_sub_f32_e32 v44, v43, v37
	v_sub_f32_e32 v45, v43, v44
	v_sub_f32_e32 v41, v46, v41
	v_sub_f32_e32 v37, v37, v45
	v_sub_f32_e32 v42, v42, v44
	v_add_f32_e32 v37, v42, v37
	v_add_f32_e32 v42, v41, v36
	v_sub_f32_e32 v44, v42, v41
	v_sub_f32_e32 v45, v42, v44
	v_sub_f32_e32 v41, v41, v45
	v_sub_f32_e32 v36, v36, v44
	v_add_f32_e32 v37, v42, v37
	v_add_f32_e32 v36, v36, v41
	v_add_f32_e32 v41, v43, v37
	v_sub_f32_e32 v42, v41, v43
	v_sub_f32_e32 v37, v37, v42
	v_add_f32_e32 v36, v36, v37
	v_add_f32_e32 v36, v41, v36
	v_cndmask_b32_e32 v36, v104, v36, vcc
	v_cmp_lt_f32_e64 vcc, |v40|, s45
	v_and_b32_e32 v37, 63, v105
	s_nop 0
	v_cndmask_b32_e32 v36, v36, v40, vcc
	v_cmp_ne_u32_e32 vcc, 63, v37
	v_fmac_f32_e32 v39, 0x3fb8aa3b, v36
	v_add_f32_e32 v36, v38, v39
	v_addc_co_u32_e32 v40, vcc, 0, v105, vcc
	v_lshlrev_b32_e32 v108, 2, v40
	ds_bpermute_b32 v40, v108, v36
	v_cmp_gt_u32_e32 vcc, 62, v37
	v_sub_f32_e32 v35, v35, v39
	s_waitcnt lgkmcnt(0)
	v_add_f32_e32 v40, v36, v40
	v_cndmask_b32_e64 v41, 0, 2, vcc
	v_cndmask_b32_e64 v40, v40, v36, s[8:9]
	v_add_lshl_u32 v109, v41, v105, 2
	ds_bpermute_b32 v41, v109, v40
	v_cmp_gt_u32_e32 vcc, 60, v37
	s_waitcnt lgkmcnt(0)
	v_add_f32_e32 v41, v40, v41
	v_cndmask_b32_e64 v40, v40, v41, s[10:11]
	v_cndmask_b32_e64 v41, 0, 4, vcc
	v_add_lshl_u32 v110, v41, v105, 2
	ds_bpermute_b32 v41, v110, v40
	v_cmp_gt_u32_e32 vcc, 56, v37
	s_waitcnt lgkmcnt(0)
	v_add_f32_e32 v41, v40, v41
	v_cndmask_b32_e64 v40, v40, v41, s[12:13]
	v_cndmask_b32_e64 v41, 0, 8, vcc
	v_add_lshl_u32 v111, v41, v105, 2
	ds_bpermute_b32 v41, v111, v40
	v_cmp_gt_u32_e32 vcc, 48, v37
	s_waitcnt lgkmcnt(0)
	v_add_f32_e32 v41, v40, v41
	v_cndmask_b32_e64 v37, 0, 16, vcc
	v_cndmask_b32_e64 v40, v40, v41, s[14:15]
	v_add_lshl_u32 v112, v37, v105, 2
	ds_bpermute_b32 v37, v112, v40
	s_waitcnt lgkmcnt(0)
	v_add_f32_e32 v37, v40, v37
	v_cndmask_b32_e64 v37, v40, v37, s[16:17]
	v_lshlrev_b32_e32 v40, 2, v105
	v_or_b32_e32 v113, 0x80, v40
	ds_bpermute_b32 v41, v113, v37
	v_and_b32_e32 v106, 0x100, v40
	s_waitcnt lgkmcnt(0)
	v_add_f32_e32 v41, v37, v41
	v_cndmask_b32_e64 v44, v37, v41, s[18:19]
	v_sub_f32_e32 v36, v44, v36
	v_add_f32_e32 v37, v39, v36
	v_sub_f32_e32 v34, v34, v37
	v_cmp_gt_f32_e32 vcc, s24, v34
	v_sub_f32_e32 v35, v35, v36
	s_nop 0
	v_cndmask_b32_e32 v37, 0, v103, vcc
	v_add_f32_e32 v34, v34, v37
	v_cndmask_b32_e32 v37, 0, v102, vcc
	v_cmp_gt_f32_e32 vcc, s24, v35
	v_exp_f32_e32 v34, v34
	s_nop 0
	v_cndmask_b32_e32 v36, 0, v103, vcc
	v_add_f32_e32 v35, v35, v36
	v_exp_f32_e32 v35, v35
	v_cndmask_b32_e32 v36, 0, v102, vcc
	v_ldexp_f32 v34, v34, v37
	v_ldexp_f32 v35, v35, v36
	ds_write_b64 v100, v[34:35] offset:512
	s_waitcnt lgkmcnt(0)
	ds_read2_b32 v[34:35], v99 offset0:128 offset1:132
	ds_read2_b32 v[42:43], v99 offset0:136 offset1:140
	ds_read2_b32 v[66:67], v99 offset0:144 offset1:148
	ds_read2_b32 v[68:69], v99 offset0:152 offset1:156
	ds_read2_b32 v[74:75], v99 offset0:160 offset1:164
	ds_read2_b32 v[76:77], v99 offset0:168 offset1:172
	ds_read2_b32 v[38:39], v99 offset0:176 offset1:180
	ds_read2_b32 v[40:41], v99 offset0:184 offset1:188
	s_waitcnt vmcnt(7) lgkmcnt(7)
	v_pk_fma_f32 v[70:71], v[30:31], v[34:35], 0 op_sel_hi:[1,0,0]
	v_add_co_u32_e32 v30, vcc, s25, v50
	v_pk_fma_f32 v[72:73], v[32:33], v[34:35], 0 op_sel_hi:[1,0,0]
	s_nop 0
	v_addc_co_u32_e32 v31, vcc, 0, v51, vcc
	v_add_co_u32_e32 v34, vcc, s43, v50
	v_mov_b32_e32 v64, v35
	s_nop 0
	v_addc_co_u32_e32 v35, vcc, 0, v51, vcc
	v_add_co_u32_e32 v46, vcc, s44, v50
	s_waitcnt vmcnt(6)
	v_pk_fma_f32 v[2:3], v[2:3], v[64:65], v[70:71] op_sel_hi:[1,0,1]
	v_addc_co_u32_e32 v47, vcc, 0, v51, vcc
	v_add_co_u32_e32 v52, vcc, s26, v50
	global_load_dwordx4 v[46:49], v[46:47], off nt
	s_nop 0
	v_addc_co_u32_e32 v53, vcc, 0, v51, vcc
	v_add_co_u32_e32 v56, vcc, s27, v50
	global_load_dwordx4 v[52:55], v[52:53], off offset:2048 nt
	s_nop 0
	v_addc_co_u32_e32 v57, vcc, 0, v51, vcc
	v_add_co_u32_e32 v60, vcc, s28, v50
	global_load_dwordx4 v[56:59], v[56:57], off nt
	s_nop 0
	v_addc_co_u32_e32 v61, vcc, 0, v51, vcc
	global_load_dwordx4 v[60:63], v[60:61], off offset:2048 nt
	s_waitcnt lgkmcnt(6)
	v_mov_b32_e32 v78, v43
	s_waitcnt vmcnt(9)
	v_pk_fma_f32 v[2:3], v[6:7], v[42:43], v[2:3] op_sel_hi:[1,0,1]
	s_waitcnt lgkmcnt(5)
	v_mov_b32_e32 v80, v67
	s_waitcnt vmcnt(7)
	v_pk_fma_f32 v[2:3], v[14:15], v[78:79], v[2:3] op_sel_hi:[1,0,1]
	s_waitcnt lgkmcnt(4)
	v_mov_b32_e32 v94, v69
	v_pk_fma_f32 v[2:3], v[10:11], v[66:67], v[2:3] op_sel_hi:[1,0,1]
	s_waitcnt lgkmcnt(3)
	v_mov_b32_e32 v10, v75
	s_waitcnt vmcnt(6)
	v_pk_fma_f32 v[2:3], v[18:19], v[80:81], v[2:3] op_sel_hi:[1,0,1]
	s_waitcnt lgkmcnt(2)
	v_mov_b32_e32 v14, v77
	s_waitcnt vmcnt(5)
	v_pk_fma_f32 v[2:3], v[22:23], v[68:69], v[2:3] op_sel_hi:[1,0,1]
	global_load_dwordx4 v[30:33], v[30:31], off nt
	s_waitcnt vmcnt(5)
; template <int NB>
; __device__ __forceinline__ void sb_decode_task(const Params& P, float* lds, int task) {
;     ...
; #pragma unroll
;     for (int vb = 0; vb < NBT; ++vb) {
;         if (vb + 1 < NBT) {
; #pragma unroll
;             for (int i = 0; i < NB; ++i) nx[i] = *(const float4*)(Vp + (size_t)(4 * NB * (vb + 1) + 4 * i + g) * (SH * HD)); }
; #pragma unroll
;         for (int i = 0; i < NB; ++i) { const float w = wl[4 * NB * vb + 4 * i + g]; o4.x += w * cur[i].x; o4.y += w * cur[i].y; o4.z += w * cur[i].z; o4.w += w * cur[i].w; }
; #pragma unroll
;         for (int i = 0; i < NB; ++i) cur[i] = nx[i];
;     }
	v_pk_fma_f32 v[2:3], v[26:27], v[94:95], v[2:3] op_sel_hi:[1,0,1]
	global_load_dwordx4 v[34:37], v[34:35], off offset:2048 nt
	s_waitcnt vmcnt(5)
	v_pk_fma_f32 v[2:3], v[46:47], v[74:75], v[2:3] op_sel_hi:[1,0,1]
	s_waitcnt vmcnt(4)
	v_pk_fma_f32 v[2:3], v[52:53], v[10:11], v[2:3] op_sel_hi:[1,0,1]
	s_waitcnt vmcnt(3)
	v_pk_fma_f32 v[2:3], v[56:57], v[76:77], v[2:3] op_sel_hi:[1,0,1]
	s_waitcnt vmcnt(2)
	v_pk_fma_f32 v[6:7], v[60:61], v[14:15], v[2:3] op_sel_hi:[1,0,1]
	v_pk_fma_f32 v[2:3], v[4:5], v[64:65], v[72:73] op_sel_hi:[1,0,1]
	v_add_co_u32_e32 v4, vcc, s29, v50
	v_pk_fma_f32 v[2:3], v[8:9], v[42:43], v[2:3] op_sel_hi:[1,0,1]
	s_nop 0
	v_addc_co_u32_e32 v5, vcc, 0, v51, vcc
	v_pk_fma_f32 v[2:3], v[16:17], v[78:79], v[2:3] op_sel_hi:[1,0,1]
	s_waitcnt lgkmcnt(0)
	v_mov_b32_e32 v42, v41
	v_pk_fma_f32 v[2:3], v[12:13], v[66:67], v[2:3] op_sel_hi:[1,0,1]
	s_waitcnt vmcnt(1)
	v_pk_fma_f32 v[6:7], v[30:31], v[38:39], v[6:7] op_sel_hi:[1,0,1]
	v_pk_fma_f32 v[2:3], v[20:21], v[80:81], v[2:3] op_sel_hi:[1,0,1]
	s_nop 0
	v_pk_fma_f32 v[2:3], v[24:25], v[68:69], v[2:3] op_sel_hi:[1,0,1]
	s_nop 0
	v_pk_fma_f32 v[2:3], v[28:29], v[94:95], v[2:3] op_sel_hi:[1,0,1]
	v_mov_b32_e32 v28, v39
	v_pk_fma_f32 v[2:3], v[48:49], v[74:75], v[2:3] op_sel_hi:[1,0,1]
	s_waitcnt vmcnt(0)
	v_pk_fma_f32 v[6:7], v[34:35], v[28:29], v[6:7] op_sel_hi:[1,0,1]
	v_pk_fma_f32 v[2:3], v[54:55], v[10:11], v[2:3] op_sel_hi:[1,0,1]
	s_nop 0
	v_pk_fma_f32 v[2:3], v[58:59], v[76:77], v[2:3] op_sel_hi:[1,0,1]
	s_nop 0
	v_pk_fma_f32 v[2:3], v[62:63], v[14:15], v[2:3] op_sel_hi:[1,0,1]
	ds_read2_b32 v[14:15], v99 offset0:192 offset1:196
	ds_read2_b32 v[12:13], v99 offset0:200 offset1:204
	ds_read2_b32 v[10:11], v99 offset0:208 offset1:212
	ds_read2_b32 v[8:9], v99 offset0:216 offset1:220
	global_load_dwordx4 v[16:19], v[4:5], off nt
	v_add_co_u32_e32 v4, vcc, s68, v50
	v_pk_fma_f32 v[2:3], v[32:33], v[38:39], v[2:3] op_sel_hi:[1,0,1]
	s_nop 0
	v_addc_co_u32_e32 v5, vcc, 0, v51, vcc
	global_load_dwordx4 v[20:23], v[4:5], off offset:2048 nt
	v_add_co_u32_e32 v4, vcc, s69, v50
	v_pk_fma_f32 v[2:3], v[36:37], v[28:29], v[2:3] op_sel_hi:[1,0,1]
	s_nop 0
	v_addc_co_u32_e32 v5, vcc, 0, v51, vcc
	global_load_dwordx4 v[24:27], v[4:5], off nt
	v_add_co_u32_e32 v4, vcc, s70, v50
	s_waitcnt lgkmcnt(0)
	v_mov_b32_e32 v36, v9
	v_addc_co_u32_e32 v5, vcc, 0, v51, vcc
	global_load_dwordx4 v[46:49], v[4:5], off offset:2048 nt
	v_add_co_u32_e32 v4, vcc, s71, v50
	ds_read2_b32 v[30:31], v99 offset0:224 offset1:228
	s_nop 0
	v_addc_co_u32_e32 v5, vcc, 0, v51, vcc
	global_load_dwordx4 v[52:55], v[4:5], off nt
	v_add_co_u32_e32 v4, vcc, s72, v50
	s_waitcnt vmcnt(4)
	v_pk_fma_f32 v[2:3], v[18:19], v[40:41], v[2:3] op_sel_hi:[1,0,1]
	v_addc_co_u32_e32 v5, vcc, 0, v51, vcc
	global_load_dwordx4 v[56:59], v[4:5], off offset:2048 nt
	v_add_co_u32_e32 v4, vcc, s73, v50
	s_waitcnt vmcnt(4)
	v_pk_fma_f32 v[2:3], v[22:23], v[42:43], v[2:3] op_sel_hi:[1,0,1]
	v_addc_co_u32_e32 v5, vcc, 0, v51, vcc
	global_load_dwordx4 v[60:63], v[4:5], off nt
	v_add_co_u32_e32 v4, vcc, s74, v50
	s_waitcnt vmcnt(4)
	v_pk_fma_f32 v[2:3], v[26:27], v[14:15], v[2:3] op_sel_hi:[1,0,1]
	v_addc_co_u32_e32 v5, vcc, 0, v51, vcc
	global_load_dwordx4 v[64:67], v[4:5], off offset:2048 nt
	v_add_co_u32_e32 v4, vcc, s75, v50
	v_mov_b32_e32 v18, v15
	s_nop 0
	v_addc_co_u32_e32 v5, vcc, 0, v51, vcc
	global_load_dwordx4 v[68:71], v[4:5], off nt
	v_pk_fma_f32 v[6:7], v[16:17], v[40:41], v[6:7] op_sel_hi:[1,0,1]
	s_waitcnt vmcnt(5)
	v_pk_fma_f32 v[2:3], v[48:49], v[18:19], v[2:3] op_sel_hi:[1,0,1]
	v_pk_fma_f32 v[6:7], v[20:21], v[42:43], v[6:7] op_sel_hi:[1,0,1]
	s_waitcnt vmcnt(4)
	v_pk_fma_f32 v[2:3], v[54:55], v[12:13], v[2:3] op_sel_hi:[1,0,1]
	v_mov_b32_e32 v22, v13
	v_pk_fma_f32 v[6:7], v[24:25], v[14:15], v[6:7] op_sel_hi:[1,0,1]
	v_mov_b32_e32 v26, v11
	v_pk_fma_f32 v[6:7], v[46:47], v[18:19], v[6:7] op_sel_hi:[1,0,1]
	s_waitcnt vmcnt(3)
	v_pk_fma_f32 v[2:3], v[58:59], v[22:23], v[2:3] op_sel_hi:[1,0,1]
	v_pk_fma_f32 v[6:7], v[52:53], v[12:13], v[6:7] op_sel_hi:[1,0,1]
	s_waitcnt vmcnt(2)
	v_pk_fma_f32 v[2:3], v[62:63], v[10:11], v[2:3] op_sel_hi:[1,0,1]
	v_pk_fma_f32 v[6:7], v[56:57], v[22:23], v[6:7] op_sel_hi:[1,0,1]
	s_waitcnt vmcnt(1)
; template <int NB>
; __device__ __forceinline__ void sb_decode_task(const Params& P, float* lds, int task) {
;     ...
;     for (int vb = 0; vb < NBT; ++vb) {
;         if (vb + 1 < NBT) {
; #pragma unroll
;             for (int i = 0; i < NB; ++i) nx[i] = *(const float4*)(Vp + (size_t)(4 * NB * (vb + 1) + 4 * i + g) * (SH * HD)); }
; #pragma unroll
;         for (int i = 0; i < NB; ++i) { const float w = wl[4 * NB * vb + 4 * i + g]; o4.x += w * cur[i].x; o4.y += w * cur[i].y; o4.z += w * cur[i].z; o4.w += w * cur[i].w; }
; #pragma unroll
;         for (int i = 0; i < NB; ++i) cur[i] = nx[i];
;     }
; #pragma unroll
;     for (int off = 16; off < 64; off <<= 1) { o4.x += __shfl_xor(o4.x, off); o4.y += __shfl_xor(o4.y, off); o4.z += __shfl_xor(o4.z, off); o4.w += __shfl_xor(o4.w, off); }
;     if (g == 0) *(float4*)(dpart + (size_t)task * HD + 4 * c) = o4;
	v_pk_fma_f32 v[2:3], v[66:67], v[26:27], v[2:3] op_sel_hi:[1,0,1]
	v_pk_fma_f32 v[6:7], v[60:61], v[10:11], v[6:7] op_sel_hi:[1,0,1]
	v_and_b32_e32 v10, 64, v105
	v_pk_fma_f32 v[6:7], v[64:65], v[26:27], v[6:7] op_sel_hi:[1,0,1]
	v_add_u32_e32 v37, 64, v10
	v_xor_b32_e32 v10, 16, v105
	s_waitcnt vmcnt(0)
	v_pk_fma_f32 v[32:33], v[70:71], v[8:9], v[2:3] op_sel_hi:[1,0,1]
	v_add_co_u32_e32 v2, vcc, s80, v50
	v_pk_fma_f32 v[34:35], v[68:69], v[8:9], v[6:7] op_sel_hi:[1,0,1]
	s_nop 0
	v_addc_co_u32_e32 v3, vcc, 0, v51, vcc
	v_add_co_u32_e32 v6, vcc, s81, v50
	global_load_dwordx4 v[2:5], v[2:3], off offset:2048 nt
	s_nop 0
	v_addc_co_u32_e32 v7, vcc, 0, v51, vcc
	v_cmp_lt_i32_e32 vcc, v10, v37
	global_load_dwordx4 v[6:9], v[6:7], off nt
	ds_read2_b32 v[42:43], v99 offset0:232 offset1:236
	ds_read2_b32 v[40:41], v99 offset0:240 offset1:244
	ds_read2_b32 v[38:39], v99 offset0:248 offset1:252
	v_cndmask_b32_e32 v10, v105, v10, vcc
	v_lshlrev_b32_e32 v107, 2, v10
	v_add_co_u32_e32 v10, vcc, s82, v50
	s_waitcnt lgkmcnt(2)
	v_mov_b32_e32 v54, v43
	v_addc_co_u32_e32 v11, vcc, 0, v51, vcc
	v_add_co_u32_e32 v14, vcc, s83, v50
	global_load_dwordx4 v[10:13], v[10:11], off offset:2048 nt
	s_nop 0
	v_addc_co_u32_e32 v15, vcc, 0, v51, vcc
	v_add_co_u32_e32 v18, vcc, s84, v50
	global_load_dwordx4 v[14:17], v[14:15], off nt
	s_nop 0
	v_addc_co_u32_e32 v19, vcc, 0, v51, vcc
	v_add_co_u32_e32 v22, vcc, s85, v50
	global_load_dwordx4 v[18:21], v[18:19], off offset:2048 nt
	s_nop 0
	v_addc_co_u32_e32 v23, vcc, 0, v51, vcc
	v_add_co_u32_e32 v26, vcc, s86, v50
	global_load_dwordx4 v[22:25], v[22:23], off nt
	s_nop 0
	v_addc_co_u32_e32 v27, vcc, 0, v51, vcc
	v_add_co_u32_e32 v46, vcc, s87, v50
	global_load_dwordx4 v[26:29], v[26:27], off offset:2048 nt
	s_nop 0
	v_addc_co_u32_e32 v47, vcc, 0, v51, vcc
	v_add_co_u32_e32 v50, vcc, s88, v50
	global_load_dwordx4 v[46:49], v[46:47], off nt
	s_nop 0
	v_addc_co_u32_e32 v51, vcc, 0, v51, vcc
	global_load_dwordx4 v[50:53], v[50:51], off offset:2048 nt
	s_waitcnt lgkmcnt(1)
	v_mov_b32_e32 v56, v41
	s_waitcnt lgkmcnt(0)
	v_mov_b32_e32 v58, v39
	s_waitcnt vmcnt(8)
	v_pk_fma_f32 v[2:3], v[2:3], v[36:37], v[34:35] op_sel_hi:[1,0,1]
	v_mov_b32_e32 v34, v31
	v_pk_fma_f32 v[4:5], v[4:5], v[36:37], v[32:33] op_sel_hi:[1,0,1]
	s_waitcnt vmcnt(7)
	v_pk_fma_f32 v[2:3], v[6:7], v[30:31], v[2:3] op_sel_hi:[1,0,1]
	v_pk_fma_f32 v[4:5], v[8:9], v[30:31], v[4:5] op_sel_hi:[1,0,1]
	s_waitcnt vmcnt(6)
	v_pk_fma_f32 v[2:3], v[10:11], v[34:35], v[2:3] op_sel_hi:[1,0,1]
	v_pk_fma_f32 v[4:5], v[12:13], v[34:35], v[4:5] op_sel_hi:[1,0,1]
	ds_bpermute_b32 v10, v106, v44
	s_waitcnt vmcnt(5)
	v_pk_fma_f32 v[2:3], v[14:15], v[42:43], v[2:3] op_sel_hi:[1,0,1]
	v_pk_fma_f32 v[4:5], v[16:17], v[42:43], v[4:5] op_sel_hi:[1,0,1]
	s_waitcnt vmcnt(4)
	v_pk_fma_f32 v[2:3], v[18:19], v[54:55], v[2:3] op_sel_hi:[1,0,1]
	v_pk_fma_f32 v[4:5], v[20:21], v[54:55], v[4:5] op_sel_hi:[1,0,1]
	s_waitcnt vmcnt(3)
	v_pk_fma_f32 v[2:3], v[22:23], v[40:41], v[2:3] op_sel_hi:[1,0,1]
	v_pk_fma_f32 v[4:5], v[24:25], v[40:41], v[4:5] op_sel_hi:[1,0,1]
	s_waitcnt vmcnt(2)
	v_pk_fma_f32 v[2:3], v[26:27], v[56:57], v[2:3] op_sel_hi:[1,0,1]
	v_pk_fma_f32 v[4:5], v[28:29], v[56:57], v[4:5] op_sel_hi:[1,0,1]
	s_waitcnt vmcnt(1)
	v_pk_fma_f32 v[2:3], v[46:47], v[38:39], v[2:3] op_sel_hi:[1,0,1]
	v_pk_fma_f32 v[4:5], v[48:49], v[38:39], v[4:5] op_sel_hi:[1,0,1]
	s_waitcnt vmcnt(0)
	v_pk_fma_f32 v[2:3], v[50:51], v[58:59], v[2:3] op_sel_hi:[1,0,1]
	ds_bpermute_b32 v6, v107, v2
	ds_bpermute_b32 v7, v107, v3
	v_pk_fma_f32 v[4:5], v[52:53], v[58:59], v[4:5] op_sel_hi:[1,0,1]
	s_waitcnt lgkmcnt(0)
	v_pk_add_f32 v[2:3], v[2:3], v[6:7]
	ds_bpermute_b32 v6, v107, v4
	ds_bpermute_b32 v7, v107, v5
	s_waitcnt lgkmcnt(0)
	v_pk_add_f32 v[4:5], v[4:5], v[6:7]
	v_xor_b32_e32 v6, 32, v105
	v_cmp_lt_i32_e32 vcc, v6, v37
	s_nop 1
	v_cndmask_b32_e32 v6, v105, v6, vcc
	v_lshlrev_b32_e32 v114, 2, v6
	ds_bpermute_b32 v6, v114, v2
	ds_bpermute_b32 v7, v114, v3
	ds_bpermute_b32 v8, v114, v4
	ds_bpermute_b32 v9, v114, v5
	s_and_saveexec_b64 s[0:1], s[20:21]
	s_cbranch_execz .LBB0_1347
	s_ashr_i32 s35, s34, 31
	s_lshl_b64 s[36:37], s[34:35], 8
	v_lshl_add_u64 v[12:13], v[88:89], 0, s[36:37]
	s_waitcnt lgkmcnt(2)
	v_pk_add_f32 v[2:3], v[2:3], v[6:7]
	s_waitcnt lgkmcnt(0)
	v_pk_add_f32 v[4:5], v[4:5], v[8:9]
	global_store_dwordx4 v[12:13], v[2:5], off

; __device__ __forceinline__ float bf2f(bf16_t b) { return __uint_as_float(((unsigned)b) << 16); }
; template <int NB>
; __device__ __forceinline__ void sb_decode_task(const Params& P, float* lds, int task) {
;     const int tid = threadIdx.x, lane = tid & 63, wave = tid >> 6;
;     const bf16_t* qb = (const bf16_t*)(P.ws + WS_QB);
;     float* dpart = (float*)(P.ws + WS_DPART); float* dl = (float*)(P.ws + WS_DL);
;     float* zl = lds + DEC_LDS_OFF / 4 + wave * 256; float* wl = zl + 128;
;     const int c = lane & 15, g = lane >> 4;
;     constexpr int NBT = 32 / NB;
;     const int h = task % SH, bj = task / SH, b = bj / NPAGES;
;     const int page = P.page_table[bj];
;     const float* Kp = P.cache_k + ((size_t)page * PAGE * SH + h) * HD + 4 * c;
;     const float* Vp = P.cache_v + ((size_t)page * PAGE * SH + h) * HD + 4 * c;
;     const bf16_t* qp = qb + (size_t)(NTOK + b) * SBW + h * 64 + 4 * c;
;     const float q0 = bf2f(qp[0]), q1 = bf2f(qp[1]), q2 = bf2f(qp[2]), q3 = bf2f(qp[3]);
;     const float bias = P.sb_bias[h] * LOG2E;
;     float4 cur[NB], nx[NB];
; #pragma unroll
;     for (int i = 0; i < NB; ++i) cur[i] = *(const float4*)(Kp + (size_t)(4 * i + g) * (SH * HD));
; #pragma unroll
;     for (int kb = 0; kb < NBT; ++kb) {
;         const float* np = (kb + 1 < NBT) ? Kp + (size_t)(4 * NB * (kb + 1)) * (SH * HD) : Vp;
; #pragma unroll
;         for (int i = 0; i < NB; ++i) nx[i] = *(const float4*)(np + (size_t)(4 * i + g) * (SH * HD));
; #pragma unroll
;         for (int i = 0; i < NB; ++i) { const int s = 4 * NB * kb + 4 * i + g;
;             float part = q0 * cur[i].x + q1 * cur[i].y + q2 * cur[i].z + q3 * cur[i].w; part = sum16(part);
;             if (c == 0) zl[s] = part + bias; }
; #pragma unroll
;         for (int i = 0; i < NB; ++i) cur[i] = nx[i];
;     }
.LBB0_1349:
	s_or_b64 exec, exec, s[0:1]
	v_readlane_b32 s30, v252, 48
	s_add_i32 s36, s34, 1
	v_readlane_b32 s31, v252, 49
	s_mul_hi_i32 s1, s36, 0x2aaaaaab
	s_load_dwordx16 s[52:67], s[30:31], 0x0
	s_lshr_b32 s3, s1, 31
	s_add_i32 s0, s1, s3
	s_ashr_i32 s1, s1, 7
	s_mul_i32 s33, s0, 6
	s_add_i32 s3, s1, s3
	s_ashr_i32 s1, s0, 31
	s_sub_i32 s90, s36, s33
	s_lshl_b64 s[0:1], s[0:1], 2
	s_waitcnt lgkmcnt(0)
	s_add_u32 s0, s62, s0
	s_addc_u32 s1, s63, s1
	global_load_dword v2, v83, s[0:1]
	s_add_i32 s0, s3, 0x4000
	s_ashr_i32 s91, s90, 31
	s_mul_hi_i32 s1, s0, 0x300
	s_mulk_i32 s0, 0x300
	s_add_u32 s3, s38, s0
	s_addc_u32 s33, s39, s1
	s_lshl_b32 s0, s90, 6
	s_ashr_i32 s1, s0, 31
	s_lshl_b64 s[0:1], s[0:1], 1
	s_add_u32 s0, s3, s0
	s_addc_u32 s1, s33, s1
	v_readlane_b32 s52, v252, 16
	v_readlane_b32 s53, v252, 17
	v_readlane_b32 s60, v252, 24
	v_readlane_b32 s61, v252, 25
	s_mov_b64 s[52:53], s[60:61]
	v_mov_b32_e32 v93, v83
	v_readlane_b32 s54, v252, 18
	v_readlane_b32 s55, v252, 19
	v_readlane_b32 s56, v252, 20
	v_readlane_b32 s57, v252, 21
	v_readlane_b32 s58, v252, 22
	v_readlane_b32 s59, v252, 23
	v_readlane_b32 s62, v252, 26
	v_readlane_b32 s63, v252, 27
	v_readlane_b32 s64, v252, 28
	v_readlane_b32 s65, v252, 29
	v_readlane_b32 s66, v252, 30
	v_readlane_b32 s67, v252, 31
	s_waitcnt vmcnt(0)
	v_mul_hi_i32 v3, v2, s48
	v_mul_lo_u32 v2, v2, s48
	v_lshl_add_u64 v[94:95], v[2:3], 0, s[90:91]
	v_lshlrev_b64 v[2:3], 8, v[94:95]
	v_lshl_add_u64 v[70:71], v[84:85], 0, v[2:3]
	global_load_dwordx2 v[2:3], v101, s[0:1]
	s_lshl_b64 s[0:1], s[90:91], 2
	s_add_u32 s0, s52, s0
	s_addc_u32 s1, s53, s1
	global_load_dword v22, v83, s[0:1]
	v_lshl_add_u64 v[18:19], v[70:71], 0, v[82:83]
	v_lshl_add_u64 v[20:21], v[70:71], 0, v[92:93]
	global_load_dwordx4 v[14:17], v[18:19], off nt
	s_mov_b64 s[0:1], 0xc000
	global_load_dwordx4 v[62:65], v[20:21], off nt
	s_waitcnt vmcnt(3)
	v_lshlrev_b32_e32 v116, 16, v2
	v_and_b32_e32 v118, 0xffff0000, v2
	v_add_co_u32_e32 v2, vcc, s50, v18
	v_lshlrev_b32_e32 v117, 16, v3
	v_and_b32_e32 v115, 0xffff0000, v3
	v_addc_co_u32_e32 v3, vcc, 0, v19, vcc
	global_load_dwordx4 v[10:13], v[2:3], off offset:2048 nt
	v_add_co_u32_e32 v2, vcc, s51, v18
	s_waitcnt vmcnt(3)
	v_mul_f32_e32 v119, 0x3fb8aa3b, v22
	v_addc_co_u32_e32 v3, vcc, 0, v19, vcc
	global_load_dwordx4 v[6:9], v[2:3], off nt
	v_add_co_u32_e32 v2, vcc, s49, v18
	v_lshl_add_u64 v[22:23], v[70:71], 0, s[0:1]
	s_nop 0
	v_addc_co_u32_e32 v3, vcc, 0, v19, vcc
	v_add_co_u32_e32 v20, vcc, s92, v18
	v_lshl_add_u64 v[30:31], v[22:23], 0, v[82:83]
	s_nop 0
	v_addc_co_u32_e32 v21, vcc, 0, v19, vcc
	global_load_dwordx4 v[58:61], v[20:21], off offset:2048 nt
	v_add_co_u32_e32 v20, vcc, s93, v18
	v_lshl_add_u64 v[22:23], v[22:23], 0, v[92:93]
	s_nop 0
	v_addc_co_u32_e32 v21, vcc, 0, v19, vcc
	v_add_co_u32_e32 v18, vcc, s96, v18
	global_load_dwordx4 v[54:57], v[20:21], off nt
	s_nop 0
	v_addc_co_u32_e32 v19, vcc, 0, v19, vcc
	global_load_dwordx4 v[50:53], v[18:19], off offset:2048 nt
	v_add_co_u32_e32 v18, vcc, s50, v30
	global_load_dwordx4 v[22:25], v[22:23], off nt
	s_nop 0
	v_addc_co_u32_e32 v19, vcc, 0, v31, vcc
	global_load_dwordx4 v[34:37], v[18:19], off offset:2048 nt
	v_add_co_u32_e32 v18, vcc, s51, v30
	global_load_dwordx4 v[2:5], v[2:3], off offset:2048 nt
	s_nop 0
	v_addc_co_u32_e32 v19, vcc, 0, v31, vcc
	global_load_dwordx4 v[26:29], v[18:19], off nt
	v_add_co_u32_e32 v18, vcc, s49, v30
	global_load_dwordx4 v[46:49], v[30:31], off nt
	s_nop 0
	v_addc_co_u32_e32 v19, vcc, 0, v31, vcc
	v_add_co_u32_e32 v32, vcc, s92, v30
	global_load_dwordx4 v[18:21], v[18:19], off offset:2048 nt
	s_nop 0
	v_addc_co_u32_e32 v33, vcc, 0, v31, vcc
	global_load_dwordx4 v[38:41], v[32:33], off offset:2048 nt
	v_add_co_u32_e32 v32, vcc, s93, v30
	s_waitcnt vmcnt(13)
	v_mul_f32_e32 v15, v15, v118
	v_addc_co_u32_e32 v33, vcc, 0, v31, vcc
	v_add_co_u32_e32 v30, vcc, s96, v30
	global_load_dwordx4 v[42:45], v[32:33], off nt
	s_nop 0
	v_addc_co_u32_e32 v31, vcc, 0, v31, vcc
	global_load_dwordx4 v[30:33], v[30:31], off offset:2048 nt
	v_fmac_f32_e32 v15, v14, v116
	v_fmac_f32_e32 v15, v16, v117
	v_fmac_f32_e32 v15, v17, v115
	s_nop 1
	v_add_f32_dpp v14, v15, v15 quad_perm:[1,0,3,2] row_mask:0xf bank_mask:0xf bound_ctrl:1
	s_nop 1
	v_add_f32_dpp v14, v14, v14 quad_perm:[2,3,0,1] row_mask:0xf bank_mask:0xf bound_ctrl:1
	s_nop 1
	v_add_f32_dpp v14, v14, v14 row_ror:4 row_mask:0xf bank_mask:0xf bound_ctrl:1
	s_nop 1
	v_mov_b32_dpp v15, v14 row_ror:8 row_mask:0xf bank_mask:0xf bound_ctrl:1
	s_and_saveexec_b64 s[0:1], s[6:7]
	v_add_f32_e32 v14, v14, v15
	v_add_f32_e32 v14, v119, v14
	ds_write_b32 v99, v14
	s_or_b64 exec, exec, s[0:1]
	s_waitcnt vmcnt(13)
	v_mul_f32_e32 v11, v11, v118
	v_fmac_f32_e32 v11, v10, v116
	v_fmac_f32_e32 v11, v12, v117
	v_fmac_f32_e32 v11, v13, v115
	s_nop 1
	v_add_f32_dpp v10, v11, v11 quad_perm:[1,0,3,2] row_mask:0xf bank_mask:0xf bound_ctrl:1
	s_nop 1
	v_add_f32_dpp v10, v10, v10 quad_perm:[2,3,0,1] row_mask:0xf bank_mask:0xf bound_ctrl:1
	s_nop 1
	v_add_f32_dpp v10, v10, v10 row_ror:4 row_mask:0xf bank_mask:0xf bound_ctrl:1
	s_nop 1
	v_mov_b32_dpp v11, v10 row_ror:8 row_mask:0xf bank_mask:0xf bound_ctrl:1
	s_and_saveexec_b64 s[0:1], s[6:7]
	v_add_f32_e32 v10, v10, v11
	v_add_f32_e32 v10, v119, v10
	ds_write_b32 v99, v10 offset:16
	s_or_b64 exec, exec, s[0:1]
	s_waitcnt vmcnt(12)
; template <int NB>
; __device__ __forceinline__ void sb_decode_task(const Params& P, float* lds, int task) {
;     ...
;     for (int i = 0; i < NB; ++i) cur[i] = *(const float4*)(Kp + (size_t)(4 * i + g) * (SH * HD));
; #pragma unroll
;     for (int kb = 0; kb < NBT; ++kb) {
;         const float* np = (kb + 1 < NBT) ? Kp + (size_t)(4 * NB * (kb + 1)) * (SH * HD) : Vp;
; #pragma unroll
;         for (int i = 0; i < NB; ++i) nx[i] = *(const float4*)(np + (size_t)(4 * i + g) * (SH * HD));
; #pragma unroll
;         for (int i = 0; i < NB; ++i) { const int s = 4 * NB * kb + 4 * i + g;
;             float part = q0 * cur[i].x + q1 * cur[i].y + q2 * cur[i].z + q3 * cur[i].w; part = sum16(part);
;             if (c == 0) zl[s] = part + bias; }
; #pragma unroll
;         for (int i = 0; i < NB; ++i) cur[i] = nx[i];
;     }
	v_mul_f32_e32 v7, v7, v118
	v_fmac_f32_e32 v7, v6, v116
	v_fmac_f32_e32 v7, v8, v117
	v_fmac_f32_e32 v7, v9, v115
	s_nop 1
	v_add_f32_dpp v6, v7, v7 quad_perm:[1,0,3,2] row_mask:0xf bank_mask:0xf bound_ctrl:1
	s_nop 1
	v_add_f32_dpp v6, v6, v6 quad_perm:[2,3,0,1] row_mask:0xf bank_mask:0xf bound_ctrl:1
	s_nop 1
	v_add_f32_dpp v6, v6, v6 row_ror:4 row_mask:0xf bank_mask:0xf bound_ctrl:1
	s_nop 1
	v_mov_b32_dpp v7, v6 row_ror:8 row_mask:0xf bank_mask:0xf bound_ctrl:1
	s_and_saveexec_b64 s[0:1], s[6:7]
	v_add_f32_e32 v6, v6, v7
	v_add_f32_e32 v6, v119, v6
	ds_write_b32 v99, v6 offset:32
	s_or_b64 exec, exec, s[0:1]
	s_waitcnt vmcnt(6)
	v_mul_f32_e32 v3, v3, v118
	v_fmac_f32_e32 v3, v2, v116
	v_fmac_f32_e32 v3, v4, v117
	v_fmac_f32_e32 v3, v5, v115
	s_nop 1
	v_add_f32_dpp v2, v3, v3 quad_perm:[1,0,3,2] row_mask:0xf bank_mask:0xf bound_ctrl:1
	s_nop 1
	v_add_f32_dpp v2, v2, v2 quad_perm:[2,3,0,1] row_mask:0xf bank_mask:0xf bound_ctrl:1
	s_nop 1
	v_add_f32_dpp v2, v2, v2 row_ror:4 row_mask:0xf bank_mask:0xf bound_ctrl:1
	s_nop 1
	v_mov_b32_dpp v3, v2 row_ror:8 row_mask:0xf bank_mask:0xf bound_ctrl:1
	s_and_saveexec_b64 s[0:1], s[6:7]
	v_add_f32_e32 v2, v2, v3
	v_add_f32_e32 v2, v119, v2
	ds_write_b32 v99, v2 offset:48
	s_or_b64 exec, exec, s[0:1]
	v_mul_f32_e32 v2, v63, v118
	v_fmac_f32_e32 v2, v62, v116
	v_fmac_f32_e32 v2, v64, v117
	v_fmac_f32_e32 v2, v65, v115
	s_nop 1
	v_add_f32_dpp v2, v2, v2 quad_perm:[1,0,3,2] row_mask:0xf bank_mask:0xf bound_ctrl:1
	s_nop 1
	v_add_f32_dpp v2, v2, v2 quad_perm:[2,3,0,1] row_mask:0xf bank_mask:0xf bound_ctrl:1
	s_nop 1
	v_add_f32_dpp v2, v2, v2 row_ror:4 row_mask:0xf bank_mask:0xf bound_ctrl:1
	s_nop 1
	v_mov_b32_dpp v3, v2 row_ror:8 row_mask:0xf bank_mask:0xf bound_ctrl:1
	s_and_saveexec_b64 s[0:1], s[6:7]
	v_add_f32_e32 v2, v2, v3
	v_add_f32_e32 v2, v119, v2
	ds_write_b32 v99, v2 offset:64
	s_or_b64 exec, exec, s[0:1]
	v_mul_f32_e32 v2, v59, v118
	v_fmac_f32_e32 v2, v58, v116
	v_fmac_f32_e32 v2, v60, v117
	v_fmac_f32_e32 v2, v61, v115
	s_nop 1
	v_add_f32_dpp v2, v2, v2 quad_perm:[1,0,3,2] row_mask:0xf bank_mask:0xf bound_ctrl:1
	s_nop 1
	v_add_f32_dpp v2, v2, v2 quad_perm:[2,3,0,1] row_mask:0xf bank_mask:0xf bound_ctrl:1
	s_nop 1
	v_add_f32_dpp v2, v2, v2 row_ror:4 row_mask:0xf bank_mask:0xf bound_ctrl:1
	s_nop 1
	v_mov_b32_dpp v3, v2 row_ror:8 row_mask:0xf bank_mask:0xf bound_ctrl:1
	s_and_saveexec_b64 s[0:1], s[6:7]
	v_add_f32_e32 v2, v2, v3
	v_add_f32_e32 v2, v119, v2
	ds_write_b32 v99, v2 offset:80
	s_or_b64 exec, exec, s[0:1]
	v_mul_f32_e32 v2, v55, v118
	v_fmac_f32_e32 v2, v54, v116
	v_fmac_f32_e32 v2, v56, v117
	v_fmac_f32_e32 v2, v57, v115
	s_nop 1
	v_add_f32_dpp v2, v2, v2 quad_perm:[1,0,3,2] row_mask:0xf bank_mask:0xf bound_ctrl:1
	s_nop 1
	v_add_f32_dpp v2, v2, v2 quad_perm:[2,3,0,1] row_mask:0xf bank_mask:0xf bound_ctrl:1
	s_nop 1
	v_add_f32_dpp v2, v2, v2 row_ror:4 row_mask:0xf bank_mask:0xf bound_ctrl:1
	s_nop 1
	v_mov_b32_dpp v3, v2 row_ror:8 row_mask:0xf bank_mask:0xf bound_ctrl:1
	s_and_saveexec_b64 s[0:1], s[6:7]
	v_add_f32_e32 v2, v2, v3
	v_add_f32_e32 v2, v119, v2
	ds_write_b32 v99, v2 offset:96
	s_or_b64 exec, exec, s[0:1]
	v_mul_f32_e32 v2, v51, v118
	v_fmac_f32_e32 v2, v50, v116
	v_fmac_f32_e32 v2, v52, v117
	v_fmac_f32_e32 v2, v53, v115
	s_nop 1
	v_add_f32_dpp v2, v2, v2 quad_perm:[1,0,3,2] row_mask:0xf bank_mask:0xf bound_ctrl:1
	s_nop 1
	v_add_f32_dpp v2, v2, v2 quad_perm:[2,3,0,1] row_mask:0xf bank_mask:0xf bound_ctrl:1
	s_nop 1
	v_add_f32_dpp v2, v2, v2 row_ror:4 row_mask:0xf bank_mask:0xf bound_ctrl:1
	s_nop 1
	v_mov_b32_dpp v3, v2 row_ror:8 row_mask:0xf bank_mask:0xf bound_ctrl:1
	s_and_saveexec_b64 s[0:1], s[6:7]
	v_add_f32_e32 v2, v2, v3
	v_add_f32_e32 v2, v119, v2
	ds_write_b32 v99, v2 offset:112
	s_or_b64 exec, exec, s[0:1]
	s_mov_b64 s[0:1], 0x18000
	v_lshl_add_u64 v[2:3], v[70:71], 0, s[0:1]
	v_lshl_add_u64 v[4:5], v[2:3], 0, v[82:83]
	v_add_co_u32_e32 v6, vcc, 0x1000, v4
	v_mov_b32_e32 v93, v83
	s_nop 0
	v_addc_co_u32_e32 v7, vcc, 0, v5, vcc
	global_load_dwordx4 v[74:77], v[4:5], off nt
	global_load_dwordx4 v[66:69], v[6:7], off offset:2048 nt
	v_add_co_u32_e32 v6, vcc, 0x3000, v4
	v_lshl_add_u64 v[2:3], v[2:3], 0, v[92:93]
	s_nop 0
	v_addc_co_u32_e32 v7, vcc, 0, v5, vcc
	v_add_co_u32_e32 v8, vcc, s49, v4
	s_waitcnt vmcnt(6)
	v_mul_f32_e32 v47, v47, v118
	v_addc_co_u32_e32 v9, vcc, 0, v5, vcc
	global_load_dwordx4 v[58:61], v[6:7], off nt
	global_load_dwordx4 v[50:53], v[8:9], off offset:2048 nt
	v_add_co_u32_e32 v6, vcc, 0x7000, v4
	v_fmac_f32_e32 v47, v46, v116
	s_nop 0
	v_addc_co_u32_e32 v7, vcc, 0, v5, vcc
	global_load_dwordx4 v[14:17], v[2:3], off nt
	global_load_dwordx4 v[10:13], v[6:7], off offset:2048 nt
	v_add_co_u32_e32 v2, vcc, 0x9000, v4
	v_fmac_f32_e32 v47, v48, v117
	s_nop 0
	v_addc_co_u32_e32 v3, vcc, 0, v5, vcc
	v_add_co_u32_e32 v4, vcc, 0xa000, v4
	v_fmac_f32_e32 v47, v49, v115
	s_nop 0
	v_addc_co_u32_e32 v5, vcc, 0, v5, vcc
	global_load_dwordx4 v[6:9], v[2:3], off nt
	s_nop 0
	global_load_dwordx4 v[2:5], v[4:5], off offset:2048 nt
	v_add_f32_dpp v46, v47, v47 quad_perm:[1,0,3,2] row_mask:0xf bank_mask:0xf bound_ctrl:1
	s_nop 1
	v_add_f32_dpp v46, v46, v46 quad_perm:[2,3,0,1] row_mask:0xf bank_mask:0xf bound_ctrl:1
	s_nop 1
	v_add_f32_dpp v46, v46, v46 row_ror:4 row_mask:0xf bank_mask:0xf bound_ctrl:1
	s_nop 1
	v_mov_b32_dpp v47, v46 row_ror:8 row_mask:0xf bank_mask:0xf bound_ctrl:1
	s_and_saveexec_b64 s[0:1], s[6:7]
	v_add_f32_e32 v46, v46, v47
	v_add_f32_e32 v46, v119, v46
	ds_write_b32 v99, v46 offset:128
	s_or_b64 exec, exec, s[0:1]
	v_mul_f32_e32 v35, v35, v118
	v_fmac_f32_e32 v35, v34, v116
	v_fmac_f32_e32 v35, v36, v117
	v_fmac_f32_e32 v35, v37, v115
	s_nop 1
	v_add_f32_dpp v34, v35, v35 quad_perm:[1,0,3,2] row_mask:0xf bank_mask:0xf bound_ctrl:1
	s_nop 1
	v_add_f32_dpp v34, v34, v34 quad_perm:[2,3,0,1] row_mask:0xf bank_mask:0xf bound_ctrl:1
	s_nop 1
	v_add_f32_dpp v34, v34, v34 row_ror:4 row_mask:0xf bank_mask:0xf bound_ctrl:1
	s_nop 1
	v_mov_b32_dpp v35, v34 row_ror:8 row_mask:0xf bank_mask:0xf bound_ctrl:1
	s_and_saveexec_b64 s[0:1], s[6:7]
	v_add_f32_e32 v34, v34, v35
	v_add_f32_e32 v34, v119, v34
	ds_write_b32 v99, v34 offset:144
	s_or_b64 exec, exec, s[0:1]
	v_mul_f32_e32 v27, v27, v118
	v_fmac_f32_e32 v27, v26, v116
	v_fmac_f32_e32 v27, v28, v117
	v_fmac_f32_e32 v27, v29, v115
	s_nop 1
	v_add_f32_dpp v26, v27, v27 quad_perm:[1,0,3,2] row_mask:0xf bank_mask:0xf bound_ctrl:1
	s_nop 1
	v_add_f32_dpp v26, v26, v26 quad_perm:[2,3,0,1] row_mask:0xf bank_mask:0xf bound_ctrl:1
	s_nop 1
	v_add_f32_dpp v26, v26, v26 row_ror:4 row_mask:0xf bank_mask:0xf bound_ctrl:1
	s_nop 1
	v_mov_b32_dpp v27, v26 row_ror:8 row_mask:0xf bank_mask:0xf bound_ctrl:1
	s_and_saveexec_b64 s[0:1], s[6:7]
	v_add_f32_e32 v26, v26, v27
	v_add_f32_e32 v26, v119, v26
	ds_write_b32 v99, v26 offset:160
	s_or_b64 exec, exec, s[0:1]
	s_waitcnt vmcnt(11)
; template <int NB>
; __device__ __forceinline__ void sb_decode_task(const Params& P, float* lds, int task) {
;     ...
;     for (int i = 0; i < NB; ++i) cur[i] = *(const float4*)(Kp + (size_t)(4 * i + g) * (SH * HD));
; #pragma unroll
;     for (int kb = 0; kb < NBT; ++kb) {
;         const float* np = (kb + 1 < NBT) ? Kp + (size_t)(4 * NB * (kb + 1)) * (SH * HD) : Vp;
; #pragma unroll
;         for (int i = 0; i < NB; ++i) nx[i] = *(const float4*)(np + (size_t)(4 * i + g) * (SH * HD));
; #pragma unroll
;         for (int i = 0; i < NB; ++i) { const int s = 4 * NB * kb + 4 * i + g;
;             float part = q0 * cur[i].x + q1 * cur[i].y + q2 * cur[i].z + q3 * cur[i].w; part = sum16(part);
;             if (c == 0) zl[s] = part + bias; }
; #pragma unroll
;         for (int i = 0; i < NB; ++i) cur[i] = nx[i];
;     }
	v_mul_f32_e32 v19, v19, v118
	v_fmac_f32_e32 v19, v18, v116
	v_fmac_f32_e32 v19, v20, v117
	v_fmac_f32_e32 v19, v21, v115
	s_nop 1
	v_add_f32_dpp v18, v19, v19 quad_perm:[1,0,3,2] row_mask:0xf bank_mask:0xf bound_ctrl:1
	s_nop 1
	v_add_f32_dpp v18, v18, v18 quad_perm:[2,3,0,1] row_mask:0xf bank_mask:0xf bound_ctrl:1
	s_nop 1
	v_add_f32_dpp v18, v18, v18 row_ror:4 row_mask:0xf bank_mask:0xf bound_ctrl:1
	s_nop 1
	v_mov_b32_dpp v19, v18 row_ror:8 row_mask:0xf bank_mask:0xf bound_ctrl:1
	s_and_saveexec_b64 s[0:1], s[6:7]
	v_add_f32_e32 v18, v18, v19
	v_add_f32_e32 v18, v119, v18
	ds_write_b32 v99, v18 offset:176
	s_or_b64 exec, exec, s[0:1]
	v_mul_f32_e32 v18, v23, v118
	v_fmac_f32_e32 v18, v22, v116
	v_fmac_f32_e32 v18, v24, v117
	v_fmac_f32_e32 v18, v25, v115
	s_nop 1
	v_add_f32_dpp v18, v18, v18 quad_perm:[1,0,3,2] row_mask:0xf bank_mask:0xf bound_ctrl:1
	s_nop 1
	v_add_f32_dpp v18, v18, v18 quad_perm:[2,3,0,1] row_mask:0xf bank_mask:0xf bound_ctrl:1
	s_nop 1
	v_add_f32_dpp v18, v18, v18 row_ror:4 row_mask:0xf bank_mask:0xf bound_ctrl:1
	s_nop 1
	v_mov_b32_dpp v19, v18 row_ror:8 row_mask:0xf bank_mask:0xf bound_ctrl:1
	s_and_saveexec_b64 s[0:1], s[6:7]
	v_add_f32_e32 v18, v18, v19
	v_add_f32_e32 v18, v119, v18
	ds_write_b32 v99, v18 offset:192
	s_or_b64 exec, exec, s[0:1]
	s_waitcnt vmcnt(10)
	v_mul_f32_e32 v18, v39, v118
	v_fmac_f32_e32 v18, v38, v116
	v_fmac_f32_e32 v18, v40, v117
	v_fmac_f32_e32 v18, v41, v115
	s_nop 1
	v_add_f32_dpp v18, v18, v18 quad_perm:[1,0,3,2] row_mask:0xf bank_mask:0xf bound_ctrl:1
	s_nop 1
	v_add_f32_dpp v18, v18, v18 quad_perm:[2,3,0,1] row_mask:0xf bank_mask:0xf bound_ctrl:1
	s_nop 1
	v_add_f32_dpp v18, v18, v18 row_ror:4 row_mask:0xf bank_mask:0xf bound_ctrl:1
	s_nop 1
	v_mov_b32_dpp v19, v18 row_ror:8 row_mask:0xf bank_mask:0xf bound_ctrl:1
	s_and_saveexec_b64 s[0:1], s[6:7]
	v_add_f32_e32 v18, v18, v19
	v_add_f32_e32 v18, v119, v18
	ds_write_b32 v99, v18 offset:208
	s_or_b64 exec, exec, s[0:1]
	s_waitcnt vmcnt(9)
	v_mul_f32_e32 v18, v43, v118
	v_fmac_f32_e32 v18, v42, v116
	v_fmac_f32_e32 v18, v44, v117
	v_fmac_f32_e32 v18, v45, v115
	s_nop 1
	v_add_f32_dpp v18, v18, v18 quad_perm:[1,0,3,2] row_mask:0xf bank_mask:0xf bound_ctrl:1
	s_nop 1
	v_add_f32_dpp v18, v18, v18 quad_perm:[2,3,0,1] row_mask:0xf bank_mask:0xf bound_ctrl:1
	s_nop 1
	v_add_f32_dpp v18, v18, v18 row_ror:4 row_mask:0xf bank_mask:0xf bound_ctrl:1
	s_nop 1
	v_mov_b32_dpp v19, v18 row_ror:8 row_mask:0xf bank_mask:0xf bound_ctrl:1
	s_and_saveexec_b64 s[0:1], s[6:7]
	v_add_f32_e32 v18, v18, v19
	v_add_f32_e32 v18, v119, v18
	ds_write_b32 v99, v18 offset:224
	s_or_b64 exec, exec, s[0:1]
	s_waitcnt vmcnt(8)
	v_mul_f32_e32 v18, v31, v118
	v_fmac_f32_e32 v18, v30, v116
	v_fmac_f32_e32 v18, v32, v117
	v_fmac_f32_e32 v18, v33, v115
	s_nop 1
	v_add_f32_dpp v18, v18, v18 quad_perm:[1,0,3,2] row_mask:0xf bank_mask:0xf bound_ctrl:1
	s_nop 1
	v_add_f32_dpp v18, v18, v18 quad_perm:[2,3,0,1] row_mask:0xf bank_mask:0xf bound_ctrl:1
	s_nop 1
	v_add_f32_dpp v18, v18, v18 row_ror:4 row_mask:0xf bank_mask:0xf bound_ctrl:1
	s_nop 1
	v_mov_b32_dpp v19, v18 row_ror:8 row_mask:0xf bank_mask:0xf bound_ctrl:1
	s_and_saveexec_b64 s[0:1], s[6:7]
	v_add_f32_e32 v18, v18, v19
	v_add_f32_e32 v18, v119, v18
	ds_write_b32 v99, v18 offset:240
	s_or_b64 exec, exec, s[0:1]
	s_mov_b64 s[0:1], 0x24000
	v_lshl_add_u64 v[18:19], v[70:71], 0, s[0:1]
	v_lshl_add_u64 v[20:21], v[18:19], 0, v[82:83]
	v_add_co_u32_e32 v22, vcc, 0x1000, v20
	v_mov_b32_e32 v93, v83
	s_nop 0
	v_addc_co_u32_e32 v23, vcc, 0, v21, vcc
	global_load_dwordx4 v[78:81], v[20:21], off nt
	global_load_dwordx4 v[70:73], v[22:23], off offset:2048 nt
	v_add_co_u32_e32 v22, vcc, 0x3000, v20
	v_lshl_add_u64 v[18:19], v[18:19], 0, v[92:93]
	s_nop 0
	v_addc_co_u32_e32 v23, vcc, 0, v21, vcc
	v_add_co_u32_e32 v24, vcc, s49, v20
	s_nop 1
	v_addc_co_u32_e32 v25, vcc, 0, v21, vcc
	global_load_dwordx4 v[62:65], v[22:23], off nt
	global_load_dwordx4 v[54:57], v[24:25], off offset:2048 nt
	v_add_co_u32_e32 v22, vcc, 0x7000, v20
	s_nop 1
	v_addc_co_u32_e32 v23, vcc, 0, v21, vcc
	global_load_dwordx4 v[46:49], v[18:19], off nt
	global_load_dwordx4 v[42:45], v[22:23], off offset:2048 nt
	v_add_co_u32_e32 v18, vcc, 0x9000, v20
	s_nop 1
	v_addc_co_u32_e32 v19, vcc, 0, v21, vcc
	v_add_co_u32_e32 v20, vcc, 0xa000, v20
	s_nop 1
	v_addc_co_u32_e32 v21, vcc, 0, v21, vcc
	global_load_dwordx4 v[38:41], v[18:19], off nt
	global_load_dwordx4 v[34:37], v[20:21], off offset:2048 nt
	s_waitcnt vmcnt(15)
	v_mul_f32_e32 v18, v75, v118
	v_fmac_f32_e32 v18, v74, v116
	v_fmac_f32_e32 v18, v76, v117
	v_fmac_f32_e32 v18, v77, v115
	s_nop 1
	v_add_f32_dpp v18, v18, v18 quad_perm:[1,0,3,2] row_mask:0xf bank_mask:0xf bound_ctrl:1
	s_nop 1
	v_add_f32_dpp v18, v18, v18 quad_perm:[2,3,0,1] row_mask:0xf bank_mask:0xf bound_ctrl:1
	s_nop 1
	v_add_f32_dpp v18, v18, v18 row_ror:4 row_mask:0xf bank_mask:0xf bound_ctrl:1
	s_nop 1
	v_mov_b32_dpp v19, v18 row_ror:8 row_mask:0xf bank_mask:0xf bound_ctrl:1
	s_and_saveexec_b64 s[0:1], s[6:7]
	v_add_f32_e32 v18, v18, v19
	v_add_f32_e32 v18, v119, v18
	ds_write_b32 v99, v18 offset:256
	s_or_b64 exec, exec, s[0:1]
	s_waitcnt vmcnt(14)
	v_mul_f32_e32 v18, v67, v118
	v_fmac_f32_e32 v18, v66, v116
	v_fmac_f32_e32 v18, v68, v117
	v_fmac_f32_e32 v18, v69, v115
	s_nop 1
	v_add_f32_dpp v18, v18, v18 quad_perm:[1,0,3,2] row_mask:0xf bank_mask:0xf bound_ctrl:1
	s_nop 1
	v_add_f32_dpp v18, v18, v18 quad_perm:[2,3,0,1] row_mask:0xf bank_mask:0xf bound_ctrl:1
	s_nop 1
	v_add_f32_dpp v18, v18, v18 row_ror:4 row_mask:0xf bank_mask:0xf bound_ctrl:1
	s_nop 1
	v_mov_b32_dpp v19, v18 row_ror:8 row_mask:0xf bank_mask:0xf bound_ctrl:1
	s_and_saveexec_b64 s[0:1], s[6:7]
	v_add_f32_e32 v18, v18, v19
	v_add_f32_e32 v18, v119, v18
	ds_write_b32 v99, v18 offset:272
	s_or_b64 exec, exec, s[0:1]
	s_waitcnt vmcnt(13)
; template <int NB>
; __device__ __forceinline__ void sb_decode_task(const Params& P, float* lds, int task) {
;     ...
;     for (int i = 0; i < NB; ++i) cur[i] = *(const float4*)(Kp + (size_t)(4 * i + g) * (SH * HD));
; #pragma unroll
;     for (int kb = 0; kb < NBT; ++kb) {
;         const float* np = (kb + 1 < NBT) ? Kp + (size_t)(4 * NB * (kb + 1)) * (SH * HD) : Vp;
; #pragma unroll
;         for (int i = 0; i < NB; ++i) nx[i] = *(const float4*)(np + (size_t)(4 * i + g) * (SH * HD));
; #pragma unroll
;         for (int i = 0; i < NB; ++i) { const int s = 4 * NB * kb + 4 * i + g;
;             float part = q0 * cur[i].x + q1 * cur[i].y + q2 * cur[i].z + q3 * cur[i].w; part = sum16(part);
;             if (c == 0) zl[s] = part + bias; }
; #pragma unroll
;         for (int i = 0; i < NB; ++i) cur[i] = nx[i];
;     }
	v_mul_f32_e32 v18, v59, v118
	v_fmac_f32_e32 v18, v58, v116
	v_fmac_f32_e32 v18, v60, v117
	v_fmac_f32_e32 v18, v61, v115
	s_nop 1
	v_add_f32_dpp v18, v18, v18 quad_perm:[1,0,3,2] row_mask:0xf bank_mask:0xf bound_ctrl:1
	s_nop 1
	v_add_f32_dpp v18, v18, v18 quad_perm:[2,3,0,1] row_mask:0xf bank_mask:0xf bound_ctrl:1
	s_nop 1
	v_add_f32_dpp v18, v18, v18 row_ror:4 row_mask:0xf bank_mask:0xf bound_ctrl:1
	s_nop 1
	v_mov_b32_dpp v19, v18 row_ror:8 row_mask:0xf bank_mask:0xf bound_ctrl:1
	s_and_saveexec_b64 s[0:1], s[6:7]
	v_add_f32_e32 v18, v18, v19
	v_add_f32_e32 v18, v119, v18
	ds_write_b32 v99, v18 offset:288
	s_or_b64 exec, exec, s[0:1]
	s_waitcnt vmcnt(12)
	v_mul_f32_e32 v18, v51, v118
	v_fmac_f32_e32 v18, v50, v116
	v_fmac_f32_e32 v18, v52, v117
	v_fmac_f32_e32 v18, v53, v115
	s_nop 1
	v_add_f32_dpp v18, v18, v18 quad_perm:[1,0,3,2] row_mask:0xf bank_mask:0xf bound_ctrl:1
	s_nop 1
	v_add_f32_dpp v18, v18, v18 quad_perm:[2,3,0,1] row_mask:0xf bank_mask:0xf bound_ctrl:1
	s_nop 1
	v_add_f32_dpp v18, v18, v18 row_ror:4 row_mask:0xf bank_mask:0xf bound_ctrl:1
	s_nop 1
	v_mov_b32_dpp v19, v18 row_ror:8 row_mask:0xf bank_mask:0xf bound_ctrl:1
	s_and_saveexec_b64 s[0:1], s[6:7]
	v_add_f32_e32 v18, v18, v19
	v_add_f32_e32 v18, v119, v18
	ds_write_b32 v99, v18 offset:304
	s_or_b64 exec, exec, s[0:1]
	s_waitcnt vmcnt(11)
	v_mul_f32_e32 v15, v15, v118
	v_fmac_f32_e32 v15, v14, v116
	v_fmac_f32_e32 v15, v16, v117
	v_fmac_f32_e32 v15, v17, v115
	s_nop 1
	v_add_f32_dpp v14, v15, v15 quad_perm:[1,0,3,2] row_mask:0xf bank_mask:0xf bound_ctrl:1
	s_nop 1
	v_add_f32_dpp v14, v14, v14 quad_perm:[2,3,0,1] row_mask:0xf bank_mask:0xf bound_ctrl:1
	s_nop 1
	v_add_f32_dpp v14, v14, v14 row_ror:4 row_mask:0xf bank_mask:0xf bound_ctrl:1
	s_nop 1
	v_mov_b32_dpp v15, v14 row_ror:8 row_mask:0xf bank_mask:0xf bound_ctrl:1
	s_and_saveexec_b64 s[0:1], s[6:7]
	v_add_f32_e32 v14, v14, v15
	v_add_f32_e32 v14, v119, v14
	ds_write_b32 v99, v14 offset:320
	s_or_b64 exec, exec, s[0:1]
	s_waitcnt vmcnt(10)
	v_mul_f32_e32 v11, v11, v118
	v_fmac_f32_e32 v11, v10, v116
	v_fmac_f32_e32 v11, v12, v117
	v_fmac_f32_e32 v11, v13, v115
	s_nop 1
	v_add_f32_dpp v10, v11, v11 quad_perm:[1,0,3,2] row_mask:0xf bank_mask:0xf bound_ctrl:1
	s_nop 1
	v_add_f32_dpp v10, v10, v10 quad_perm:[2,3,0,1] row_mask:0xf bank_mask:0xf bound_ctrl:1
	s_nop 1
	v_add_f32_dpp v10, v10, v10 row_ror:4 row_mask:0xf bank_mask:0xf bound_ctrl:1
	s_nop 1
	v_mov_b32_dpp v11, v10 row_ror:8 row_mask:0xf bank_mask:0xf bound_ctrl:1
	s_and_saveexec_b64 s[0:1], s[6:7]
	v_add_f32_e32 v10, v10, v11
	v_add_f32_e32 v10, v119, v10
	ds_write_b32 v99, v10 offset:336
	s_or_b64 exec, exec, s[0:1]
	s_waitcnt vmcnt(9)
	v_mul_f32_e32 v7, v7, v118
	v_fmac_f32_e32 v7, v6, v116
	v_fmac_f32_e32 v7, v8, v117
	v_fmac_f32_e32 v7, v9, v115
	s_nop 1
	v_add_f32_dpp v6, v7, v7 quad_perm:[1,0,3,2] row_mask:0xf bank_mask:0xf bound_ctrl:1
	s_nop 1
	v_add_f32_dpp v6, v6, v6 quad_perm:[2,3,0,1] row_mask:0xf bank_mask:0xf bound_ctrl:1
	s_nop 1
	v_add_f32_dpp v6, v6, v6 row_ror:4 row_mask:0xf bank_mask:0xf bound_ctrl:1
	s_nop 1
	v_mov_b32_dpp v7, v6 row_ror:8 row_mask:0xf bank_mask:0xf bound_ctrl:1
	s_and_saveexec_b64 s[0:1], s[6:7]
	v_add_f32_e32 v6, v6, v7
	v_add_f32_e32 v6, v119, v6
	ds_write_b32 v99, v6 offset:352
	s_or_b64 exec, exec, s[0:1]
	s_waitcnt vmcnt(8)
	v_mul_f32_e32 v3, v3, v118
	v_fmac_f32_e32 v3, v2, v116
	v_fmac_f32_e32 v3, v4, v117
	v_fmac_f32_e32 v3, v5, v115
	s_nop 1
	v_add_f32_dpp v2, v3, v3 quad_perm:[1,0,3,2] row_mask:0xf bank_mask:0xf bound_ctrl:1
	s_nop 1
	v_add_f32_dpp v2, v2, v2 quad_perm:[2,3,0,1] row_mask:0xf bank_mask:0xf bound_ctrl:1
	s_nop 1
	v_add_f32_dpp v2, v2, v2 row_ror:4 row_mask:0xf bank_mask:0xf bound_ctrl:1
	s_nop 1
	v_mov_b32_dpp v3, v2 row_ror:8 row_mask:0xf bank_mask:0xf bound_ctrl:1
	s_and_saveexec_b64 s[0:1], s[6:7]
	v_add_f32_e32 v2, v2, v3
	v_add_f32_e32 v2, v119, v2
	ds_write_b32 v99, v2 offset:368
	s_or_b64 exec, exec, s[0:1]
	v_lshlrev_b64 v[2:3], 6, v[94:95]
	v_lshl_add_u64 v[6:7], v[2:3], 2, v[86:87]
	v_lshl_add_u64 v[50:51], v[6:7], 0, v[82:83]
	v_add_co_u32_e32 v2, vcc, 0x1000, v50
	v_mov_b32_e32 v93, v83
	s_nop 0
	v_addc_co_u32_e32 v3, vcc, 0, v51, vcc
	v_add_co_u32_e32 v8, vcc, 0x3000, v50
	v_lshl_add_u64 v[10:11], v[6:7], 0, v[92:93]
	s_nop 0
	v_addc_co_u32_e32 v9, vcc, 0, v51, vcc
	v_add_co_u32_e32 v14, vcc, s49, v50
	global_load_dwordx4 v[30:33], v[50:51], off nt
	s_nop 0
	global_load_dwordx4 v[2:5], v[2:3], off offset:2048 nt
	v_addc_co_u32_e32 v15, vcc, 0, v51, vcc
	v_add_co_u32_e32 v18, vcc, 0x7000, v50
	global_load_dwordx4 v[6:9], v[8:9], off nt
	s_nop 0
	global_load_dwordx4 v[10:13], v[10:11], off nt
	v_addc_co_u32_e32 v19, vcc, 0, v51, vcc
	v_add_co_u32_e32 v22, vcc, 0x9000, v50
	global_load_dwordx4 v[14:17], v[14:15], off offset:2048 nt
	s_nop 0
	global_load_dwordx4 v[18:21], v[18:19], off offset:2048 nt
	v_addc_co_u32_e32 v23, vcc, 0, v51, vcc
	v_add_co_u32_e32 v26, vcc, 0xa000, v50
	s_waitcnt vmcnt(13)
	v_mul_f32_e32 v52, v79, v118
	v_addc_co_u32_e32 v27, vcc, 0, v51, vcc
	global_load_dwordx4 v[22:25], v[22:23], off nt
	s_nop 0
	global_load_dwordx4 v[26:29], v[26:27], off offset:2048 nt
	v_fmac_f32_e32 v52, v78, v116
	v_fmac_f32_e32 v52, v80, v117
	v_fmac_f32_e32 v52, v81, v115
	s_nop 1
	v_add_f32_dpp v52, v52, v52 quad_perm:[1,0,3,2] row_mask:0xf bank_mask:0xf bound_ctrl:1
	s_nop 1
	v_add_f32_dpp v52, v52, v52 quad_perm:[2,3,0,1] row_mask:0xf bank_mask:0xf bound_ctrl:1
	s_nop 1
	v_add_f32_dpp v52, v52, v52 row_ror:4 row_mask:0xf bank_mask:0xf bound_ctrl:1
	s_nop 1
	v_mov_b32_dpp v53, v52 row_ror:8 row_mask:0xf bank_mask:0xf bound_ctrl:1
	s_and_saveexec_b64 s[0:1], s[6:7]
	v_add_f32_e32 v52, v52, v53
	v_add_f32_e32 v52, v119, v52
	ds_write_b32 v99, v52 offset:384
	s_or_b64 exec, exec, s[0:1]
	s_waitcnt vmcnt(14)
; template <int NB>
; __device__ __forceinline__ void sb_decode_task(const Params& P, float* lds, int task) {
;     ...
;         for (int i = 0; i < NB; ++i) { const int s = 4 * NB * kb + 4 * i + g;
;             float part = q0 * cur[i].x + q1 * cur[i].y + q2 * cur[i].z + q3 * cur[i].w; part = sum16(part);
;             if (c == 0) zl[s] = part + bias; }
; #pragma unroll
;         for (int i = 0; i < NB; ++i) cur[i] = nx[i];
;     }
;     asm volatile("s_waitcnt lgkmcnt(0)" ::: "memory");
;     __builtin_amdgcn_wave_barrier();
;     const float z0 = zl[2 * lane], z1 = zl[2 * lane + 1];
	v_mul_f32_e32 v52, v71, v118
	v_fmac_f32_e32 v52, v70, v116
	v_fmac_f32_e32 v52, v72, v117
	v_fmac_f32_e32 v52, v73, v115
	s_nop 1
	v_add_f32_dpp v52, v52, v52 quad_perm:[1,0,3,2] row_mask:0xf bank_mask:0xf bound_ctrl:1
	s_nop 1
	v_add_f32_dpp v52, v52, v52 quad_perm:[2,3,0,1] row_mask:0xf bank_mask:0xf bound_ctrl:1
	s_nop 1
	v_add_f32_dpp v52, v52, v52 row_ror:4 row_mask:0xf bank_mask:0xf bound_ctrl:1
	s_nop 1
	v_mov_b32_dpp v53, v52 row_ror:8 row_mask:0xf bank_mask:0xf bound_ctrl:1
	s_and_saveexec_b64 s[0:1], s[6:7]
	v_add_f32_e32 v52, v52, v53
	v_add_f32_e32 v52, v119, v52
	ds_write_b32 v99, v52 offset:400
	s_or_b64 exec, exec, s[0:1]
	s_waitcnt vmcnt(13)
	v_mul_f32_e32 v52, v63, v118
	v_fmac_f32_e32 v52, v62, v116
	v_fmac_f32_e32 v52, v64, v117
	v_fmac_f32_e32 v52, v65, v115
	s_nop 1
	v_add_f32_dpp v52, v52, v52 quad_perm:[1,0,3,2] row_mask:0xf bank_mask:0xf bound_ctrl:1
	s_nop 1
	v_add_f32_dpp v52, v52, v52 quad_perm:[2,3,0,1] row_mask:0xf bank_mask:0xf bound_ctrl:1
	s_nop 1
	v_add_f32_dpp v52, v52, v52 row_ror:4 row_mask:0xf bank_mask:0xf bound_ctrl:1
	s_nop 1
	v_mov_b32_dpp v53, v52 row_ror:8 row_mask:0xf bank_mask:0xf bound_ctrl:1
	s_and_saveexec_b64 s[0:1], s[6:7]
	v_add_f32_e32 v52, v52, v53
	v_add_f32_e32 v52, v119, v52
	ds_write_b32 v99, v52 offset:416
	s_or_b64 exec, exec, s[0:1]
	s_waitcnt vmcnt(12)
	v_mul_f32_e32 v52, v55, v118
	v_fmac_f32_e32 v52, v54, v116
	v_fmac_f32_e32 v52, v56, v117
	v_fmac_f32_e32 v52, v57, v115
	s_nop 1
	v_add_f32_dpp v52, v52, v52 quad_perm:[1,0,3,2] row_mask:0xf bank_mask:0xf bound_ctrl:1
	s_nop 1
	v_add_f32_dpp v52, v52, v52 quad_perm:[2,3,0,1] row_mask:0xf bank_mask:0xf bound_ctrl:1
	s_nop 1
	v_add_f32_dpp v52, v52, v52 row_ror:4 row_mask:0xf bank_mask:0xf bound_ctrl:1
	s_nop 1
	v_mov_b32_dpp v53, v52 row_ror:8 row_mask:0xf bank_mask:0xf bound_ctrl:1
	s_and_saveexec_b64 s[0:1], s[6:7]
	v_add_f32_e32 v52, v52, v53
	v_add_f32_e32 v52, v119, v52
	ds_write_b32 v99, v52 offset:432
	s_or_b64 exec, exec, s[0:1]
	s_waitcnt vmcnt(11)
	v_mul_f32_e32 v47, v47, v118
	v_fmac_f32_e32 v47, v46, v116
	v_fmac_f32_e32 v47, v48, v117
	v_fmac_f32_e32 v47, v49, v115
	s_nop 1
	v_add_f32_dpp v46, v47, v47 quad_perm:[1,0,3,2] row_mask:0xf bank_mask:0xf bound_ctrl:1
	s_nop 1
	v_add_f32_dpp v46, v46, v46 quad_perm:[2,3,0,1] row_mask:0xf bank_mask:0xf bound_ctrl:1
	s_nop 1
	v_add_f32_dpp v46, v46, v46 row_ror:4 row_mask:0xf bank_mask:0xf bound_ctrl:1
	s_nop 1
	v_mov_b32_dpp v47, v46 row_ror:8 row_mask:0xf bank_mask:0xf bound_ctrl:1
	s_and_saveexec_b64 s[0:1], s[6:7]
	v_add_f32_e32 v46, v46, v47
	v_add_f32_e32 v46, v119, v46
	ds_write_b32 v99, v46 offset:448
	s_or_b64 exec, exec, s[0:1]
	s_waitcnt vmcnt(10)
	v_mul_f32_e32 v43, v43, v118
	v_fmac_f32_e32 v43, v42, v116
	v_fmac_f32_e32 v43, v44, v117
	v_fmac_f32_e32 v43, v45, v115
	s_nop 1
	v_add_f32_dpp v42, v43, v43 quad_perm:[1,0,3,2] row_mask:0xf bank_mask:0xf bound_ctrl:1
	s_nop 1
	v_add_f32_dpp v42, v42, v42 quad_perm:[2,3,0,1] row_mask:0xf bank_mask:0xf bound_ctrl:1
	s_nop 1
	v_add_f32_dpp v42, v42, v42 row_ror:4 row_mask:0xf bank_mask:0xf bound_ctrl:1
	s_nop 1
	v_mov_b32_dpp v43, v42 row_ror:8 row_mask:0xf bank_mask:0xf bound_ctrl:1
	s_and_saveexec_b64 s[0:1], s[6:7]
	v_add_f32_e32 v42, v42, v43
	v_add_f32_e32 v42, v119, v42
	ds_write_b32 v99, v42 offset:464
	s_or_b64 exec, exec, s[0:1]
	s_waitcnt vmcnt(9)
	v_mul_f32_e32 v39, v39, v118
	v_fmac_f32_e32 v39, v38, v116
	v_fmac_f32_e32 v39, v40, v117
	v_fmac_f32_e32 v39, v41, v115
	s_nop 1
	v_add_f32_dpp v38, v39, v39 quad_perm:[1,0,3,2] row_mask:0xf bank_mask:0xf bound_ctrl:1
	s_nop 1
	v_add_f32_dpp v38, v38, v38 quad_perm:[2,3,0,1] row_mask:0xf bank_mask:0xf bound_ctrl:1
	s_nop 1
	v_add_f32_dpp v38, v38, v38 row_ror:4 row_mask:0xf bank_mask:0xf bound_ctrl:1
	s_nop 1
	v_mov_b32_dpp v39, v38 row_ror:8 row_mask:0xf bank_mask:0xf bound_ctrl:1
	s_and_saveexec_b64 s[0:1], s[6:7]
	v_add_f32_e32 v38, v38, v39
	v_add_f32_e32 v38, v119, v38
	ds_write_b32 v99, v38 offset:480
	s_or_b64 exec, exec, s[0:1]
	s_waitcnt vmcnt(8)
	v_mul_f32_e32 v35, v35, v118
	v_fmac_f32_e32 v35, v34, v116
	v_fmac_f32_e32 v35, v36, v117
	v_fmac_f32_e32 v35, v37, v115
	s_nop 1
	v_add_f32_dpp v34, v35, v35 quad_perm:[1,0,3,2] row_mask:0xf bank_mask:0xf bound_ctrl:1
	s_nop 1
	v_add_f32_dpp v34, v34, v34 quad_perm:[2,3,0,1] row_mask:0xf bank_mask:0xf bound_ctrl:1
	s_nop 1
	v_add_f32_dpp v34, v34, v34 row_ror:4 row_mask:0xf bank_mask:0xf bound_ctrl:1
	s_nop 1
	v_mov_b32_dpp v35, v34 row_ror:8 row_mask:0xf bank_mask:0xf bound_ctrl:1
	s_and_saveexec_b64 s[0:1], s[6:7]
	v_add_f32_e32 v34, v34, v35
	v_add_f32_e32 v34, v119, v34
	ds_write_b32 v99, v34 offset:496
	s_or_b64 exec, exec, s[0:1]
	s_waitcnt lgkmcnt(0)
	ds_read_b64 v[34:35], v100
	s_waitcnt lgkmcnt(0)
; __device__ __forceinline__ float softplus2_(float z2) { return fmaxf(z2, 0.f) + log1pf(exp2f(-fabsf(z2))) * LOG2E; }
; template <int NB>
; __device__ __forceinline__ void sb_decode_task(const Params& P, float* lds, int task) {
;     ...
;     const float z0 = zl[2 * lane], z1 = zl[2 * lane + 1];
;     const float sp0 = softplus2_(z0), sp1 = softplus2_(z1);
;     float incl = sp0 + sp1;
	v_cmp_gt_f32_e64 vcc, |v34|, s97
	s_nop 1
	v_cndmask_b32_e32 v37, 0, v103, vcc
	v_sub_f32_e64 v37, v37, |v34|
	v_exp_f32_e32 v37, v37
	v_max_f32_e32 v36, v34, v34
	v_max_f32_e32 v38, 0, v36
	v_cndmask_b32_e32 v36, 0, v102, vcc
	v_ldexp_f32 v39, v37, v36
	v_add_f32_e32 v40, 1.0, v39
	v_add_f32_e32 v36, -1.0, v40
	v_sub_f32_e32 v37, v36, v40
	v_add_f32_e32 v37, 1.0, v37
	v_sub_f32_e32 v36, v39, v36
	v_add_f32_e32 v41, v36, v37
	v_frexp_mant_f32_e32 v36, v40
	v_cmp_gt_f32_e32 vcc, s47, v36
	v_cvt_f64_f32_e32 v[36:37], v40
	v_frexp_exp_i32_f64_e32 v36, v[36:37]
	v_subbrev_co_u32_e32 v36, vcc, 0, v36, vcc
	v_sub_u32_e32 v37, 0, v36
	v_ldexp_f32 v40, v40, v37
	v_ldexp_f32 v37, v41, v37
	v_add_f32_e32 v41, -1.0, v40
	v_add_f32_e32 v42, 1.0, v41
	v_sub_f32_e32 v42, v40, v42
	v_add_f32_e32 v42, v37, v42
	v_add_f32_e32 v43, v41, v42
	v_sub_f32_e32 v41, v41, v43
	v_add_f32_e32 v41, v42, v41
	v_add_f32_e32 v42, 1.0, v40
	v_add_f32_e32 v44, -1.0, v42
	v_sub_f32_e32 v40, v40, v44
	v_add_f32_e32 v37, v37, v40
	v_add_f32_e32 v40, v42, v37
	v_sub_f32_e32 v42, v42, v40
	v_add_f32_e32 v37, v37, v42
	v_rcp_f32_e32 v42, v40
	v_cvt_f32_i32_e32 v36, v36
	v_cmp_neq_f32_e32 vcc, s46, v39
	v_mul_f32_e32 v44, v43, v42
	v_mul_f32_e32 v45, v40, v44
	v_fma_f32 v46, v44, v40, -v45
	v_fmac_f32_e32 v46, v44, v37
	v_add_f32_e32 v47, v45, v46
	v_sub_f32_e32 v48, v43, v47
	v_sub_f32_e32 v43, v43, v48
	v_sub_f32_e32 v45, v47, v45
	v_sub_f32_e32 v43, v43, v47
	v_add_f32_e32 v41, v41, v43
	v_sub_f32_e32 v43, v45, v46
	v_add_f32_e32 v41, v43, v41
	v_add_f32_e32 v43, v48, v41
	v_mul_f32_e32 v45, v42, v43
	v_mul_f32_e32 v46, v40, v45
	v_fma_f32 v40, v45, v40, -v46
	v_fmac_f32_e32 v40, v45, v37
	v_sub_f32_e32 v37, v48, v43
	v_add_f32_e32 v37, v41, v37
	v_add_f32_e32 v41, v46, v40
	v_sub_f32_e32 v47, v43, v41
	v_sub_f32_e32 v43, v43, v47
	v_sub_f32_e32 v46, v41, v46
	v_sub_f32_e32 v41, v43, v41
	v_add_f32_e32 v37, v37, v41
	v_sub_f32_e32 v40, v46, v40
	v_add_f32_e32 v37, v40, v37
	v_add_f32_e32 v40, v44, v45
	v_add_f32_e32 v37, v47, v37
	v_sub_f32_e32 v41, v40, v44
	v_mul_f32_e32 v37, v42, v37
	v_sub_f32_e32 v41, v45, v41
	v_add_f32_e32 v37, v41, v37
	v_mul_f32_e32 v44, 0x3f317218, v36
	v_add_f32_e32 v41, v40, v37
	v_fma_f32 v45, v36, s95, -v44
	v_mul_f32_e32 v42, v41, v41
	v_fmac_f32_e32 v45, 0xb102e308, v36
	v_sub_f32_e32 v36, v41, v40
	v_fmamk_f32 v43, v42, 0x3e9b6dac, v1
	v_sub_f32_e32 v36, v37, v36
	v_add_f32_e32 v37, v44, v45
	v_fmaak_f32 v43, v42, v43, 0x3f2aaada
	v_sub_f32_e32 v40, v37, v44
	v_ldexp_f32 v44, v41, 1
	v_mul_f32_e32 v41, v41, v42
	v_mul_f32_e32 v41, v41, v43
	v_add_f32_e32 v42, v44, v41
	v_sub_f32_e32 v43, v42, v44
	v_ldexp_f32 v36, v36, 1
	v_sub_f32_e32 v41, v41, v43
	v_add_f32_e32 v36, v36, v41
	v_add_f32_e32 v41, v42, v36
	v_sub_f32_e32 v42, v41, v42
	v_sub_f32_e32 v36, v36, v42
	v_add_f32_e32 v42, v37, v41
	v_sub_f32_e32 v43, v42, v37
	v_sub_f32_e32 v44, v42, v43
	v_sub_f32_e32 v40, v45, v40
	v_sub_f32_e32 v37, v37, v44
	v_sub_f32_e32 v41, v41, v43
	v_add_f32_e32 v37, v41, v37
	v_add_f32_e32 v41, v40, v36
	v_sub_f32_e32 v43, v41, v40
	v_sub_f32_e32 v44, v41, v43
	v_sub_f32_e32 v40, v40, v44
	v_sub_f32_e32 v36, v36, v43
	v_add_f32_e32 v37, v41, v37
	v_add_f32_e32 v36, v36, v40
	v_add_f32_e32 v40, v42, v37
	v_sub_f32_e32 v41, v40, v42
	v_sub_f32_e32 v37, v37, v41
	v_add_f32_e32 v36, v36, v37
	v_add_f32_e32 v36, v40, v36
	v_cndmask_b32_e32 v36, v104, v36, vcc
	v_cmp_lt_f32_e64 vcc, |v39|, s45
	s_nop 1
	v_cndmask_b32_e32 v36, v36, v39, vcc
	v_cmp_gt_f32_e64 vcc, |v35|, s97
	v_fmac_f32_e32 v38, 0x3fb8aa3b, v36
	v_max_f32_e32 v36, v35, v35
	v_cndmask_b32_e32 v37, 0, v103, vcc
	v_sub_f32_e64 v37, v37, |v35|
	v_exp_f32_e32 v37, v37
	v_max_f32_e32 v39, 0, v36
	v_cndmask_b32_e32 v36, 0, v102, vcc
	v_sub_f32_e32 v34, v34, v38
	v_ldexp_f32 v40, v37, v36
	v_add_f32_e32 v41, 1.0, v40
	v_add_f32_e32 v36, -1.0, v41
	v_sub_f32_e32 v37, v36, v41
	v_add_f32_e32 v37, 1.0, v37
	v_sub_f32_e32 v36, v40, v36
	v_add_f32_e32 v42, v36, v37
	v_frexp_mant_f32_e32 v36, v41
	v_cmp_gt_f32_e32 vcc, s47, v36
	v_cvt_f64_f32_e32 v[36:37], v41
	v_frexp_exp_i32_f64_e32 v36, v[36:37]
	v_subbrev_co_u32_e32 v36, vcc, 0, v36, vcc
	v_sub_u32_e32 v37, 0, v36
	v_ldexp_f32 v41, v41, v37
	v_ldexp_f32 v37, v42, v37
	v_add_f32_e32 v42, -1.0, v41
	v_add_f32_e32 v43, 1.0, v42
	v_sub_f32_e32 v43, v41, v43
	v_add_f32_e32 v43, v37, v43
	v_add_f32_e32 v44, v42, v43
	v_sub_f32_e32 v42, v42, v44
	v_add_f32_e32 v42, v43, v42
	v_add_f32_e32 v43, 1.0, v41
	v_add_f32_e32 v45, -1.0, v43
	v_sub_f32_e32 v41, v41, v45
	v_add_f32_e32 v37, v37, v41
	v_add_f32_e32 v41, v43, v37
	v_sub_f32_e32 v43, v43, v41
	v_add_f32_e32 v37, v37, v43
	v_rcp_f32_e32 v43, v41
	v_cvt_f32_i32_e32 v36, v36
	v_cmp_neq_f32_e32 vcc, s46, v40
	v_mul_f32_e32 v45, v44, v43
	v_mul_f32_e32 v46, v41, v45
	v_fma_f32 v47, v45, v41, -v46
	v_fmac_f32_e32 v47, v45, v37
	v_add_f32_e32 v48, v46, v47
	v_sub_f32_e32 v49, v44, v48
	v_sub_f32_e32 v44, v44, v49
	v_sub_f32_e32 v46, v48, v46
	v_sub_f32_e32 v44, v44, v48
	v_add_f32_e32 v42, v42, v44
	v_sub_f32_e32 v44, v46, v47
	v_add_f32_e32 v42, v44, v42
	v_add_f32_e32 v44, v49, v42
	v_mul_f32_e32 v46, v43, v44
	v_mul_f32_e32 v47, v41, v46
	v_fma_f32 v41, v46, v41, -v47
	v_fmac_f32_e32 v41, v46, v37
	v_sub_f32_e32 v37, v49, v44
	v_add_f32_e32 v37, v42, v37
	v_add_f32_e32 v42, v47, v41
	v_sub_f32_e32 v48, v44, v42
	v_sub_f32_e32 v44, v44, v48
	v_sub_f32_e32 v47, v42, v47
	v_sub_f32_e32 v42, v44, v42
	v_add_f32_e32 v37, v37, v42
	v_sub_f32_e32 v41, v47, v41
	v_add_f32_e32 v37, v41, v37
	v_add_f32_e32 v41, v45, v46
	v_add_f32_e32 v37, v48, v37
	v_sub_f32_e32 v42, v41, v45
	v_mul_f32_e32 v37, v43, v37
; __device__ __forceinline__ float softplus2_(float z2) { return fmaxf(z2, 0.f) + log1pf(exp2f(-fabsf(z2))) * LOG2E; }
; template <int NB>
; __device__ __forceinline__ void sb_decode_task(const Params& P, float* lds, int task) {
;     ...
;     const float sp0 = softplus2_(z0), sp1 = softplus2_(z1);
;     float incl = sp0 + sp1;
; #pragma unroll
;     for (int off = 1; off < 64; off <<= 1) { const float t = __shfl_down(incl, off); if (lane + off < 64) incl += t; }
;     const float excl = incl - (sp0 + sp1);
;     wl[2 * lane] = exp2f(z0 - sp0 - (excl + sp1));
;     wl[2 * lane + 1] = exp2f(z1 - sp1 - excl);
;     const float Ltot = __shfl(incl, 0);
;     asm volatile("s_waitcnt lgkmcnt(0)" ::: "memory");
;     __builtin_amdgcn_wave_barrier();
;     float4 o4 = make_float4(0.f, 0.f, 0.f, 0.f);
; #pragma unroll
;     for (int vb = 0; vb < NBT; ++vb) {
;         if (vb + 1 < NBT) {
; #pragma unroll
;             for (int i = 0; i < NB; ++i) nx[i] = *(const float4*)(Vp + (size_t)(4 * NB * (vb + 1) + 4 * i + g) * (SH * HD)); }
; #pragma unroll
;         for (int i = 0; i < NB; ++i) { const float w = wl[4 * NB * vb + 4 * i + g]; o4.x += w * cur[i].x; o4.y += w * cur[i].y; o4.z += w * cur[i].z; o4.w += w * cur[i].w; }
	v_sub_f32_e32 v42, v46, v42
	v_add_f32_e32 v37, v42, v37
	v_mul_f32_e32 v45, 0x3f317218, v36
	v_add_f32_e32 v42, v41, v37
	v_fma_f32 v46, v36, s95, -v45
	v_mul_f32_e32 v43, v42, v42
	v_fmac_f32_e32 v46, 0xb102e308, v36
	v_sub_f32_e32 v36, v42, v41
	v_fmamk_f32 v44, v43, 0x3e9b6dac, v1
	v_sub_f32_e32 v36, v37, v36
	v_add_f32_e32 v37, v45, v46
	v_fmaak_f32 v44, v43, v44, 0x3f2aaada
	v_sub_f32_e32 v41, v37, v45
	v_ldexp_f32 v45, v42, 1
	v_mul_f32_e32 v42, v42, v43
	v_mul_f32_e32 v42, v42, v44
	v_add_f32_e32 v43, v45, v42
	v_sub_f32_e32 v44, v43, v45
	v_ldexp_f32 v36, v36, 1
	v_sub_f32_e32 v42, v42, v44
	v_add_f32_e32 v36, v36, v42
	v_add_f32_e32 v42, v43, v36
	v_sub_f32_e32 v43, v42, v43
	v_sub_f32_e32 v36, v36, v43
	v_add_f32_e32 v43, v37, v42
	v_sub_f32_e32 v44, v43, v37
	v_sub_f32_e32 v45, v43, v44
	v_sub_f32_e32 v41, v46, v41
	v_sub_f32_e32 v37, v37, v45
	v_sub_f32_e32 v42, v42, v44
	v_add_f32_e32 v37, v42, v37
	v_add_f32_e32 v42, v41, v36
	v_sub_f32_e32 v44, v42, v41
	v_sub_f32_e32 v45, v42, v44
	v_sub_f32_e32 v41, v41, v45
	v_sub_f32_e32 v36, v36, v44
	v_add_f32_e32 v37, v42, v37
	v_add_f32_e32 v36, v36, v41
	v_add_f32_e32 v41, v43, v37
	v_sub_f32_e32 v42, v41, v43
	v_sub_f32_e32 v37, v37, v42
	v_add_f32_e32 v36, v36, v37
	v_add_f32_e32 v36, v41, v36
	v_cndmask_b32_e32 v36, v104, v36, vcc
	v_cmp_lt_f32_e64 vcc, |v40|, s45
	s_nop 1
	v_cndmask_b32_e32 v36, v36, v40, vcc
	v_fmac_f32_e32 v39, 0x3fb8aa3b, v36
	v_add_f32_e32 v36, v38, v39
	ds_bpermute_b32 v37, v108, v36
	v_sub_f32_e32 v35, v35, v39
	s_waitcnt lgkmcnt(0)
	v_add_f32_e32 v37, v36, v37
	v_cndmask_b32_e64 v37, v37, v36, s[8:9]
	ds_bpermute_b32 v40, v109, v37
	s_waitcnt lgkmcnt(0)
	v_add_f32_e32 v40, v37, v40
	v_cndmask_b32_e64 v37, v37, v40, s[10:11]
	ds_bpermute_b32 v40, v110, v37
	s_waitcnt lgkmcnt(0)
	v_add_f32_e32 v40, v37, v40
	v_cndmask_b32_e64 v37, v37, v40, s[12:13]
	ds_bpermute_b32 v40, v111, v37
	s_waitcnt lgkmcnt(0)
	v_add_f32_e32 v40, v37, v40
	v_cndmask_b32_e64 v37, v37, v40, s[14:15]
	ds_bpermute_b32 v40, v112, v37
	s_waitcnt lgkmcnt(0)
	v_add_f32_e32 v40, v37, v40
	v_cndmask_b32_e64 v37, v37, v40, s[16:17]
	ds_bpermute_b32 v40, v113, v37
	s_waitcnt lgkmcnt(0)
	v_add_f32_e32 v40, v37, v40
	v_cndmask_b32_e64 v44, v37, v40, s[18:19]
	v_sub_f32_e32 v36, v44, v36
	v_add_f32_e32 v37, v39, v36
	v_sub_f32_e32 v34, v34, v37
	v_cmp_gt_f32_e32 vcc, s24, v34
	v_sub_f32_e32 v35, v35, v36
	s_nop 0
	v_cndmask_b32_e32 v37, 0, v103, vcc
	v_add_f32_e32 v34, v34, v37
	v_cndmask_b32_e32 v37, 0, v102, vcc
	v_cmp_gt_f32_e32 vcc, s24, v35
	v_exp_f32_e32 v34, v34
	s_nop 0
	v_cndmask_b32_e32 v36, 0, v103, vcc
	v_add_f32_e32 v35, v35, v36
	v_exp_f32_e32 v35, v35
	v_cndmask_b32_e32 v36, 0, v102, vcc
	v_ldexp_f32 v34, v34, v37
	v_ldexp_f32 v35, v35, v36
	ds_write_b64 v100, v[34:35] offset:512
	s_waitcnt lgkmcnt(0)
	ds_read2_b32 v[34:35], v99 offset0:128 offset1:132
	ds_read2_b32 v[42:43], v99 offset0:136 offset1:140
	ds_read2_b32 v[66:67], v99 offset0:144 offset1:148
	ds_read2_b32 v[68:69], v99 offset0:152 offset1:156
	ds_read2_b32 v[74:75], v99 offset0:160 offset1:164
	ds_read2_b32 v[76:77], v99 offset0:168 offset1:172
	ds_read2_b32 v[38:39], v99 offset0:176 offset1:180
	ds_read2_b32 v[40:41], v99 offset0:184 offset1:188
	s_waitcnt vmcnt(7) lgkmcnt(7)
	v_pk_fma_f32 v[70:71], v[30:31], v[34:35], 0 op_sel_hi:[1,0,0]
	v_add_co_u32_e32 v30, vcc, s25, v50
	v_pk_fma_f32 v[72:73], v[32:33], v[34:35], 0 op_sel_hi:[1,0,0]
	s_nop 0
	v_addc_co_u32_e32 v31, vcc, 0, v51, vcc
	v_add_co_u32_e32 v34, vcc, s43, v50
	v_mov_b32_e32 v64, v35
	s_nop 0
	v_addc_co_u32_e32 v35, vcc, 0, v51, vcc
	v_add_co_u32_e32 v46, vcc, s44, v50
	s_waitcnt vmcnt(6)
	v_pk_fma_f32 v[2:3], v[2:3], v[64:65], v[70:71] op_sel_hi:[1,0,1]
	v_addc_co_u32_e32 v47, vcc, 0, v51, vcc
	v_add_co_u32_e32 v52, vcc, s26, v50
	global_load_dwordx4 v[46:49], v[46:47], off nt
	s_nop 0
	v_addc_co_u32_e32 v53, vcc, 0, v51, vcc
	v_add_co_u32_e32 v56, vcc, s27, v50
	global_load_dwordx4 v[52:55], v[52:53], off offset:2048 nt
	s_nop 0
	v_addc_co_u32_e32 v57, vcc, 0, v51, vcc
	v_add_co_u32_e32 v60, vcc, s28, v50
	global_load_dwordx4 v[56:59], v[56:57], off nt
	s_nop 0
	v_addc_co_u32_e32 v61, vcc, 0, v51, vcc
	global_load_dwordx4 v[60:63], v[60:61], off offset:2048 nt
	s_waitcnt lgkmcnt(6)
	v_mov_b32_e32 v78, v43
	s_waitcnt vmcnt(9)
	v_pk_fma_f32 v[2:3], v[6:7], v[42:43], v[2:3] op_sel_hi:[1,0,1]
	s_waitcnt lgkmcnt(5)
	v_mov_b32_e32 v80, v67
	s_waitcnt vmcnt(7)
	v_pk_fma_f32 v[2:3], v[14:15], v[78:79], v[2:3] op_sel_hi:[1,0,1]
	s_waitcnt lgkmcnt(4)
	v_mov_b32_e32 v94, v69
	v_pk_fma_f32 v[2:3], v[10:11], v[66:67], v[2:3] op_sel_hi:[1,0,1]
	s_waitcnt lgkmcnt(3)
	v_mov_b32_e32 v10, v75
	s_waitcnt vmcnt(6)
	v_pk_fma_f32 v[2:3], v[18:19], v[80:81], v[2:3] op_sel_hi:[1,0,1]
	s_waitcnt lgkmcnt(2)
	v_mov_b32_e32 v14, v77
	s_waitcnt vmcnt(5)
	v_pk_fma_f32 v[2:3], v[22:23], v[68:69], v[2:3] op_sel_hi:[1,0,1]
	global_load_dwordx4 v[30:33], v[30:31], off nt
	s_waitcnt vmcnt(5)
	v_pk_fma_f32 v[2:3], v[26:27], v[94:95], v[2:3] op_sel_hi:[1,0,1]
	global_load_dwordx4 v[34:37], v[34:35], off offset:2048 nt
	s_waitcnt vmcnt(5)
	v_pk_fma_f32 v[2:3], v[46:47], v[74:75], v[2:3] op_sel_hi:[1,0,1]
	s_waitcnt vmcnt(4)
	v_pk_fma_f32 v[2:3], v[52:53], v[10:11], v[2:3] op_sel_hi:[1,0,1]
	s_waitcnt vmcnt(3)
	v_pk_fma_f32 v[2:3], v[56:57], v[76:77], v[2:3] op_sel_hi:[1,0,1]
	s_waitcnt vmcnt(2)
	v_pk_fma_f32 v[6:7], v[60:61], v[14:15], v[2:3] op_sel_hi:[1,0,1]
	v_pk_fma_f32 v[2:3], v[4:5], v[64:65], v[72:73] op_sel_hi:[1,0,1]
	v_add_co_u32_e32 v4, vcc, s29, v50
	v_pk_fma_f32 v[2:3], v[8:9], v[42:43], v[2:3] op_sel_hi:[1,0,1]
	s_nop 0
	v_addc_co_u32_e32 v5, vcc, 0, v51, vcc
	v_pk_fma_f32 v[2:3], v[16:17], v[78:79], v[2:3] op_sel_hi:[1,0,1]
	s_waitcnt lgkmcnt(0)
; template <int NB>
; __device__ __forceinline__ void sb_decode_task(const Params& P, float* lds, int task) {
;     ...
; #pragma unroll
;     for (int vb = 0; vb < NBT; ++vb) {
;         if (vb + 1 < NBT) {
; #pragma unroll
;             for (int i = 0; i < NB; ++i) nx[i] = *(const float4*)(Vp + (size_t)(4 * NB * (vb + 1) + 4 * i + g) * (SH * HD)); }
; #pragma unroll
;         for (int i = 0; i < NB; ++i) { const float w = wl[4 * NB * vb + 4 * i + g]; o4.x += w * cur[i].x; o4.y += w * cur[i].y; o4.z += w * cur[i].z; o4.w += w * cur[i].w; }
; #pragma unroll
;         for (int i = 0; i < NB; ++i) cur[i] = nx[i];
;     }
	v_mov_b32_e32 v42, v41
	v_pk_fma_f32 v[2:3], v[12:13], v[66:67], v[2:3] op_sel_hi:[1,0,1]
	s_waitcnt vmcnt(1)
	v_pk_fma_f32 v[6:7], v[30:31], v[38:39], v[6:7] op_sel_hi:[1,0,1]
	v_pk_fma_f32 v[2:3], v[20:21], v[80:81], v[2:3] op_sel_hi:[1,0,1]
	s_nop 0
	v_pk_fma_f32 v[2:3], v[24:25], v[68:69], v[2:3] op_sel_hi:[1,0,1]
	s_nop 0
	v_pk_fma_f32 v[2:3], v[28:29], v[94:95], v[2:3] op_sel_hi:[1,0,1]
	v_mov_b32_e32 v28, v39
	v_pk_fma_f32 v[2:3], v[48:49], v[74:75], v[2:3] op_sel_hi:[1,0,1]
	s_waitcnt vmcnt(0)
	v_pk_fma_f32 v[6:7], v[34:35], v[28:29], v[6:7] op_sel_hi:[1,0,1]
	v_pk_fma_f32 v[2:3], v[54:55], v[10:11], v[2:3] op_sel_hi:[1,0,1]
	s_nop 0
	v_pk_fma_f32 v[2:3], v[58:59], v[76:77], v[2:3] op_sel_hi:[1,0,1]
	s_nop 0
	v_pk_fma_f32 v[2:3], v[62:63], v[14:15], v[2:3] op_sel_hi:[1,0,1]
	ds_read2_b32 v[14:15], v99 offset0:192 offset1:196
	ds_read2_b32 v[12:13], v99 offset0:200 offset1:204
	ds_read2_b32 v[10:11], v99 offset0:208 offset1:212
	ds_read2_b32 v[8:9], v99 offset0:216 offset1:220
	global_load_dwordx4 v[16:19], v[4:5], off nt
	v_add_co_u32_e32 v4, vcc, s68, v50
	v_pk_fma_f32 v[2:3], v[32:33], v[38:39], v[2:3] op_sel_hi:[1,0,1]
	s_nop 0
	v_addc_co_u32_e32 v5, vcc, 0, v51, vcc
	global_load_dwordx4 v[20:23], v[4:5], off offset:2048 nt
	v_add_co_u32_e32 v4, vcc, s69, v50
	v_pk_fma_f32 v[2:3], v[36:37], v[28:29], v[2:3] op_sel_hi:[1,0,1]
	s_nop 0
	v_addc_co_u32_e32 v5, vcc, 0, v51, vcc
	global_load_dwordx4 v[24:27], v[4:5], off nt
	v_add_co_u32_e32 v4, vcc, s70, v50
	s_waitcnt lgkmcnt(0)
	v_mov_b32_e32 v36, v9
	v_addc_co_u32_e32 v5, vcc, 0, v51, vcc
	global_load_dwordx4 v[46:49], v[4:5], off offset:2048 nt
	v_add_co_u32_e32 v4, vcc, s71, v50
	ds_read2_b32 v[30:31], v99 offset0:224 offset1:228
	s_nop 0
	v_addc_co_u32_e32 v5, vcc, 0, v51, vcc
	global_load_dwordx4 v[52:55], v[4:5], off nt
	v_add_co_u32_e32 v4, vcc, s72, v50
	s_waitcnt vmcnt(4)
	v_pk_fma_f32 v[2:3], v[18:19], v[40:41], v[2:3] op_sel_hi:[1,0,1]
	v_addc_co_u32_e32 v5, vcc, 0, v51, vcc
	global_load_dwordx4 v[56:59], v[4:5], off offset:2048 nt
	v_add_co_u32_e32 v4, vcc, s73, v50
	s_waitcnt vmcnt(4)
	v_pk_fma_f32 v[2:3], v[22:23], v[42:43], v[2:3] op_sel_hi:[1,0,1]
	v_addc_co_u32_e32 v5, vcc, 0, v51, vcc
	global_load_dwordx4 v[60:63], v[4:5], off nt
	v_add_co_u32_e32 v4, vcc, s74, v50
	s_waitcnt vmcnt(4)
	v_pk_fma_f32 v[2:3], v[26:27], v[14:15], v[2:3] op_sel_hi:[1,0,1]
	v_addc_co_u32_e32 v5, vcc, 0, v51, vcc
	global_load_dwordx4 v[64:67], v[4:5], off offset:2048 nt
	v_add_co_u32_e32 v4, vcc, s75, v50
	v_mov_b32_e32 v18, v15
	s_nop 0
	v_addc_co_u32_e32 v5, vcc, 0, v51, vcc
	global_load_dwordx4 v[68:71], v[4:5], off nt
	v_pk_fma_f32 v[6:7], v[16:17], v[40:41], v[6:7] op_sel_hi:[1,0,1]
	s_waitcnt vmcnt(5)
	v_pk_fma_f32 v[2:3], v[48:49], v[18:19], v[2:3] op_sel_hi:[1,0,1]
	v_pk_fma_f32 v[6:7], v[20:21], v[42:43], v[6:7] op_sel_hi:[1,0,1]
	s_waitcnt vmcnt(4)
	v_pk_fma_f32 v[2:3], v[54:55], v[12:13], v[2:3] op_sel_hi:[1,0,1]
	v_mov_b32_e32 v22, v13
	v_pk_fma_f32 v[6:7], v[24:25], v[14:15], v[6:7] op_sel_hi:[1,0,1]
	v_mov_b32_e32 v26, v11
	v_pk_fma_f32 v[6:7], v[46:47], v[18:19], v[6:7] op_sel_hi:[1,0,1]
	s_waitcnt vmcnt(3)
	v_pk_fma_f32 v[2:3], v[58:59], v[22:23], v[2:3] op_sel_hi:[1,0,1]
	v_pk_fma_f32 v[6:7], v[52:53], v[12:13], v[6:7] op_sel_hi:[1,0,1]
	s_waitcnt vmcnt(2)
	v_pk_fma_f32 v[2:3], v[62:63], v[10:11], v[2:3] op_sel_hi:[1,0,1]
	v_pk_fma_f32 v[6:7], v[56:57], v[22:23], v[6:7] op_sel_hi:[1,0,1]
	s_waitcnt vmcnt(1)
	v_pk_fma_f32 v[2:3], v[66:67], v[26:27], v[2:3] op_sel_hi:[1,0,1]
	v_pk_fma_f32 v[6:7], v[60:61], v[10:11], v[6:7] op_sel_hi:[1,0,1]
	s_waitcnt vmcnt(0)
; template <int NB>
; __device__ __forceinline__ void sb_decode_task(const Params& P, float* lds, int task) {
;     ...
;     for (int vb = 0; vb < NBT; ++vb) {
;         if (vb + 1 < NBT) {
; #pragma unroll
;             for (int i = 0; i < NB; ++i) nx[i] = *(const float4*)(Vp + (size_t)(4 * NB * (vb + 1) + 4 * i + g) * (SH * HD)); }
; #pragma unroll
;         for (int i = 0; i < NB; ++i) { const float w = wl[4 * NB * vb + 4 * i + g]; o4.x += w * cur[i].x; o4.y += w * cur[i].y; o4.z += w * cur[i].z; o4.w += w * cur[i].w; }
; #pragma unroll
;         for (int i = 0; i < NB; ++i) cur[i] = nx[i];
;     }
; #pragma unroll
;     for (int off = 16; off < 64; off <<= 1) { o4.x += __shfl_xor(o4.x, off); o4.y += __shfl_xor(o4.y, off); o4.z += __shfl_xor(o4.z, off); o4.w += __shfl_xor(o4.w, off); }
;     if (g == 0) *(float4*)(dpart + (size_t)task * HD + 4 * c) = o4;
	v_pk_fma_f32 v[32:33], v[70:71], v[8:9], v[2:3] op_sel_hi:[1,0,1]
	v_add_co_u32_e32 v2, vcc, s80, v50
	v_pk_fma_f32 v[6:7], v[64:65], v[26:27], v[6:7] op_sel_hi:[1,0,1]
	s_nop 0
	v_addc_co_u32_e32 v3, vcc, 0, v51, vcc
	v_pk_fma_f32 v[34:35], v[68:69], v[8:9], v[6:7] op_sel_hi:[1,0,1]
	v_add_co_u32_e32 v6, vcc, s81, v50
	global_load_dwordx4 v[2:5], v[2:3], off offset:2048 nt
	s_nop 0
	v_addc_co_u32_e32 v7, vcc, 0, v51, vcc
	v_add_co_u32_e32 v10, vcc, s82, v50
	global_load_dwordx4 v[6:9], v[6:7], off nt
	s_nop 0
	v_addc_co_u32_e32 v11, vcc, 0, v51, vcc
	v_add_co_u32_e32 v14, vcc, s83, v50
	ds_read2_b32 v[42:43], v99 offset0:232 offset1:236
	ds_read2_b32 v[40:41], v99 offset0:240 offset1:244
	ds_read2_b32 v[38:39], v99 offset0:248 offset1:252
	v_addc_co_u32_e32 v15, vcc, 0, v51, vcc
	v_add_co_u32_e32 v18, vcc, s84, v50
	global_load_dwordx4 v[10:13], v[10:11], off offset:2048 nt
	s_nop 0
	v_addc_co_u32_e32 v19, vcc, 0, v51, vcc
	v_add_co_u32_e32 v22, vcc, s85, v50
	global_load_dwordx4 v[14:17], v[14:15], off nt
	s_nop 0
	v_addc_co_u32_e32 v23, vcc, 0, v51, vcc
	v_add_co_u32_e32 v26, vcc, s86, v50
	global_load_dwordx4 v[18:21], v[18:19], off offset:2048 nt
	s_nop 0
	v_addc_co_u32_e32 v27, vcc, 0, v51, vcc
	v_add_co_u32_e32 v46, vcc, s87, v50
	global_load_dwordx4 v[22:25], v[22:23], off nt
	s_nop 0
	v_addc_co_u32_e32 v47, vcc, 0, v51, vcc
	global_load_dwordx4 v[26:29], v[26:27], off offset:2048 nt
	v_add_co_u32_e32 v50, vcc, s88, v50
	global_load_dwordx4 v[46:49], v[46:47], off nt
	s_nop 0
	v_addc_co_u32_e32 v51, vcc, 0, v51, vcc
	global_load_dwordx4 v[50:53], v[50:51], off offset:2048 nt
	s_waitcnt lgkmcnt(2)
	v_mov_b32_e32 v54, v43
	s_waitcnt lgkmcnt(1)
	v_mov_b32_e32 v56, v41
	s_waitcnt lgkmcnt(0)
	v_mov_b32_e32 v58, v39
	s_waitcnt vmcnt(8)
	v_pk_fma_f32 v[2:3], v[2:3], v[36:37], v[34:35] op_sel_hi:[1,0,1]
	v_mov_b32_e32 v34, v31
	v_pk_fma_f32 v[4:5], v[4:5], v[36:37], v[32:33] op_sel_hi:[1,0,1]
	s_waitcnt vmcnt(7)
	v_pk_fma_f32 v[2:3], v[6:7], v[30:31], v[2:3] op_sel_hi:[1,0,1]
	v_pk_fma_f32 v[4:5], v[8:9], v[30:31], v[4:5] op_sel_hi:[1,0,1]
	s_waitcnt vmcnt(6)
	v_pk_fma_f32 v[2:3], v[10:11], v[34:35], v[2:3] op_sel_hi:[1,0,1]
	v_pk_fma_f32 v[4:5], v[12:13], v[34:35], v[4:5] op_sel_hi:[1,0,1]
	ds_bpermute_b32 v10, v106, v44
	s_waitcnt vmcnt(5)
	v_pk_fma_f32 v[2:3], v[14:15], v[42:43], v[2:3] op_sel_hi:[1,0,1]
	v_pk_fma_f32 v[4:5], v[16:17], v[42:43], v[4:5] op_sel_hi:[1,0,1]
	s_waitcnt vmcnt(4)
	v_pk_fma_f32 v[2:3], v[18:19], v[54:55], v[2:3] op_sel_hi:[1,0,1]
	v_pk_fma_f32 v[4:5], v[20:21], v[54:55], v[4:5] op_sel_hi:[1,0,1]
	s_waitcnt vmcnt(3)
	v_pk_fma_f32 v[2:3], v[22:23], v[40:41], v[2:3] op_sel_hi:[1,0,1]
	v_pk_fma_f32 v[4:5], v[24:25], v[40:41], v[4:5] op_sel_hi:[1,0,1]
	s_waitcnt vmcnt(2)
	v_pk_fma_f32 v[2:3], v[26:27], v[56:57], v[2:3] op_sel_hi:[1,0,1]
	v_pk_fma_f32 v[4:5], v[28:29], v[56:57], v[4:5] op_sel_hi:[1,0,1]
	s_waitcnt vmcnt(1)
	v_pk_fma_f32 v[2:3], v[46:47], v[38:39], v[2:3] op_sel_hi:[1,0,1]
	v_pk_fma_f32 v[4:5], v[48:49], v[38:39], v[4:5] op_sel_hi:[1,0,1]
	s_waitcnt vmcnt(0)
	v_pk_fma_f32 v[2:3], v[50:51], v[58:59], v[2:3] op_sel_hi:[1,0,1]
	ds_bpermute_b32 v6, v107, v2
	ds_bpermute_b32 v7, v107, v3
	v_pk_fma_f32 v[4:5], v[52:53], v[58:59], v[4:5] op_sel_hi:[1,0,1]
	s_waitcnt lgkmcnt(0)
	v_pk_add_f32 v[2:3], v[2:3], v[6:7]
	ds_bpermute_b32 v6, v107, v4
	ds_bpermute_b32 v7, v107, v5
	s_waitcnt lgkmcnt(0)
	v_pk_add_f32 v[4:5], v[4:5], v[6:7]
	ds_bpermute_b32 v6, v114, v2
	ds_bpermute_b32 v7, v114, v3
	ds_bpermute_b32 v8, v114, v4
	ds_bpermute_b32 v9, v114, v5
	s_and_saveexec_b64 s[0:1], s[20:21]
	s_cbranch_execz .LBB0_1415
	s_ashr_i32 s37, s36, 31
	s_lshl_b64 s[90:91], s[36:37], 8
	v_lshl_add_u64 v[12:13], v[88:89], 0, s[90:91]
	s_waitcnt lgkmcnt(2)
	v_pk_add_f32 v[2:3], v[2:3], v[6:7]
	s_waitcnt lgkmcnt(0)
	v_pk_add_f32 v[4:5], v[4:5], v[8:9]
	global_store_dwordx4 v[12:13], v[2:5], off

; __device__ __forceinline__ float bf2f(bf16_t b) { return __uint_as_float(((unsigned)b) << 16); }
; template <int NB>
; __device__ __forceinline__ void sb_decode_task(const Params& P, float* lds, int task) {
;     ...
;     const int h = task % SH, bj = task / SH, b = bj / NPAGES;
;     const int page = P.page_table[bj];
;     const float* Kp = P.cache_k + ((size_t)page * PAGE * SH + h) * HD + 4 * c;
;     const float* Vp = P.cache_v + ((size_t)page * PAGE * SH + h) * HD + 4 * c;
;     const bf16_t* qp = qb + (size_t)(NTOK + b) * SBW + h * 64 + 4 * c;
;     const float q0 = bf2f(qp[0]), q1 = bf2f(qp[1]), q2 = bf2f(qp[2]), q3 = bf2f(qp[3]);
;     const float bias = P.sb_bias[h] * LOG2E;
;     float4 cur[NB], nx[NB];
; #pragma unroll
;     for (int i = 0; i < NB; ++i) cur[i] = *(const float4*)(Kp + (size_t)(4 * i + g) * (SH * HD));
; #pragma unroll
;     for (int kb = 0; kb < NBT; ++kb) {
;         const float* np = (kb + 1 < NBT) ? Kp + (size_t)(4 * NB * (kb + 1)) * (SH * HD) : Vp;
; #pragma unroll
;         for (int i = 0; i < NB; ++i) nx[i] = *(const float4*)(np + (size_t)(4 * i + g) * (SH * HD));
; #pragma unroll
;         for (int i = 0; i < NB; ++i) { const int s = 4 * NB * kb + 4 * i + g;
;             float part = q0 * cur[i].x + q1 * cur[i].y + q2 * cur[i].z + q3 * cur[i].w; part = sum16(part);
;             if (c == 0) zl[s] = part + bias; }
; #pragma unroll
;         for (int i = 0; i < NB; ++i) cur[i] = nx[i];
;     }
.LBB0_1418:
	s_and_b64 vcc, exec, s[0:1]
	s_cbranch_vccz .LBB0_1267
	v_readlane_b32 s90, v252, 48
	v_readlane_b32 s91, v252, 49
	s_load_dwordx16 s[52:67], s[90:91], 0x0
	s_lshr_b32 s1, s2, 31
	s_add_i32 s0, s2, s1
	s_ashr_i32 s2, s2, 7
	s_mul_i32 s3, s0, 6
	s_add_i32 s2, s2, s1
	s_ashr_i32 s1, s0, 31
	s_sub_i32 s36, s34, s3
	s_lshl_b64 s[0:1], s[0:1], 2
	s_waitcnt lgkmcnt(0)
	s_add_u32 s0, s62, s0
	s_addc_u32 s1, s63, s1
	global_load_dword v2, v83, s[0:1]
	s_add_i32 s0, s2, 0x4000
	s_ashr_i32 s37, s36, 31
	s_mul_hi_i32 s1, s0, 0x300
	s_mulk_i32 s0, 0x300
	s_add_u32 s2, s38, s0
	s_addc_u32 s3, s39, s1
	s_lshl_b32 s0, s36, 6
	s_ashr_i32 s1, s0, 31
	s_lshl_b64 s[0:1], s[0:1], 1
	s_add_u32 s0, s2, s0
	s_addc_u32 s1, s3, s1
	v_readlane_b32 s52, v252, 16
	v_readlane_b32 s53, v252, 17
	v_readlane_b32 s60, v252, 24
	v_readlane_b32 s61, v252, 25
	s_mov_b64 s[52:53], s[60:61]
	v_readlane_b32 s54, v252, 18
	v_readlane_b32 s55, v252, 19
	v_readlane_b32 s56, v252, 20
	v_readlane_b32 s57, v252, 21
	v_readlane_b32 s58, v252, 22
	v_readlane_b32 s59, v252, 23
	v_readlane_b32 s62, v252, 26
	v_readlane_b32 s63, v252, 27
	v_readlane_b32 s64, v252, 28
	v_readlane_b32 s65, v252, 29
	v_readlane_b32 s66, v252, 30
	v_readlane_b32 s67, v252, 31
	s_waitcnt vmcnt(0)
	v_mul_hi_i32 v3, v2, s48
	v_mul_lo_u32 v2, v2, s48
	v_lshl_add_u64 v[42:43], v[2:3], 0, s[36:37]
	v_lshlrev_b64 v[2:3], 8, v[42:43]
	v_lshl_add_u64 v[38:39], v[84:85], 0, v[2:3]
	global_load_dwordx2 v[2:3], v101, s[0:1]
	s_lshl_b64 s[0:1], s[36:37], 2
	s_add_u32 s0, s52, s0
	s_addc_u32 s1, s53, s1
	global_load_dword v6, v83, s[0:1]
	s_waitcnt vmcnt(1)
	v_lshlrev_b32_e32 v45, 16, v2
	v_and_b32_e32 v47, 0xffff0000, v2
	v_lshlrev_b32_e32 v46, 16, v3
	v_and_b32_e32 v44, 0xffff0000, v3
	v_lshl_add_u64 v[2:3], v[38:39], 0, v[82:83]
	v_add_co_u32_e32 v4, vcc, s50, v2
	global_load_dwordx4 v[30:33], v[2:3], off nt
	s_nop 0
	v_addc_co_u32_e32 v5, vcc, 0, v3, vcc
	global_load_dwordx4 v[26:29], v[4:5], off offset:2048 nt
	v_add_co_u32_e32 v4, vcc, s51, v2
	s_waitcnt vmcnt(2)
	v_mul_f32_e32 v48, 0x3fb8aa3b, v6
	v_addc_co_u32_e32 v5, vcc, 0, v3, vcc
	global_load_dwordx4 v[22:25], v[4:5], off nt
	v_add_co_u32_e32 v4, vcc, s49, v2
	s_waitcnt vmcnt(2)
	v_mul_f32_e32 v31, v31, v47
	v_addc_co_u32_e32 v5, vcc, 0, v3, vcc
	global_load_dwordx4 v[14:17], v[4:5], off offset:2048 nt
	v_add_co_u32_e32 v4, vcc, s89, v2
	v_fmac_f32_e32 v31, v30, v45
	s_nop 0
	v_addc_co_u32_e32 v5, vcc, 0, v3, vcc
	global_load_dwordx4 v[18:21], v[4:5], off nt
	v_add_co_u32_e32 v4, vcc, s92, v2
	v_fmac_f32_e32 v31, v32, v46
	s_nop 0
	v_addc_co_u32_e32 v5, vcc, 0, v3, vcc
	global_load_dwordx4 v[6:9], v[4:5], off offset:2048 nt
	v_add_co_u32_e32 v4, vcc, s93, v2
	v_fmac_f32_e32 v31, v33, v44
	s_nop 0
	v_addc_co_u32_e32 v5, vcc, 0, v3, vcc
	v_add_co_u32_e32 v2, vcc, s96, v2
	global_load_dwordx4 v[10:13], v[4:5], off nt
	s_nop 0
	v_addc_co_u32_e32 v3, vcc, 0, v3, vcc
	global_load_dwordx4 v[2:5], v[2:3], off offset:2048 nt
	v_add_f32_dpp v30, v31, v31 quad_perm:[1,0,3,2] row_mask:0xf bank_mask:0xf bound_ctrl:1
	s_nop 1
	v_add_f32_dpp v30, v30, v30 quad_perm:[2,3,0,1] row_mask:0xf bank_mask:0xf bound_ctrl:1
	s_nop 1
	v_add_f32_dpp v30, v30, v30 row_ror:4 row_mask:0xf bank_mask:0xf bound_ctrl:1
	s_nop 1
	v_mov_b32_dpp v31, v30 row_ror:8 row_mask:0xf bank_mask:0xf bound_ctrl:1
	s_and_saveexec_b64 s[0:1], s[6:7]
	v_add_f32_e32 v30, v30, v31
	v_add_f32_e32 v30, v48, v30
	ds_write_b32 v99, v30
	s_or_b64 exec, exec, s[0:1]
	s_waitcnt vmcnt(6)
	v_mul_f32_e32 v27, v27, v47
	v_fmac_f32_e32 v27, v26, v45
	v_fmac_f32_e32 v27, v28, v46
	v_fmac_f32_e32 v27, v29, v44
	s_nop 1
	v_add_f32_dpp v26, v27, v27 quad_perm:[1,0,3,2] row_mask:0xf bank_mask:0xf bound_ctrl:1
	s_nop 1
	v_add_f32_dpp v26, v26, v26 quad_perm:[2,3,0,1] row_mask:0xf bank_mask:0xf bound_ctrl:1
	s_nop 1
	v_add_f32_dpp v26, v26, v26 row_ror:4 row_mask:0xf bank_mask:0xf bound_ctrl:1
	s_nop 1
	v_mov_b32_dpp v27, v26 row_ror:8 row_mask:0xf bank_mask:0xf bound_ctrl:1
	s_and_saveexec_b64 s[0:1], s[6:7]
	v_add_f32_e32 v26, v26, v27
	v_add_f32_e32 v26, v48, v26
	ds_write_b32 v99, v26 offset:16
	s_or_b64 exec, exec, s[0:1]
	s_waitcnt vmcnt(5)
	v_mul_f32_e32 v23, v23, v47
	v_fmac_f32_e32 v23, v22, v45
	v_fmac_f32_e32 v23, v24, v46
	v_fmac_f32_e32 v23, v25, v44
	s_nop 1
	v_add_f32_dpp v22, v23, v23 quad_perm:[1,0,3,2] row_mask:0xf bank_mask:0xf bound_ctrl:1
	s_nop 1
	v_add_f32_dpp v22, v22, v22 quad_perm:[2,3,0,1] row_mask:0xf bank_mask:0xf bound_ctrl:1
	s_nop 1
	v_add_f32_dpp v22, v22, v22 row_ror:4 row_mask:0xf bank_mask:0xf bound_ctrl:1
	s_nop 1
	v_mov_b32_dpp v23, v22 row_ror:8 row_mask:0xf bank_mask:0xf bound_ctrl:1
	s_and_saveexec_b64 s[0:1], s[6:7]
	v_add_f32_e32 v22, v22, v23
	v_add_f32_e32 v22, v48, v22
	ds_write_b32 v99, v22 offset:32
	s_or_b64 exec, exec, s[0:1]
	s_waitcnt vmcnt(4)
	v_mul_f32_e32 v15, v15, v47
	v_fmac_f32_e32 v15, v14, v45
	v_fmac_f32_e32 v15, v16, v46
	v_fmac_f32_e32 v15, v17, v44
	s_nop 1
	v_add_f32_dpp v14, v15, v15 quad_perm:[1,0,3,2] row_mask:0xf bank_mask:0xf bound_ctrl:1
	s_nop 1
	v_add_f32_dpp v14, v14, v14 quad_perm:[2,3,0,1] row_mask:0xf bank_mask:0xf bound_ctrl:1
	s_nop 1
	v_add_f32_dpp v14, v14, v14 row_ror:4 row_mask:0xf bank_mask:0xf bound_ctrl:1
	s_nop 1
	v_mov_b32_dpp v15, v14 row_ror:8 row_mask:0xf bank_mask:0xf bound_ctrl:1
	s_and_saveexec_b64 s[0:1], s[6:7]
	v_add_f32_e32 v14, v14, v15
	v_add_f32_e32 v14, v48, v14
	ds_write_b32 v99, v14 offset:48
	s_or_b64 exec, exec, s[0:1]
	v_lshl_add_u64 v[14:15], v[38:39], 0, v[82:83]
	v_add_co_u32_e32 v16, vcc, 0xc000, v14
	s_waitcnt vmcnt(3)
; template <int NB>
; __device__ __forceinline__ void sb_decode_task(const Params& P, float* lds, int task) {
;     ...
;     for (int i = 0; i < NB; ++i) cur[i] = *(const float4*)(Kp + (size_t)(4 * i + g) * (SH * HD));
; #pragma unroll
;     for (int kb = 0; kb < NBT; ++kb) {
;         const float* np = (kb + 1 < NBT) ? Kp + (size_t)(4 * NB * (kb + 1)) * (SH * HD) : Vp;
; #pragma unroll
;         for (int i = 0; i < NB; ++i) nx[i] = *(const float4*)(np + (size_t)(4 * i + g) * (SH * HD));
; #pragma unroll
;         for (int i = 0; i < NB; ++i) { const int s = 4 * NB * kb + 4 * i + g;
;             float part = q0 * cur[i].x + q1 * cur[i].y + q2 * cur[i].z + q3 * cur[i].w; part = sum16(part);
;             if (c == 0) zl[s] = part + bias; }
; #pragma unroll
;         for (int i = 0; i < NB; ++i) cur[i] = nx[i];
;     }
	v_mul_f32_e32 v19, v19, v47
	v_addc_co_u32_e32 v17, vcc, 0, v15, vcc
	v_add_co_u32_e32 v22, vcc, 0xd000, v14
	v_fmac_f32_e32 v19, v18, v45
	s_nop 0
	v_addc_co_u32_e32 v23, vcc, 0, v15, vcc
	global_load_dwordx4 v[30:33], v[16:17], off nt
	global_load_dwordx4 v[26:29], v[22:23], off offset:2048 nt
	v_add_co_u32_e32 v16, vcc, 0xf000, v14
	v_fmac_f32_e32 v19, v20, v46
	s_nop 0
	v_addc_co_u32_e32 v17, vcc, 0, v15, vcc
	v_add_co_u32_e32 v14, vcc, 0x10000, v14
	v_fmac_f32_e32 v19, v21, v44
	s_nop 0
	v_addc_co_u32_e32 v15, vcc, 0, v15, vcc
	global_load_dwordx4 v[22:25], v[16:17], off nt
	s_nop 0
	global_load_dwordx4 v[14:17], v[14:15], off offset:2048 nt
	v_add_f32_dpp v18, v19, v19 quad_perm:[1,0,3,2] row_mask:0xf bank_mask:0xf bound_ctrl:1
	s_nop 1
	v_add_f32_dpp v18, v18, v18 quad_perm:[2,3,0,1] row_mask:0xf bank_mask:0xf bound_ctrl:1
	s_nop 1
	v_add_f32_dpp v18, v18, v18 row_ror:4 row_mask:0xf bank_mask:0xf bound_ctrl:1
	s_nop 1
	v_mov_b32_dpp v19, v18 row_ror:8 row_mask:0xf bank_mask:0xf bound_ctrl:1
	s_and_saveexec_b64 s[0:1], s[6:7]
	v_add_f32_e32 v18, v18, v19
	v_add_f32_e32 v18, v48, v18
	ds_write_b32 v99, v18 offset:64
	s_or_b64 exec, exec, s[0:1]
	s_waitcnt vmcnt(6)
	v_mul_f32_e32 v7, v7, v47
	v_fmac_f32_e32 v7, v6, v45
	v_fmac_f32_e32 v7, v8, v46
	v_fmac_f32_e32 v7, v9, v44
	s_nop 1
	v_add_f32_dpp v6, v7, v7 quad_perm:[1,0,3,2] row_mask:0xf bank_mask:0xf bound_ctrl:1
	s_nop 1
	v_add_f32_dpp v6, v6, v6 quad_perm:[2,3,0,1] row_mask:0xf bank_mask:0xf bound_ctrl:1
	s_nop 1
	v_add_f32_dpp v6, v6, v6 row_ror:4 row_mask:0xf bank_mask:0xf bound_ctrl:1
	s_nop 1
	v_mov_b32_dpp v7, v6 row_ror:8 row_mask:0xf bank_mask:0xf bound_ctrl:1
	s_and_saveexec_b64 s[0:1], s[6:7]
	v_add_f32_e32 v6, v6, v7
	v_add_f32_e32 v6, v48, v6
	ds_write_b32 v99, v6 offset:80
	s_or_b64 exec, exec, s[0:1]
	s_waitcnt vmcnt(5)
	v_mul_f32_e32 v6, v11, v47
	v_fmac_f32_e32 v6, v10, v45
	v_fmac_f32_e32 v6, v12, v46
	v_fmac_f32_e32 v6, v13, v44
	s_nop 1
	v_add_f32_dpp v6, v6, v6 quad_perm:[1,0,3,2] row_mask:0xf bank_mask:0xf bound_ctrl:1
	s_nop 1
	v_add_f32_dpp v6, v6, v6 quad_perm:[2,3,0,1] row_mask:0xf bank_mask:0xf bound_ctrl:1
	s_nop 1
	v_add_f32_dpp v6, v6, v6 row_ror:4 row_mask:0xf bank_mask:0xf bound_ctrl:1
	s_nop 1
	v_mov_b32_dpp v7, v6 row_ror:8 row_mask:0xf bank_mask:0xf bound_ctrl:1
	s_and_saveexec_b64 s[0:1], s[6:7]
	v_add_f32_e32 v6, v6, v7
	v_add_f32_e32 v6, v48, v6
	ds_write_b32 v99, v6 offset:96
	s_or_b64 exec, exec, s[0:1]
	s_waitcnt vmcnt(4)
	v_mul_f32_e32 v3, v3, v47
	v_fmac_f32_e32 v3, v2, v45
	v_fmac_f32_e32 v3, v4, v46
	v_fmac_f32_e32 v3, v5, v44
	s_nop 1
	v_add_f32_dpp v2, v3, v3 quad_perm:[1,0,3,2] row_mask:0xf bank_mask:0xf bound_ctrl:1
	s_nop 1
	v_add_f32_dpp v2, v2, v2 quad_perm:[2,3,0,1] row_mask:0xf bank_mask:0xf bound_ctrl:1
	s_nop 1
	v_add_f32_dpp v2, v2, v2 row_ror:4 row_mask:0xf bank_mask:0xf bound_ctrl:1
	s_nop 1
	v_mov_b32_dpp v3, v2 row_ror:8 row_mask:0xf bank_mask:0xf bound_ctrl:1
	s_and_saveexec_b64 s[0:1], s[6:7]
	v_add_f32_e32 v2, v2, v3
	v_add_f32_e32 v2, v48, v2
	ds_write_b32 v99, v2 offset:112
	s_or_b64 exec, exec, s[0:1]
	v_lshl_add_u64 v[2:3], v[38:39], 0, v[82:83]
	v_add_co_u32_e32 v4, vcc, 0x12000, v2
	s_nop 1
	v_addc_co_u32_e32 v5, vcc, 0, v3, vcc
	v_add_co_u32_e32 v6, vcc, 0x13000, v2
	s_nop 1
	v_addc_co_u32_e32 v7, vcc, 0, v3, vcc
	global_load_dwordx4 v[34:37], v[4:5], off nt
	global_load_dwordx4 v[18:21], v[6:7], off offset:2048 nt
	v_add_co_u32_e32 v4, vcc, 0x15000, v2
	s_waitcnt vmcnt(5)
	v_mul_f32_e32 v6, v31, v47
	v_addc_co_u32_e32 v5, vcc, 0, v3, vcc
	v_add_co_u32_e32 v2, vcc, 0x16000, v2
	v_fmac_f32_e32 v6, v30, v45
	s_nop 0
	v_addc_co_u32_e32 v3, vcc, 0, v3, vcc
	global_load_dwordx4 v[10:13], v[4:5], off nt
	s_nop 0
	global_load_dwordx4 v[2:5], v[2:3], off offset:2048 nt
	v_fmac_f32_e32 v6, v32, v46
	v_fmac_f32_e32 v6, v33, v44
	s_nop 1
	v_add_f32_dpp v6, v6, v6 quad_perm:[1,0,3,2] row_mask:0xf bank_mask:0xf bound_ctrl:1
	s_nop 1
	v_add_f32_dpp v6, v6, v6 quad_perm:[2,3,0,1] row_mask:0xf bank_mask:0xf bound_ctrl:1
	s_nop 1
	v_add_f32_dpp v6, v6, v6 row_ror:4 row_mask:0xf bank_mask:0xf bound_ctrl:1
	s_nop 1
	v_mov_b32_dpp v7, v6 row_ror:8 row_mask:0xf bank_mask:0xf bound_ctrl:1
	s_and_saveexec_b64 s[0:1], s[6:7]
	v_add_f32_e32 v6, v6, v7
	v_add_f32_e32 v6, v48, v6
	ds_write_b32 v99, v6 offset:128
	s_or_b64 exec, exec, s[0:1]
	s_waitcnt vmcnt(6)
	v_mul_f32_e32 v6, v27, v47
	v_fmac_f32_e32 v6, v26, v45
	v_fmac_f32_e32 v6, v28, v46
	v_fmac_f32_e32 v6, v29, v44
	s_nop 1
	v_add_f32_dpp v6, v6, v6 quad_perm:[1,0,3,2] row_mask:0xf bank_mask:0xf bound_ctrl:1
	s_nop 1
	v_add_f32_dpp v6, v6, v6 quad_perm:[2,3,0,1] row_mask:0xf bank_mask:0xf bound_ctrl:1
	s_nop 1
	v_add_f32_dpp v6, v6, v6 row_ror:4 row_mask:0xf bank_mask:0xf bound_ctrl:1
	s_nop 1
	v_mov_b32_dpp v7, v6 row_ror:8 row_mask:0xf bank_mask:0xf bound_ctrl:1
	s_and_saveexec_b64 s[0:1], s[6:7]
	v_add_f32_e32 v6, v6, v7
	v_add_f32_e32 v6, v48, v6
	ds_write_b32 v99, v6 offset:144
	s_or_b64 exec, exec, s[0:1]
	s_waitcnt vmcnt(5)
	v_mul_f32_e32 v6, v23, v47
	v_fmac_f32_e32 v6, v22, v45
	v_fmac_f32_e32 v6, v24, v46
	v_fmac_f32_e32 v6, v25, v44
	s_nop 1
	v_add_f32_dpp v6, v6, v6 quad_perm:[1,0,3,2] row_mask:0xf bank_mask:0xf bound_ctrl:1
	s_nop 1
	v_add_f32_dpp v6, v6, v6 quad_perm:[2,3,0,1] row_mask:0xf bank_mask:0xf bound_ctrl:1
	s_nop 1
	v_add_f32_dpp v6, v6, v6 row_ror:4 row_mask:0xf bank_mask:0xf bound_ctrl:1
	s_nop 1
	v_mov_b32_dpp v7, v6 row_ror:8 row_mask:0xf bank_mask:0xf bound_ctrl:1
	s_and_saveexec_b64 s[0:1], s[6:7]
	v_add_f32_e32 v6, v6, v7
	v_add_f32_e32 v6, v48, v6
	ds_write_b32 v99, v6 offset:160
	s_or_b64 exec, exec, s[0:1]
	s_waitcnt vmcnt(4)
; template <int NB>
; __device__ __forceinline__ void sb_decode_task(const Params& P, float* lds, int task) {
;     ...
;     for (int i = 0; i < NB; ++i) cur[i] = *(const float4*)(Kp + (size_t)(4 * i + g) * (SH * HD));
; #pragma unroll
;     for (int kb = 0; kb < NBT; ++kb) {
;         const float* np = (kb + 1 < NBT) ? Kp + (size_t)(4 * NB * (kb + 1)) * (SH * HD) : Vp;
; #pragma unroll
;         for (int i = 0; i < NB; ++i) nx[i] = *(const float4*)(np + (size_t)(4 * i + g) * (SH * HD));
; #pragma unroll
;         for (int i = 0; i < NB; ++i) { const int s = 4 * NB * kb + 4 * i + g;
;             float part = q0 * cur[i].x + q1 * cur[i].y + q2 * cur[i].z + q3 * cur[i].w; part = sum16(part);
;             if (c == 0) zl[s] = part + bias; }
; #pragma unroll
;         for (int i = 0; i < NB; ++i) cur[i] = nx[i];
;     }
	v_mul_f32_e32 v6, v15, v47
	v_fmac_f32_e32 v6, v14, v45
	v_fmac_f32_e32 v6, v16, v46
	v_fmac_f32_e32 v6, v17, v44
	s_nop 1
	v_add_f32_dpp v6, v6, v6 quad_perm:[1,0,3,2] row_mask:0xf bank_mask:0xf bound_ctrl:1
	s_nop 1
	v_add_f32_dpp v6, v6, v6 quad_perm:[2,3,0,1] row_mask:0xf bank_mask:0xf bound_ctrl:1
	s_nop 1
	v_add_f32_dpp v6, v6, v6 row_ror:4 row_mask:0xf bank_mask:0xf bound_ctrl:1
	s_nop 1
	v_mov_b32_dpp v7, v6 row_ror:8 row_mask:0xf bank_mask:0xf bound_ctrl:1
	s_and_saveexec_b64 s[0:1], s[6:7]
	v_add_f32_e32 v6, v6, v7
	v_add_f32_e32 v6, v48, v6
	ds_write_b32 v99, v6 offset:176
	s_or_b64 exec, exec, s[0:1]
	v_lshl_add_u64 v[6:7], v[38:39], 0, v[82:83]
	v_add_co_u32_e32 v8, vcc, 0x18000, v6
	s_waitcnt vmcnt(3)
	v_mul_f32_e32 v30, v35, v47
	v_addc_co_u32_e32 v9, vcc, 0, v7, vcc
	v_add_co_u32_e32 v14, vcc, 0x19000, v6
	v_fmac_f32_e32 v30, v34, v45
	s_nop 0
	v_addc_co_u32_e32 v15, vcc, 0, v7, vcc
	global_load_dwordx4 v[26:29], v[8:9], off nt
	global_load_dwordx4 v[22:25], v[14:15], off offset:2048 nt
	v_add_co_u32_e32 v8, vcc, 0x1b000, v6
	v_fmac_f32_e32 v30, v36, v46
	s_nop 0
	v_addc_co_u32_e32 v9, vcc, 0, v7, vcc
	v_add_co_u32_e32 v6, vcc, 0x1c000, v6
	v_fmac_f32_e32 v30, v37, v44
	s_nop 0
	v_addc_co_u32_e32 v7, vcc, 0, v7, vcc
	global_load_dwordx4 v[14:17], v[8:9], off nt
	s_nop 0
	global_load_dwordx4 v[6:9], v[6:7], off offset:2048 nt
	v_add_f32_dpp v30, v30, v30 quad_perm:[1,0,3,2] row_mask:0xf bank_mask:0xf bound_ctrl:1
	s_nop 1
	v_add_f32_dpp v30, v30, v30 quad_perm:[2,3,0,1] row_mask:0xf bank_mask:0xf bound_ctrl:1
	s_nop 1
	v_add_f32_dpp v30, v30, v30 row_ror:4 row_mask:0xf bank_mask:0xf bound_ctrl:1
	s_nop 1
	v_mov_b32_dpp v31, v30 row_ror:8 row_mask:0xf bank_mask:0xf bound_ctrl:1
	s_and_saveexec_b64 s[0:1], s[6:7]
	v_add_f32_e32 v30, v30, v31
	v_add_f32_e32 v30, v48, v30
	ds_write_b32 v99, v30 offset:192
	s_or_b64 exec, exec, s[0:1]
	s_waitcnt vmcnt(6)
	v_mul_f32_e32 v19, v19, v47
	v_fmac_f32_e32 v19, v18, v45
	v_fmac_f32_e32 v19, v20, v46
	v_fmac_f32_e32 v19, v21, v44
	s_nop 1
	v_add_f32_dpp v18, v19, v19 quad_perm:[1,0,3,2] row_mask:0xf bank_mask:0xf bound_ctrl:1
	s_nop 1
	v_add_f32_dpp v18, v18, v18 quad_perm:[2,3,0,1] row_mask:0xf bank_mask:0xf bound_ctrl:1
	s_nop 1
	v_add_f32_dpp v18, v18, v18 row_ror:4 row_mask:0xf bank_mask:0xf bound_ctrl:1
	s_nop 1
	v_mov_b32_dpp v19, v18 row_ror:8 row_mask:0xf bank_mask:0xf bound_ctrl:1
	s_and_saveexec_b64 s[0:1], s[6:7]
	v_add_f32_e32 v18, v18, v19
	v_add_f32_e32 v18, v48, v18
	ds_write_b32 v99, v18 offset:208
	s_or_b64 exec, exec, s[0:1]
	s_waitcnt vmcnt(5)
	v_mul_f32_e32 v11, v11, v47
	v_fmac_f32_e32 v11, v10, v45
	v_fmac_f32_e32 v11, v12, v46
	v_fmac_f32_e32 v11, v13, v44
	s_nop 1
	v_add_f32_dpp v10, v11, v11 quad_perm:[1,0,3,2] row_mask:0xf bank_mask:0xf bound_ctrl:1
	s_nop 1
	v_add_f32_dpp v10, v10, v10 quad_perm:[2,3,0,1] row_mask:0xf bank_mask:0xf bound_ctrl:1
	s_nop 1
	v_add_f32_dpp v10, v10, v10 row_ror:4 row_mask:0xf bank_mask:0xf bound_ctrl:1
	s_nop 1
	v_mov_b32_dpp v11, v10 row_ror:8 row_mask:0xf bank_mask:0xf bound_ctrl:1
	s_and_saveexec_b64 s[0:1], s[6:7]
	v_add_f32_e32 v10, v10, v11
	v_add_f32_e32 v10, v48, v10
	ds_write_b32 v99, v10 offset:224
	s_or_b64 exec, exec, s[0:1]
	s_waitcnt vmcnt(4)
	v_mul_f32_e32 v3, v3, v47
	v_fmac_f32_e32 v3, v2, v45
	v_fmac_f32_e32 v3, v4, v46
	v_fmac_f32_e32 v3, v5, v44
	s_nop 1
	v_add_f32_dpp v2, v3, v3 quad_perm:[1,0,3,2] row_mask:0xf bank_mask:0xf bound_ctrl:1
	s_nop 1
	v_add_f32_dpp v2, v2, v2 quad_perm:[2,3,0,1] row_mask:0xf bank_mask:0xf bound_ctrl:1
	s_nop 1
	v_add_f32_dpp v2, v2, v2 row_ror:4 row_mask:0xf bank_mask:0xf bound_ctrl:1
	s_nop 1
	v_mov_b32_dpp v3, v2 row_ror:8 row_mask:0xf bank_mask:0xf bound_ctrl:1
	s_and_saveexec_b64 s[0:1], s[6:7]
	v_add_f32_e32 v2, v2, v3
	v_add_f32_e32 v2, v48, v2
	ds_write_b32 v99, v2 offset:240
	s_or_b64 exec, exec, s[0:1]
	v_lshl_add_u64 v[2:3], v[38:39], 0, v[82:83]
	v_add_co_u32_e32 v4, vcc, 0x1e000, v2
	s_waitcnt vmcnt(3)
	v_mul_f32_e32 v27, v27, v47
	v_addc_co_u32_e32 v5, vcc, 0, v3, vcc
	v_add_co_u32_e32 v10, vcc, 0x1f000, v2
	v_fmac_f32_e32 v27, v26, v45
	s_nop 0
	v_addc_co_u32_e32 v11, vcc, 0, v3, vcc
	global_load_dwordx4 v[30:33], v[4:5], off nt
	global_load_dwordx4 v[18:21], v[10:11], off offset:2048 nt
	v_add_co_u32_e32 v4, vcc, 0x21000, v2
	v_fmac_f32_e32 v27, v28, v46
	s_nop 0
	v_addc_co_u32_e32 v5, vcc, 0, v3, vcc
	v_add_co_u32_e32 v2, vcc, 0x22000, v2
	v_fmac_f32_e32 v27, v29, v44
	s_nop 0
	v_addc_co_u32_e32 v3, vcc, 0, v3, vcc
	global_load_dwordx4 v[10:13], v[4:5], off nt
	s_nop 0
	global_load_dwordx4 v[2:5], v[2:3], off offset:2048 nt
	v_add_f32_dpp v26, v27, v27 quad_perm:[1,0,3,2] row_mask:0xf bank_mask:0xf bound_ctrl:1
	s_nop 1
	v_add_f32_dpp v26, v26, v26 quad_perm:[2,3,0,1] row_mask:0xf bank_mask:0xf bound_ctrl:1
	s_nop 1
	v_add_f32_dpp v26, v26, v26 row_ror:4 row_mask:0xf bank_mask:0xf bound_ctrl:1
	s_nop 1
	v_mov_b32_dpp v27, v26 row_ror:8 row_mask:0xf bank_mask:0xf bound_ctrl:1
	s_and_saveexec_b64 s[0:1], s[6:7]
	v_add_f32_e32 v26, v26, v27
	v_add_f32_e32 v26, v48, v26
	ds_write_b32 v99, v26 offset:256
	s_or_b64 exec, exec, s[0:1]
	s_waitcnt vmcnt(6)
	v_mul_f32_e32 v23, v23, v47
	v_fmac_f32_e32 v23, v22, v45
	v_fmac_f32_e32 v23, v24, v46
	v_fmac_f32_e32 v23, v25, v44
	s_nop 1
	v_add_f32_dpp v22, v23, v23 quad_perm:[1,0,3,2] row_mask:0xf bank_mask:0xf bound_ctrl:1
	s_nop 1
	v_add_f32_dpp v22, v22, v22 quad_perm:[2,3,0,1] row_mask:0xf bank_mask:0xf bound_ctrl:1
	s_nop 1
	v_add_f32_dpp v22, v22, v22 row_ror:4 row_mask:0xf bank_mask:0xf bound_ctrl:1
	s_nop 1
	v_mov_b32_dpp v23, v22 row_ror:8 row_mask:0xf bank_mask:0xf bound_ctrl:1
	s_and_saveexec_b64 s[0:1], s[6:7]
	v_add_f32_e32 v22, v22, v23
	v_add_f32_e32 v22, v48, v22
	ds_write_b32 v99, v22 offset:272
	s_or_b64 exec, exec, s[0:1]
	s_waitcnt vmcnt(5)
; template <int NB>
; __device__ __forceinline__ void sb_decode_task(const Params& P, float* lds, int task) {
;     ...
;     for (int i = 0; i < NB; ++i) cur[i] = *(const float4*)(Kp + (size_t)(4 * i + g) * (SH * HD));
; #pragma unroll
;     for (int kb = 0; kb < NBT; ++kb) {
;         const float* np = (kb + 1 < NBT) ? Kp + (size_t)(4 * NB * (kb + 1)) * (SH * HD) : Vp;
; #pragma unroll
;         for (int i = 0; i < NB; ++i) nx[i] = *(const float4*)(np + (size_t)(4 * i + g) * (SH * HD));
; #pragma unroll
;         for (int i = 0; i < NB; ++i) { const int s = 4 * NB * kb + 4 * i + g;
;             float part = q0 * cur[i].x + q1 * cur[i].y + q2 * cur[i].z + q3 * cur[i].w; part = sum16(part);
;             if (c == 0) zl[s] = part + bias; }
; #pragma unroll
;         for (int i = 0; i < NB; ++i) cur[i] = nx[i];
;     }
	v_mul_f32_e32 v15, v15, v47
	v_fmac_f32_e32 v15, v14, v45
	v_fmac_f32_e32 v15, v16, v46
	v_fmac_f32_e32 v15, v17, v44
	s_nop 1
	v_add_f32_dpp v14, v15, v15 quad_perm:[1,0,3,2] row_mask:0xf bank_mask:0xf bound_ctrl:1
	s_nop 1
	v_add_f32_dpp v14, v14, v14 quad_perm:[2,3,0,1] row_mask:0xf bank_mask:0xf bound_ctrl:1
	s_nop 1
	v_add_f32_dpp v14, v14, v14 row_ror:4 row_mask:0xf bank_mask:0xf bound_ctrl:1
	s_nop 1
	v_mov_b32_dpp v15, v14 row_ror:8 row_mask:0xf bank_mask:0xf bound_ctrl:1
	s_and_saveexec_b64 s[0:1], s[6:7]
	v_add_f32_e32 v14, v14, v15
	v_add_f32_e32 v14, v48, v14
	ds_write_b32 v99, v14 offset:288
	s_or_b64 exec, exec, s[0:1]
	s_waitcnt vmcnt(4)
	v_mul_f32_e32 v7, v7, v47
	v_fmac_f32_e32 v7, v6, v45
	v_fmac_f32_e32 v7, v8, v46
	v_fmac_f32_e32 v7, v9, v44
	s_nop 1
	v_add_f32_dpp v6, v7, v7 quad_perm:[1,0,3,2] row_mask:0xf bank_mask:0xf bound_ctrl:1
	s_nop 1
	v_add_f32_dpp v6, v6, v6 quad_perm:[2,3,0,1] row_mask:0xf bank_mask:0xf bound_ctrl:1
	s_nop 1
	v_add_f32_dpp v6, v6, v6 row_ror:4 row_mask:0xf bank_mask:0xf bound_ctrl:1
	s_nop 1
	v_mov_b32_dpp v7, v6 row_ror:8 row_mask:0xf bank_mask:0xf bound_ctrl:1
	s_and_saveexec_b64 s[0:1], s[6:7]
	v_add_f32_e32 v6, v6, v7
	v_add_f32_e32 v6, v48, v6
	ds_write_b32 v99, v6 offset:304
	s_or_b64 exec, exec, s[0:1]
	v_lshl_add_u64 v[6:7], v[38:39], 0, v[82:83]
	v_add_co_u32_e32 v8, vcc, 0x24000, v6
	s_waitcnt vmcnt(3)
	v_mul_f32_e32 v22, v31, v47
	v_addc_co_u32_e32 v9, vcc, 0, v7, vcc
	v_add_co_u32_e32 v14, vcc, 0x25000, v6
	v_fmac_f32_e32 v22, v30, v45
	s_nop 0
	v_addc_co_u32_e32 v15, vcc, 0, v7, vcc
	global_load_dwordx4 v[34:37], v[8:9], off nt
	global_load_dwordx4 v[26:29], v[14:15], off offset:2048 nt
	v_add_co_u32_e32 v8, vcc, 0x27000, v6
	v_fmac_f32_e32 v22, v32, v46
	s_nop 0
	v_addc_co_u32_e32 v9, vcc, 0, v7, vcc
	v_add_co_u32_e32 v6, vcc, 0x28000, v6
	v_fmac_f32_e32 v22, v33, v44
	s_nop 0
	v_addc_co_u32_e32 v7, vcc, 0, v7, vcc
	global_load_dwordx4 v[14:17], v[8:9], off nt
	s_nop 0
	global_load_dwordx4 v[6:9], v[6:7], off offset:2048 nt
	v_add_f32_dpp v22, v22, v22 quad_perm:[1,0,3,2] row_mask:0xf bank_mask:0xf bound_ctrl:1
	s_nop 1
	v_add_f32_dpp v22, v22, v22 quad_perm:[2,3,0,1] row_mask:0xf bank_mask:0xf bound_ctrl:1
	s_nop 1
	v_add_f32_dpp v22, v22, v22 row_ror:4 row_mask:0xf bank_mask:0xf bound_ctrl:1
	s_nop 1
	v_mov_b32_dpp v23, v22 row_ror:8 row_mask:0xf bank_mask:0xf bound_ctrl:1
	s_and_saveexec_b64 s[0:1], s[6:7]
	v_add_f32_e32 v22, v22, v23
	v_add_f32_e32 v22, v48, v22
	ds_write_b32 v99, v22 offset:320
	s_or_b64 exec, exec, s[0:1]
	s_waitcnt vmcnt(6)
	v_mul_f32_e32 v19, v19, v47
	v_fmac_f32_e32 v19, v18, v45
	v_fmac_f32_e32 v19, v20, v46
	v_fmac_f32_e32 v19, v21, v44
	s_nop 1
	v_add_f32_dpp v18, v19, v19 quad_perm:[1,0,3,2] row_mask:0xf bank_mask:0xf bound_ctrl:1
	s_nop 1
	v_add_f32_dpp v18, v18, v18 quad_perm:[2,3,0,1] row_mask:0xf bank_mask:0xf bound_ctrl:1
	s_nop 1
	v_add_f32_dpp v18, v18, v18 row_ror:4 row_mask:0xf bank_mask:0xf bound_ctrl:1
	s_nop 1
	v_mov_b32_dpp v19, v18 row_ror:8 row_mask:0xf bank_mask:0xf bound_ctrl:1
	s_and_saveexec_b64 s[0:1], s[6:7]
	v_add_f32_e32 v18, v18, v19
	v_add_f32_e32 v18, v48, v18
	ds_write_b32 v99, v18 offset:336
	s_or_b64 exec, exec, s[0:1]
	s_waitcnt vmcnt(5)
	v_mul_f32_e32 v11, v11, v47
	v_fmac_f32_e32 v11, v10, v45
	v_fmac_f32_e32 v11, v12, v46
	v_fmac_f32_e32 v11, v13, v44
	s_nop 1
	v_add_f32_dpp v10, v11, v11 quad_perm:[1,0,3,2] row_mask:0xf bank_mask:0xf bound_ctrl:1
	s_nop 1
	v_add_f32_dpp v10, v10, v10 quad_perm:[2,3,0,1] row_mask:0xf bank_mask:0xf bound_ctrl:1
	s_nop 1
	v_add_f32_dpp v10, v10, v10 row_ror:4 row_mask:0xf bank_mask:0xf bound_ctrl:1
	s_nop 1
	v_mov_b32_dpp v11, v10 row_ror:8 row_mask:0xf bank_mask:0xf bound_ctrl:1
	s_and_saveexec_b64 s[0:1], s[6:7]
	v_add_f32_e32 v10, v10, v11
	v_add_f32_e32 v10, v48, v10
	ds_write_b32 v99, v10 offset:352
	s_or_b64 exec, exec, s[0:1]
	s_waitcnt vmcnt(4)
	v_mul_f32_e32 v3, v3, v47
	v_fmac_f32_e32 v3, v2, v45
	v_fmac_f32_e32 v3, v4, v46
	v_fmac_f32_e32 v3, v5, v44
	s_nop 1
	v_add_f32_dpp v2, v3, v3 quad_perm:[1,0,3,2] row_mask:0xf bank_mask:0xf bound_ctrl:1
	s_nop 1
	v_add_f32_dpp v2, v2, v2 quad_perm:[2,3,0,1] row_mask:0xf bank_mask:0xf bound_ctrl:1
	s_nop 1
	v_add_f32_dpp v2, v2, v2 row_ror:4 row_mask:0xf bank_mask:0xf bound_ctrl:1
	s_nop 1
	v_mov_b32_dpp v3, v2 row_ror:8 row_mask:0xf bank_mask:0xf bound_ctrl:1
	s_and_saveexec_b64 s[0:1], s[6:7]
	v_add_f32_e32 v2, v2, v3
	v_add_f32_e32 v2, v48, v2
	ds_write_b32 v99, v2 offset:368
	s_or_b64 exec, exec, s[0:1]
	v_lshl_add_u64 v[2:3], v[38:39], 0, v[82:83]
	v_add_co_u32_e32 v4, vcc, 0x2a000, v2
	s_nop 1
	v_addc_co_u32_e32 v5, vcc, 0, v3, vcc
	v_add_co_u32_e32 v10, vcc, 0x2b000, v2
	s_nop 1
	v_addc_co_u32_e32 v11, vcc, 0, v3, vcc
	global_load_dwordx4 v[38:41], v[4:5], off nt
	global_load_dwordx4 v[30:33], v[10:11], off offset:2048 nt
	v_add_co_u32_e32 v4, vcc, 0x2d000, v2
	s_nop 1
	v_addc_co_u32_e32 v5, vcc, 0, v3, vcc
	v_add_co_u32_e32 v2, vcc, 0x2e000, v2
	s_nop 1
	v_addc_co_u32_e32 v3, vcc, 0, v3, vcc
	global_load_dwordx4 v[22:25], v[4:5], off nt
	global_load_dwordx4 v[18:21], v[2:3], off offset:2048 nt
	s_waitcnt vmcnt(7)
	v_mul_f32_e32 v2, v35, v47
	v_fmac_f32_e32 v2, v34, v45
	v_fmac_f32_e32 v2, v36, v46
	v_fmac_f32_e32 v2, v37, v44
	s_nop 1
	v_add_f32_dpp v2, v2, v2 quad_perm:[1,0,3,2] row_mask:0xf bank_mask:0xf bound_ctrl:1
	s_nop 1
	v_add_f32_dpp v2, v2, v2 quad_perm:[2,3,0,1] row_mask:0xf bank_mask:0xf bound_ctrl:1
	s_nop 1
	v_add_f32_dpp v2, v2, v2 row_ror:4 row_mask:0xf bank_mask:0xf bound_ctrl:1
	s_nop 1
	v_mov_b32_dpp v3, v2 row_ror:8 row_mask:0xf bank_mask:0xf bound_ctrl:1
	s_and_saveexec_b64 s[0:1], s[6:7]
	v_add_f32_e32 v2, v2, v3
	v_add_f32_e32 v2, v48, v2
	ds_write_b32 v99, v2 offset:384
	s_or_b64 exec, exec, s[0:1]
	s_waitcnt vmcnt(6)
; template <int NB>
; __device__ __forceinline__ void sb_decode_task(const Params& P, float* lds, int task) {
;     ...
;     for (int kb = 0; kb < NBT; ++kb) {
;         const float* np = (kb + 1 < NBT) ? Kp + (size_t)(4 * NB * (kb + 1)) * (SH * HD) : Vp;
; #pragma unroll
;         for (int i = 0; i < NB; ++i) nx[i] = *(const float4*)(np + (size_t)(4 * i + g) * (SH * HD));
; #pragma unroll
;         for (int i = 0; i < NB; ++i) { const int s = 4 * NB * kb + 4 * i + g;
;             float part = q0 * cur[i].x + q1 * cur[i].y + q2 * cur[i].z + q3 * cur[i].w; part = sum16(part);
;             if (c == 0) zl[s] = part + bias; }
; #pragma unroll
;         for (int i = 0; i < NB; ++i) cur[i] = nx[i];
;     }
	v_mul_f32_e32 v2, v27, v47
	v_fmac_f32_e32 v2, v26, v45
	v_fmac_f32_e32 v2, v28, v46
	v_fmac_f32_e32 v2, v29, v44
	s_nop 1
	v_add_f32_dpp v2, v2, v2 quad_perm:[1,0,3,2] row_mask:0xf bank_mask:0xf bound_ctrl:1
	s_nop 1
	v_add_f32_dpp v2, v2, v2 quad_perm:[2,3,0,1] row_mask:0xf bank_mask:0xf bound_ctrl:1
	s_nop 1
	v_add_f32_dpp v2, v2, v2 row_ror:4 row_mask:0xf bank_mask:0xf bound_ctrl:1
	s_nop 1
	v_mov_b32_dpp v3, v2 row_ror:8 row_mask:0xf bank_mask:0xf bound_ctrl:1
	s_and_saveexec_b64 s[0:1], s[6:7]
	v_add_f32_e32 v2, v2, v3
	v_add_f32_e32 v2, v48, v2
	ds_write_b32 v99, v2 offset:400
	s_or_b64 exec, exec, s[0:1]
	s_waitcnt vmcnt(5)
	v_mul_f32_e32 v2, v15, v47
	v_fmac_f32_e32 v2, v14, v45
	v_fmac_f32_e32 v2, v16, v46
	v_fmac_f32_e32 v2, v17, v44
	s_nop 1
	v_add_f32_dpp v2, v2, v2 quad_perm:[1,0,3,2] row_mask:0xf bank_mask:0xf bound_ctrl:1
	s_nop 1
	v_add_f32_dpp v2, v2, v2 quad_perm:[2,3,0,1] row_mask:0xf bank_mask:0xf bound_ctrl:1
	s_nop 1
	v_add_f32_dpp v2, v2, v2 row_ror:4 row_mask:0xf bank_mask:0xf bound_ctrl:1
	s_nop 1
	v_mov_b32_dpp v3, v2 row_ror:8 row_mask:0xf bank_mask:0xf bound_ctrl:1
	s_and_saveexec_b64 s[0:1], s[6:7]
	v_add_f32_e32 v2, v2, v3
	v_add_f32_e32 v2, v48, v2
	ds_write_b32 v99, v2 offset:416
	s_or_b64 exec, exec, s[0:1]
	s_waitcnt vmcnt(4)
	v_mul_f32_e32 v2, v7, v47
	v_fmac_f32_e32 v2, v6, v45
	v_fmac_f32_e32 v2, v8, v46
	v_fmac_f32_e32 v2, v9, v44
	s_nop 1
	v_add_f32_dpp v2, v2, v2 quad_perm:[1,0,3,2] row_mask:0xf bank_mask:0xf bound_ctrl:1
	s_nop 1
	v_add_f32_dpp v2, v2, v2 quad_perm:[2,3,0,1] row_mask:0xf bank_mask:0xf bound_ctrl:1
	s_nop 1
	v_add_f32_dpp v2, v2, v2 row_ror:4 row_mask:0xf bank_mask:0xf bound_ctrl:1
	s_nop 1
	v_mov_b32_dpp v3, v2 row_ror:8 row_mask:0xf bank_mask:0xf bound_ctrl:1
	s_and_saveexec_b64 s[0:1], s[6:7]
	v_add_f32_e32 v2, v2, v3
	v_add_f32_e32 v2, v48, v2
	ds_write_b32 v99, v2 offset:432
	s_or_b64 exec, exec, s[0:1]
	v_lshlrev_b64 v[2:3], 6, v[42:43]
	v_lshl_add_u64 v[34:35], v[2:3], 2, v[90:91]
	v_add_co_u32_e32 v2, vcc, 0x1000, v34
	s_waitcnt vmcnt(3)
	v_mul_f32_e32 v26, v39, v47
	v_addc_co_u32_e32 v3, vcc, 0, v35, vcc
	v_add_co_u32_e32 v6, vcc, 0x3000, v34
	global_load_dwordx4 v[14:17], v[34:35], off nt
	s_nop 0
	global_load_dwordx4 v[2:5], v[2:3], off offset:2048 nt
	v_addc_co_u32_e32 v7, vcc, 0, v35, vcc
	v_add_co_u32_e32 v10, vcc, s49, v34
	v_fmac_f32_e32 v26, v38, v45
	s_nop 0
	v_addc_co_u32_e32 v11, vcc, 0, v35, vcc
	global_load_dwordx4 v[6:9], v[6:7], off nt
	s_nop 0
	global_load_dwordx4 v[10:13], v[10:11], off offset:2048 nt
	v_fmac_f32_e32 v26, v40, v46
	v_fmac_f32_e32 v26, v41, v44
	s_nop 1
	v_add_f32_dpp v26, v26, v26 quad_perm:[1,0,3,2] row_mask:0xf bank_mask:0xf bound_ctrl:1
	s_nop 1
	v_add_f32_dpp v26, v26, v26 quad_perm:[2,3,0,1] row_mask:0xf bank_mask:0xf bound_ctrl:1
	s_nop 1
	v_add_f32_dpp v26, v26, v26 row_ror:4 row_mask:0xf bank_mask:0xf bound_ctrl:1
	s_nop 1
	v_mov_b32_dpp v27, v26 row_ror:8 row_mask:0xf bank_mask:0xf bound_ctrl:1
	s_and_saveexec_b64 s[0:1], s[6:7]
	v_add_f32_e32 v26, v26, v27
	v_add_f32_e32 v26, v48, v26
	ds_write_b32 v99, v26 offset:448
	s_or_b64 exec, exec, s[0:1]
	s_waitcnt vmcnt(6)
	v_mul_f32_e32 v26, v31, v47
	v_fmac_f32_e32 v26, v30, v45
	v_fmac_f32_e32 v26, v32, v46
	v_fmac_f32_e32 v26, v33, v44
	s_nop 1
	v_add_f32_dpp v26, v26, v26 quad_perm:[1,0,3,2] row_mask:0xf bank_mask:0xf bound_ctrl:1
	s_nop 1
	v_add_f32_dpp v26, v26, v26 quad_perm:[2,3,0,1] row_mask:0xf bank_mask:0xf bound_ctrl:1
	s_nop 1
	v_add_f32_dpp v26, v26, v26 row_ror:4 row_mask:0xf bank_mask:0xf bound_ctrl:1
	s_nop 1
	v_mov_b32_dpp v27, v26 row_ror:8 row_mask:0xf bank_mask:0xf bound_ctrl:1
	s_and_saveexec_b64 s[0:1], s[6:7]
	v_add_f32_e32 v26, v26, v27
	v_add_f32_e32 v26, v48, v26
	ds_write_b32 v99, v26 offset:464
	s_or_b64 exec, exec, s[0:1]
	s_waitcnt vmcnt(5)
	v_mul_f32_e32 v23, v23, v47
	v_fmac_f32_e32 v23, v22, v45
	v_fmac_f32_e32 v23, v24, v46
	v_fmac_f32_e32 v23, v25, v44
	s_nop 1
	v_add_f32_dpp v22, v23, v23 quad_perm:[1,0,3,2] row_mask:0xf bank_mask:0xf bound_ctrl:1
	s_nop 1
	v_add_f32_dpp v22, v22, v22 quad_perm:[2,3,0,1] row_mask:0xf bank_mask:0xf bound_ctrl:1
	s_nop 1
	v_add_f32_dpp v22, v22, v22 row_ror:4 row_mask:0xf bank_mask:0xf bound_ctrl:1
	s_nop 1
	v_mov_b32_dpp v23, v22 row_ror:8 row_mask:0xf bank_mask:0xf bound_ctrl:1
	s_and_saveexec_b64 s[0:1], s[6:7]
	v_add_f32_e32 v22, v22, v23
	v_add_f32_e32 v22, v48, v22
	ds_write_b32 v99, v22 offset:480
	s_or_b64 exec, exec, s[0:1]
	s_waitcnt vmcnt(4)
	v_mul_f32_e32 v19, v19, v47
	v_fmac_f32_e32 v19, v18, v45
	v_fmac_f32_e32 v19, v20, v46
	v_fmac_f32_e32 v19, v21, v44
	s_nop 1
	v_add_f32_dpp v18, v19, v19 quad_perm:[1,0,3,2] row_mask:0xf bank_mask:0xf bound_ctrl:1
	s_nop 1
	v_add_f32_dpp v18, v18, v18 quad_perm:[2,3,0,1] row_mask:0xf bank_mask:0xf bound_ctrl:1
	s_nop 1
	v_add_f32_dpp v18, v18, v18 row_ror:4 row_mask:0xf bank_mask:0xf bound_ctrl:1
	s_nop 1
	v_mov_b32_dpp v19, v18 row_ror:8 row_mask:0xf bank_mask:0xf bound_ctrl:1
	s_and_saveexec_b64 s[0:1], s[6:7]
	v_add_f32_e32 v18, v18, v19
	v_add_f32_e32 v18, v48, v18
	ds_write_b32 v99, v18 offset:496
	s_or_b64 exec, exec, s[0:1]
	s_waitcnt lgkmcnt(0)
	ds_read_b64 v[18:19], v100
	s_waitcnt lgkmcnt(0)
; __device__ __forceinline__ float softplus2_(float z2) { return fmaxf(z2, 0.f) + log1pf(exp2f(-fabsf(z2))) * LOG2E; }
; template <int NB>
; __device__ __forceinline__ void sb_decode_task(const Params& P, float* lds, int task) {
;     ...
;     const float z0 = zl[2 * lane], z1 = zl[2 * lane + 1];
;     const float sp0 = softplus2_(z0), sp1 = softplus2_(z1);
	v_cmp_gt_f32_e64 vcc, |v18|, s97
	s_nop 1
	v_cndmask_b32_e32 v21, 0, v103, vcc
	v_sub_f32_e64 v21, v21, |v18|
	v_exp_f32_e32 v21, v21
	v_max_f32_e32 v20, v18, v18
	v_max_f32_e32 v22, 0, v20
	v_cndmask_b32_e32 v20, 0, v102, vcc
	v_ldexp_f32 v23, v21, v20
	v_add_f32_e32 v24, 1.0, v23
	v_add_f32_e32 v20, -1.0, v24
	v_sub_f32_e32 v21, v20, v24
	v_add_f32_e32 v21, 1.0, v21
	v_sub_f32_e32 v20, v23, v20
	v_add_f32_e32 v25, v20, v21
	v_frexp_mant_f32_e32 v20, v24
	v_cmp_gt_f32_e32 vcc, s47, v20
	v_cvt_f64_f32_e32 v[20:21], v24
	v_frexp_exp_i32_f64_e32 v20, v[20:21]
	v_subbrev_co_u32_e32 v20, vcc, 0, v20, vcc
	v_sub_u32_e32 v21, 0, v20
	v_ldexp_f32 v24, v24, v21
	v_ldexp_f32 v21, v25, v21
	v_add_f32_e32 v25, -1.0, v24
	v_add_f32_e32 v26, 1.0, v25
	v_sub_f32_e32 v26, v24, v26
	v_add_f32_e32 v26, v21, v26
	v_add_f32_e32 v27, v25, v26
	v_sub_f32_e32 v25, v25, v27
	v_add_f32_e32 v25, v26, v25
	v_add_f32_e32 v26, 1.0, v24
	v_add_f32_e32 v28, -1.0, v26
	v_sub_f32_e32 v24, v24, v28
	v_add_f32_e32 v21, v21, v24
	v_add_f32_e32 v24, v26, v21
	v_sub_f32_e32 v26, v26, v24
	v_add_f32_e32 v21, v21, v26
	v_rcp_f32_e32 v26, v24
	v_cvt_f32_i32_e32 v20, v20
	v_cmp_neq_f32_e32 vcc, s46, v23
	v_mul_f32_e32 v28, v27, v26
	v_mul_f32_e32 v29, v24, v28
	v_fma_f32 v30, v28, v24, -v29
	v_fmac_f32_e32 v30, v28, v21
	v_add_f32_e32 v31, v29, v30
	v_sub_f32_e32 v32, v27, v31
	v_sub_f32_e32 v27, v27, v32
	v_sub_f32_e32 v29, v31, v29
	v_sub_f32_e32 v27, v27, v31
	v_add_f32_e32 v25, v25, v27
	v_sub_f32_e32 v27, v29, v30
	v_add_f32_e32 v25, v27, v25
	v_add_f32_e32 v27, v32, v25
	v_mul_f32_e32 v29, v26, v27
	v_mul_f32_e32 v30, v24, v29
	v_fma_f32 v24, v29, v24, -v30
	v_fmac_f32_e32 v24, v29, v21
	v_sub_f32_e32 v21, v32, v27
	v_add_f32_e32 v21, v25, v21
	v_add_f32_e32 v25, v30, v24
	v_sub_f32_e32 v31, v27, v25
	v_sub_f32_e32 v27, v27, v31
	v_sub_f32_e32 v30, v25, v30
	v_sub_f32_e32 v25, v27, v25
	v_add_f32_e32 v21, v21, v25
	v_sub_f32_e32 v24, v30, v24
	v_add_f32_e32 v21, v24, v21
	v_add_f32_e32 v24, v28, v29
	v_add_f32_e32 v21, v31, v21
	v_sub_f32_e32 v25, v24, v28
	v_mul_f32_e32 v21, v26, v21
	v_sub_f32_e32 v25, v29, v25
	v_add_f32_e32 v21, v25, v21
	v_mul_f32_e32 v28, 0x3f317218, v20
	v_add_f32_e32 v25, v24, v21
	v_fma_f32 v29, v20, s95, -v28
	v_mul_f32_e32 v26, v25, v25
	v_fmac_f32_e32 v29, 0xb102e308, v20
	v_sub_f32_e32 v20, v25, v24
	v_fmamk_f32 v27, v26, 0x3e9b6dac, v1
	v_sub_f32_e32 v20, v21, v20
	v_add_f32_e32 v21, v28, v29
	v_fmaak_f32 v27, v26, v27, 0x3f2aaada
	v_sub_f32_e32 v24, v21, v28
	v_ldexp_f32 v28, v25, 1
	v_mul_f32_e32 v25, v25, v26
	v_mul_f32_e32 v25, v25, v27
	v_add_f32_e32 v26, v28, v25
	v_sub_f32_e32 v27, v26, v28
	v_ldexp_f32 v20, v20, 1
	v_sub_f32_e32 v25, v25, v27
	v_add_f32_e32 v20, v20, v25
	v_add_f32_e32 v25, v26, v20
	v_sub_f32_e32 v26, v25, v26
	v_sub_f32_e32 v20, v20, v26
	v_add_f32_e32 v26, v21, v25
	v_sub_f32_e32 v27, v26, v21
	v_sub_f32_e32 v28, v26, v27
	v_sub_f32_e32 v24, v29, v24
	v_sub_f32_e32 v21, v21, v28
	v_sub_f32_e32 v25, v25, v27
	v_add_f32_e32 v21, v25, v21
	v_add_f32_e32 v25, v24, v20
	v_sub_f32_e32 v27, v25, v24
	v_sub_f32_e32 v28, v25, v27
	v_sub_f32_e32 v24, v24, v28
	v_sub_f32_e32 v20, v20, v27
	v_add_f32_e32 v21, v25, v21
	v_add_f32_e32 v20, v20, v24
	v_add_f32_e32 v24, v26, v21
	v_sub_f32_e32 v25, v24, v26
	v_sub_f32_e32 v21, v21, v25
	v_add_f32_e32 v20, v20, v21
	v_add_f32_e32 v20, v24, v20
	v_cndmask_b32_e32 v20, v104, v20, vcc
	v_cmp_lt_f32_e64 vcc, |v23|, s45
	s_nop 1
	v_cndmask_b32_e32 v20, v20, v23, vcc
	v_cmp_gt_f32_e64 vcc, |v19|, s97
	v_fmac_f32_e32 v22, 0x3fb8aa3b, v20
	v_max_f32_e32 v20, v19, v19
	v_cndmask_b32_e32 v21, 0, v103, vcc
	v_sub_f32_e64 v21, v21, |v19|
	v_exp_f32_e32 v21, v21
	v_max_f32_e32 v23, 0, v20
	v_cndmask_b32_e32 v20, 0, v102, vcc
	v_sub_f32_e32 v18, v18, v22
	v_ldexp_f32 v24, v21, v20
	v_add_f32_e32 v25, 1.0, v24
	v_add_f32_e32 v20, -1.0, v25
	v_sub_f32_e32 v21, v20, v25
	v_add_f32_e32 v21, 1.0, v21
	v_sub_f32_e32 v20, v24, v20
	v_add_f32_e32 v26, v20, v21
	v_frexp_mant_f32_e32 v20, v25
	v_cmp_gt_f32_e32 vcc, s47, v20
	v_cvt_f64_f32_e32 v[20:21], v25
	v_frexp_exp_i32_f64_e32 v20, v[20:21]
	v_subbrev_co_u32_e32 v20, vcc, 0, v20, vcc
	v_sub_u32_e32 v21, 0, v20
	v_ldexp_f32 v25, v25, v21
	v_ldexp_f32 v21, v26, v21
	v_add_f32_e32 v26, -1.0, v25
	v_add_f32_e32 v27, 1.0, v26
	v_sub_f32_e32 v27, v25, v27
	v_add_f32_e32 v27, v21, v27
	v_add_f32_e32 v28, v26, v27
	v_sub_f32_e32 v26, v26, v28
	v_add_f32_e32 v26, v27, v26
	v_add_f32_e32 v27, 1.0, v25
	v_add_f32_e32 v29, -1.0, v27
	v_sub_f32_e32 v25, v25, v29
	v_add_f32_e32 v21, v21, v25
	v_add_f32_e32 v25, v27, v21
	v_sub_f32_e32 v27, v27, v25
	v_add_f32_e32 v21, v21, v27
	v_rcp_f32_e32 v27, v25
	v_cvt_f32_i32_e32 v20, v20
	v_cmp_neq_f32_e32 vcc, s46, v24
	v_mul_f32_e32 v29, v28, v27
	v_mul_f32_e32 v30, v25, v29
	v_fma_f32 v31, v29, v25, -v30
	v_fmac_f32_e32 v31, v29, v21
	v_add_f32_e32 v32, v30, v31
	v_sub_f32_e32 v33, v28, v32
	v_sub_f32_e32 v28, v28, v33
	v_sub_f32_e32 v30, v32, v30
	v_sub_f32_e32 v28, v28, v32
	v_add_f32_e32 v26, v26, v28
	v_sub_f32_e32 v28, v30, v31
	v_add_f32_e32 v26, v28, v26
	v_add_f32_e32 v28, v33, v26
	v_mul_f32_e32 v30, v27, v28
	v_mul_f32_e32 v31, v25, v30
	v_fma_f32 v25, v30, v25, -v31
	v_fmac_f32_e32 v25, v30, v21
	v_sub_f32_e32 v21, v33, v28
	v_add_f32_e32 v21, v26, v21
	v_add_f32_e32 v26, v31, v25
	v_sub_f32_e32 v32, v28, v26
	v_sub_f32_e32 v28, v28, v32
	v_sub_f32_e32 v31, v26, v31
	v_sub_f32_e32 v26, v28, v26
	v_add_f32_e32 v21, v21, v26
	v_sub_f32_e32 v25, v31, v25
	v_add_f32_e32 v21, v25, v21
	v_add_f32_e32 v25, v29, v30
	v_add_f32_e32 v21, v32, v21
	v_sub_f32_e32 v26, v25, v29
	v_mul_f32_e32 v21, v27, v21
; __device__ __forceinline__ float softplus2_(float z2) { return fmaxf(z2, 0.f) + log1pf(exp2f(-fabsf(z2))) * LOG2E; }
; template <int NB>
; __device__ __forceinline__ void sb_decode_task(const Params& P, float* lds, int task) {
;     ...
;     const float sp0 = softplus2_(z0), sp1 = softplus2_(z1);
;     float incl = sp0 + sp1;
; #pragma unroll
;     for (int off = 1; off < 64; off <<= 1) { const float t = __shfl_down(incl, off); if (lane + off < 64) incl += t; }
;     const float excl = incl - (sp0 + sp1);
;     wl[2 * lane] = exp2f(z0 - sp0 - (excl + sp1));
;     wl[2 * lane + 1] = exp2f(z1 - sp1 - excl);
;     const float Ltot = __shfl(incl, 0);
;     asm volatile("s_waitcnt lgkmcnt(0)" ::: "memory");
;     __builtin_amdgcn_wave_barrier();
;     float4 o4 = make_float4(0.f, 0.f, 0.f, 0.f);
; #pragma unroll
;     for (int vb = 0; vb < NBT; ++vb) {
;         if (vb + 1 < NBT) {
; #pragma unroll
;             for (int i = 0; i < NB; ++i) nx[i] = *(const float4*)(Vp + (size_t)(4 * NB * (vb + 1) + 4 * i + g) * (SH * HD)); }
; #pragma unroll
;         for (int i = 0; i < NB; ++i) { const float w = wl[4 * NB * vb + 4 * i + g]; o4.x += w * cur[i].x; o4.y += w * cur[i].y; o4.z += w * cur[i].z; o4.w += w * cur[i].w; }
	v_sub_f32_e32 v26, v30, v26
	v_add_f32_e32 v21, v26, v21
	v_mul_f32_e32 v29, 0x3f317218, v20
	v_add_f32_e32 v26, v25, v21
	v_fma_f32 v30, v20, s95, -v29
	v_mul_f32_e32 v27, v26, v26
	v_fmac_f32_e32 v30, 0xb102e308, v20
	v_sub_f32_e32 v20, v26, v25
	v_fmamk_f32 v28, v27, 0x3e9b6dac, v1
	v_sub_f32_e32 v20, v21, v20
	v_add_f32_e32 v21, v29, v30
	v_fmaak_f32 v28, v27, v28, 0x3f2aaada
	v_sub_f32_e32 v25, v21, v29
	v_ldexp_f32 v29, v26, 1
	v_mul_f32_e32 v26, v26, v27
	v_mul_f32_e32 v26, v26, v28
	v_add_f32_e32 v27, v29, v26
	v_sub_f32_e32 v28, v27, v29
	v_ldexp_f32 v20, v20, 1
	v_sub_f32_e32 v26, v26, v28
	v_add_f32_e32 v20, v20, v26
	v_add_f32_e32 v26, v27, v20
	v_sub_f32_e32 v27, v26, v27
	v_sub_f32_e32 v20, v20, v27
	v_add_f32_e32 v27, v21, v26
	v_sub_f32_e32 v28, v27, v21
	v_sub_f32_e32 v29, v27, v28
	v_sub_f32_e32 v25, v30, v25
	v_sub_f32_e32 v21, v21, v29
	v_sub_f32_e32 v26, v26, v28
	v_add_f32_e32 v21, v26, v21
	v_add_f32_e32 v26, v25, v20
	v_sub_f32_e32 v28, v26, v25
	v_sub_f32_e32 v29, v26, v28
	v_sub_f32_e32 v25, v25, v29
	v_sub_f32_e32 v20, v20, v28
	v_add_f32_e32 v21, v26, v21
	v_add_f32_e32 v20, v20, v25
	v_add_f32_e32 v25, v27, v21
	v_sub_f32_e32 v26, v25, v27
	v_sub_f32_e32 v21, v21, v26
	v_add_f32_e32 v20, v20, v21
	v_add_f32_e32 v20, v25, v20
	v_cndmask_b32_e32 v20, v104, v20, vcc
	v_cmp_lt_f32_e64 vcc, |v24|, s45
	v_and_b32_e32 v21, 63, v105
	s_nop 0
	v_cndmask_b32_e32 v20, v20, v24, vcc
	v_cmp_ne_u32_e32 vcc, 63, v21
	v_fmac_f32_e32 v23, 0x3fb8aa3b, v20
	v_add_f32_e32 v20, v22, v23
	v_addc_co_u32_e32 v24, vcc, 0, v105, vcc
	v_lshlrev_b32_e32 v46, 2, v24
	ds_bpermute_b32 v24, v46, v20
	v_cmp_gt_u32_e32 vcc, 62, v21
	v_sub_f32_e32 v19, v19, v23
	s_waitcnt lgkmcnt(0)
	v_add_f32_e32 v24, v20, v24
	v_cndmask_b32_e64 v25, 0, 2, vcc
	v_cndmask_b32_e64 v24, v24, v20, s[8:9]
	v_add_lshl_u32 v47, v25, v105, 2
	ds_bpermute_b32 v25, v47, v24
	v_cmp_gt_u32_e32 vcc, 60, v21
	s_waitcnt lgkmcnt(0)
	v_add_f32_e32 v25, v24, v25
	v_cndmask_b32_e64 v24, v24, v25, s[10:11]
	v_cndmask_b32_e64 v25, 0, 4, vcc
	v_add_lshl_u32 v48, v25, v105, 2
	ds_bpermute_b32 v25, v48, v24
	v_cmp_gt_u32_e32 vcc, 56, v21
	s_waitcnt lgkmcnt(0)
	v_add_f32_e32 v25, v24, v25
	v_cndmask_b32_e64 v24, v24, v25, s[12:13]
	v_cndmask_b32_e64 v25, 0, 8, vcc
	v_add_lshl_u32 v49, v25, v105, 2
	ds_bpermute_b32 v25, v49, v24
	v_cmp_gt_u32_e32 vcc, 48, v21
	s_waitcnt lgkmcnt(0)
	v_add_f32_e32 v25, v24, v25
	v_cndmask_b32_e64 v21, 0, 16, vcc
	v_cndmask_b32_e64 v24, v24, v25, s[14:15]
	v_add_lshl_u32 v50, v21, v105, 2
	ds_bpermute_b32 v21, v50, v24
	s_waitcnt lgkmcnt(0)
	v_add_f32_e32 v21, v24, v21
	v_cndmask_b32_e64 v21, v24, v21, s[16:17]
	v_lshlrev_b32_e32 v24, 2, v105
	v_or_b32_e32 v51, 0x80, v24
	ds_bpermute_b32 v25, v51, v21
	v_and_b32_e32 v44, 0x100, v24
	s_waitcnt lgkmcnt(0)
	v_add_f32_e32 v25, v21, v25
	v_cndmask_b32_e64 v31, v21, v25, s[18:19]
	v_sub_f32_e32 v20, v31, v20
	v_add_f32_e32 v21, v23, v20
	v_sub_f32_e32 v18, v18, v21
	v_cmp_gt_f32_e32 vcc, s24, v18
	v_sub_f32_e32 v19, v19, v20
	s_nop 0
	v_cndmask_b32_e32 v21, 0, v103, vcc
	v_add_f32_e32 v18, v18, v21
	v_cndmask_b32_e32 v21, 0, v102, vcc
	v_cmp_gt_f32_e32 vcc, s24, v19
	v_exp_f32_e32 v18, v18
	s_nop 0
	v_cndmask_b32_e32 v20, 0, v103, vcc
	v_add_f32_e32 v19, v19, v20
	v_exp_f32_e32 v19, v19
	v_cndmask_b32_e32 v20, 0, v102, vcc
	v_ldexp_f32 v18, v18, v21
	v_ldexp_f32 v19, v19, v20
	ds_write_b64 v100, v[18:19] offset:512
	s_waitcnt lgkmcnt(0)
	ds_read2_b32 v[18:19], v99 offset0:128 offset1:132
	ds_read2_b32 v[32:33], v99 offset0:136 offset1:140
	ds_read2_b32 v[62:63], v99 offset0:144 offset1:148
	ds_read2_b32 v[64:65], v99 offset0:152 offset1:156
	ds_read2_b32 v[66:67], v99 offset0:160 offset1:164
	ds_read2_b32 v[68:69], v99 offset0:168 offset1:172
	s_waitcnt vmcnt(3) lgkmcnt(5)
	v_pk_fma_f32 v[36:37], v[14:15], v[18:19], 0 op_sel_hi:[1,0,0]
	v_add_co_u32_e32 v14, vcc, s89, v34
	v_pk_fma_f32 v[60:61], v[16:17], v[18:19], 0 op_sel_hi:[1,0,0]
	s_nop 0
	v_addc_co_u32_e32 v15, vcc, 0, v35, vcc
	v_add_co_u32_e32 v18, vcc, s92, v34
	v_mov_b32_e32 v30, v19
	s_nop 0
	v_addc_co_u32_e32 v19, vcc, 0, v35, vcc
	v_add_co_u32_e32 v22, vcc, s93, v34
	s_waitcnt vmcnt(2)
	v_pk_fma_f32 v[2:3], v[2:3], v[30:31], v[36:37] op_sel_hi:[1,0,1]
	v_addc_co_u32_e32 v23, vcc, 0, v35, vcc
	v_add_co_u32_e32 v26, vcc, s96, v34
	s_waitcnt vmcnt(1) lgkmcnt(4)
	v_pk_fma_f32 v[2:3], v[6:7], v[32:33], v[2:3] op_sel_hi:[1,0,1]
	v_addc_co_u32_e32 v27, vcc, 0, v35, vcc
	v_add_co_u32_e32 v6, vcc, s44, v34
	global_load_dwordx4 v[14:17], v[14:15], off nt
	s_nop 0
	v_addc_co_u32_e32 v7, vcc, 0, v35, vcc
	global_load_dwordx4 v[18:21], v[18:19], off offset:2048 nt
	v_mov_b32_e32 v70, v33
	global_load_dwordx4 v[36:39], v[6:7], off nt
	v_add_co_u32_e32 v6, vcc, s26, v34
	global_load_dwordx4 v[22:25], v[22:23], off nt
	s_nop 0
	v_addc_co_u32_e32 v7, vcc, 0, v35, vcc
	global_load_dwordx4 v[26:29], v[26:27], off offset:2048 nt
	s_waitcnt vmcnt(5)
	v_pk_fma_f32 v[2:3], v[10:11], v[70:71], v[2:3] op_sel_hi:[1,0,1]
	global_load_dwordx4 v[40:43], v[6:7], off offset:2048 nt
	v_add_co_u32_e32 v6, vcc, s27, v34
	s_waitcnt lgkmcnt(2)
	v_mov_b32_e32 v10, v65
	v_addc_co_u32_e32 v7, vcc, 0, v35, vcc
	global_load_dwordx4 v[52:55], v[6:7], off nt
	v_add_co_u32_e32 v6, vcc, s28, v34
	s_waitcnt vmcnt(6)
	v_pk_fma_f32 v[2:3], v[14:15], v[62:63], v[2:3] op_sel_hi:[1,0,1]
	v_addc_co_u32_e32 v7, vcc, 0, v35, vcc
	global_load_dwordx4 v[56:59], v[6:7], off offset:2048 nt
	v_mov_b32_e32 v6, v63
	s_waitcnt vmcnt(6)
	v_pk_fma_f32 v[2:3], v[18:19], v[6:7], v[2:3] op_sel_hi:[1,0,1]
	s_waitcnt lgkmcnt(1)
	v_mov_b32_e32 v14, v67
	s_waitcnt lgkmcnt(0)
	v_mov_b32_e32 v18, v69
	s_waitcnt vmcnt(4)
; template <int NB>
; __device__ __forceinline__ void sb_decode_task(const Params& P, float* lds, int task) {
;     ...
;     for (int vb = 0; vb < NBT; ++vb) {
;         if (vb + 1 < NBT) {
; #pragma unroll
;             for (int i = 0; i < NB; ++i) nx[i] = *(const float4*)(Vp + (size_t)(4 * NB * (vb + 1) + 4 * i + g) * (SH * HD)); }
; #pragma unroll
;         for (int i = 0; i < NB; ++i) { const float w = wl[4 * NB * vb + 4 * i + g]; o4.x += w * cur[i].x; o4.y += w * cur[i].y; o4.z += w * cur[i].z; o4.w += w * cur[i].w; }
; #pragma unroll
;         for (int i = 0; i < NB; ++i) cur[i] = nx[i];
;     }
	v_pk_fma_f32 v[2:3], v[22:23], v[64:65], v[2:3] op_sel_hi:[1,0,1]
	s_waitcnt vmcnt(3)
	v_pk_fma_f32 v[2:3], v[26:27], v[10:11], v[2:3] op_sel_hi:[1,0,1]
	s_nop 0
	v_pk_fma_f32 v[2:3], v[36:37], v[66:67], v[2:3] op_sel_hi:[1,0,1]
	s_waitcnt vmcnt(2)
	v_pk_fma_f32 v[2:3], v[40:41], v[14:15], v[2:3] op_sel_hi:[1,0,1]
	s_waitcnt vmcnt(1)
	v_pk_fma_f32 v[2:3], v[52:53], v[68:69], v[2:3] op_sel_hi:[1,0,1]
	s_waitcnt vmcnt(0)
	v_pk_fma_f32 v[56:57], v[56:57], v[18:19], v[2:3] op_sel_hi:[1,0,1]
	v_pk_fma_f32 v[2:3], v[4:5], v[30:31], v[60:61] op_sel_hi:[1,0,1]
	s_nop 0
	v_pk_fma_f32 v[2:3], v[8:9], v[32:33], v[2:3] op_sel_hi:[1,0,1]
	ds_read2_b32 v[8:9], v99 offset0:176 offset1:180
	v_pk_fma_f32 v[2:3], v[12:13], v[70:71], v[2:3] op_sel_hi:[1,0,1]
	s_waitcnt lgkmcnt(0)
	v_mov_b32_e32 v76, v9
	v_pk_fma_f32 v[2:3], v[16:17], v[62:63], v[2:3] op_sel_hi:[1,0,1]
	s_nop 0
	v_pk_fma_f32 v[2:3], v[20:21], v[6:7], v[2:3] op_sel_hi:[1,0,1]
	s_nop 0
	v_pk_fma_f32 v[2:3], v[24:25], v[64:65], v[2:3] op_sel_hi:[1,0,1]
	s_nop 0
	v_pk_fma_f32 v[2:3], v[28:29], v[10:11], v[2:3] op_sel_hi:[1,0,1]
	s_nop 0
	v_pk_fma_f32 v[2:3], v[38:39], v[66:67], v[2:3] op_sel_hi:[1,0,1]
	s_nop 0
	v_pk_fma_f32 v[2:3], v[42:43], v[14:15], v[2:3] op_sel_hi:[1,0,1]
	s_nop 0
	v_pk_fma_f32 v[2:3], v[54:55], v[68:69], v[2:3] op_sel_hi:[1,0,1]
	s_nop 0
	v_pk_fma_f32 v[6:7], v[58:59], v[18:19], v[2:3] op_sel_hi:[1,0,1]
	v_add_co_u32_e32 v2, vcc, s25, v34
	s_nop 1
	v_addc_co_u32_e32 v3, vcc, 0, v35, vcc
	global_load_dwordx4 v[10:13], v[2:3], off nt
	v_add_co_u32_e32 v2, vcc, s43, v34
	s_waitcnt vmcnt(0)
	v_pk_fma_f32 v[10:11], v[10:11], v[8:9], v[56:57] op_sel_hi:[1,0,1]
	v_addc_co_u32_e32 v3, vcc, 0, v35, vcc
	global_load_dwordx4 v[14:17], v[2:3], off offset:2048 nt
	v_add_co_u32_e32 v2, vcc, s80, v34
	ds_read2_b32 v[32:33], v99 offset0:184 offset1:188
	ds_read2_b32 v[68:69], v99 offset0:192 offset1:196
	ds_read2_b32 v[70:71], v99 offset0:200 offset1:204
	ds_read2_b32 v[72:73], v99 offset0:208 offset1:212
	ds_read2_b32 v[74:75], v99 offset0:216 offset1:220
	v_addc_co_u32_e32 v3, vcc, 0, v35, vcc
	v_add_co_u32_e32 v18, vcc, s29, v34
	global_load_dwordx4 v[2:5], v[2:3], off offset:2048 nt
	s_nop 0
	v_addc_co_u32_e32 v19, vcc, 0, v35, vcc
	v_add_co_u32_e32 v22, vcc, s68, v34
	global_load_dwordx4 v[18:21], v[18:19], off nt
	s_nop 0
	v_addc_co_u32_e32 v23, vcc, 0, v35, vcc
	v_add_co_u32_e32 v26, vcc, s69, v34
	global_load_dwordx4 v[22:25], v[22:23], off offset:2048 nt
	s_nop 0
	v_addc_co_u32_e32 v27, vcc, 0, v35, vcc
	v_add_co_u32_e32 v36, vcc, s70, v34
	global_load_dwordx4 v[26:29], v[26:27], off nt
	s_nop 0
	v_addc_co_u32_e32 v37, vcc, 0, v35, vcc
	v_add_co_u32_e32 v40, vcc, s71, v34
	global_load_dwordx4 v[36:39], v[36:37], off offset:2048 nt
	s_nop 0
	v_addc_co_u32_e32 v41, vcc, 0, v35, vcc
	v_add_co_u32_e32 v52, vcc, s72, v34
	global_load_dwordx4 v[40:43], v[40:41], off nt
	s_nop 0
	v_addc_co_u32_e32 v53, vcc, 0, v35, vcc
	global_load_dwordx4 v[52:55], v[52:53], off offset:2048 nt
	v_pk_fma_f32 v[6:7], v[12:13], v[8:9], v[6:7] op_sel_hi:[1,0,1]
	s_waitcnt lgkmcnt(4)
	v_mov_b32_e32 v78, v33
	s_waitcnt lgkmcnt(0)
	v_mov_b32_e32 v30, v75
	s_waitcnt vmcnt(7)
	v_pk_fma_f32 v[10:11], v[14:15], v[76:77], v[10:11] op_sel_hi:[1,0,1]
	v_add_co_u32_e32 v14, vcc, s73, v34
	v_pk_fma_f32 v[6:7], v[16:17], v[76:77], v[6:7] op_sel_hi:[1,0,1]
	s_nop 0
	v_addc_co_u32_e32 v15, vcc, 0, v35, vcc
	global_load_dwordx4 v[56:59], v[14:15], off nt
	v_add_co_u32_e32 v14, vcc, s74, v34
	s_nop 1
	v_addc_co_u32_e32 v15, vcc, 0, v35, vcc
	global_load_dwordx4 v[60:63], v[14:15], off offset:2048 nt
	v_add_co_u32_e32 v14, vcc, s75, v34
	s_nop 1
	v_addc_co_u32_e32 v15, vcc, 0, v35, vcc
	global_load_dwordx4 v[64:67], v[14:15], off nt
	s_waitcnt vmcnt(8)
	v_pk_fma_f32 v[10:11], v[18:19], v[32:33], v[10:11] op_sel_hi:[1,0,1]
	v_pk_fma_f32 v[6:7], v[20:21], v[32:33], v[6:7] op_sel_hi:[1,0,1]
	s_waitcnt vmcnt(7)
	v_pk_fma_f32 v[10:11], v[22:23], v[78:79], v[10:11] op_sel_hi:[1,0,1]
	v_pk_fma_f32 v[6:7], v[24:25], v[78:79], v[6:7] op_sel_hi:[1,0,1]
	v_mov_b32_e32 v14, v69
	s_waitcnt vmcnt(6)
	v_pk_fma_f32 v[10:11], v[26:27], v[68:69], v[10:11] op_sel_hi:[1,0,1]
	v_pk_fma_f32 v[6:7], v[28:29], v[68:69], v[6:7] op_sel_hi:[1,0,1]
	v_mov_b32_e32 v18, v71
	v_mov_b32_e32 v22, v73
	s_waitcnt vmcnt(5)
	v_pk_fma_f32 v[10:11], v[36:37], v[14:15], v[10:11] op_sel_hi:[1,0,1]
	v_pk_fma_f32 v[6:7], v[38:39], v[14:15], v[6:7] op_sel_hi:[1,0,1]
	ds_read2_b32 v[38:39], v99 offset0:224 offset1:228
	ds_read2_b32 v[32:33], v99 offset0:232 offset1:236
	s_waitcnt vmcnt(4)
; template <int NB>
; __device__ __forceinline__ void sb_decode_task(const Params& P, float* lds, int task) {
;     ...
;         for (int i = 0; i < NB; ++i) { const float w = wl[4 * NB * vb + 4 * i + g]; o4.x += w * cur[i].x; o4.y += w * cur[i].y; o4.z += w * cur[i].z; o4.w += w * cur[i].w; }
; #pragma unroll
;         for (int i = 0; i < NB; ++i) cur[i] = nx[i];
;     }
; #pragma unroll
;     for (int off = 16; off < 64; off <<= 1) { o4.x += __shfl_xor(o4.x, off); o4.y += __shfl_xor(o4.y, off); o4.z += __shfl_xor(o4.z, off); o4.w += __shfl_xor(o4.w, off); }
;     if (g == 0) *(float4*)(dpart + (size_t)task * HD + 4 * c) = o4;
;     if (lane == 0) dl[task] = Ltot;
	v_pk_fma_f32 v[10:11], v[40:41], v[70:71], v[10:11] op_sel_hi:[1,0,1]
	v_pk_fma_f32 v[6:7], v[42:43], v[70:71], v[6:7] op_sel_hi:[1,0,1]
	s_waitcnt vmcnt(3)
	v_pk_fma_f32 v[10:11], v[52:53], v[18:19], v[10:11] op_sel_hi:[1,0,1]
	v_pk_fma_f32 v[6:7], v[54:55], v[18:19], v[6:7] op_sel_hi:[1,0,1]
	s_waitcnt vmcnt(2)
	v_pk_fma_f32 v[10:11], v[56:57], v[72:73], v[10:11] op_sel_hi:[1,0,1]
	v_pk_fma_f32 v[6:7], v[58:59], v[72:73], v[6:7] op_sel_hi:[1,0,1]
	s_waitcnt vmcnt(1)
	v_pk_fma_f32 v[10:11], v[60:61], v[22:23], v[10:11] op_sel_hi:[1,0,1]
	v_pk_fma_f32 v[6:7], v[62:63], v[22:23], v[6:7] op_sel_hi:[1,0,1]
	s_waitcnt vmcnt(0)
	v_pk_fma_f32 v[26:27], v[64:65], v[74:75], v[10:11] op_sel_hi:[1,0,1]
	v_pk_fma_f32 v[36:37], v[66:67], v[74:75], v[6:7] op_sel_hi:[1,0,1]
	v_add_co_u32_e32 v6, vcc, s81, v34
	v_and_b32_e32 v10, 64, v105
	s_nop 0
	v_addc_co_u32_e32 v7, vcc, 0, v35, vcc
	v_add_u32_e32 v60, 64, v10
	v_xor_b32_e32 v10, 16, v105
	v_cmp_lt_i32_e32 vcc, v10, v60
	global_load_dwordx4 v[6:9], v[6:7], off nt
	ds_read2_b32 v[42:43], v99 offset0:240 offset1:244
	ds_read2_b32 v[40:41], v99 offset0:248 offset1:252
	v_cndmask_b32_e32 v10, v105, v10, vcc
	v_lshlrev_b32_e32 v45, 2, v10
	v_add_co_u32_e32 v10, vcc, s82, v34
	v_pk_fma_f32 v[2:3], v[2:3], v[30:31], v[26:27] op_sel_hi:[1,0,1]
	s_nop 0
	v_addc_co_u32_e32 v11, vcc, 0, v35, vcc
	v_add_co_u32_e32 v14, vcc, s83, v34
	global_load_dwordx4 v[10:13], v[10:11], off offset:2048 nt
	s_nop 0
	v_addc_co_u32_e32 v15, vcc, 0, v35, vcc
	v_add_co_u32_e32 v18, vcc, s84, v34
	global_load_dwordx4 v[14:17], v[14:15], off nt
	s_nop 0
	v_addc_co_u32_e32 v19, vcc, 0, v35, vcc
	v_add_co_u32_e32 v22, vcc, s85, v34
	global_load_dwordx4 v[18:21], v[18:19], off offset:2048 nt
	s_nop 0
	v_addc_co_u32_e32 v23, vcc, 0, v35, vcc
	v_add_co_u32_e32 v26, vcc, s86, v34
	global_load_dwordx4 v[22:25], v[22:23], off nt
	s_nop 0
	v_addc_co_u32_e32 v27, vcc, 0, v35, vcc
	v_add_co_u32_e32 v52, vcc, s87, v34
	global_load_dwordx4 v[26:29], v[26:27], off offset:2048 nt
	s_nop 0
	v_addc_co_u32_e32 v53, vcc, 0, v35, vcc
	v_add_co_u32_e32 v34, vcc, s88, v34
	global_load_dwordx4 v[52:55], v[52:53], off nt
	s_nop 0
	v_addc_co_u32_e32 v35, vcc, 0, v35, vcc
	global_load_dwordx4 v[56:59], v[34:35], off offset:2048 nt
	v_pk_fma_f32 v[4:5], v[4:5], v[30:31], v[36:37] op_sel_hi:[1,0,1]
	s_waitcnt vmcnt(7) lgkmcnt(3)
	v_pk_fma_f32 v[2:3], v[6:7], v[38:39], v[2:3] op_sel_hi:[1,0,1]
	v_mov_b32_e32 v6, v39
	v_pk_fma_f32 v[4:5], v[8:9], v[38:39], v[4:5] op_sel_hi:[1,0,1]
	s_waitcnt vmcnt(6)
	v_pk_fma_f32 v[2:3], v[10:11], v[6:7], v[2:3] op_sel_hi:[1,0,1]
	v_pk_fma_f32 v[4:5], v[12:13], v[6:7], v[4:5] op_sel_hi:[1,0,1]
	s_waitcnt lgkmcnt(2)
	v_mov_b32_e32 v10, v33
	s_waitcnt vmcnt(5)
	v_pk_fma_f32 v[4:5], v[16:17], v[32:33], v[4:5] op_sel_hi:[1,0,1]
	v_pk_fma_f32 v[2:3], v[14:15], v[32:33], v[2:3] op_sel_hi:[1,0,1]
	s_waitcnt lgkmcnt(1)
	v_mov_b32_e32 v14, v43
	s_waitcnt vmcnt(4)
	v_pk_fma_f32 v[4:5], v[20:21], v[10:11], v[4:5] op_sel_hi:[1,0,1]
	v_pk_fma_f32 v[2:3], v[18:19], v[10:11], v[2:3] op_sel_hi:[1,0,1]
	s_waitcnt lgkmcnt(0)
	v_mov_b32_e32 v18, v41
	ds_bpermute_b32 v10, v44, v31
	s_waitcnt vmcnt(3)
	v_pk_fma_f32 v[4:5], v[24:25], v[42:43], v[4:5] op_sel_hi:[1,0,1]
	v_pk_fma_f32 v[2:3], v[22:23], v[42:43], v[2:3] op_sel_hi:[1,0,1]
	s_waitcnt vmcnt(2)
	v_pk_fma_f32 v[4:5], v[28:29], v[14:15], v[4:5] op_sel_hi:[1,0,1]
	v_pk_fma_f32 v[2:3], v[26:27], v[14:15], v[2:3] op_sel_hi:[1,0,1]
	s_waitcnt vmcnt(1)
	v_pk_fma_f32 v[4:5], v[54:55], v[40:41], v[4:5] op_sel_hi:[1,0,1]
	v_pk_fma_f32 v[2:3], v[52:53], v[40:41], v[2:3] op_sel_hi:[1,0,1]
	s_waitcnt vmcnt(0)
	v_pk_fma_f32 v[4:5], v[58:59], v[18:19], v[4:5] op_sel_hi:[1,0,1]
	ds_bpermute_b32 v6, v45, v4
	ds_bpermute_b32 v7, v45, v5
	v_pk_fma_f32 v[2:3], v[56:57], v[18:19], v[2:3] op_sel_hi:[1,0,1]
	ds_bpermute_b32 v22, v45, v2
	ds_bpermute_b32 v23, v45, v3
	s_waitcnt lgkmcnt(2)
	v_pk_add_f32 v[4:5], v[4:5], v[6:7]
	v_xor_b32_e32 v6, 32, v105
	v_cmp_lt_i32_e32 vcc, v6, v60
	s_waitcnt lgkmcnt(0)
	v_pk_add_f32 v[2:3], v[2:3], v[22:23]
	v_cndmask_b32_e32 v6, v105, v6, vcc
	v_lshlrev_b32_e32 v52, 2, v6
	ds_bpermute_b32 v6, v52, v2
	ds_bpermute_b32 v7, v52, v3
	ds_bpermute_b32 v8, v52, v4
	ds_bpermute_b32 v9, v52, v5
	s_and_saveexec_b64 s[0:1], s[20:21]
	s_cbranch_execz .LBB0_1485
	s_ashr_i32 s35, s34, 31
	s_lshl_b64 s[2:3], s[34:35], 8
	v_lshl_add_u64 v[12:13], v[88:89], 0, s[2:3]
	s_waitcnt lgkmcnt(2)
	v_pk_add_f32 v[2:3], v[2:3], v[6:7]
	s_waitcnt lgkmcnt(0)
	v_pk_add_f32 v[4:5], v[4:5], v[8:9]
	global_store_dwordx4 v[12:13], v[2:5], off

; __device__ __forceinline__ float bf2f(bf16_t b) { return __uint_as_float(((unsigned)b) << 16); }
; template <int NB>
; __device__ __forceinline__ void sb_decode_task(const Params& P, float* lds, int task) {
;     ...
;     constexpr int NBT = 32 / NB;
;     const int h = task % SH, bj = task / SH, b = bj / NPAGES;
;     const int page = P.page_table[bj];
;     const float* Kp = P.cache_k + ((size_t)page * PAGE * SH + h) * HD + 4 * c;
;     const float* Vp = P.cache_v + ((size_t)page * PAGE * SH + h) * HD + 4 * c;
;     const bf16_t* qp = qb + (size_t)(NTOK + b) * SBW + h * 64 + 4 * c;
;     const float q0 = bf2f(qp[0]), q1 = bf2f(qp[1]), q2 = bf2f(qp[2]), q3 = bf2f(qp[3]);
;     const float bias = P.sb_bias[h] * LOG2E;
;     float4 cur[NB], nx[NB];
; #pragma unroll
;     for (int i = 0; i < NB; ++i) cur[i] = *(const float4*)(Kp + (size_t)(4 * i + g) * (SH * HD));
; #pragma unroll
;     for (int kb = 0; kb < NBT; ++kb) {
;         const float* np = (kb + 1 < NBT) ? Kp + (size_t)(4 * NB * (kb + 1)) * (SH * HD) : Vp;
; #pragma unroll
;         for (int i = 0; i < NB; ++i) nx[i] = *(const float4*)(np + (size_t)(4 * i + g) * (SH * HD));
; #pragma unroll
;         for (int i = 0; i < NB; ++i) { const int s = 4 * NB * kb + 4 * i + g;
;             float part = q0 * cur[i].x + q1 * cur[i].y + q2 * cur[i].z + q3 * cur[i].w; part = sum16(part);
;             if (c == 0) zl[s] = part + bias; }
.LBB0_1487:
	s_or_b64 exec, exec, s[0:1]
	v_readlane_b32 s36, v252, 48
	s_add_i32 s34, s34, 1
	v_readlane_b32 s37, v252, 49
	s_mul_hi_i32 s1, s34, 0x2aaaaaab
	s_load_dwordx16 s[52:67], s[36:37], 0x0
	s_lshr_b32 s3, s1, 31
	s_add_i32 s0, s1, s3
	s_ashr_i32 s1, s1, 7
	s_mul_i32 s2, s0, 6
	s_add_i32 s33, s1, s3
	s_ashr_i32 s1, s0, 31
	s_sub_i32 s2, s34, s2
	s_lshl_b64 s[0:1], s[0:1], 2
	s_waitcnt lgkmcnt(0)
	s_add_u32 s0, s62, s0
	s_addc_u32 s1, s63, s1
	global_load_dword v2, v83, s[0:1]
	s_add_i32 s0, s33, 0x4000
	s_ashr_i32 s3, s2, 31
	s_mul_hi_i32 s1, s0, 0x300
	s_mulk_i32 s0, 0x300
	s_add_u32 s33, s38, s0
	s_addc_u32 s35, s39, s1
	s_lshl_b32 s0, s2, 6
	s_ashr_i32 s1, s0, 31
	s_lshl_b64 s[0:1], s[0:1], 1
	s_add_u32 s0, s33, s0
	s_addc_u32 s1, s35, s1
	v_readlane_b32 s52, v252, 16
	v_readlane_b32 s53, v252, 17
	v_readlane_b32 s60, v252, 24
	v_readlane_b32 s61, v252, 25
	s_mov_b64 s[52:53], s[60:61]
	v_readlane_b32 s54, v252, 18
	v_readlane_b32 s55, v252, 19
	v_readlane_b32 s56, v252, 20
	v_readlane_b32 s57, v252, 21
	v_readlane_b32 s58, v252, 22
	v_readlane_b32 s59, v252, 23
	v_readlane_b32 s62, v252, 26
	v_readlane_b32 s63, v252, 27
	v_readlane_b32 s64, v252, 28
	v_readlane_b32 s65, v252, 29
	v_readlane_b32 s66, v252, 30
	v_readlane_b32 s67, v252, 31
	s_waitcnt vmcnt(0)
	v_mul_hi_i32 v3, v2, s48
	v_mul_lo_u32 v2, v2, s48
	v_lshl_add_u64 v[42:43], v[2:3], 0, s[2:3]
	v_lshlrev_b64 v[2:3], 8, v[42:43]
	v_lshl_add_u64 v[38:39], v[84:85], 0, v[2:3]
	global_load_dwordx2 v[2:3], v101, s[0:1]
	s_lshl_b64 s[0:1], s[2:3], 2
	s_add_u32 s0, s52, s0
	s_addc_u32 s1, s53, s1
	global_load_dword v6, v83, s[0:1]
	s_waitcnt vmcnt(1)
	v_lshlrev_b32_e32 v54, 16, v2
	v_and_b32_e32 v56, 0xffff0000, v2
	v_lshlrev_b32_e32 v55, 16, v3
	v_and_b32_e32 v53, 0xffff0000, v3
	v_lshl_add_u64 v[2:3], v[38:39], 0, v[82:83]
	v_add_co_u32_e32 v4, vcc, s50, v2
	global_load_dwordx4 v[30:33], v[2:3], off nt
	s_nop 0
	v_addc_co_u32_e32 v5, vcc, 0, v3, vcc
	global_load_dwordx4 v[26:29], v[4:5], off offset:2048 nt
	v_add_co_u32_e32 v4, vcc, s51, v2
	s_waitcnt vmcnt(2)
	v_mul_f32_e32 v57, 0x3fb8aa3b, v6
	v_addc_co_u32_e32 v5, vcc, 0, v3, vcc
	global_load_dwordx4 v[22:25], v[4:5], off nt
	v_add_co_u32_e32 v4, vcc, s49, v2
	s_waitcnt vmcnt(2)
	v_mul_f32_e32 v31, v31, v56
	v_addc_co_u32_e32 v5, vcc, 0, v3, vcc
	global_load_dwordx4 v[14:17], v[4:5], off offset:2048 nt
	v_add_co_u32_e32 v4, vcc, s89, v2
	v_fmac_f32_e32 v31, v30, v54
	s_nop 0
	v_addc_co_u32_e32 v5, vcc, 0, v3, vcc
	global_load_dwordx4 v[18:21], v[4:5], off nt
	v_add_co_u32_e32 v4, vcc, s92, v2
	v_fmac_f32_e32 v31, v32, v55
	s_nop 0
	v_addc_co_u32_e32 v5, vcc, 0, v3, vcc
	global_load_dwordx4 v[6:9], v[4:5], off offset:2048 nt
	v_add_co_u32_e32 v4, vcc, s93, v2
	v_fmac_f32_e32 v31, v33, v53
	s_nop 0
	v_addc_co_u32_e32 v5, vcc, 0, v3, vcc
	v_add_co_u32_e32 v2, vcc, s96, v2
	global_load_dwordx4 v[10:13], v[4:5], off nt
	s_nop 0
	v_addc_co_u32_e32 v3, vcc, 0, v3, vcc
	global_load_dwordx4 v[2:5], v[2:3], off offset:2048 nt
	v_add_f32_dpp v30, v31, v31 quad_perm:[1,0,3,2] row_mask:0xf bank_mask:0xf bound_ctrl:1
	s_nop 1
	v_add_f32_dpp v30, v30, v30 quad_perm:[2,3,0,1] row_mask:0xf bank_mask:0xf bound_ctrl:1
	s_nop 1
	v_add_f32_dpp v30, v30, v30 row_ror:4 row_mask:0xf bank_mask:0xf bound_ctrl:1
	s_nop 1
	v_mov_b32_dpp v31, v30 row_ror:8 row_mask:0xf bank_mask:0xf bound_ctrl:1
	s_and_saveexec_b64 s[0:1], s[6:7]
	v_add_f32_e32 v30, v30, v31
	v_add_f32_e32 v30, v57, v30
	ds_write_b32 v99, v30
	s_or_b64 exec, exec, s[0:1]
	s_waitcnt vmcnt(6)
	v_mul_f32_e32 v27, v27, v56
	v_fmac_f32_e32 v27, v26, v54
	v_fmac_f32_e32 v27, v28, v55
	v_fmac_f32_e32 v27, v29, v53
	s_nop 1
	v_add_f32_dpp v26, v27, v27 quad_perm:[1,0,3,2] row_mask:0xf bank_mask:0xf bound_ctrl:1
	s_nop 1
	v_add_f32_dpp v26, v26, v26 quad_perm:[2,3,0,1] row_mask:0xf bank_mask:0xf bound_ctrl:1
	s_nop 1
	v_add_f32_dpp v26, v26, v26 row_ror:4 row_mask:0xf bank_mask:0xf bound_ctrl:1
	s_nop 1
	v_mov_b32_dpp v27, v26 row_ror:8 row_mask:0xf bank_mask:0xf bound_ctrl:1
	s_and_saveexec_b64 s[0:1], s[6:7]
	v_add_f32_e32 v26, v26, v27
	v_add_f32_e32 v26, v57, v26
	ds_write_b32 v99, v26 offset:16
	s_or_b64 exec, exec, s[0:1]
	s_waitcnt vmcnt(5)
	v_mul_f32_e32 v23, v23, v56
	v_fmac_f32_e32 v23, v22, v54
	v_fmac_f32_e32 v23, v24, v55
	v_fmac_f32_e32 v23, v25, v53
	s_nop 1
	v_add_f32_dpp v22, v23, v23 quad_perm:[1,0,3,2] row_mask:0xf bank_mask:0xf bound_ctrl:1
	s_nop 1
	v_add_f32_dpp v22, v22, v22 quad_perm:[2,3,0,1] row_mask:0xf bank_mask:0xf bound_ctrl:1
	s_nop 1
	v_add_f32_dpp v22, v22, v22 row_ror:4 row_mask:0xf bank_mask:0xf bound_ctrl:1
	s_nop 1
	v_mov_b32_dpp v23, v22 row_ror:8 row_mask:0xf bank_mask:0xf bound_ctrl:1
	s_and_saveexec_b64 s[0:1], s[6:7]
	v_add_f32_e32 v22, v22, v23
	v_add_f32_e32 v22, v57, v22
	ds_write_b32 v99, v22 offset:32
	s_or_b64 exec, exec, s[0:1]
	s_waitcnt vmcnt(4)
	v_mul_f32_e32 v15, v15, v56
	v_fmac_f32_e32 v15, v14, v54
	v_fmac_f32_e32 v15, v16, v55
	v_fmac_f32_e32 v15, v17, v53
	s_nop 1
	v_add_f32_dpp v14, v15, v15 quad_perm:[1,0,3,2] row_mask:0xf bank_mask:0xf bound_ctrl:1
	s_nop 1
	v_add_f32_dpp v14, v14, v14 quad_perm:[2,3,0,1] row_mask:0xf bank_mask:0xf bound_ctrl:1
	s_nop 1
	v_add_f32_dpp v14, v14, v14 row_ror:4 row_mask:0xf bank_mask:0xf bound_ctrl:1
	s_nop 1
	v_mov_b32_dpp v15, v14 row_ror:8 row_mask:0xf bank_mask:0xf bound_ctrl:1
	s_and_saveexec_b64 s[0:1], s[6:7]
	v_add_f32_e32 v14, v14, v15
	v_add_f32_e32 v14, v57, v14
	ds_write_b32 v99, v14 offset:48
	s_or_b64 exec, exec, s[0:1]
	v_lshl_add_u64 v[14:15], v[38:39], 0, v[82:83]
	v_add_co_u32_e32 v16, vcc, 0xc000, v14
	s_waitcnt vmcnt(3)
; template <int NB>
; __device__ __forceinline__ void sb_decode_task(const Params& P, float* lds, int task) {
;     ...
;     for (int kb = 0; kb < NBT; ++kb) {
;         const float* np = (kb + 1 < NBT) ? Kp + (size_t)(4 * NB * (kb + 1)) * (SH * HD) : Vp;
; #pragma unroll
;         for (int i = 0; i < NB; ++i) nx[i] = *(const float4*)(np + (size_t)(4 * i + g) * (SH * HD));
; #pragma unroll
;         for (int i = 0; i < NB; ++i) { const int s = 4 * NB * kb + 4 * i + g;
;             float part = q0 * cur[i].x + q1 * cur[i].y + q2 * cur[i].z + q3 * cur[i].w; part = sum16(part);
;             if (c == 0) zl[s] = part + bias; }
; #pragma unroll
;         for (int i = 0; i < NB; ++i) cur[i] = nx[i];
;     }
	v_mul_f32_e32 v19, v19, v56
	v_addc_co_u32_e32 v17, vcc, 0, v15, vcc
	v_add_co_u32_e32 v22, vcc, 0xd000, v14
	v_fmac_f32_e32 v19, v18, v54
	s_nop 0
	v_addc_co_u32_e32 v23, vcc, 0, v15, vcc
	global_load_dwordx4 v[30:33], v[16:17], off nt
	global_load_dwordx4 v[26:29], v[22:23], off offset:2048 nt
	v_add_co_u32_e32 v16, vcc, 0xf000, v14
	v_fmac_f32_e32 v19, v20, v55
	s_nop 0
	v_addc_co_u32_e32 v17, vcc, 0, v15, vcc
	v_add_co_u32_e32 v14, vcc, 0x10000, v14
	v_fmac_f32_e32 v19, v21, v53
	s_nop 0
	v_addc_co_u32_e32 v15, vcc, 0, v15, vcc
	global_load_dwordx4 v[22:25], v[16:17], off nt
	s_nop 0
	global_load_dwordx4 v[14:17], v[14:15], off offset:2048 nt
	v_add_f32_dpp v18, v19, v19 quad_perm:[1,0,3,2] row_mask:0xf bank_mask:0xf bound_ctrl:1
	s_nop 1
	v_add_f32_dpp v18, v18, v18 quad_perm:[2,3,0,1] row_mask:0xf bank_mask:0xf bound_ctrl:1
	s_nop 1
	v_add_f32_dpp v18, v18, v18 row_ror:4 row_mask:0xf bank_mask:0xf bound_ctrl:1
	s_nop 1
	v_mov_b32_dpp v19, v18 row_ror:8 row_mask:0xf bank_mask:0xf bound_ctrl:1
	s_and_saveexec_b64 s[0:1], s[6:7]
	v_add_f32_e32 v18, v18, v19
	v_add_f32_e32 v18, v57, v18
	ds_write_b32 v99, v18 offset:64
	s_or_b64 exec, exec, s[0:1]
	s_waitcnt vmcnt(6)
	v_mul_f32_e32 v7, v7, v56
	v_fmac_f32_e32 v7, v6, v54
	v_fmac_f32_e32 v7, v8, v55
	v_fmac_f32_e32 v7, v9, v53
	s_nop 1
	v_add_f32_dpp v6, v7, v7 quad_perm:[1,0,3,2] row_mask:0xf bank_mask:0xf bound_ctrl:1
	s_nop 1
	v_add_f32_dpp v6, v6, v6 quad_perm:[2,3,0,1] row_mask:0xf bank_mask:0xf bound_ctrl:1
	s_nop 1
	v_add_f32_dpp v6, v6, v6 row_ror:4 row_mask:0xf bank_mask:0xf bound_ctrl:1
	s_nop 1
	v_mov_b32_dpp v7, v6 row_ror:8 row_mask:0xf bank_mask:0xf bound_ctrl:1
	s_and_saveexec_b64 s[0:1], s[6:7]
	v_add_f32_e32 v6, v6, v7
	v_add_f32_e32 v6, v57, v6
	ds_write_b32 v99, v6 offset:80
	s_or_b64 exec, exec, s[0:1]
	s_waitcnt vmcnt(5)
	v_mul_f32_e32 v6, v11, v56
	v_fmac_f32_e32 v6, v10, v54
	v_fmac_f32_e32 v6, v12, v55
	v_fmac_f32_e32 v6, v13, v53
	s_nop 1
	v_add_f32_dpp v6, v6, v6 quad_perm:[1,0,3,2] row_mask:0xf bank_mask:0xf bound_ctrl:1
	s_nop 1
	v_add_f32_dpp v6, v6, v6 quad_perm:[2,3,0,1] row_mask:0xf bank_mask:0xf bound_ctrl:1
	s_nop 1
	v_add_f32_dpp v6, v6, v6 row_ror:4 row_mask:0xf bank_mask:0xf bound_ctrl:1
	s_nop 1
	v_mov_b32_dpp v7, v6 row_ror:8 row_mask:0xf bank_mask:0xf bound_ctrl:1
	s_and_saveexec_b64 s[0:1], s[6:7]
	v_add_f32_e32 v6, v6, v7
	v_add_f32_e32 v6, v57, v6
	ds_write_b32 v99, v6 offset:96
	s_or_b64 exec, exec, s[0:1]
	s_waitcnt vmcnt(4)
	v_mul_f32_e32 v3, v3, v56
	v_fmac_f32_e32 v3, v2, v54
	v_fmac_f32_e32 v3, v4, v55
	v_fmac_f32_e32 v3, v5, v53
	s_nop 1
	v_add_f32_dpp v2, v3, v3 quad_perm:[1,0,3,2] row_mask:0xf bank_mask:0xf bound_ctrl:1
	s_nop 1
	v_add_f32_dpp v2, v2, v2 quad_perm:[2,3,0,1] row_mask:0xf bank_mask:0xf bound_ctrl:1
	s_nop 1
	v_add_f32_dpp v2, v2, v2 row_ror:4 row_mask:0xf bank_mask:0xf bound_ctrl:1
	s_nop 1
	v_mov_b32_dpp v3, v2 row_ror:8 row_mask:0xf bank_mask:0xf bound_ctrl:1
	s_and_saveexec_b64 s[0:1], s[6:7]
	v_add_f32_e32 v2, v2, v3
	v_add_f32_e32 v2, v57, v2
	ds_write_b32 v99, v2 offset:112
	s_or_b64 exec, exec, s[0:1]
	v_lshl_add_u64 v[2:3], v[38:39], 0, v[82:83]
	v_add_co_u32_e32 v4, vcc, 0x12000, v2
	s_nop 1
	v_addc_co_u32_e32 v5, vcc, 0, v3, vcc
	v_add_co_u32_e32 v6, vcc, 0x13000, v2
	s_nop 1
	v_addc_co_u32_e32 v7, vcc, 0, v3, vcc
	global_load_dwordx4 v[34:37], v[4:5], off nt
	global_load_dwordx4 v[18:21], v[6:7], off offset:2048 nt
	v_add_co_u32_e32 v4, vcc, 0x15000, v2
	s_waitcnt vmcnt(5)
	v_mul_f32_e32 v6, v31, v56
	v_addc_co_u32_e32 v5, vcc, 0, v3, vcc
	v_add_co_u32_e32 v2, vcc, 0x16000, v2
	v_fmac_f32_e32 v6, v30, v54
	s_nop 0
	v_addc_co_u32_e32 v3, vcc, 0, v3, vcc
	global_load_dwordx4 v[10:13], v[4:5], off nt
	s_nop 0
	global_load_dwordx4 v[2:5], v[2:3], off offset:2048 nt
	v_fmac_f32_e32 v6, v32, v55
	v_fmac_f32_e32 v6, v33, v53
	s_nop 1
	v_add_f32_dpp v6, v6, v6 quad_perm:[1,0,3,2] row_mask:0xf bank_mask:0xf bound_ctrl:1
	s_nop 1
	v_add_f32_dpp v6, v6, v6 quad_perm:[2,3,0,1] row_mask:0xf bank_mask:0xf bound_ctrl:1
	s_nop 1
	v_add_f32_dpp v6, v6, v6 row_ror:4 row_mask:0xf bank_mask:0xf bound_ctrl:1
	s_nop 1
	v_mov_b32_dpp v7, v6 row_ror:8 row_mask:0xf bank_mask:0xf bound_ctrl:1
	s_and_saveexec_b64 s[0:1], s[6:7]
	v_add_f32_e32 v6, v6, v7
	v_add_f32_e32 v6, v57, v6
	ds_write_b32 v99, v6 offset:128
	s_or_b64 exec, exec, s[0:1]
	s_waitcnt vmcnt(6)
	v_mul_f32_e32 v6, v27, v56
	v_fmac_f32_e32 v6, v26, v54
	v_fmac_f32_e32 v6, v28, v55
	v_fmac_f32_e32 v6, v29, v53
	s_nop 1
	v_add_f32_dpp v6, v6, v6 quad_perm:[1,0,3,2] row_mask:0xf bank_mask:0xf bound_ctrl:1
	s_nop 1
	v_add_f32_dpp v6, v6, v6 quad_perm:[2,3,0,1] row_mask:0xf bank_mask:0xf bound_ctrl:1
	s_nop 1
	v_add_f32_dpp v6, v6, v6 row_ror:4 row_mask:0xf bank_mask:0xf bound_ctrl:1
	s_nop 1
	v_mov_b32_dpp v7, v6 row_ror:8 row_mask:0xf bank_mask:0xf bound_ctrl:1
	s_and_saveexec_b64 s[0:1], s[6:7]
	v_add_f32_e32 v6, v6, v7
	v_add_f32_e32 v6, v57, v6
	ds_write_b32 v99, v6 offset:144
	s_or_b64 exec, exec, s[0:1]
	s_waitcnt vmcnt(5)
	v_mul_f32_e32 v6, v23, v56
	v_fmac_f32_e32 v6, v22, v54
	v_fmac_f32_e32 v6, v24, v55
	v_fmac_f32_e32 v6, v25, v53
	s_nop 1
	v_add_f32_dpp v6, v6, v6 quad_perm:[1,0,3,2] row_mask:0xf bank_mask:0xf bound_ctrl:1
	s_nop 1
	v_add_f32_dpp v6, v6, v6 quad_perm:[2,3,0,1] row_mask:0xf bank_mask:0xf bound_ctrl:1
	s_nop 1
	v_add_f32_dpp v6, v6, v6 row_ror:4 row_mask:0xf bank_mask:0xf bound_ctrl:1
	s_nop 1
	v_mov_b32_dpp v7, v6 row_ror:8 row_mask:0xf bank_mask:0xf bound_ctrl:1
	s_and_saveexec_b64 s[0:1], s[6:7]
	v_add_f32_e32 v6, v6, v7
	v_add_f32_e32 v6, v57, v6
	ds_write_b32 v99, v6 offset:160
	s_or_b64 exec, exec, s[0:1]
	s_waitcnt vmcnt(4)
; template <int NB>
; __device__ __forceinline__ void sb_decode_task(const Params& P, float* lds, int task) {
;     ...
;     for (int kb = 0; kb < NBT; ++kb) {
;         const float* np = (kb + 1 < NBT) ? Kp + (size_t)(4 * NB * (kb + 1)) * (SH * HD) : Vp;
; #pragma unroll
;         for (int i = 0; i < NB; ++i) nx[i] = *(const float4*)(np + (size_t)(4 * i + g) * (SH * HD));
; #pragma unroll
;         for (int i = 0; i < NB; ++i) { const int s = 4 * NB * kb + 4 * i + g;
;             float part = q0 * cur[i].x + q1 * cur[i].y + q2 * cur[i].z + q3 * cur[i].w; part = sum16(part);
;             if (c == 0) zl[s] = part + bias; }
; #pragma unroll
;         for (int i = 0; i < NB; ++i) cur[i] = nx[i];
;     }
	v_mul_f32_e32 v6, v15, v56
	v_fmac_f32_e32 v6, v14, v54
	v_fmac_f32_e32 v6, v16, v55
	v_fmac_f32_e32 v6, v17, v53
	s_nop 1
	v_add_f32_dpp v6, v6, v6 quad_perm:[1,0,3,2] row_mask:0xf bank_mask:0xf bound_ctrl:1
	s_nop 1
	v_add_f32_dpp v6, v6, v6 quad_perm:[2,3,0,1] row_mask:0xf bank_mask:0xf bound_ctrl:1
	s_nop 1
	v_add_f32_dpp v6, v6, v6 row_ror:4 row_mask:0xf bank_mask:0xf bound_ctrl:1
	s_nop 1
	v_mov_b32_dpp v7, v6 row_ror:8 row_mask:0xf bank_mask:0xf bound_ctrl:1
	s_and_saveexec_b64 s[0:1], s[6:7]
	v_add_f32_e32 v6, v6, v7
	v_add_f32_e32 v6, v57, v6
	ds_write_b32 v99, v6 offset:176
	s_or_b64 exec, exec, s[0:1]
	v_lshl_add_u64 v[6:7], v[38:39], 0, v[82:83]
	v_add_co_u32_e32 v8, vcc, 0x18000, v6
	s_waitcnt vmcnt(3)
	v_mul_f32_e32 v30, v35, v56
	v_addc_co_u32_e32 v9, vcc, 0, v7, vcc
	v_add_co_u32_e32 v14, vcc, 0x19000, v6
	v_fmac_f32_e32 v30, v34, v54
	s_nop 0
	v_addc_co_u32_e32 v15, vcc, 0, v7, vcc
	global_load_dwordx4 v[26:29], v[8:9], off nt
	global_load_dwordx4 v[22:25], v[14:15], off offset:2048 nt
	v_add_co_u32_e32 v8, vcc, 0x1b000, v6
	v_fmac_f32_e32 v30, v36, v55
	s_nop 0
	v_addc_co_u32_e32 v9, vcc, 0, v7, vcc
	v_add_co_u32_e32 v6, vcc, 0x1c000, v6
	v_fmac_f32_e32 v30, v37, v53
	s_nop 0
	v_addc_co_u32_e32 v7, vcc, 0, v7, vcc
	global_load_dwordx4 v[14:17], v[8:9], off nt
	s_nop 0
	global_load_dwordx4 v[6:9], v[6:7], off offset:2048 nt
	v_add_f32_dpp v30, v30, v30 quad_perm:[1,0,3,2] row_mask:0xf bank_mask:0xf bound_ctrl:1
	s_nop 1
	v_add_f32_dpp v30, v30, v30 quad_perm:[2,3,0,1] row_mask:0xf bank_mask:0xf bound_ctrl:1
	s_nop 1
	v_add_f32_dpp v30, v30, v30 row_ror:4 row_mask:0xf bank_mask:0xf bound_ctrl:1
	s_nop 1
	v_mov_b32_dpp v31, v30 row_ror:8 row_mask:0xf bank_mask:0xf bound_ctrl:1
	s_and_saveexec_b64 s[0:1], s[6:7]
	v_add_f32_e32 v30, v30, v31
	v_add_f32_e32 v30, v57, v30
	ds_write_b32 v99, v30 offset:192
	s_or_b64 exec, exec, s[0:1]
	s_waitcnt vmcnt(6)
	v_mul_f32_e32 v19, v19, v56
	v_fmac_f32_e32 v19, v18, v54
	v_fmac_f32_e32 v19, v20, v55
	v_fmac_f32_e32 v19, v21, v53
	s_nop 1
	v_add_f32_dpp v18, v19, v19 quad_perm:[1,0,3,2] row_mask:0xf bank_mask:0xf bound_ctrl:1
	s_nop 1
	v_add_f32_dpp v18, v18, v18 quad_perm:[2,3,0,1] row_mask:0xf bank_mask:0xf bound_ctrl:1
	s_nop 1
	v_add_f32_dpp v18, v18, v18 row_ror:4 row_mask:0xf bank_mask:0xf bound_ctrl:1
	s_nop 1
	v_mov_b32_dpp v19, v18 row_ror:8 row_mask:0xf bank_mask:0xf bound_ctrl:1
	s_and_saveexec_b64 s[0:1], s[6:7]
	v_add_f32_e32 v18, v18, v19
	v_add_f32_e32 v18, v57, v18
	ds_write_b32 v99, v18 offset:208
	s_or_b64 exec, exec, s[0:1]
	s_waitcnt vmcnt(5)
	v_mul_f32_e32 v11, v11, v56
	v_fmac_f32_e32 v11, v10, v54
	v_fmac_f32_e32 v11, v12, v55
	v_fmac_f32_e32 v11, v13, v53
	s_nop 1
	v_add_f32_dpp v10, v11, v11 quad_perm:[1,0,3,2] row_mask:0xf bank_mask:0xf bound_ctrl:1
	s_nop 1
	v_add_f32_dpp v10, v10, v10 quad_perm:[2,3,0,1] row_mask:0xf bank_mask:0xf bound_ctrl:1
	s_nop 1
	v_add_f32_dpp v10, v10, v10 row_ror:4 row_mask:0xf bank_mask:0xf bound_ctrl:1
	s_nop 1
	v_mov_b32_dpp v11, v10 row_ror:8 row_mask:0xf bank_mask:0xf bound_ctrl:1
	s_and_saveexec_b64 s[0:1], s[6:7]
	v_add_f32_e32 v10, v10, v11
	v_add_f32_e32 v10, v57, v10
	ds_write_b32 v99, v10 offset:224
	s_or_b64 exec, exec, s[0:1]
	s_waitcnt vmcnt(4)
	v_mul_f32_e32 v3, v3, v56
	v_fmac_f32_e32 v3, v2, v54
	v_fmac_f32_e32 v3, v4, v55
	v_fmac_f32_e32 v3, v5, v53
	s_nop 1
	v_add_f32_dpp v2, v3, v3 quad_perm:[1,0,3,2] row_mask:0xf bank_mask:0xf bound_ctrl:1
	s_nop 1
	v_add_f32_dpp v2, v2, v2 quad_perm:[2,3,0,1] row_mask:0xf bank_mask:0xf bound_ctrl:1
	s_nop 1
	v_add_f32_dpp v2, v2, v2 row_ror:4 row_mask:0xf bank_mask:0xf bound_ctrl:1
	s_nop 1
	v_mov_b32_dpp v3, v2 row_ror:8 row_mask:0xf bank_mask:0xf bound_ctrl:1
	s_and_saveexec_b64 s[0:1], s[6:7]
	v_add_f32_e32 v2, v2, v3
	v_add_f32_e32 v2, v57, v2
	ds_write_b32 v99, v2 offset:240
	s_or_b64 exec, exec, s[0:1]
	v_lshl_add_u64 v[2:3], v[38:39], 0, v[82:83]
	v_add_co_u32_e32 v4, vcc, 0x1e000, v2
	s_waitcnt vmcnt(3)
	v_mul_f32_e32 v27, v27, v56
	v_addc_co_u32_e32 v5, vcc, 0, v3, vcc
	v_add_co_u32_e32 v10, vcc, 0x1f000, v2
	v_fmac_f32_e32 v27, v26, v54
	s_nop 0
	v_addc_co_u32_e32 v11, vcc, 0, v3, vcc
	global_load_dwordx4 v[30:33], v[4:5], off nt
	global_load_dwordx4 v[18:21], v[10:11], off offset:2048 nt
	v_add_co_u32_e32 v4, vcc, 0x21000, v2
	v_fmac_f32_e32 v27, v28, v55
	s_nop 0
	v_addc_co_u32_e32 v5, vcc, 0, v3, vcc
	v_add_co_u32_e32 v2, vcc, 0x22000, v2
	v_fmac_f32_e32 v27, v29, v53
	s_nop 0
	v_addc_co_u32_e32 v3, vcc, 0, v3, vcc
	global_load_dwordx4 v[10:13], v[4:5], off nt
	s_nop 0
	global_load_dwordx4 v[2:5], v[2:3], off offset:2048 nt
	v_add_f32_dpp v26, v27, v27 quad_perm:[1,0,3,2] row_mask:0xf bank_mask:0xf bound_ctrl:1
	s_nop 1
	v_add_f32_dpp v26, v26, v26 quad_perm:[2,3,0,1] row_mask:0xf bank_mask:0xf bound_ctrl:1
	s_nop 1
	v_add_f32_dpp v26, v26, v26 row_ror:4 row_mask:0xf bank_mask:0xf bound_ctrl:1
	s_nop 1
	v_mov_b32_dpp v27, v26 row_ror:8 row_mask:0xf bank_mask:0xf bound_ctrl:1
	s_and_saveexec_b64 s[0:1], s[6:7]
	v_add_f32_e32 v26, v26, v27
	v_add_f32_e32 v26, v57, v26
	ds_write_b32 v99, v26 offset:256
	s_or_b64 exec, exec, s[0:1]
	s_waitcnt vmcnt(6)
	v_mul_f32_e32 v23, v23, v56
	v_fmac_f32_e32 v23, v22, v54
	v_fmac_f32_e32 v23, v24, v55
	v_fmac_f32_e32 v23, v25, v53
	s_nop 1
	v_add_f32_dpp v22, v23, v23 quad_perm:[1,0,3,2] row_mask:0xf bank_mask:0xf bound_ctrl:1
	s_nop 1
	v_add_f32_dpp v22, v22, v22 quad_perm:[2,3,0,1] row_mask:0xf bank_mask:0xf bound_ctrl:1
	s_nop 1
	v_add_f32_dpp v22, v22, v22 row_ror:4 row_mask:0xf bank_mask:0xf bound_ctrl:1
	s_nop 1
	v_mov_b32_dpp v23, v22 row_ror:8 row_mask:0xf bank_mask:0xf bound_ctrl:1
	s_and_saveexec_b64 s[0:1], s[6:7]
	v_add_f32_e32 v22, v22, v23
	v_add_f32_e32 v22, v57, v22
	ds_write_b32 v99, v22 offset:272
	s_or_b64 exec, exec, s[0:1]
	s_waitcnt vmcnt(5)
; template <int NB>
; __device__ __forceinline__ void sb_decode_task(const Params& P, float* lds, int task) {
;     ...
;     for (int kb = 0; kb < NBT; ++kb) {
;         const float* np = (kb + 1 < NBT) ? Kp + (size_t)(4 * NB * (kb + 1)) * (SH * HD) : Vp;
; #pragma unroll
;         for (int i = 0; i < NB; ++i) nx[i] = *(const float4*)(np + (size_t)(4 * i + g) * (SH * HD));
; #pragma unroll
;         for (int i = 0; i < NB; ++i) { const int s = 4 * NB * kb + 4 * i + g;
;             float part = q0 * cur[i].x + q1 * cur[i].y + q2 * cur[i].z + q3 * cur[i].w; part = sum16(part);
;             if (c == 0) zl[s] = part + bias; }
; #pragma unroll
;         for (int i = 0; i < NB; ++i) cur[i] = nx[i];
;     }
	v_mul_f32_e32 v15, v15, v56
	v_fmac_f32_e32 v15, v14, v54
	v_fmac_f32_e32 v15, v16, v55
	v_fmac_f32_e32 v15, v17, v53
	s_nop 1
	v_add_f32_dpp v14, v15, v15 quad_perm:[1,0,3,2] row_mask:0xf bank_mask:0xf bound_ctrl:1
	s_nop 1
	v_add_f32_dpp v14, v14, v14 quad_perm:[2,3,0,1] row_mask:0xf bank_mask:0xf bound_ctrl:1
	s_nop 1
	v_add_f32_dpp v14, v14, v14 row_ror:4 row_mask:0xf bank_mask:0xf bound_ctrl:1
	s_nop 1
	v_mov_b32_dpp v15, v14 row_ror:8 row_mask:0xf bank_mask:0xf bound_ctrl:1
	s_and_saveexec_b64 s[0:1], s[6:7]
	v_add_f32_e32 v14, v14, v15
	v_add_f32_e32 v14, v57, v14
	ds_write_b32 v99, v14 offset:288
	s_or_b64 exec, exec, s[0:1]
	s_waitcnt vmcnt(4)
	v_mul_f32_e32 v7, v7, v56
	v_fmac_f32_e32 v7, v6, v54
	v_fmac_f32_e32 v7, v8, v55
	v_fmac_f32_e32 v7, v9, v53
	s_nop 1
	v_add_f32_dpp v6, v7, v7 quad_perm:[1,0,3,2] row_mask:0xf bank_mask:0xf bound_ctrl:1
	s_nop 1
	v_add_f32_dpp v6, v6, v6 quad_perm:[2,3,0,1] row_mask:0xf bank_mask:0xf bound_ctrl:1
	s_nop 1
	v_add_f32_dpp v6, v6, v6 row_ror:4 row_mask:0xf bank_mask:0xf bound_ctrl:1
	s_nop 1
	v_mov_b32_dpp v7, v6 row_ror:8 row_mask:0xf bank_mask:0xf bound_ctrl:1
	s_and_saveexec_b64 s[0:1], s[6:7]
	v_add_f32_e32 v6, v6, v7
	v_add_f32_e32 v6, v57, v6
	ds_write_b32 v99, v6 offset:304
	s_or_b64 exec, exec, s[0:1]
	v_lshl_add_u64 v[6:7], v[38:39], 0, v[82:83]
	v_add_co_u32_e32 v8, vcc, 0x24000, v6
	s_waitcnt vmcnt(3)
	v_mul_f32_e32 v22, v31, v56
	v_addc_co_u32_e32 v9, vcc, 0, v7, vcc
	v_add_co_u32_e32 v14, vcc, 0x25000, v6
	v_fmac_f32_e32 v22, v30, v54
	s_nop 0
	v_addc_co_u32_e32 v15, vcc, 0, v7, vcc
	global_load_dwordx4 v[34:37], v[8:9], off nt
	global_load_dwordx4 v[26:29], v[14:15], off offset:2048 nt
	v_add_co_u32_e32 v8, vcc, 0x27000, v6
	v_fmac_f32_e32 v22, v32, v55
	s_nop 0
	v_addc_co_u32_e32 v9, vcc, 0, v7, vcc
	v_add_co_u32_e32 v6, vcc, 0x28000, v6
	v_fmac_f32_e32 v22, v33, v53
	s_nop 0
	v_addc_co_u32_e32 v7, vcc, 0, v7, vcc
	global_load_dwordx4 v[14:17], v[8:9], off nt
	s_nop 0
	global_load_dwordx4 v[6:9], v[6:7], off offset:2048 nt
	v_add_f32_dpp v22, v22, v22 quad_perm:[1,0,3,2] row_mask:0xf bank_mask:0xf bound_ctrl:1
	s_nop 1
	v_add_f32_dpp v22, v22, v22 quad_perm:[2,3,0,1] row_mask:0xf bank_mask:0xf bound_ctrl:1
	s_nop 1
	v_add_f32_dpp v22, v22, v22 row_ror:4 row_mask:0xf bank_mask:0xf bound_ctrl:1
	s_nop 1
	v_mov_b32_dpp v23, v22 row_ror:8 row_mask:0xf bank_mask:0xf bound_ctrl:1
	s_and_saveexec_b64 s[0:1], s[6:7]
	v_add_f32_e32 v22, v22, v23
	v_add_f32_e32 v22, v57, v22
	ds_write_b32 v99, v22 offset:320
	s_or_b64 exec, exec, s[0:1]
	s_waitcnt vmcnt(6)
	v_mul_f32_e32 v19, v19, v56
	v_fmac_f32_e32 v19, v18, v54
	v_fmac_f32_e32 v19, v20, v55
	v_fmac_f32_e32 v19, v21, v53
	s_nop 1
	v_add_f32_dpp v18, v19, v19 quad_perm:[1,0,3,2] row_mask:0xf bank_mask:0xf bound_ctrl:1
	s_nop 1
	v_add_f32_dpp v18, v18, v18 quad_perm:[2,3,0,1] row_mask:0xf bank_mask:0xf bound_ctrl:1
	s_nop 1
	v_add_f32_dpp v18, v18, v18 row_ror:4 row_mask:0xf bank_mask:0xf bound_ctrl:1
	s_nop 1
	v_mov_b32_dpp v19, v18 row_ror:8 row_mask:0xf bank_mask:0xf bound_ctrl:1
	s_and_saveexec_b64 s[0:1], s[6:7]
	v_add_f32_e32 v18, v18, v19
	v_add_f32_e32 v18, v57, v18
	ds_write_b32 v99, v18 offset:336
	s_or_b64 exec, exec, s[0:1]
	s_waitcnt vmcnt(5)
	v_mul_f32_e32 v11, v11, v56
	v_fmac_f32_e32 v11, v10, v54
	v_fmac_f32_e32 v11, v12, v55
	v_fmac_f32_e32 v11, v13, v53
	s_nop 1
	v_add_f32_dpp v10, v11, v11 quad_perm:[1,0,3,2] row_mask:0xf bank_mask:0xf bound_ctrl:1
	s_nop 1
	v_add_f32_dpp v10, v10, v10 quad_perm:[2,3,0,1] row_mask:0xf bank_mask:0xf bound_ctrl:1
	s_nop 1
	v_add_f32_dpp v10, v10, v10 row_ror:4 row_mask:0xf bank_mask:0xf bound_ctrl:1
	s_nop 1
	v_mov_b32_dpp v11, v10 row_ror:8 row_mask:0xf bank_mask:0xf bound_ctrl:1
	s_and_saveexec_b64 s[0:1], s[6:7]
	v_add_f32_e32 v10, v10, v11
	v_add_f32_e32 v10, v57, v10
	ds_write_b32 v99, v10 offset:352
	s_or_b64 exec, exec, s[0:1]
	s_waitcnt vmcnt(4)
	v_mul_f32_e32 v3, v3, v56
	v_fmac_f32_e32 v3, v2, v54
	v_fmac_f32_e32 v3, v4, v55
	v_fmac_f32_e32 v3, v5, v53
	s_nop 1
	v_add_f32_dpp v2, v3, v3 quad_perm:[1,0,3,2] row_mask:0xf bank_mask:0xf bound_ctrl:1
	s_nop 1
	v_add_f32_dpp v2, v2, v2 quad_perm:[2,3,0,1] row_mask:0xf bank_mask:0xf bound_ctrl:1
	s_nop 1
	v_add_f32_dpp v2, v2, v2 row_ror:4 row_mask:0xf bank_mask:0xf bound_ctrl:1
	s_nop 1
	v_mov_b32_dpp v3, v2 row_ror:8 row_mask:0xf bank_mask:0xf bound_ctrl:1
	s_and_saveexec_b64 s[0:1], s[6:7]
	v_add_f32_e32 v2, v2, v3
	v_add_f32_e32 v2, v57, v2
	ds_write_b32 v99, v2 offset:368
	s_or_b64 exec, exec, s[0:1]
	v_lshl_add_u64 v[2:3], v[38:39], 0, v[82:83]
	v_add_co_u32_e32 v4, vcc, 0x2a000, v2
	s_nop 1
	v_addc_co_u32_e32 v5, vcc, 0, v3, vcc
	v_add_co_u32_e32 v10, vcc, 0x2b000, v2
	s_nop 1
	v_addc_co_u32_e32 v11, vcc, 0, v3, vcc
	global_load_dwordx4 v[38:41], v[4:5], off nt
	global_load_dwordx4 v[30:33], v[10:11], off offset:2048 nt
	v_add_co_u32_e32 v4, vcc, 0x2d000, v2
	s_nop 1
	v_addc_co_u32_e32 v5, vcc, 0, v3, vcc
	v_add_co_u32_e32 v2, vcc, 0x2e000, v2
	s_nop 1
	v_addc_co_u32_e32 v3, vcc, 0, v3, vcc
	global_load_dwordx4 v[22:25], v[4:5], off nt
	global_load_dwordx4 v[18:21], v[2:3], off offset:2048 nt
	s_waitcnt vmcnt(7)
	v_mul_f32_e32 v2, v35, v56
	v_fmac_f32_e32 v2, v34, v54
	v_fmac_f32_e32 v2, v36, v55
	v_fmac_f32_e32 v2, v37, v53
	s_nop 1
	v_add_f32_dpp v2, v2, v2 quad_perm:[1,0,3,2] row_mask:0xf bank_mask:0xf bound_ctrl:1
	s_nop 1
	v_add_f32_dpp v2, v2, v2 quad_perm:[2,3,0,1] row_mask:0xf bank_mask:0xf bound_ctrl:1
	s_nop 1
	v_add_f32_dpp v2, v2, v2 row_ror:4 row_mask:0xf bank_mask:0xf bound_ctrl:1
	s_nop 1
	v_mov_b32_dpp v3, v2 row_ror:8 row_mask:0xf bank_mask:0xf bound_ctrl:1
	s_and_saveexec_b64 s[0:1], s[6:7]
	v_add_f32_e32 v2, v2, v3
	v_add_f32_e32 v2, v57, v2
	ds_write_b32 v99, v2 offset:384
	s_or_b64 exec, exec, s[0:1]
	s_waitcnt vmcnt(6)
; template <int NB>
; __device__ __forceinline__ void sb_decode_task(const Params& P, float* lds, int task) {
;     ...
;     for (int kb = 0; kb < NBT; ++kb) {
;         const float* np = (kb + 1 < NBT) ? Kp + (size_t)(4 * NB * (kb + 1)) * (SH * HD) : Vp;
; #pragma unroll
;         for (int i = 0; i < NB; ++i) nx[i] = *(const float4*)(np + (size_t)(4 * i + g) * (SH * HD));
; #pragma unroll
;         for (int i = 0; i < NB; ++i) { const int s = 4 * NB * kb + 4 * i + g;
;             float part = q0 * cur[i].x + q1 * cur[i].y + q2 * cur[i].z + q3 * cur[i].w; part = sum16(part);
;             if (c == 0) zl[s] = part + bias; }
; #pragma unroll
;         for (int i = 0; i < NB; ++i) cur[i] = nx[i];
;     }
	v_mul_f32_e32 v2, v27, v56
	v_fmac_f32_e32 v2, v26, v54
	v_fmac_f32_e32 v2, v28, v55
	v_fmac_f32_e32 v2, v29, v53
	s_nop 1
	v_add_f32_dpp v2, v2, v2 quad_perm:[1,0,3,2] row_mask:0xf bank_mask:0xf bound_ctrl:1
	s_nop 1
	v_add_f32_dpp v2, v2, v2 quad_perm:[2,3,0,1] row_mask:0xf bank_mask:0xf bound_ctrl:1
	s_nop 1
	v_add_f32_dpp v2, v2, v2 row_ror:4 row_mask:0xf bank_mask:0xf bound_ctrl:1
	s_nop 1
	v_mov_b32_dpp v3, v2 row_ror:8 row_mask:0xf bank_mask:0xf bound_ctrl:1
	s_and_saveexec_b64 s[0:1], s[6:7]
	v_add_f32_e32 v2, v2, v3
	v_add_f32_e32 v2, v57, v2
	ds_write_b32 v99, v2 offset:400
	s_or_b64 exec, exec, s[0:1]
	s_waitcnt vmcnt(5)
	v_mul_f32_e32 v2, v15, v56
	v_fmac_f32_e32 v2, v14, v54
	v_fmac_f32_e32 v2, v16, v55
	v_fmac_f32_e32 v2, v17, v53
	s_nop 1
	v_add_f32_dpp v2, v2, v2 quad_perm:[1,0,3,2] row_mask:0xf bank_mask:0xf bound_ctrl:1
	s_nop 1
	v_add_f32_dpp v2, v2, v2 quad_perm:[2,3,0,1] row_mask:0xf bank_mask:0xf bound_ctrl:1
	s_nop 1
	v_add_f32_dpp v2, v2, v2 row_ror:4 row_mask:0xf bank_mask:0xf bound_ctrl:1
	s_nop 1
	v_mov_b32_dpp v3, v2 row_ror:8 row_mask:0xf bank_mask:0xf bound_ctrl:1
	s_and_saveexec_b64 s[0:1], s[6:7]
	v_add_f32_e32 v2, v2, v3
	v_add_f32_e32 v2, v57, v2
	ds_write_b32 v99, v2 offset:416
	s_or_b64 exec, exec, s[0:1]
	s_waitcnt vmcnt(4)
	v_mul_f32_e32 v2, v7, v56
	v_fmac_f32_e32 v2, v6, v54
	v_fmac_f32_e32 v2, v8, v55
	v_fmac_f32_e32 v2, v9, v53
	s_nop 1
	v_add_f32_dpp v2, v2, v2 quad_perm:[1,0,3,2] row_mask:0xf bank_mask:0xf bound_ctrl:1
	s_nop 1
	v_add_f32_dpp v2, v2, v2 quad_perm:[2,3,0,1] row_mask:0xf bank_mask:0xf bound_ctrl:1
	s_nop 1
	v_add_f32_dpp v2, v2, v2 row_ror:4 row_mask:0xf bank_mask:0xf bound_ctrl:1
	s_nop 1
	v_mov_b32_dpp v3, v2 row_ror:8 row_mask:0xf bank_mask:0xf bound_ctrl:1
	s_and_saveexec_b64 s[0:1], s[6:7]
	v_add_f32_e32 v2, v2, v3
	v_add_f32_e32 v2, v57, v2
	ds_write_b32 v99, v2 offset:432
	s_or_b64 exec, exec, s[0:1]
	v_lshlrev_b64 v[2:3], 6, v[42:43]
	v_lshl_add_u64 v[34:35], v[2:3], 2, v[90:91]
	v_add_co_u32_e32 v2, vcc, 0x1000, v34
	s_waitcnt vmcnt(3)
	v_mul_f32_e32 v26, v39, v56
	v_addc_co_u32_e32 v3, vcc, 0, v35, vcc
	v_add_co_u32_e32 v6, vcc, 0x3000, v34
	global_load_dwordx4 v[14:17], v[34:35], off nt
	s_nop 0
	global_load_dwordx4 v[2:5], v[2:3], off offset:2048 nt
	v_addc_co_u32_e32 v7, vcc, 0, v35, vcc
	v_add_co_u32_e32 v10, vcc, s49, v34
	v_fmac_f32_e32 v26, v38, v54
	s_nop 0
	v_addc_co_u32_e32 v11, vcc, 0, v35, vcc
	global_load_dwordx4 v[6:9], v[6:7], off nt
	s_nop 0
	global_load_dwordx4 v[10:13], v[10:11], off offset:2048 nt
	v_fmac_f32_e32 v26, v40, v55
	v_fmac_f32_e32 v26, v41, v53
	s_nop 1
	v_add_f32_dpp v26, v26, v26 quad_perm:[1,0,3,2] row_mask:0xf bank_mask:0xf bound_ctrl:1
	s_nop 1
	v_add_f32_dpp v26, v26, v26 quad_perm:[2,3,0,1] row_mask:0xf bank_mask:0xf bound_ctrl:1
	s_nop 1
	v_add_f32_dpp v26, v26, v26 row_ror:4 row_mask:0xf bank_mask:0xf bound_ctrl:1
	s_nop 1
	v_mov_b32_dpp v27, v26 row_ror:8 row_mask:0xf bank_mask:0xf bound_ctrl:1
	s_and_saveexec_b64 s[0:1], s[6:7]
	v_add_f32_e32 v26, v26, v27
	v_add_f32_e32 v26, v57, v26
	ds_write_b32 v99, v26 offset:448
	s_or_b64 exec, exec, s[0:1]
	s_waitcnt vmcnt(6)
	v_mul_f32_e32 v26, v31, v56
	v_fmac_f32_e32 v26, v30, v54
	v_fmac_f32_e32 v26, v32, v55
	v_fmac_f32_e32 v26, v33, v53
	s_nop 1
	v_add_f32_dpp v26, v26, v26 quad_perm:[1,0,3,2] row_mask:0xf bank_mask:0xf bound_ctrl:1
	s_nop 1
	v_add_f32_dpp v26, v26, v26 quad_perm:[2,3,0,1] row_mask:0xf bank_mask:0xf bound_ctrl:1
	s_nop 1
	v_add_f32_dpp v26, v26, v26 row_ror:4 row_mask:0xf bank_mask:0xf bound_ctrl:1
	s_nop 1
	v_mov_b32_dpp v27, v26 row_ror:8 row_mask:0xf bank_mask:0xf bound_ctrl:1
	s_and_saveexec_b64 s[0:1], s[6:7]
	v_add_f32_e32 v26, v26, v27
	v_add_f32_e32 v26, v57, v26
	ds_write_b32 v99, v26 offset:464
	s_or_b64 exec, exec, s[0:1]
	s_waitcnt vmcnt(5)
	v_mul_f32_e32 v23, v23, v56
	v_fmac_f32_e32 v23, v22, v54
	v_fmac_f32_e32 v23, v24, v55
	v_fmac_f32_e32 v23, v25, v53
	s_nop 1
	v_add_f32_dpp v22, v23, v23 quad_perm:[1,0,3,2] row_mask:0xf bank_mask:0xf bound_ctrl:1
	s_nop 1
	v_add_f32_dpp v22, v22, v22 quad_perm:[2,3,0,1] row_mask:0xf bank_mask:0xf bound_ctrl:1
	s_nop 1
	v_add_f32_dpp v22, v22, v22 row_ror:4 row_mask:0xf bank_mask:0xf bound_ctrl:1
	s_nop 1
	v_mov_b32_dpp v23, v22 row_ror:8 row_mask:0xf bank_mask:0xf bound_ctrl:1
	s_and_saveexec_b64 s[0:1], s[6:7]
	v_add_f32_e32 v22, v22, v23
	v_add_f32_e32 v22, v57, v22
	ds_write_b32 v99, v22 offset:480
	s_or_b64 exec, exec, s[0:1]
	s_waitcnt vmcnt(4)
	v_mul_f32_e32 v19, v19, v56
	v_fmac_f32_e32 v19, v18, v54
	v_fmac_f32_e32 v19, v20, v55
	v_fmac_f32_e32 v19, v21, v53
	s_nop 1
	v_add_f32_dpp v18, v19, v19 quad_perm:[1,0,3,2] row_mask:0xf bank_mask:0xf bound_ctrl:1
	s_nop 1
	v_add_f32_dpp v18, v18, v18 quad_perm:[2,3,0,1] row_mask:0xf bank_mask:0xf bound_ctrl:1
	s_nop 1
	v_add_f32_dpp v18, v18, v18 row_ror:4 row_mask:0xf bank_mask:0xf bound_ctrl:1
	s_nop 1
	v_mov_b32_dpp v19, v18 row_ror:8 row_mask:0xf bank_mask:0xf bound_ctrl:1
	s_and_saveexec_b64 s[0:1], s[6:7]
	v_add_f32_e32 v18, v18, v19
	v_add_f32_e32 v18, v57, v18
	ds_write_b32 v99, v18 offset:496
	s_or_b64 exec, exec, s[0:1]
	s_waitcnt lgkmcnt(0)
	ds_read_b64 v[18:19], v100
	s_waitcnt lgkmcnt(0)
; __device__ __forceinline__ float softplus2_(float z2) { return fmaxf(z2, 0.f) + log1pf(exp2f(-fabsf(z2))) * LOG2E; }
; template <int NB>
; __device__ __forceinline__ void sb_decode_task(const Params& P, float* lds, int task) {
;     ...
;     const float z0 = zl[2 * lane], z1 = zl[2 * lane + 1];
;     const float sp0 = softplus2_(z0), sp1 = softplus2_(z1);
	v_cmp_gt_f32_e64 vcc, |v18|, s97
	s_nop 1
	v_cndmask_b32_e32 v21, 0, v103, vcc
	v_sub_f32_e64 v21, v21, |v18|
	v_exp_f32_e32 v21, v21
	v_max_f32_e32 v20, v18, v18
	v_max_f32_e32 v22, 0, v20
	v_cndmask_b32_e32 v20, 0, v102, vcc
	v_ldexp_f32 v23, v21, v20
	v_add_f32_e32 v24, 1.0, v23
	v_add_f32_e32 v20, -1.0, v24
	v_sub_f32_e32 v21, v20, v24
	v_add_f32_e32 v21, 1.0, v21
	v_sub_f32_e32 v20, v23, v20
	v_add_f32_e32 v25, v20, v21
	v_frexp_mant_f32_e32 v20, v24
	v_cmp_gt_f32_e32 vcc, s47, v20
	v_cvt_f64_f32_e32 v[20:21], v24
	v_frexp_exp_i32_f64_e32 v20, v[20:21]
	v_subbrev_co_u32_e32 v20, vcc, 0, v20, vcc
	v_sub_u32_e32 v21, 0, v20
	v_ldexp_f32 v24, v24, v21
	v_ldexp_f32 v21, v25, v21
	v_add_f32_e32 v25, -1.0, v24
	v_add_f32_e32 v26, 1.0, v25
	v_sub_f32_e32 v26, v24, v26
	v_add_f32_e32 v26, v21, v26
	v_add_f32_e32 v27, v25, v26
	v_sub_f32_e32 v25, v25, v27
	v_add_f32_e32 v25, v26, v25
	v_add_f32_e32 v26, 1.0, v24
	v_add_f32_e32 v28, -1.0, v26
	v_sub_f32_e32 v24, v24, v28
	v_add_f32_e32 v21, v21, v24
	v_add_f32_e32 v24, v26, v21
	v_sub_f32_e32 v26, v26, v24
	v_add_f32_e32 v21, v21, v26
	v_rcp_f32_e32 v26, v24
	v_cvt_f32_i32_e32 v20, v20
	v_cmp_neq_f32_e32 vcc, s46, v23
	v_mul_f32_e32 v28, v27, v26
	v_mul_f32_e32 v29, v24, v28
	v_fma_f32 v30, v28, v24, -v29
	v_fmac_f32_e32 v30, v28, v21
	v_add_f32_e32 v31, v29, v30
	v_sub_f32_e32 v32, v27, v31
	v_sub_f32_e32 v27, v27, v32
	v_sub_f32_e32 v29, v31, v29
	v_sub_f32_e32 v27, v27, v31
	v_add_f32_e32 v25, v25, v27
	v_sub_f32_e32 v27, v29, v30
	v_add_f32_e32 v25, v27, v25
	v_add_f32_e32 v27, v32, v25
	v_mul_f32_e32 v29, v26, v27
	v_mul_f32_e32 v30, v24, v29
	v_fma_f32 v24, v29, v24, -v30
	v_fmac_f32_e32 v24, v29, v21
	v_sub_f32_e32 v21, v32, v27
	v_add_f32_e32 v21, v25, v21
	v_add_f32_e32 v25, v30, v24
	v_sub_f32_e32 v31, v27, v25
	v_sub_f32_e32 v27, v27, v31
	v_sub_f32_e32 v30, v25, v30
	v_sub_f32_e32 v25, v27, v25
	v_add_f32_e32 v21, v21, v25
	v_sub_f32_e32 v24, v30, v24
	v_add_f32_e32 v21, v24, v21
	v_add_f32_e32 v24, v28, v29
	v_add_f32_e32 v21, v31, v21
	v_sub_f32_e32 v25, v24, v28
	v_mul_f32_e32 v21, v26, v21
	v_sub_f32_e32 v25, v29, v25
	v_add_f32_e32 v21, v25, v21
	v_mul_f32_e32 v28, 0x3f317218, v20
	v_add_f32_e32 v25, v24, v21
	v_fma_f32 v29, v20, s95, -v28
	v_mul_f32_e32 v26, v25, v25
	v_fmac_f32_e32 v29, 0xb102e308, v20
	v_sub_f32_e32 v20, v25, v24
	v_fmamk_f32 v27, v26, 0x3e9b6dac, v1
	v_sub_f32_e32 v20, v21, v20
	v_add_f32_e32 v21, v28, v29
	v_fmaak_f32 v27, v26, v27, 0x3f2aaada
	v_sub_f32_e32 v24, v21, v28
	v_ldexp_f32 v28, v25, 1
	v_mul_f32_e32 v25, v25, v26
	v_mul_f32_e32 v25, v25, v27
	v_add_f32_e32 v26, v28, v25
	v_sub_f32_e32 v27, v26, v28
	v_ldexp_f32 v20, v20, 1
	v_sub_f32_e32 v25, v25, v27
	v_add_f32_e32 v20, v20, v25
	v_add_f32_e32 v25, v26, v20
	v_sub_f32_e32 v26, v25, v26
	v_sub_f32_e32 v20, v20, v26
	v_add_f32_e32 v26, v21, v25
	v_sub_f32_e32 v27, v26, v21
	v_sub_f32_e32 v28, v26, v27
	v_sub_f32_e32 v24, v29, v24
	v_sub_f32_e32 v21, v21, v28
	v_sub_f32_e32 v25, v25, v27
	v_add_f32_e32 v21, v25, v21
	v_add_f32_e32 v25, v24, v20
	v_sub_f32_e32 v27, v25, v24
	v_sub_f32_e32 v28, v25, v27
	v_sub_f32_e32 v24, v24, v28
	v_sub_f32_e32 v20, v20, v27
	v_add_f32_e32 v21, v25, v21
	v_add_f32_e32 v20, v20, v24
	v_add_f32_e32 v24, v26, v21
	v_sub_f32_e32 v25, v24, v26
	v_sub_f32_e32 v21, v21, v25
	v_add_f32_e32 v20, v20, v21
	v_add_f32_e32 v20, v24, v20
	v_cndmask_b32_e32 v20, v104, v20, vcc
	v_cmp_lt_f32_e64 vcc, |v23|, s45
	s_nop 1
	v_cndmask_b32_e32 v20, v20, v23, vcc
	v_cmp_gt_f32_e64 vcc, |v19|, s97
	v_fmac_f32_e32 v22, 0x3fb8aa3b, v20
	v_max_f32_e32 v20, v19, v19
	v_cndmask_b32_e32 v21, 0, v103, vcc
	v_sub_f32_e64 v21, v21, |v19|
	v_exp_f32_e32 v21, v21
	v_max_f32_e32 v23, 0, v20
	v_cndmask_b32_e32 v20, 0, v102, vcc
	v_sub_f32_e32 v18, v18, v22
	v_ldexp_f32 v24, v21, v20
	v_add_f32_e32 v25, 1.0, v24
	v_add_f32_e32 v20, -1.0, v25
	v_sub_f32_e32 v21, v20, v25
	v_add_f32_e32 v21, 1.0, v21
	v_sub_f32_e32 v20, v24, v20
	v_add_f32_e32 v26, v20, v21
	v_frexp_mant_f32_e32 v20, v25
	v_cmp_gt_f32_e32 vcc, s47, v20
	v_cvt_f64_f32_e32 v[20:21], v25
	v_frexp_exp_i32_f64_e32 v20, v[20:21]
	v_subbrev_co_u32_e32 v20, vcc, 0, v20, vcc
	v_sub_u32_e32 v21, 0, v20
	v_ldexp_f32 v25, v25, v21
	v_ldexp_f32 v21, v26, v21
	v_add_f32_e32 v26, -1.0, v25
	v_add_f32_e32 v27, 1.0, v26
	v_sub_f32_e32 v27, v25, v27
	v_add_f32_e32 v27, v21, v27
	v_add_f32_e32 v28, v26, v27
	v_sub_f32_e32 v26, v26, v28
	v_add_f32_e32 v26, v27, v26
	v_add_f32_e32 v27, 1.0, v25
	v_add_f32_e32 v29, -1.0, v27
	v_sub_f32_e32 v25, v25, v29
	v_add_f32_e32 v21, v21, v25
	v_add_f32_e32 v25, v27, v21
	v_sub_f32_e32 v27, v27, v25
	v_add_f32_e32 v21, v21, v27
	v_rcp_f32_e32 v27, v25
	v_cvt_f32_i32_e32 v20, v20
	v_cmp_neq_f32_e32 vcc, s46, v24
	v_mul_f32_e32 v29, v28, v27
	v_mul_f32_e32 v30, v25, v29
	v_fma_f32 v31, v29, v25, -v30
	v_fmac_f32_e32 v31, v29, v21
	v_add_f32_e32 v32, v30, v31
	v_sub_f32_e32 v33, v28, v32
	v_sub_f32_e32 v28, v28, v33
	v_sub_f32_e32 v30, v32, v30
	v_sub_f32_e32 v28, v28, v32
	v_add_f32_e32 v26, v26, v28
	v_sub_f32_e32 v28, v30, v31
	v_add_f32_e32 v26, v28, v26
	v_add_f32_e32 v28, v33, v26
	v_mul_f32_e32 v30, v27, v28
	v_mul_f32_e32 v31, v25, v30
	v_fma_f32 v25, v30, v25, -v31
	v_fmac_f32_e32 v25, v30, v21
	v_sub_f32_e32 v21, v33, v28
	v_add_f32_e32 v21, v26, v21
	v_add_f32_e32 v26, v31, v25
	v_sub_f32_e32 v32, v28, v26
	v_sub_f32_e32 v28, v28, v32
	v_sub_f32_e32 v31, v26, v31
	v_sub_f32_e32 v26, v28, v26
	v_add_f32_e32 v21, v21, v26
	v_sub_f32_e32 v25, v31, v25
	v_add_f32_e32 v21, v25, v21
	v_add_f32_e32 v25, v29, v30
	v_add_f32_e32 v21, v32, v21
	v_sub_f32_e32 v26, v25, v29
	v_mul_f32_e32 v21, v27, v21
; __device__ __forceinline__ float softplus2_(float z2) { return fmaxf(z2, 0.f) + log1pf(exp2f(-fabsf(z2))) * LOG2E; }
; template <int NB>
; __device__ __forceinline__ void sb_decode_task(const Params& P, float* lds, int task) {
;     ...
;     const float sp0 = softplus2_(z0), sp1 = softplus2_(z1);
;     float incl = sp0 + sp1;
; #pragma unroll
;     for (int off = 1; off < 64; off <<= 1) { const float t = __shfl_down(incl, off); if (lane + off < 64) incl += t; }
;     const float excl = incl - (sp0 + sp1);
;     wl[2 * lane] = exp2f(z0 - sp0 - (excl + sp1));
;     wl[2 * lane + 1] = exp2f(z1 - sp1 - excl);
;     const float Ltot = __shfl(incl, 0);
;     asm volatile("s_waitcnt lgkmcnt(0)" ::: "memory");
;     __builtin_amdgcn_wave_barrier();
;     float4 o4 = make_float4(0.f, 0.f, 0.f, 0.f);
; #pragma unroll
;     for (int vb = 0; vb < NBT; ++vb) {
;         if (vb + 1 < NBT) {
; #pragma unroll
;             for (int i = 0; i < NB; ++i) nx[i] = *(const float4*)(Vp + (size_t)(4 * NB * (vb + 1) + 4 * i + g) * (SH * HD)); }
; #pragma unroll
;         for (int i = 0; i < NB; ++i) { const float w = wl[4 * NB * vb + 4 * i + g]; o4.x += w * cur[i].x; o4.y += w * cur[i].y; o4.z += w * cur[i].z; o4.w += w * cur[i].w; }
	v_sub_f32_e32 v26, v30, v26
	v_add_f32_e32 v21, v26, v21
	v_mul_f32_e32 v29, 0x3f317218, v20
	v_add_f32_e32 v26, v25, v21
	v_fma_f32 v30, v20, s95, -v29
	v_mul_f32_e32 v27, v26, v26
	v_fmac_f32_e32 v30, 0xb102e308, v20
	v_sub_f32_e32 v20, v26, v25
	v_fmamk_f32 v28, v27, 0x3e9b6dac, v1
	v_sub_f32_e32 v20, v21, v20
	v_add_f32_e32 v21, v29, v30
	v_fmaak_f32 v28, v27, v28, 0x3f2aaada
	v_sub_f32_e32 v25, v21, v29
	v_ldexp_f32 v29, v26, 1
	v_mul_f32_e32 v26, v26, v27
	v_mul_f32_e32 v26, v26, v28
	v_add_f32_e32 v27, v29, v26
	v_sub_f32_e32 v28, v27, v29
	v_ldexp_f32 v20, v20, 1
	v_sub_f32_e32 v26, v26, v28
	v_add_f32_e32 v20, v20, v26
	v_add_f32_e32 v26, v27, v20
	v_sub_f32_e32 v27, v26, v27
	v_sub_f32_e32 v20, v20, v27
	v_add_f32_e32 v27, v21, v26
	v_sub_f32_e32 v28, v27, v21
	v_sub_f32_e32 v29, v27, v28
	v_sub_f32_e32 v25, v30, v25
	v_sub_f32_e32 v21, v21, v29
	v_sub_f32_e32 v26, v26, v28
	v_add_f32_e32 v21, v26, v21
	v_add_f32_e32 v26, v25, v20
	v_sub_f32_e32 v28, v26, v25
	v_sub_f32_e32 v29, v26, v28
	v_sub_f32_e32 v25, v25, v29
	v_sub_f32_e32 v20, v20, v28
	v_add_f32_e32 v21, v26, v21
	v_add_f32_e32 v20, v20, v25
	v_add_f32_e32 v25, v27, v21
	v_sub_f32_e32 v26, v25, v27
	v_sub_f32_e32 v21, v21, v26
	v_add_f32_e32 v20, v20, v21
	v_add_f32_e32 v20, v25, v20
	v_cndmask_b32_e32 v20, v104, v20, vcc
	v_cmp_lt_f32_e64 vcc, |v24|, s45
	s_nop 1
	v_cndmask_b32_e32 v20, v20, v24, vcc
	v_fmac_f32_e32 v23, 0x3fb8aa3b, v20
	v_add_f32_e32 v20, v22, v23
	ds_bpermute_b32 v21, v46, v20
	v_sub_f32_e32 v19, v19, v23
	s_waitcnt lgkmcnt(0)
	v_add_f32_e32 v21, v20, v21
	v_cndmask_b32_e64 v21, v21, v20, s[8:9]
	ds_bpermute_b32 v24, v47, v21
	s_waitcnt lgkmcnt(0)
	v_add_f32_e32 v24, v21, v24
	v_cndmask_b32_e64 v21, v21, v24, s[10:11]
	ds_bpermute_b32 v24, v48, v21
	s_waitcnt lgkmcnt(0)
	v_add_f32_e32 v24, v21, v24
	v_cndmask_b32_e64 v21, v21, v24, s[12:13]
	ds_bpermute_b32 v24, v49, v21
	s_waitcnt lgkmcnt(0)
	v_add_f32_e32 v24, v21, v24
	v_cndmask_b32_e64 v21, v21, v24, s[14:15]
	ds_bpermute_b32 v24, v50, v21
	s_waitcnt lgkmcnt(0)
	v_add_f32_e32 v24, v21, v24
	v_cndmask_b32_e64 v21, v21, v24, s[16:17]
	ds_bpermute_b32 v24, v51, v21
	s_waitcnt lgkmcnt(0)
	v_add_f32_e32 v24, v21, v24
	v_cndmask_b32_e64 v31, v21, v24, s[18:19]
	v_sub_f32_e32 v20, v31, v20
	v_add_f32_e32 v21, v23, v20
	v_sub_f32_e32 v18, v18, v21
	v_cmp_gt_f32_e32 vcc, s24, v18
	v_sub_f32_e32 v19, v19, v20
	s_nop 0
	v_cndmask_b32_e32 v21, 0, v103, vcc
	v_add_f32_e32 v18, v18, v21
	v_cndmask_b32_e32 v21, 0, v102, vcc
	v_cmp_gt_f32_e32 vcc, s24, v19
	v_exp_f32_e32 v18, v18
	s_nop 0
	v_cndmask_b32_e32 v20, 0, v103, vcc
	v_add_f32_e32 v19, v19, v20
	v_exp_f32_e32 v19, v19
	v_cndmask_b32_e32 v20, 0, v102, vcc
	v_ldexp_f32 v18, v18, v21
	v_ldexp_f32 v19, v19, v20
	ds_write_b64 v100, v[18:19] offset:512
	s_waitcnt lgkmcnt(0)
	ds_read2_b32 v[18:19], v99 offset0:128 offset1:132
	ds_read2_b32 v[32:33], v99 offset0:136 offset1:140
	ds_read2_b32 v[58:59], v99 offset0:144 offset1:148
	ds_read2_b32 v[60:61], v99 offset0:152 offset1:156
	ds_read2_b32 v[62:63], v99 offset0:160 offset1:164
	ds_read2_b32 v[64:65], v99 offset0:168 offset1:172
	s_waitcnt vmcnt(3) lgkmcnt(5)
	v_pk_fma_f32 v[36:37], v[14:15], v[18:19], 0 op_sel_hi:[1,0,0]
	v_add_co_u32_e32 v14, vcc, s89, v34
	v_pk_fma_f32 v[50:51], v[16:17], v[18:19], 0 op_sel_hi:[1,0,0]
	s_nop 0
	v_addc_co_u32_e32 v15, vcc, 0, v35, vcc
	v_add_co_u32_e32 v18, vcc, s92, v34
	v_mov_b32_e32 v30, v19
	s_nop 0
	v_addc_co_u32_e32 v19, vcc, 0, v35, vcc
	v_add_co_u32_e32 v22, vcc, s93, v34
	s_waitcnt vmcnt(2)
	v_pk_fma_f32 v[2:3], v[2:3], v[30:31], v[36:37] op_sel_hi:[1,0,1]
	v_addc_co_u32_e32 v23, vcc, 0, v35, vcc
	v_add_co_u32_e32 v26, vcc, s96, v34
	s_waitcnt vmcnt(1) lgkmcnt(4)
	v_pk_fma_f32 v[2:3], v[6:7], v[32:33], v[2:3] op_sel_hi:[1,0,1]
	v_addc_co_u32_e32 v27, vcc, 0, v35, vcc
	v_add_co_u32_e32 v6, vcc, s44, v34
	global_load_dwordx4 v[14:17], v[14:15], off nt
	s_nop 0
	v_addc_co_u32_e32 v7, vcc, 0, v35, vcc
	global_load_dwordx4 v[18:21], v[18:19], off offset:2048 nt
	v_mov_b32_e32 v66, v33
	global_load_dwordx4 v[36:39], v[6:7], off nt
	v_add_co_u32_e32 v6, vcc, s26, v34
	global_load_dwordx4 v[22:25], v[22:23], off nt
	s_nop 0
	v_addc_co_u32_e32 v7, vcc, 0, v35, vcc
	global_load_dwordx4 v[26:29], v[26:27], off offset:2048 nt
	s_waitcnt vmcnt(5)
	v_pk_fma_f32 v[2:3], v[10:11], v[66:67], v[2:3] op_sel_hi:[1,0,1]
	global_load_dwordx4 v[40:43], v[6:7], off offset:2048 nt
	v_add_co_u32_e32 v6, vcc, s27, v34
	s_waitcnt lgkmcnt(2)
	v_mov_b32_e32 v10, v61
	v_addc_co_u32_e32 v7, vcc, 0, v35, vcc
	global_load_dwordx4 v[46:49], v[6:7], off nt
	v_add_co_u32_e32 v6, vcc, s28, v34
	s_waitcnt vmcnt(6)
	v_pk_fma_f32 v[2:3], v[14:15], v[58:59], v[2:3] op_sel_hi:[1,0,1]
	v_addc_co_u32_e32 v7, vcc, 0, v35, vcc
	global_load_dwordx4 v[54:57], v[6:7], off offset:2048 nt
	v_mov_b32_e32 v6, v59
	s_waitcnt vmcnt(6)
	v_pk_fma_f32 v[2:3], v[18:19], v[6:7], v[2:3] op_sel_hi:[1,0,1]
	s_waitcnt lgkmcnt(1)
	v_mov_b32_e32 v14, v63
	s_waitcnt lgkmcnt(0)
	v_mov_b32_e32 v18, v65
	s_waitcnt vmcnt(4)
	v_pk_fma_f32 v[2:3], v[22:23], v[60:61], v[2:3] op_sel_hi:[1,0,1]
	s_waitcnt vmcnt(3)
	v_pk_fma_f32 v[2:3], v[26:27], v[10:11], v[2:3] op_sel_hi:[1,0,1]
	s_nop 0
	v_pk_fma_f32 v[2:3], v[36:37], v[62:63], v[2:3] op_sel_hi:[1,0,1]
	s_waitcnt vmcnt(2)
	v_pk_fma_f32 v[2:3], v[40:41], v[14:15], v[2:3] op_sel_hi:[1,0,1]
	s_waitcnt vmcnt(1)
	v_pk_fma_f32 v[2:3], v[46:47], v[64:65], v[2:3] op_sel_hi:[1,0,1]
	s_waitcnt vmcnt(0)
	v_pk_fma_f32 v[54:55], v[54:55], v[18:19], v[2:3] op_sel_hi:[1,0,1]
	v_pk_fma_f32 v[2:3], v[4:5], v[30:31], v[50:51] op_sel_hi:[1,0,1]
	s_nop 0
	v_pk_fma_f32 v[2:3], v[8:9], v[32:33], v[2:3] op_sel_hi:[1,0,1]
	ds_read2_b32 v[8:9], v99 offset0:176 offset1:180
	v_pk_fma_f32 v[2:3], v[12:13], v[66:67], v[2:3] op_sel_hi:[1,0,1]
	s_waitcnt lgkmcnt(0)
; template <int NB>
; __device__ __forceinline__ void sb_decode_task(const Params& P, float* lds, int task) {
;     ...
;     for (int vb = 0; vb < NBT; ++vb) {
;         if (vb + 1 < NBT) {
; #pragma unroll
;             for (int i = 0; i < NB; ++i) nx[i] = *(const float4*)(Vp + (size_t)(4 * NB * (vb + 1) + 4 * i + g) * (SH * HD)); }
; #pragma unroll
;         for (int i = 0; i < NB; ++i) { const float w = wl[4 * NB * vb + 4 * i + g]; o4.x += w * cur[i].x; o4.y += w * cur[i].y; o4.z += w * cur[i].z; o4.w += w * cur[i].w; }
; #pragma unroll
;         for (int i = 0; i < NB; ++i) cur[i] = nx[i];
;     }
	v_mov_b32_e32 v72, v9
	v_pk_fma_f32 v[2:3], v[16:17], v[58:59], v[2:3] op_sel_hi:[1,0,1]
	s_nop 0
	v_pk_fma_f32 v[2:3], v[20:21], v[6:7], v[2:3] op_sel_hi:[1,0,1]
	s_nop 0
	v_pk_fma_f32 v[2:3], v[24:25], v[60:61], v[2:3] op_sel_hi:[1,0,1]
	s_nop 0
	v_pk_fma_f32 v[2:3], v[28:29], v[10:11], v[2:3] op_sel_hi:[1,0,1]
	s_nop 0
	v_pk_fma_f32 v[2:3], v[38:39], v[62:63], v[2:3] op_sel_hi:[1,0,1]
	s_nop 0
	v_pk_fma_f32 v[2:3], v[42:43], v[14:15], v[2:3] op_sel_hi:[1,0,1]
	s_nop 0
	v_pk_fma_f32 v[2:3], v[48:49], v[64:65], v[2:3] op_sel_hi:[1,0,1]
	s_nop 0
	v_pk_fma_f32 v[6:7], v[56:57], v[18:19], v[2:3] op_sel_hi:[1,0,1]
	v_add_co_u32_e32 v2, vcc, s25, v34
	s_nop 1
	v_addc_co_u32_e32 v3, vcc, 0, v35, vcc
	global_load_dwordx4 v[10:13], v[2:3], off nt
	v_add_co_u32_e32 v2, vcc, s43, v34
	s_waitcnt vmcnt(0)
	v_pk_fma_f32 v[10:11], v[10:11], v[8:9], v[54:55] op_sel_hi:[1,0,1]
	v_addc_co_u32_e32 v3, vcc, 0, v35, vcc
	global_load_dwordx4 v[14:17], v[2:3], off offset:2048 nt
	v_add_co_u32_e32 v2, vcc, s80, v34
	ds_read2_b32 v[32:33], v99 offset0:184 offset1:188
	ds_read2_b32 v[50:51], v99 offset0:192 offset1:196
	ds_read2_b32 v[66:67], v99 offset0:200 offset1:204
	ds_read2_b32 v[68:69], v99 offset0:208 offset1:212
	ds_read2_b32 v[70:71], v99 offset0:216 offset1:220
	v_addc_co_u32_e32 v3, vcc, 0, v35, vcc
	v_add_co_u32_e32 v18, vcc, s29, v34
	global_load_dwordx4 v[2:5], v[2:3], off offset:2048 nt
	s_nop 0
	v_addc_co_u32_e32 v19, vcc, 0, v35, vcc
	v_add_co_u32_e32 v22, vcc, s68, v34
	global_load_dwordx4 v[18:21], v[18:19], off nt
	s_nop 0
	v_addc_co_u32_e32 v23, vcc, 0, v35, vcc
	v_add_co_u32_e32 v26, vcc, s69, v34
	global_load_dwordx4 v[22:25], v[22:23], off offset:2048 nt
	s_nop 0
	v_addc_co_u32_e32 v27, vcc, 0, v35, vcc
	v_add_co_u32_e32 v36, vcc, s70, v34
	global_load_dwordx4 v[26:29], v[26:27], off nt
	s_nop 0
	v_addc_co_u32_e32 v37, vcc, 0, v35, vcc
	v_add_co_u32_e32 v40, vcc, s71, v34
	global_load_dwordx4 v[36:39], v[36:37], off offset:2048 nt
	s_nop 0
	v_addc_co_u32_e32 v41, vcc, 0, v35, vcc
	v_add_co_u32_e32 v46, vcc, s72, v34
	global_load_dwordx4 v[40:43], v[40:41], off nt
	s_nop 0
	v_addc_co_u32_e32 v47, vcc, 0, v35, vcc
	global_load_dwordx4 v[46:49], v[46:47], off offset:2048 nt
	v_pk_fma_f32 v[6:7], v[12:13], v[8:9], v[6:7] op_sel_hi:[1,0,1]
	s_waitcnt lgkmcnt(4)
	v_mov_b32_e32 v74, v33
	s_waitcnt lgkmcnt(0)
	v_mov_b32_e32 v30, v71
	s_waitcnt vmcnt(7)
	v_pk_fma_f32 v[10:11], v[14:15], v[72:73], v[10:11] op_sel_hi:[1,0,1]
	v_add_co_u32_e32 v14, vcc, s73, v34
	v_pk_fma_f32 v[6:7], v[16:17], v[72:73], v[6:7] op_sel_hi:[1,0,1]
	s_nop 0
	v_addc_co_u32_e32 v15, vcc, 0, v35, vcc
	global_load_dwordx4 v[54:57], v[14:15], off nt
	v_add_co_u32_e32 v14, vcc, s74, v34
	s_nop 1
	v_addc_co_u32_e32 v15, vcc, 0, v35, vcc
	global_load_dwordx4 v[58:61], v[14:15], off offset:2048 nt
	v_add_co_u32_e32 v14, vcc, s75, v34
	s_nop 1
	v_addc_co_u32_e32 v15, vcc, 0, v35, vcc
	global_load_dwordx4 v[62:65], v[14:15], off nt
	s_waitcnt vmcnt(8)
	v_pk_fma_f32 v[6:7], v[20:21], v[32:33], v[6:7] op_sel_hi:[1,0,1]
	v_pk_fma_f32 v[10:11], v[18:19], v[32:33], v[10:11] op_sel_hi:[1,0,1]
	s_waitcnt vmcnt(7)
	v_pk_fma_f32 v[6:7], v[24:25], v[74:75], v[6:7] op_sel_hi:[1,0,1]
	v_mov_b32_e32 v14, v51
	s_waitcnt vmcnt(6)
	v_pk_fma_f32 v[6:7], v[28:29], v[50:51], v[6:7] op_sel_hi:[1,0,1]
	v_pk_fma_f32 v[10:11], v[22:23], v[74:75], v[10:11] op_sel_hi:[1,0,1]
	v_mov_b32_e32 v18, v67
	v_pk_fma_f32 v[10:11], v[26:27], v[50:51], v[10:11] op_sel_hi:[1,0,1]
	v_mov_b32_e32 v22, v69
	s_waitcnt vmcnt(5)
	v_pk_fma_f32 v[6:7], v[38:39], v[14:15], v[6:7] op_sel_hi:[1,0,1]
	v_pk_fma_f32 v[10:11], v[36:37], v[14:15], v[10:11] op_sel_hi:[1,0,1]
	ds_read2_b32 v[38:39], v99 offset0:224 offset1:228
	ds_read2_b32 v[32:33], v99 offset0:232 offset1:236
	s_waitcnt vmcnt(4)
	v_pk_fma_f32 v[6:7], v[42:43], v[66:67], v[6:7] op_sel_hi:[1,0,1]
	v_pk_fma_f32 v[10:11], v[40:41], v[66:67], v[10:11] op_sel_hi:[1,0,1]
	s_waitcnt vmcnt(3)
; template <int NB>
; __device__ __forceinline__ void sb_decode_task(const Params& P, float* lds, int task) {
;     ...
;     for (int vb = 0; vb < NBT; ++vb) {
;         if (vb + 1 < NBT) {
; #pragma unroll
;             for (int i = 0; i < NB; ++i) nx[i] = *(const float4*)(Vp + (size_t)(4 * NB * (vb + 1) + 4 * i + g) * (SH * HD)); }
; #pragma unroll
;         for (int i = 0; i < NB; ++i) { const float w = wl[4 * NB * vb + 4 * i + g]; o4.x += w * cur[i].x; o4.y += w * cur[i].y; o4.z += w * cur[i].z; o4.w += w * cur[i].w; }
; #pragma unroll
;         for (int i = 0; i < NB; ++i) cur[i] = nx[i];
;     }
; #pragma unroll
;     for (int off = 16; off < 64; off <<= 1) { o4.x += __shfl_xor(o4.x, off); o4.y += __shfl_xor(o4.y, off); o4.z += __shfl_xor(o4.z, off); o4.w += __shfl_xor(o4.w, off); }
;     if (g == 0) *(float4*)(dpart + (size_t)task * HD + 4 * c) = o4;
;     if (lane == 0) dl[task] = Ltot;
	v_pk_fma_f32 v[6:7], v[48:49], v[18:19], v[6:7] op_sel_hi:[1,0,1]
	v_pk_fma_f32 v[10:11], v[46:47], v[18:19], v[10:11] op_sel_hi:[1,0,1]
	s_waitcnt vmcnt(2)
	v_pk_fma_f32 v[6:7], v[56:57], v[68:69], v[6:7] op_sel_hi:[1,0,1]
	v_pk_fma_f32 v[10:11], v[54:55], v[68:69], v[10:11] op_sel_hi:[1,0,1]
	s_waitcnt vmcnt(1)
	v_pk_fma_f32 v[6:7], v[60:61], v[22:23], v[6:7] op_sel_hi:[1,0,1]
	v_pk_fma_f32 v[10:11], v[58:59], v[22:23], v[10:11] op_sel_hi:[1,0,1]
	s_waitcnt vmcnt(0)
	v_pk_fma_f32 v[36:37], v[64:65], v[70:71], v[6:7] op_sel_hi:[1,0,1]
	v_add_co_u32_e32 v6, vcc, s81, v34
	v_pk_fma_f32 v[26:27], v[62:63], v[70:71], v[10:11] op_sel_hi:[1,0,1]
	s_nop 0
	v_addc_co_u32_e32 v7, vcc, 0, v35, vcc
	v_add_co_u32_e32 v10, vcc, s82, v34
	global_load_dwordx4 v[6:9], v[6:7], off nt
	s_nop 0
	v_addc_co_u32_e32 v11, vcc, 0, v35, vcc
	v_add_co_u32_e32 v14, vcc, s83, v34
	ds_read2_b32 v[42:43], v99 offset0:240 offset1:244
	ds_read2_b32 v[40:41], v99 offset0:248 offset1:252
	v_addc_co_u32_e32 v15, vcc, 0, v35, vcc
	v_add_co_u32_e32 v18, vcc, s84, v34
	global_load_dwordx4 v[10:13], v[10:11], off offset:2048 nt
	s_nop 0
	v_addc_co_u32_e32 v19, vcc, 0, v35, vcc
	v_add_co_u32_e32 v22, vcc, s85, v34
	v_pk_fma_f32 v[2:3], v[2:3], v[30:31], v[26:27] op_sel_hi:[1,0,1]
	s_nop 0
	v_addc_co_u32_e32 v23, vcc, 0, v35, vcc
	v_add_co_u32_e32 v26, vcc, s86, v34
	global_load_dwordx4 v[14:17], v[14:15], off nt
	s_nop 0
	v_addc_co_u32_e32 v27, vcc, 0, v35, vcc
	global_load_dwordx4 v[18:21], v[18:19], off offset:2048 nt
	v_add_co_u32_e32 v46, vcc, s87, v34
	global_load_dwordx4 v[22:25], v[22:23], off nt
	s_nop 0
	v_addc_co_u32_e32 v47, vcc, 0, v35, vcc
	global_load_dwordx4 v[26:29], v[26:27], off offset:2048 nt
	v_add_co_u32_e32 v34, vcc, s88, v34
	global_load_dwordx4 v[46:49], v[46:47], off nt
	s_nop 0
	v_addc_co_u32_e32 v35, vcc, 0, v35, vcc
	global_load_dwordx4 v[54:57], v[34:35], off offset:2048 nt
	v_pk_fma_f32 v[4:5], v[4:5], v[30:31], v[36:37] op_sel_hi:[1,0,1]
	s_waitcnt vmcnt(7) lgkmcnt(3)
	v_pk_fma_f32 v[2:3], v[6:7], v[38:39], v[2:3] op_sel_hi:[1,0,1]
	v_mov_b32_e32 v6, v39
	v_pk_fma_f32 v[4:5], v[8:9], v[38:39], v[4:5] op_sel_hi:[1,0,1]
	s_waitcnt vmcnt(6)
	v_pk_fma_f32 v[2:3], v[10:11], v[6:7], v[2:3] op_sel_hi:[1,0,1]
	v_pk_fma_f32 v[4:5], v[12:13], v[6:7], v[4:5] op_sel_hi:[1,0,1]
	s_waitcnt lgkmcnt(2)
	v_mov_b32_e32 v10, v33
	s_waitcnt vmcnt(5)
	v_pk_fma_f32 v[2:3], v[14:15], v[32:33], v[2:3] op_sel_hi:[1,0,1]
	v_pk_fma_f32 v[4:5], v[16:17], v[32:33], v[4:5] op_sel_hi:[1,0,1]
	s_waitcnt lgkmcnt(1)
	v_mov_b32_e32 v14, v43
	s_waitcnt vmcnt(4)
	v_pk_fma_f32 v[2:3], v[18:19], v[10:11], v[2:3] op_sel_hi:[1,0,1]
	v_pk_fma_f32 v[4:5], v[20:21], v[10:11], v[4:5] op_sel_hi:[1,0,1]
	s_waitcnt lgkmcnt(0)
	v_mov_b32_e32 v18, v41
	s_waitcnt vmcnt(3)
	v_pk_fma_f32 v[2:3], v[22:23], v[42:43], v[2:3] op_sel_hi:[1,0,1]
	v_pk_fma_f32 v[4:5], v[24:25], v[42:43], v[4:5] op_sel_hi:[1,0,1]
	ds_bpermute_b32 v10, v44, v31
	s_waitcnt vmcnt(2)
	v_pk_fma_f32 v[2:3], v[26:27], v[14:15], v[2:3] op_sel_hi:[1,0,1]
	v_pk_fma_f32 v[4:5], v[28:29], v[14:15], v[4:5] op_sel_hi:[1,0,1]
	s_waitcnt vmcnt(1)
	v_pk_fma_f32 v[2:3], v[46:47], v[40:41], v[2:3] op_sel_hi:[1,0,1]
	v_pk_fma_f32 v[4:5], v[48:49], v[40:41], v[4:5] op_sel_hi:[1,0,1]
	s_waitcnt vmcnt(0)
	v_pk_fma_f32 v[2:3], v[54:55], v[18:19], v[2:3] op_sel_hi:[1,0,1]
	v_pk_fma_f32 v[4:5], v[56:57], v[18:19], v[4:5] op_sel_hi:[1,0,1]
	ds_bpermute_b32 v22, v45, v2
	ds_bpermute_b32 v23, v45, v3
	ds_bpermute_b32 v6, v45, v4
	ds_bpermute_b32 v7, v45, v5
	s_waitcnt lgkmcnt(2)
	v_pk_add_f32 v[2:3], v[2:3], v[22:23]
	s_waitcnt lgkmcnt(0)
	v_pk_add_f32 v[4:5], v[4:5], v[6:7]
	ds_bpermute_b32 v6, v52, v2
	ds_bpermute_b32 v7, v52, v3
	ds_bpermute_b32 v8, v52, v4
	ds_bpermute_b32 v9, v52, v5
	s_and_saveexec_b64 s[0:1], s[20:21]
	s_cbranch_execz .LBB0_1553
	s_ashr_i32 s35, s34, 31
	s_lshl_b64 s[2:3], s[34:35], 8
	v_lshl_add_u64 v[12:13], v[88:89], 0, s[2:3]
	s_waitcnt lgkmcnt(2)
	v_pk_add_f32 v[2:3], v[2:3], v[6:7]
	s_waitcnt lgkmcnt(0)
	v_pk_add_f32 v[4:5], v[4:5], v[8:9]
	global_store_dwordx4 v[12:13], v[2:5], off
